# st_pair permlane exchange with the placeholder nops dropped and hazard wait states re-derived from the gfx950 tables (78 states inserted)
# speedup vs baseline: 1.0007x; 1.0007x over previous
.LBB0_147:
	s_waitcnt lgkmcnt(0)
	s_barrier
	ds_read_b128 v[224:227], v184
	ds_read_b128 v[228:231], v184 offset:1024
	ds_read_b128 v[232:235], v184 offset:2048
	ds_read_b128 v[236:239], v184 offset:3072
	ds_read_b128 v[190:193], v185
	ds_read_b128 v[194:197], v185 offset:1024
	ds_read_b128 v[198:201], v185 offset:2048
	ds_read_b128 v[204:207], v185 offset:3072
	ds_read_b128 v[208:211], v185 offset:4096
	ds_read_b128 v[212:215], v185 offset:5120
	ds_read_b128 v[216:219], v185 offset:6144
	ds_read_b128 v[220:223], v185 offset:7168
	s_movk_i32 vcc_lo, 0x6000
	s_cmp_eq_u32 m0, 2
	s_cselect_b32 vcc_lo, 0xffff4000, vcc_lo
	s_add_u32 m0, m0, 1
	s_cmp_eq_u32 m0, 3
	s_cselect_b32 m0, 0, m0
	v_add_u32_e32 v185, vcc_lo, v185
	v_add_u32_e32 v184, vcc_lo, v184
	v_xor_b32_e32 v185, 64, v185
	v_xor_b32_e32 v184, 64, v184
	s_waitcnt lgkmcnt(7)
	v_mfma_f32_16x16x32_bf16 v[172:175], v[224:227], v[190:193], v[172:175]
	v_mfma_f32_16x16x32_bf16 v[168:171], v[228:231], v[190:193], v[168:171]
	v_mfma_f32_16x16x32_bf16 v[164:167], v[232:235], v[190:193], v[164:167]
	v_mfma_f32_16x16x32_bf16 v[160:163], v[236:239], v[190:193], v[160:163]
	ds_read_b128 v[190:193], v185
	s_waitcnt lgkmcnt(7)
	v_mfma_f32_16x16x32_bf16 v[156:159], v[224:227], v[194:197], v[156:159]
	v_mfma_f32_16x16x32_bf16 v[152:155], v[228:231], v[194:197], v[152:155]
	v_mfma_f32_16x16x32_bf16 v[148:151], v[232:235], v[194:197], v[148:151]
	v_mfma_f32_16x16x32_bf16 v[144:147], v[236:239], v[194:197], v[144:147]
	ds_read_b128 v[194:197], v185 offset:1024
	s_waitcnt lgkmcnt(7)
	v_mfma_f32_16x16x32_bf16 v[136:139], v[224:227], v[198:201], v[136:139]
	v_mfma_f32_16x16x32_bf16 v[132:135], v[228:231], v[198:201], v[132:135]
	v_mfma_f32_16x16x32_bf16 v[128:131], v[232:235], v[198:201], v[128:131]
	v_mfma_f32_16x16x32_bf16 v[124:127], v[236:239], v[198:201], v[124:127]
	ds_read_b128 v[198:201], v185 offset:2048
	s_waitcnt lgkmcnt(7)
	v_mfma_f32_16x16x32_bf16 v[120:123], v[224:227], v[204:207], v[120:123]
	v_mfma_f32_16x16x32_bf16 v[108:111], v[228:231], v[204:207], v[108:111]
	v_mfma_f32_16x16x32_bf16 v[100:103], v[232:235], v[204:207], v[100:103]
	v_mfma_f32_16x16x32_bf16 v[96:99], v[236:239], v[204:207], v[96:99]
	ds_read_b128 v[204:207], v185 offset:3072
	s_waitcnt lgkmcnt(7)
	v_mfma_f32_16x16x32_bf16 v[92:95], v[224:227], v[208:211], v[92:95]
	v_mfma_f32_16x16x32_bf16 v[84:87], v[228:231], v[208:211], v[84:87]
	v_mfma_f32_16x16x32_bf16 v[76:79], v[232:235], v[208:211], v[76:79]
	v_mfma_f32_16x16x32_bf16 v[72:75], v[236:239], v[208:211], v[72:75]
	ds_read_b128 v[208:211], v185 offset:4096
	s_waitcnt lgkmcnt(7)
	v_mfma_f32_16x16x32_bf16 v[64:67], v[224:227], v[212:215], v[64:67]
	v_mfma_f32_16x16x32_bf16 v[52:55], v[228:231], v[212:215], v[52:55]
	v_mfma_f32_16x16x32_bf16 v[48:51], v[232:235], v[212:215], v[48:51]
	v_mfma_f32_16x16x32_bf16 v[44:47], v[236:239], v[212:215], v[44:47]
	ds_read_b128 v[212:215], v185 offset:5120
	s_waitcnt lgkmcnt(7)
	v_mfma_f32_16x16x32_bf16 v[36:39], v[224:227], v[216:219], v[36:39]
	v_mfma_f32_16x16x32_bf16 v[28:31], v[228:231], v[216:219], v[28:31]
	v_mfma_f32_16x16x32_bf16 v[24:27], v[232:235], v[216:219], v[24:27]
	v_mfma_f32_16x16x32_bf16 v[20:23], v[236:239], v[216:219], v[20:23]
	ds_read_b128 v[216:219], v185 offset:6144
	s_waitcnt lgkmcnt(7)
	v_mfma_f32_16x16x32_bf16 v[12:15], v[224:227], v[220:223], v[12:15]
	v_mfma_f32_16x16x32_bf16 v[4:7], v[228:231], v[220:223], v[4:7]
	v_mfma_f32_16x16x32_bf16 v[0:3], v[232:235], v[220:223], v[0:3]
	v_mfma_f32_16x16x32_bf16 v[140:143], v[236:239], v[220:223], v[140:143]
	ds_read_b128 v[220:223], v185 offset:7168
	ds_read_b128 v[224:227], v184
	ds_read_b128 v[228:231], v184 offset:1024
	ds_read_b128 v[232:235], v184 offset:2048
	ds_read_b128 v[236:239], v184 offset:3072
	s_movk_i32 vcc_lo, 0x6000
	s_cmp_eq_u32 m0, 2
	s_cselect_b32 vcc_lo, 0xffff4000, vcc_lo
	s_add_u32 m0, m0, 1
	s_cmp_eq_u32 m0, 3
	s_cselect_b32 m0, 0, m0
	v_add_u32_e32 v185, vcc_lo, v185
	v_add_u32_e32 v184, vcc_lo, v184
	v_xor_b32_e32 v185, 64, v185
	v_xor_b32_e32 v184, 64, v184
	s_sub_u32 vcc_lo, s8, s98
	v_add_u32_e32 v186, vcc_lo, v178
	v_add_u32_e32 v187, vcc_lo, v180
	s_barrier
	s_waitcnt lgkmcnt(0)
	v_mfma_f32_16x16x32_bf16 v[172:175], v[224:227], v[190:193], v[172:175]
	s_waitcnt vmcnt(11)
	v_mfma_f32_16x16x32_bf16 v[168:171], v[228:231], v[190:193], v[168:171]
	ds_write_b128 v183, v[116:119]
	v_add_u32_e32 v116, s26, v187
	v_mfma_f32_16x16x32_bf16 v[164:167], v[232:235], v[190:193], v[164:167]
	global_load_dwordx4 v[116:119], v116, s[98:99] offset:128
	v_mfma_f32_16x16x32_bf16 v[160:163], v[236:239], v[190:193], v[160:163]
	s_waitcnt vmcnt(11)
	ds_write_b128 v183, v[112:115] offset:2048
	v_mfma_f32_16x16x32_bf16 v[156:159], v[224:227], v[194:197], v[156:159]
	v_add_u32_e32 v112, s27, v187
	v_mfma_f32_16x16x32_bf16 v[152:155], v[228:231], v[194:197], v[152:155]
	global_load_dwordx4 v[112:115], v112, s[98:99] offset:128
	s_waitcnt vmcnt(11)
	v_mfma_f32_16x16x32_bf16 v[148:151], v[232:235], v[194:197], v[148:151]
	ds_write_b128 v183, v[104:107] offset:4096
	v_mfma_f32_16x16x32_bf16 v[144:147], v[236:239], v[194:197], v[144:147]
	v_add_u32_e32 v104, s20, v187
	global_load_dwordx4 v[104:107], v104, s[98:99] offset:128
	v_mfma_f32_16x16x32_bf16 v[136:139], v[224:227], v[198:201], v[136:139]
	s_waitcnt vmcnt(11)
	v_mfma_f32_16x16x32_bf16 v[132:135], v[228:231], v[198:201], v[132:135]
	ds_write_b128 v183, v[88:91] offset:6144
	v_add_u32_e32 v88, s21, v187
	v_mfma_f32_16x16x32_bf16 v[128:131], v[232:235], v[198:201], v[128:131]
	global_load_dwordx4 v[88:91], v88, s[98:99] offset:128
	v_mfma_f32_16x16x32_bf16 v[124:127], v[236:239], v[198:201], v[124:127]
	s_waitcnt vmcnt(11)
	ds_write_b128 v183, v[80:83] offset:8192
	v_mfma_f32_16x16x32_bf16 v[120:123], v[224:227], v[204:207], v[120:123]
	v_add_u32_e32 v80, s56, v187
	v_mfma_f32_16x16x32_bf16 v[108:111], v[228:231], v[204:207], v[108:111]
	global_load_dwordx4 v[80:83], v80, s[98:99] offset:128
	s_waitcnt vmcnt(11)
	v_mfma_f32_16x16x32_bf16 v[100:103], v[232:235], v[204:207], v[100:103]
	ds_write_b128 v183, v[68:71] offset:10240
	v_mfma_f32_16x16x32_bf16 v[96:99], v[236:239], v[204:207], v[96:99]
	v_add_u32_e32 v68, s57, v187
	global_load_dwordx4 v[68:71], v68, s[98:99] offset:128
	v_mfma_f32_16x16x32_bf16 v[92:95], v[224:227], v[208:211], v[92:95]
	s_waitcnt vmcnt(11)
	v_mfma_f32_16x16x32_bf16 v[84:87], v[228:231], v[208:211], v[84:87]
	ds_write_b128 v183, v[60:63] offset:12288
	v_add_u32_e32 v60, s24, v187
	v_mfma_f32_16x16x32_bf16 v[76:79], v[232:235], v[208:211], v[76:79]
	global_load_dwordx4 v[60:63], v60, s[98:99] offset:128
	v_mfma_f32_16x16x32_bf16 v[72:75], v[236:239], v[208:211], v[72:75]
	s_waitcnt vmcnt(11)
	ds_write_b128 v183, v[40:43] offset:14336
	v_mfma_f32_16x16x32_bf16 v[64:67], v[224:227], v[212:215], v[64:67]
	v_add_u32_e32 v40, s96, v187
	v_mfma_f32_16x16x32_bf16 v[52:55], v[228:231], v[212:215], v[52:55]
	global_load_dwordx4 v[40:43], v40, s[98:99] offset:128
	s_waitcnt vmcnt(11)
	v_mfma_f32_16x16x32_bf16 v[48:51], v[232:235], v[212:215], v[48:51]
	ds_write_b128 v183, v[56:59] offset:16384
	v_mfma_f32_16x16x32_bf16 v[44:47], v[236:239], v[212:215], v[44:47]
	v_mov_b32_e32 v56, v186
	global_load_dwordx4 v[56:59], v56, s[98:99] offset:128
	v_mfma_f32_16x16x32_bf16 v[36:39], v[224:227], v[216:219], v[36:39]
	s_waitcnt vmcnt(11)
	v_mfma_f32_16x16x32_bf16 v[28:31], v[228:231], v[216:219], v[28:31]
	ds_write_b128 v183, v[32:35] offset:18432
	v_add_u32_e32 v32, s31, v186
	v_mfma_f32_16x16x32_bf16 v[24:27], v[232:235], v[216:219], v[24:27]
	global_load_dwordx4 v[32:35], v32, s[98:99] offset:128
	v_mfma_f32_16x16x32_bf16 v[20:23], v[236:239], v[216:219], v[20:23]
	s_waitcnt vmcnt(11)
	ds_write_b128 v183, v[16:19] offset:20480
	v_mfma_f32_16x16x32_bf16 v[12:15], v[224:227], v[220:223], v[12:15]
	v_add_u32_e32 v16, s14, v186
	v_mfma_f32_16x16x32_bf16 v[4:7], v[228:231], v[220:223], v[4:7]
	global_load_dwordx4 v[16:19], v16, s[98:99] offset:128
	s_waitcnt vmcnt(11)
	v_mfma_f32_16x16x32_bf16 v[0:3], v[232:235], v[220:223], v[0:3]
	ds_write_b128 v183, v[8:11] offset:22528
	v_mfma_f32_16x16x32_bf16 v[140:143], v[236:239], v[220:223], v[140:143]
	v_add_u32_e32 v8, s13, v186
	global_load_dwordx4 v[8:11], v8, s[98:99] offset:128
	v_cmp_gt_u32_e32 vcc, 0x6000, v183
	v_add_u32_e32 v182, 0xc000, v183
	v_add_u32_e32 v183, 0xffffa000, v183
	s_nop 0
	v_cndmask_b32_e32 v183, v183, v182, vcc
	s_add_u32 s8, s8, 0x80
	s_addc_u32 s9, s9, 0
	s_cmpk_lg_i32 s8, 0x780
	s_cbranch_scc1 .LBB0_147
	s_waitcnt lgkmcnt(0)
	s_barrier
	ds_read_b128 v[224:227], v184
	ds_read_b128 v[228:231], v184 offset:1024
	ds_read_b128 v[232:235], v184 offset:2048
	ds_read_b128 v[236:239], v184 offset:3072
	ds_read_b128 v[190:193], v185
	ds_read_b128 v[194:197], v185 offset:1024
	ds_read_b128 v[198:201], v185 offset:2048
	ds_read_b128 v[204:207], v185 offset:3072
	ds_read_b128 v[208:211], v185 offset:4096
	ds_read_b128 v[212:215], v185 offset:5120
	ds_read_b128 v[216:219], v185 offset:6144
	ds_read_b128 v[220:223], v185 offset:7168
	s_movk_i32 vcc_lo, 0x6000
	s_cmp_eq_u32 m0, 2
	s_cselect_b32 vcc_lo, 0xffff4000, vcc_lo
	s_add_u32 m0, m0, 1
	s_cmp_eq_u32 m0, 3
	s_cselect_b32 m0, 0, m0
	v_add_u32_e32 v185, vcc_lo, v185
	v_add_u32_e32 v184, vcc_lo, v184
	v_xor_b32_e32 v185, 64, v185
	v_xor_b32_e32 v184, 64, v184
	s_waitcnt lgkmcnt(7)
	v_mfma_f32_16x16x32_bf16 v[172:175], v[224:227], v[190:193], v[172:175]
	v_mfma_f32_16x16x32_bf16 v[168:171], v[228:231], v[190:193], v[168:171]
	v_mfma_f32_16x16x32_bf16 v[164:167], v[232:235], v[190:193], v[164:167]
	v_mfma_f32_16x16x32_bf16 v[160:163], v[236:239], v[190:193], v[160:163]
	ds_read_b128 v[190:193], v185
	s_waitcnt lgkmcnt(7)
	v_mfma_f32_16x16x32_bf16 v[156:159], v[224:227], v[194:197], v[156:159]
	v_mfma_f32_16x16x32_bf16 v[152:155], v[228:231], v[194:197], v[152:155]
	v_mfma_f32_16x16x32_bf16 v[148:151], v[232:235], v[194:197], v[148:151]
	v_mfma_f32_16x16x32_bf16 v[144:147], v[236:239], v[194:197], v[144:147]
	ds_read_b128 v[194:197], v185 offset:1024
	s_waitcnt lgkmcnt(7)
	v_mfma_f32_16x16x32_bf16 v[136:139], v[224:227], v[198:201], v[136:139]
	v_mfma_f32_16x16x32_bf16 v[132:135], v[228:231], v[198:201], v[132:135]
	v_mfma_f32_16x16x32_bf16 v[128:131], v[232:235], v[198:201], v[128:131]
	v_mfma_f32_16x16x32_bf16 v[124:127], v[236:239], v[198:201], v[124:127]
	ds_read_b128 v[198:201], v185 offset:2048
	s_waitcnt lgkmcnt(7)
	v_mfma_f32_16x16x32_bf16 v[120:123], v[224:227], v[204:207], v[120:123]
	v_mfma_f32_16x16x32_bf16 v[108:111], v[228:231], v[204:207], v[108:111]
	v_mfma_f32_16x16x32_bf16 v[100:103], v[232:235], v[204:207], v[100:103]
	v_mfma_f32_16x16x32_bf16 v[96:99], v[236:239], v[204:207], v[96:99]
	ds_read_b128 v[204:207], v185 offset:3072
	s_waitcnt lgkmcnt(7)
	v_mfma_f32_16x16x32_bf16 v[92:95], v[224:227], v[208:211], v[92:95]
	v_mfma_f32_16x16x32_bf16 v[84:87], v[228:231], v[208:211], v[84:87]
	v_mfma_f32_16x16x32_bf16 v[76:79], v[232:235], v[208:211], v[76:79]
	v_mfma_f32_16x16x32_bf16 v[72:75], v[236:239], v[208:211], v[72:75]
	ds_read_b128 v[208:211], v185 offset:4096
	s_waitcnt lgkmcnt(7)
	v_mfma_f32_16x16x32_bf16 v[64:67], v[224:227], v[212:215], v[64:67]
	v_mfma_f32_16x16x32_bf16 v[52:55], v[228:231], v[212:215], v[52:55]
	v_mfma_f32_16x16x32_bf16 v[48:51], v[232:235], v[212:215], v[48:51]
	v_mfma_f32_16x16x32_bf16 v[44:47], v[236:239], v[212:215], v[44:47]
	ds_read_b128 v[212:215], v185 offset:5120
	s_waitcnt lgkmcnt(7)
	v_mfma_f32_16x16x32_bf16 v[36:39], v[224:227], v[216:219], v[36:39]
	v_mfma_f32_16x16x32_bf16 v[28:31], v[228:231], v[216:219], v[28:31]
	v_mfma_f32_16x16x32_bf16 v[24:27], v[232:235], v[216:219], v[24:27]
	v_mfma_f32_16x16x32_bf16 v[20:23], v[236:239], v[216:219], v[20:23]
	ds_read_b128 v[216:219], v185 offset:6144
	s_waitcnt lgkmcnt(7)
	v_mfma_f32_16x16x32_bf16 v[12:15], v[224:227], v[220:223], v[12:15]
	v_mfma_f32_16x16x32_bf16 v[4:7], v[228:231], v[220:223], v[4:7]
	v_mfma_f32_16x16x32_bf16 v[0:3], v[232:235], v[220:223], v[0:3]
	v_mfma_f32_16x16x32_bf16 v[140:143], v[236:239], v[220:223], v[140:143]
	ds_read_b128 v[220:223], v185 offset:7168
	ds_read_b128 v[224:227], v184
	ds_read_b128 v[228:231], v184 offset:1024
	ds_read_b128 v[232:235], v184 offset:2048
	ds_read_b128 v[236:239], v184 offset:3072
	s_movk_i32 vcc_lo, 0x6000
	s_cmp_eq_u32 m0, 2
	s_cselect_b32 vcc_lo, 0xffff4000, vcc_lo
	s_add_u32 m0, m0, 1
	s_cmp_eq_u32 m0, 3
	s_cselect_b32 m0, 0, m0
	v_add_u32_e32 v185, vcc_lo, v185
	v_add_u32_e32 v184, vcc_lo, v184
	v_xor_b32_e32 v185, 64, v185
	v_xor_b32_e32 v184, 64, v184
	s_waitcnt lgkmcnt(0)
	v_mfma_f32_16x16x32_bf16 v[172:175], v[224:227], v[190:193], v[172:175]
	v_mfma_f32_16x16x32_bf16 v[168:171], v[228:231], v[190:193], v[168:171]
	v_mfma_f32_16x16x32_bf16 v[164:167], v[232:235], v[190:193], v[164:167]
	v_mfma_f32_16x16x32_bf16 v[160:163], v[236:239], v[190:193], v[160:163]
	v_mfma_f32_16x16x32_bf16 v[156:159], v[224:227], v[194:197], v[156:159]
	v_mfma_f32_16x16x32_bf16 v[152:155], v[228:231], v[194:197], v[152:155]
	v_mfma_f32_16x16x32_bf16 v[148:151], v[232:235], v[194:197], v[148:151]
	v_mfma_f32_16x16x32_bf16 v[144:147], v[236:239], v[194:197], v[144:147]
	v_mfma_f32_16x16x32_bf16 v[136:139], v[224:227], v[198:201], v[136:139]
	v_mfma_f32_16x16x32_bf16 v[132:135], v[228:231], v[198:201], v[132:135]
	v_mfma_f32_16x16x32_bf16 v[128:131], v[232:235], v[198:201], v[128:131]
	v_mfma_f32_16x16x32_bf16 v[124:127], v[236:239], v[198:201], v[124:127]
	v_mfma_f32_16x16x32_bf16 v[120:123], v[224:227], v[204:207], v[120:123]
	v_mfma_f32_16x16x32_bf16 v[108:111], v[228:231], v[204:207], v[108:111]
	v_mfma_f32_16x16x32_bf16 v[100:103], v[232:235], v[204:207], v[100:103]
	v_mfma_f32_16x16x32_bf16 v[96:99], v[236:239], v[204:207], v[96:99]
	v_mfma_f32_16x16x32_bf16 v[92:95], v[224:227], v[208:211], v[92:95]
	v_mfma_f32_16x16x32_bf16 v[84:87], v[228:231], v[208:211], v[84:87]
	v_mfma_f32_16x16x32_bf16 v[76:79], v[232:235], v[208:211], v[76:79]
	v_mfma_f32_16x16x32_bf16 v[72:75], v[236:239], v[208:211], v[72:75]
	v_mfma_f32_16x16x32_bf16 v[64:67], v[224:227], v[212:215], v[64:67]
	v_mfma_f32_16x16x32_bf16 v[52:55], v[228:231], v[212:215], v[52:55]
	v_mfma_f32_16x16x32_bf16 v[48:51], v[232:235], v[212:215], v[48:51]
	v_mfma_f32_16x16x32_bf16 v[44:47], v[236:239], v[212:215], v[44:47]
	v_mfma_f32_16x16x32_bf16 v[36:39], v[224:227], v[216:219], v[36:39]
	v_mfma_f32_16x16x32_bf16 v[28:31], v[228:231], v[216:219], v[28:31]
	v_mfma_f32_16x16x32_bf16 v[24:27], v[232:235], v[216:219], v[24:27]
	v_mfma_f32_16x16x32_bf16 v[20:23], v[236:239], v[216:219], v[20:23]
	v_mfma_f32_16x16x32_bf16 v[12:15], v[224:227], v[220:223], v[12:15]
	v_mfma_f32_16x16x32_bf16 v[4:7], v[228:231], v[220:223], v[4:7]
	v_mfma_f32_16x16x32_bf16 v[0:3], v[232:235], v[220:223], v[0:3]
	v_mfma_f32_16x16x32_bf16 v[140:143], v[236:239], v[220:223], v[140:143]
	v_lshrrev_b32_e32 v224, 4, v188
	v_and_b32_e32 v225, 7, v188
	v_bitop3_b32 v226, v224, v225, 3 bitop3:0x6c
	v_lshlrev_b32_e32 v227, 7, v188
	v_bfe_u32 v228, v188, 4, 2
	v_and_b32_e32 v229, 0xffffc780, v227
	v_and_b32_e32 v227, 0x2780, v227
	v_bitop3_b32 v228, v228, v225, 4 bitop3:0x36
	v_lshlrev_b32_e32 v226, 4, v226
	v_lshlrev_b32_e32 v228, 4, v228
	v_or_b32_e32 v185, v229, v226
	v_or_b32_e32 v184, v227, v226
	v_or_b32_e32 v183, v229, v228
	v_or_b32_e32 v182, v227, v228
	s_waitcnt vmcnt(0)
	s_barrier
	s_waitcnt vmcnt(10)
	ds_write_b128 v176, v[116:119]
	s_waitcnt vmcnt(9)
	ds_write_b128 v176, v[112:115] offset:4096
	s_waitcnt vmcnt(8)
	ds_write_b128 v176, v[104:107] offset:8192
	s_waitcnt vmcnt(7)
	ds_write_b128 v176, v[88:91] offset:12288
	s_waitcnt vmcnt(6)
	ds_write_b128 v176, v[80:83] offset:16384
	s_waitcnt vmcnt(5)
	ds_write_b128 v176, v[68:71] offset:20480
	s_waitcnt vmcnt(4)
	ds_write_b128 v176, v[60:63] offset:24576
	s_waitcnt vmcnt(3)
	ds_write_b128 v176, v[40:43] offset:28672
	ds_write_b128 v176, v[56:59] offset:32768
	s_waitcnt vmcnt(2)
	ds_write_b128 v176, v[32:35] offset:36864
	s_waitcnt vmcnt(1)
	ds_write_b128 v176, v[16:19] offset:40960
	s_waitcnt vmcnt(0)
	ds_write_b128 v176, v[8:11] offset:45056
	s_waitcnt lgkmcnt(0)
	s_barrier
	ds_read_b128 v[8:11], v185
	ds_read_b128 v[16:19], v185 offset:2048
	ds_read_b128 v[32:35], v185 offset:4096
	ds_read_b128 v[40:43], v185 offset:6144
	ds_read_b128 v[56:59], v185 offset:8192
	ds_read_b128 v[60:63], v185 offset:10240
	ds_read_b128 v[68:71], v185 offset:12288
	ds_read_b128 v[80:83], v185 offset:14336
	ds_read_b128 v[88:91], v184 offset:32768
	ds_read_b128 v[104:107], v184 offset:34816
	ds_read_b128 v[112:115], v184 offset:36864
	ds_read_b128 v[116:119], v184 offset:38912
	s_waitcnt lgkmcnt(3)
	v_mfma_f32_16x16x32_bf16 v[172:175], v[88:91], v[8:11], v[172:175]
	s_waitcnt lgkmcnt(2)
	v_mfma_f32_16x16x32_bf16 v[168:171], v[104:107], v[8:11], v[168:171]
	s_waitcnt lgkmcnt(1)
	v_mfma_f32_16x16x32_bf16 v[164:167], v[112:115], v[8:11], v[164:167]
	s_waitcnt lgkmcnt(0)
	v_mfma_f32_16x16x32_bf16 v[8:11], v[116:119], v[8:11], v[160:163]
	v_mfma_f32_16x16x32_bf16 v[156:159], v[88:91], v[16:19], v[156:159]
	v_mfma_f32_16x16x32_bf16 v[152:155], v[104:107], v[16:19], v[152:155]
	v_mfma_f32_16x16x32_bf16 v[148:151], v[112:115], v[16:19], v[148:151]
	v_mfma_f32_16x16x32_bf16 v[16:19], v[116:119], v[16:19], v[144:147]
	v_mfma_f32_16x16x32_bf16 v[136:139], v[88:91], v[32:35], v[136:139]
	v_mfma_f32_16x16x32_bf16 v[132:135], v[104:107], v[32:35], v[132:135]
	v_mfma_f32_16x16x32_bf16 v[128:131], v[112:115], v[32:35], v[128:131]
	v_mfma_f32_16x16x32_bf16 v[32:35], v[116:119], v[32:35], v[124:127]
	v_mfma_f32_16x16x32_bf16 v[120:123], v[88:91], v[40:43], v[120:123]
	v_mfma_f32_16x16x32_bf16 v[108:111], v[104:107], v[40:43], v[108:111]
	v_mfma_f32_16x16x32_bf16 v[100:103], v[112:115], v[40:43], v[100:103]
	v_mfma_f32_16x16x32_bf16 v[40:43], v[116:119], v[40:43], v[96:99]
	v_mfma_f32_16x16x32_bf16 v[92:95], v[88:91], v[56:59], v[92:95]
	v_mfma_f32_16x16x32_bf16 v[84:87], v[104:107], v[56:59], v[84:87]
	v_mfma_f32_16x16x32_bf16 v[76:79], v[112:115], v[56:59], v[76:79]
	v_mfma_f32_16x16x32_bf16 v[56:59], v[116:119], v[56:59], v[72:75]
	v_mfma_f32_16x16x32_bf16 v[64:67], v[88:91], v[60:63], v[64:67]
	v_mfma_f32_16x16x32_bf16 v[52:55], v[104:107], v[60:63], v[52:55]
	v_mfma_f32_16x16x32_bf16 v[72:75], v[112:115], v[60:63], v[48:51]
	v_mfma_f32_16x16x32_bf16 v[60:63], v[116:119], v[60:63], v[44:47]
	v_mfma_f32_16x16x32_bf16 v[96:99], v[88:91], v[68:71], v[36:39]
	v_mfma_f32_16x16x32_bf16 v[28:31], v[104:107], v[68:71], v[28:31]
	v_mfma_f32_16x16x32_bf16 v[124:127], v[112:115], v[68:71], v[24:27]
	v_mfma_f32_16x16x32_bf16 v[20:23], v[116:119], v[68:71], v[20:23]
	v_mfma_f32_16x16x32_bf16 v[12:15], v[88:91], v[80:83], v[12:15]
	v_mfma_f32_16x16x32_bf16 v[4:7], v[104:107], v[80:83], v[4:7]
	v_mfma_f32_16x16x32_bf16 v[0:3], v[112:115], v[80:83], v[0:3]
	v_mfma_f32_16x16x32_bf16 v[68:71], v[116:119], v[80:83], v[140:143]
	ds_read_b128 v[24:27], v183
	ds_read_b128 v[36:39], v183 offset:2048
	ds_read_b128 v[44:47], v183 offset:4096
	ds_read_b128 v[80:83], v183 offset:6144
	ds_read_b128 v[88:91], v183 offset:8192
	ds_read_b128 v[104:107], v183 offset:10240
	ds_read_b128 v[112:115], v183 offset:12288
	ds_read_b128 v[116:119], v183 offset:14336
	ds_read_b128 v[140:143], v182 offset:32768
	ds_read_b128 v[144:147], v182 offset:34816
	ds_read_b128 v[160:163], v182 offset:36864
	ds_read_b128 v[178:181], v182 offset:38912
	s_waitcnt lgkmcnt(3)
	v_mfma_f32_16x16x32_bf16 v[172:175], v[140:143], v[24:27], v[172:175]
	v_mov_b32_e32 v49, v188
	v_cmp_lt_i32_e32 vcc, v189, v202
	s_waitcnt lgkmcnt(2)
	v_mfma_f32_16x16x32_bf16 v[168:171], v[144:147], v[24:27], v[168:171]
	v_mov_b32_e32 v48, v188
	v_readlane_b32 s8, v253, 24
	s_waitcnt lgkmcnt(1)
	v_mfma_f32_16x16x32_bf16 v[164:167], v[160:163], v[24:27], v[164:167]
	v_and_b32_e32 v50, 0xffffff80, v48
	v_add_u32_e32 v51, s11, v50
	v_and_or_b32 v50, v48, 64, s12
	s_waitcnt lgkmcnt(0)
	v_mfma_f32_16x16x32_bf16 v[8:11], v[178:181], v[24:27], v[8:11]
	v_bfe_u32 v26, v49, 4, 1
	v_cndmask_b32_e32 v24, v203, v189, vcc
	v_cmp_eq_u32_e32 vcc, 0, v26
	v_lshlrev_b32_e32 v186, 2, v24
	v_mfma_f32_16x16x32_bf16 v[182:185], v[178:181], v[36:39], v[16:19]
	v_and_or_b32 v48, v49, 15, v51
	v_ashrrev_i32_e32 v51, 31, v50
	v_lshl_add_u64 v[50:51], v[50:51], 1, s[6:7]
	v_lshlrev_b32_e32 v176, 5, v26
	v_lshrrev_b32_e32 v27, 1, v49
	v_lshl_add_u64 v[24:25], v[50:51], 0, v[176:177]
	v_and_b32_e32 v176, 16, v27
	v_ashrrev_i32_e32 v49, 31, v48
	v_mfma_f32_16x16x32_bf16 v[156:159], v[140:143], v[36:39], v[156:159]
	v_lshl_add_u64 v[50:51], v[24:25], 0, v[176:177]
	v_lshlrev_b64 v[24:25], 11, v[48:49]
	s_waitcnt lgkmcnt(0)
	v_mfma_f32_16x16x32_bf16 v[152:155], v[144:147], v[36:39], v[152:155]
	v_mov_b32_e32 v26, v172
	v_mov_b32_e32 v27, v168
	s_nop 1
	v_permlane16_swap_b32_e32 v26, v27
	s_waitcnt lgkmcnt(0)
	v_lshl_add_u64 v[24:25], v[50:51], 0, v[24:25]
	v_mfma_f32_16x16x32_bf16 v[148:151], v[160:163], v[36:39], v[148:151]
	v_mov_b32_e32 v16, v173
	v_mov_b32_e32 v36, v169
	s_nop 1
	v_permlane16_swap_b32_e32 v16, v36
	s_waitcnt lgkmcnt(0)
	v_cvt_pk_bf16_f32 v16, v26, v16
	v_mfma_f32_16x16x32_bf16 v[190:193], v[178:181], v[44:47], v[32:35]
	v_readlane_b32 s9, v253, 25
	s_nop 1
	v_mov_b32_e32 v17, v174
	v_mov_b32_e32 v32, v170
	s_nop 1
	v_permlane16_swap_b32_e32 v17, v32
	s_waitcnt lgkmcnt(0)
	v_mov_b32_e32 v18, v175
	v_mov_b32_e32 v19, v171
	s_nop 1
	v_permlane16_swap_b32_e32 v18, v19
	v_cvt_pk_bf16_f32 v17, v17, v18
	v_cvt_pk_bf16_f32 v18, v27, v36
	v_cvt_pk_bf16_f32 v19, v32, v19
	global_store_dwordx4 v[24:25], v[16:19], off
	v_mfma_f32_16x16x32_bf16 v[120:123], v[140:143], v[80:83], v[120:123]
	s_nop 0
	v_mfma_f32_16x16x32_bf16 v[108:111], v[144:147], v[80:83], v[108:111]
	s_waitcnt lgkmcnt(0)
	v_mov_b32_e32 v26, v164
	v_mov_b32_e32 v16, v8
	s_nop 1
	v_permlane16_swap_b32_e32 v26, v16
	s_waitcnt lgkmcnt(0)
	v_mov_b32_e32 v8, v165
	v_mov_b32_e32 v17, v9
	s_nop 1
	v_permlane16_swap_b32_e32 v8, v17
	s_waitcnt lgkmcnt(0)
	v_mov_b32_e32 v9, v166
	v_mov_b32_e32 v18, v10
	s_nop 1
	v_permlane16_swap_b32_e32 v9, v18
	s_waitcnt lgkmcnt(0)
	v_mov_b32_e32 v10, v167
	s_nop 1
	v_permlane16_swap_b32_e32 v10, v11
	v_cvt_pk_bf16_f32 v8, v26, v8
	v_cvt_pk_bf16_f32 v9, v9, v10
	v_cvt_pk_bf16_f32 v10, v16, v17
	v_cvt_pk_bf16_f32 v11, v18, v11
	global_store_dwordx4 v[24:25], v[8:11], off offset:64
	v_mfma_f32_16x16x32_bf16 v[100:103], v[160:163], v[80:83], v[100:103]
	s_nop 0
	v_or_b32_e32 v8, 16, v48
	v_ashrrev_i32_e32 v9, 31, v8
	v_lshlrev_b64 v[8:9], 11, v[8:9]
	v_mfma_f32_16x16x32_bf16 v[80:83], v[178:181], v[80:83], v[40:43]
	v_mfma_f32_16x16x32_bf16 v[40:43], v[140:143], v[104:107], v[64:67]
	s_nop 1
	s_nop 0
	v_lshl_add_u64 v[64:65], v[50:51], 0, v[8:9]
	v_mfma_f32_16x16x32_bf16 v[136:139], v[140:143], v[44:47], v[136:139]
	s_waitcnt lgkmcnt(0)
	v_mfma_f32_16x16x32_bf16 v[132:135], v[144:147], v[44:47], v[132:135]
	v_mfma_f32_16x16x32_bf16 v[128:131], v[160:163], v[44:47], v[128:131]
	v_mfma_f32_16x16x32_bf16 v[44:47], v[144:147], v[104:107], v[52:55]
	v_mfma_f32_16x16x32_bf16 v[36:39], v[178:181], v[104:107], v[60:63]
	s_nop 1
	v_mov_b32_e32 v49, v156
	v_mov_b32_e32 v54, v152
	s_nop 1
	v_permlane16_swap_b32_e32 v49, v54
	s_waitcnt lgkmcnt(0)
	v_mov_b32_e32 v8, v157
	v_mov_b32_e32 v55, v153
	s_nop 1
	v_permlane16_swap_b32_e32 v8, v55
	v_mov_b32_e32 v53, v158
	v_mov_b32_e32 v60, v154
	s_nop 1
	v_permlane16_swap_b32_e32 v53, v60
	v_mov_b32_e32 v61, v159
	v_mov_b32_e32 v62, v155
	s_nop 1
	v_permlane16_swap_b32_e32 v61, v62
	v_cvt_pk_bf16_f32 v52, v49, v8
	v_cvt_pk_bf16_f32 v53, v53, v61
	v_cvt_pk_bf16_f32 v54, v54, v55
	v_cvt_pk_bf16_f32 v55, v60, v62
	v_mfma_f32_16x16x32_bf16 v[8:11], v[140:143], v[116:119], v[12:15]
	global_store_dwordx4 v[64:65], v[52:55], off
	v_mfma_f32_16x16x32_bf16 v[12:15], v[144:147], v[116:119], v[4:7]
	s_nop 2
	v_cndmask_b32_e32 v4, v148, v182, vcc
	ds_bpermute_b32 v54, v186, v4
	s_waitcnt lgkmcnt(1)
	v_mov_b32_e32 v60, v149
	v_mov_b32_e32 v49, v183
	s_nop 1
	v_permlane16_swap_b32_e32 v60, v49
	s_waitcnt lgkmcnt(1)
	s_waitcnt lgkmcnt(0)
	v_cndmask_b32_e32 v55, v54, v148, vcc
	v_cndmask_b32_e32 v54, v182, v54, vcc
	v_mov_b32_e32 v61, v150
	v_mov_b32_e32 v62, v184
	s_nop 1
	v_permlane16_swap_b32_e32 v61, v62
	s_waitcnt lgkmcnt(0)
	v_mov_b32_e32 v63, v151
	v_mov_b32_e32 v66, v185
	s_nop 1
	v_permlane16_swap_b32_e32 v63, v66
	v_cvt_pk_bf16_f32 v52, v55, v60
	v_cvt_pk_bf16_f32 v53, v61, v63
	v_cvt_pk_bf16_f32 v54, v54, v49
	v_cvt_pk_bf16_f32 v55, v62, v66
	global_store_dwordx4 v[64:65], v[52:55], off offset:64
	s_nop 1
	v_or_b32_e32 v52, 32, v48
	v_ashrrev_i32_e32 v53, 31, v52
	v_lshlrev_b64 v[52:53], 11, v[52:53]
	v_lshl_add_u64 v[60:61], v[50:51], 0, v[52:53]
	s_waitcnt lgkmcnt(0)
	v_mov_b32_e32 v55, v136
	v_mov_b32_e32 v49, v132
	s_nop 1
	v_permlane16_swap_b32_e32 v55, v49
	s_waitcnt lgkmcnt(0)
	v_mov_b32_e32 v62, v137
	v_mov_b32_e32 v63, v133
	s_nop 1
	v_permlane16_swap_b32_e32 v62, v63
	s_waitcnt lgkmcnt(0)
	v_mov_b32_e32 v64, v138
	v_mov_b32_e32 v65, v134
	s_nop 1
	v_permlane16_swap_b32_e32 v64, v65
	s_waitcnt lgkmcnt(0)
	v_mov_b32_e32 v53, v139
	v_mov_b32_e32 v66, v135
	s_nop 1
	v_permlane16_swap_b32_e32 v53, v66
	v_cvt_pk_bf16_f32 v52, v55, v62
	v_cvt_pk_bf16_f32 v53, v64, v53
	v_cvt_pk_bf16_f32 v54, v49, v63
	v_cvt_pk_bf16_f32 v55, v65, v66
	global_store_dwordx4 v[60:61], v[52:55], off
	s_waitcnt lgkmcnt(0)
	s_nop 0
	v_mov_b32_e32 v55, v128
	v_mov_b32_e32 v49, v190
	s_nop 1
	v_permlane16_swap_b32_e32 v55, v49
	s_waitcnt lgkmcnt(0)
	v_mov_b32_e32 v62, v129
	v_mov_b32_e32 v63, v191
	s_nop 1
	v_permlane16_swap_b32_e32 v62, v63
	s_waitcnt lgkmcnt(0)
	v_mov_b32_e32 v64, v130
	v_mov_b32_e32 v65, v192
	s_nop 1
	v_permlane16_swap_b32_e32 v64, v65
	s_waitcnt lgkmcnt(0)
	v_mov_b32_e32 v53, v131
	v_mov_b32_e32 v66, v193
	s_nop 1
	v_permlane16_swap_b32_e32 v53, v66
	v_cvt_pk_bf16_f32 v52, v55, v62
	v_cvt_pk_bf16_f32 v53, v64, v53
	v_cvt_pk_bf16_f32 v54, v49, v63
	v_cvt_pk_bf16_f32 v55, v65, v66
	global_store_dwordx4 v[60:61], v[52:55], off offset:64
	s_nop 1
	v_or_b32_e32 v52, 48, v48
	v_ashrrev_i32_e32 v53, 31, v52
	v_lshlrev_b64 v[52:53], 11, v[52:53]
	v_lshl_add_u64 v[60:61], v[50:51], 0, v[52:53]
	s_waitcnt lgkmcnt(0)
	v_mov_b32_e32 v55, v120
	v_mov_b32_e32 v49, v108
	s_nop 1
	v_permlane16_swap_b32_e32 v55, v49
	s_waitcnt lgkmcnt(0)
	v_mov_b32_e32 v62, v121
	v_mov_b32_e32 v63, v109
	s_nop 1
	v_permlane16_swap_b32_e32 v62, v63
	s_waitcnt lgkmcnt(0)
	v_mov_b32_e32 v64, v122
	v_mov_b32_e32 v65, v110
	s_nop 1
	v_permlane16_swap_b32_e32 v64, v65
	s_waitcnt lgkmcnt(0)
	v_mov_b32_e32 v53, v123
	v_mov_b32_e32 v66, v111
	s_nop 1
	v_permlane16_swap_b32_e32 v53, v66
	v_cvt_pk_bf16_f32 v52, v55, v62
	v_cvt_pk_bf16_f32 v53, v64, v53
	v_cvt_pk_bf16_f32 v54, v49, v63
	v_cvt_pk_bf16_f32 v55, v65, v66
	global_store_dwordx4 v[60:61], v[52:55], off
	s_waitcnt lgkmcnt(0)
	s_nop 0
	v_mov_b32_e32 v55, v100
	v_mov_b32_e32 v49, v80
	s_nop 1
	v_permlane16_swap_b32_e32 v55, v49
	s_waitcnt lgkmcnt(0)
	v_mov_b32_e32 v62, v101
	v_mov_b32_e32 v63, v81
	s_nop 1
	v_permlane16_swap_b32_e32 v62, v63
	s_waitcnt lgkmcnt(0)
	v_mov_b32_e32 v64, v102
	v_mov_b32_e32 v65, v82
	s_nop 1
	v_permlane16_swap_b32_e32 v64, v65
	s_waitcnt lgkmcnt(0)
	v_mov_b32_e32 v53, v103
	v_mov_b32_e32 v66, v83
	s_nop 1
	v_permlane16_swap_b32_e32 v53, v66
	v_mfma_f32_16x16x32_bf16 v[92:95], v[140:143], v[88:91], v[92:95]
	v_cvt_pk_bf16_f32 v52, v55, v62
	v_cvt_pk_bf16_f32 v53, v64, v53
	v_cvt_pk_bf16_f32 v54, v49, v63
	v_mfma_f32_16x16x32_bf16 v[84:87], v[144:147], v[88:91], v[84:87]
	v_cvt_pk_bf16_f32 v55, v65, v66
	global_store_dwordx4 v[60:61], v[52:55], off offset:64
	v_mfma_f32_16x16x32_bf16 v[76:79], v[160:163], v[88:91], v[76:79]
	s_nop 0
	v_or_b32_e32 v52, 64, v48
	v_ashrrev_i32_e32 v53, 31, v52
	v_lshlrev_b64 v[52:53], 11, v[52:53]
	v_lshl_add_u64 v[60:61], v[50:51], 0, v[52:53]
	v_mfma_f32_16x16x32_bf16 v[56:59], v[178:181], v[88:91], v[56:59]
	s_waitcnt lgkmcnt(0)
	v_mov_b32_e32 v55, v92
	v_mov_b32_e32 v49, v84
	s_nop 1
	v_permlane16_swap_b32_e32 v55, v49
	s_waitcnt lgkmcnt(0)
	v_mov_b32_e32 v62, v93
	v_mov_b32_e32 v63, v85
	s_nop 1
	v_permlane16_swap_b32_e32 v62, v63
	s_waitcnt lgkmcnt(0)
	v_mov_b32_e32 v64, v94
	v_mov_b32_e32 v65, v86
	s_nop 1
	v_permlane16_swap_b32_e32 v64, v65
	s_waitcnt lgkmcnt(0)
	v_mov_b32_e32 v53, v95
	v_mov_b32_e32 v66, v87
	s_nop 1
	v_permlane16_swap_b32_e32 v53, v66
	v_cvt_pk_bf16_f32 v52, v55, v62
	v_cvt_pk_bf16_f32 v53, v64, v53
	v_cvt_pk_bf16_f32 v54, v49, v63
	v_cvt_pk_bf16_f32 v55, v65, v66
	global_store_dwordx4 v[60:61], v[52:55], off
	s_waitcnt lgkmcnt(0)
	s_nop 0
	v_mov_b32_e32 v55, v76
	v_mov_b32_e32 v49, v56
	s_nop 1
	v_permlane16_swap_b32_e32 v55, v49
	s_waitcnt lgkmcnt(0)
	v_mov_b32_e32 v56, v77
	s_nop 1
	v_permlane16_swap_b32_e32 v56, v57
	s_waitcnt lgkmcnt(0)
	v_mov_b32_e32 v62, v78
	s_nop 1
	v_permlane16_swap_b32_e32 v62, v58
	s_waitcnt lgkmcnt(0)
	v_mov_b32_e32 v53, v79
	s_nop 1
	v_permlane16_swap_b32_e32 v53, v59
	v_cvt_pk_bf16_f32 v52, v55, v56
	v_cvt_pk_bf16_f32 v53, v62, v53
	v_cvt_pk_bf16_f32 v54, v49, v57
	v_cvt_pk_bf16_f32 v55, v58, v59
	global_store_dwordx4 v[60:61], v[52:55], off offset:64
	v_mfma_f32_16x16x32_bf16 v[32:35], v[160:163], v[104:107], v[72:75]
	s_nop 0
	v_or_b32_e32 v52, 0x50, v48
	v_ashrrev_i32_e32 v53, 31, v52
	v_lshlrev_b64 v[52:53], 11, v[52:53]
	s_waitcnt lgkmcnt(0)
	s_nop 1
	v_permlane16_swap_b32_e32 v40, v44
	s_waitcnt lgkmcnt(0)
	s_nop 1
	v_permlane16_swap_b32_e32 v41, v45
	s_waitcnt lgkmcnt(0)
	s_nop 1
	v_permlane16_swap_b32_e32 v42, v46
	s_waitcnt lgkmcnt(0)
	s_nop 1
	v_permlane16_swap_b32_e32 v43, v47
	v_lshl_add_u64 v[52:53], v[50:51], 0, v[52:53]
	v_cvt_pk_bf16_f32 v40, v40, v41
	v_cvt_pk_bf16_f32 v41, v42, v43
	v_cvt_pk_bf16_f32 v42, v44, v45
	v_cvt_pk_bf16_f32 v43, v46, v47
	global_store_dwordx4 v[52:53], v[40:43], off
	v_mfma_f32_16x16x32_bf16 v[24:27], v[140:143], v[112:115], v[96:99]
	s_nop 0
	v_mfma_f32_16x16x32_bf16 v[28:31], v[144:147], v[112:115], v[28:31]
	s_waitcnt lgkmcnt(0)
	s_nop 1
	v_permlane16_swap_b32_e32 v32, v36
	s_waitcnt lgkmcnt(0)
	s_nop 1
	v_permlane16_swap_b32_e32 v33, v37
	s_waitcnt lgkmcnt(0)
	s_nop 1
	v_permlane16_swap_b32_e32 v34, v38
	s_waitcnt lgkmcnt(0)
	s_nop 1
	v_permlane16_swap_b32_e32 v35, v39
	v_cvt_pk_bf16_f32 v32, v32, v33
	v_cvt_pk_bf16_f32 v33, v34, v35
	v_cvt_pk_bf16_f32 v34, v36, v37
	v_cvt_pk_bf16_f32 v35, v38, v39
	global_store_dwordx4 v[52:53], v[32:35], off offset:64
	v_mfma_f32_16x16x32_bf16 v[16:19], v[160:163], v[112:115], v[124:127]
	s_nop 0
	v_or_b32_e32 v32, 0x60, v48
	v_ashrrev_i32_e32 v33, 31, v32
	v_lshlrev_b64 v[32:33], 11, v[32:33]
	v_mfma_f32_16x16x32_bf16 v[20:23], v[178:181], v[112:115], v[20:23]
	s_waitcnt lgkmcnt(0)
	s_nop 1
	v_permlane16_swap_b32_e32 v24, v28
	s_waitcnt lgkmcnt(0)
	s_nop 1
	v_permlane16_swap_b32_e32 v25, v29
	s_waitcnt lgkmcnt(0)
	s_nop 1
	v_permlane16_swap_b32_e32 v26, v30
	s_waitcnt lgkmcnt(0)
	s_nop 1
	v_permlane16_swap_b32_e32 v27, v31
	v_lshl_add_u64 v[32:33], v[50:51], 0, v[32:33]
	v_cvt_pk_bf16_f32 v24, v24, v25
	v_cvt_pk_bf16_f32 v25, v26, v27
	v_cvt_pk_bf16_f32 v26, v28, v29
	v_cvt_pk_bf16_f32 v27, v30, v31
	global_store_dwordx4 v[32:33], v[24:27], off
	v_mfma_f32_16x16x32_bf16 v[0:3], v[160:163], v[116:119], v[0:3]
	s_nop 0
	v_mfma_f32_16x16x32_bf16 v[4:7], v[178:181], v[116:119], v[68:71]
	s_waitcnt lgkmcnt(0)
	s_nop 1
	v_permlane16_swap_b32_e32 v16, v20
	s_waitcnt lgkmcnt(0)
	s_nop 1
	v_permlane16_swap_b32_e32 v17, v21
	s_waitcnt lgkmcnt(0)
	s_nop 1
	v_permlane16_swap_b32_e32 v18, v22
	s_waitcnt lgkmcnt(0)
	s_nop 1
	v_permlane16_swap_b32_e32 v19, v23
	v_cvt_pk_bf16_f32 v16, v16, v17
	v_cvt_pk_bf16_f32 v17, v18, v19
	v_cvt_pk_bf16_f32 v18, v20, v21
	v_cvt_pk_bf16_f32 v19, v22, v23
	global_store_dwordx4 v[32:33], v[16:19], off offset:64
	s_nop 1
	v_or_b32_e32 v16, 0x70, v48
	v_ashrrev_i32_e32 v17, 31, v16
	v_lshlrev_b64 v[16:17], 11, v[16:17]
	s_waitcnt lgkmcnt(0)
	s_nop 1
	v_permlane16_swap_b32_e32 v8, v12
	s_waitcnt lgkmcnt(0)
	s_nop 1
	v_permlane16_swap_b32_e32 v9, v13
	s_waitcnt lgkmcnt(0)
	s_nop 1
	v_permlane16_swap_b32_e32 v10, v14
	s_waitcnt lgkmcnt(0)
	s_nop 1
	v_permlane16_swap_b32_e32 v11, v15
	v_lshl_add_u64 v[16:17], v[50:51], 0, v[16:17]
	v_cvt_pk_bf16_f32 v8, v8, v9
	v_cvt_pk_bf16_f32 v9, v10, v11
	v_cvt_pk_bf16_f32 v10, v12, v13
	v_cvt_pk_bf16_f32 v11, v14, v15
	global_store_dwordx4 v[16:17], v[8:11], off
	s_nop 1
	s_waitcnt lgkmcnt(0)
	s_nop 1
	v_permlane16_swap_b32_e32 v0, v4
	s_waitcnt lgkmcnt(0)
	s_nop 1
	v_permlane16_swap_b32_e32 v1, v5
	s_waitcnt lgkmcnt(0)
	s_nop 1
	v_permlane16_swap_b32_e32 v2, v6
	s_waitcnt lgkmcnt(0)
	s_nop 1
	v_permlane16_swap_b32_e32 v3, v7
	v_cvt_pk_bf16_f32 v0, v0, v1
	v_cvt_pk_bf16_f32 v1, v2, v3
	v_cvt_pk_bf16_f32 v2, v4, v5
	v_cvt_pk_bf16_f32 v3, v6, v7
	global_store_dwordx4 v[16:17], v[0:3], off offset:64
	s_load_dword s8, s[8:9], 0x0
	s_waitcnt lgkmcnt(0)
	s_add_i32 s10, s8, s10
	s_cmpk_gt_i32 s10, 0xff
	s_cbranch_scc0 .LBB0_146

.LBB0_403:
	s_or_b64 exec, exec, s[0:1]
	s_waitcnt vmcnt(0)
	v_add_f32_e32 v128, 0, v128
	v_add_f32_e32 v128, v128, v129
	v_add_f32_e32 v128, v128, v130
	v_add_f32_e32 v128, v128, v131
	v_add_f32_e32 v128, v128, v138
	v_add_f32_e32 v128, v128, v139
	v_fmamk_f32 v128, v128, 0x3b2aaaab, v252
	v_mul_f32_e32 v129, 0x4b800000, v128
	v_cmp_gt_f32_e32 vcc, s25, v128
	v_cmp_lt_i32_e64 s[0:1], v189, v202
	v_lshrrev_b32_e32 v140, 4, v137
	v_cndmask_b32_e32 v128, v128, v129, vcc
	v_rsq_f32_e32 v128, v128
	v_cndmask_b32_e64 v129, v203, v189, s[0:1]
	v_lshlrev_b32_e32 v130, 2, v129
	v_lshlrev_b32_e32 v141, 2, v140
	v_mul_f32_e32 v129, 0x45800000, v128
	v_cndmask_b32_e32 v128, v128, v129, vcc
	v_ashrrev_i32_e32 v137, 31, v136
	v_and_b32_e32 v140, 1, v140
	v_mul_f32_e32 v138, 0x3dd53b94, v128
	v_mov_b64_e32 v[128:129], s[22:23]
	s_movk_i32 s8, 0xc00
	v_mad_i64_i32 v[146:147], s[0:1], v145, s8, v[128:129]
	v_lshlrev_b64 v[128:129], 1, v[136:137]
	v_pk_mul_f32 v[126:127], v[138:139], v[126:127] op_sel_hi:[0,1]
	v_pk_mul_f32 v[124:125], v[138:139], v[124:125] op_sel_hi:[0,1]
	v_pk_mul_f32 v[122:123], v[138:139], v[122:123] op_sel_hi:[0,1]
	v_pk_mul_f32 v[120:121], v[138:139], v[120:121] op_sel_hi:[0,1]
	v_cmp_eq_u32_e32 vcc, 0, v140
	v_and_b32_e32 v131, 8, v141
	v_lshl_add_u64 v[136:137], v[146:147], 0, v[128:129]
	v_lshlrev_b32_e32 v176, 1, v131
	s_waitcnt lgkmcnt(0)
	v_mov_b32_e32 v139, v120
	s_nop 1
	v_permlane16_swap_b32_e32 v124, v139
	s_waitcnt lgkmcnt(0)
	v_mov_b32_e32 v120, v125
	v_mov_b32_e32 v125, v121
	s_nop 1
	v_permlane16_swap_b32_e32 v120, v125
	s_waitcnt lgkmcnt(0)
	v_mov_b32_e32 v121, v126
	v_mov_b32_e32 v126, v122
	s_nop 1
	v_permlane16_swap_b32_e32 v121, v126
	s_waitcnt lgkmcnt(0)
	v_mov_b32_e32 v122, v127
	s_nop 1
	v_permlane16_swap_b32_e32 v122, v123
	v_cvt_pk_bf16_f32 v120, v124, v120
	v_cvt_pk_bf16_f32 v121, v121, v122
	v_cvt_pk_bf16_f32 v122, v139, v125
	v_lshlrev_b32_e32 v124, 5, v140
	v_mov_b32_e32 v125, v177
	v_cvt_pk_bf16_f32 v123, v126, v123
	v_lshl_add_u64 v[126:127], v[136:137], 0, v[124:125]
	v_lshl_add_u64 v[126:127], v[126:127], 0, v[176:177]
	v_pk_mul_f32 v[118:119], v[138:139], v[118:119] op_sel_hi:[0,1]
	v_pk_mul_f32 v[116:117], v[138:139], v[116:117] op_sel_hi:[0,1]
	v_pk_mul_f32 v[114:115], v[138:139], v[114:115] op_sel_hi:[0,1]
	v_pk_mul_f32 v[112:113], v[138:139], v[112:113] op_sel_hi:[0,1]
	global_store_dwordx4 v[126:127], v[120:123], off
	v_cndmask_b32_e32 v127, v119, v115, vcc
	ds_bpermute_b32 v127, v130, v127
	v_mov_b64_e32 v[120:121], s[34:35]
	v_mad_i64_i32 v[120:121], s[0:1], v145, s8, v[120:121]
	v_lshl_add_u64 v[120:121], v[120:121], 0, v[128:129]
	s_waitcnt lgkmcnt(1)
	v_mov_b32_e32 v122, v112
	s_nop 1
	v_permlane16_swap_b32_e32 v116, v122
	s_waitcnt lgkmcnt(1)
	v_mov_b32_e32 v112, v117
	v_mov_b32_e32 v117, v113
	s_nop 1
	v_permlane16_swap_b32_e32 v112, v117
	s_waitcnt lgkmcnt(1)
	v_mov_b32_e32 v113, v118
	v_mov_b32_e32 v118, v114
	s_nop 1
	v_permlane16_swap_b32_e32 v113, v118
	s_waitcnt lgkmcnt(0)
	v_cndmask_b32_e32 v114, v127, v119, vcc
	v_cvt_pk_bf16_f32 v112, v116, v112
	v_cvt_pk_bf16_f32 v113, v113, v114
	v_cvt_pk_bf16_f32 v114, v122, v117
	v_lshl_add_u64 v[116:117], v[120:121], 0, v[124:125]
	v_cndmask_b32_e32 v115, v115, v127, vcc
	v_lshl_add_u64 v[116:117], v[116:117], 0, v[176:177]
	s_mov_b32 s0, 0x3900000
	v_cvt_pk_bf16_f32 v115, v118, v115
	v_add_co_u32_e64 v116, s[0:1], s0, v116
	v_or_b32_e32 v118, 16, v143
	s_nop 0
	v_addc_co_u32_e64 v117, s[0:1], 0, v117, s[0:1]
	v_or_b32_e32 v120, v144, v118
	global_store_dwordx4 v[116:117], v[112:115], off offset:64
	s_nop 1
	v_lshlrev_b32_e32 v112, 3, v120
	v_ashrrev_i32_e32 v113, 31, v112
	v_lshl_add_u64 v[112:113], v[112:113], 2, s[4:5]
	global_load_dwordx2 v[116:117], v[112:113], off offset:16
	s_nop 0
	global_load_dwordx4 v[112:115], v[112:113], off
	s_and_saveexec_b64 s[0:1], s[40:41]
	s_cbranch_execz .LBB0_405
	v_or_b32_e32 v118, v142, v118
	v_lshlrev_b32_e32 v118, 7, v118
	v_mov_b32_e32 v119, v177
	v_lshl_add_u64 v[126:127], v[134:135], 0, v[118:119]
	v_lshl_add_u64 v[146:147], v[132:133], 0, v[118:119]
	global_load_dwordx4 v[122:125], v[126:127], off
	global_load_dwordx4 v[136:139], v[146:147], off
	s_waitcnt vmcnt(0)
	v_pk_mul_f32 v[148:149], v[108:109], v[136:137]
	v_pk_mul_f32 v[118:119], v[100:101], v[136:137]
	v_mul_f32_e32 v136, v110, v124
	v_mul_f32_e32 v150, v102, v138
	v_mul_f32_e32 v152, v110, v138
	v_mul_f32_e32 v124, v102, v124
	v_mov_b32_e32 v102, v111
	v_mov_b32_e32 v138, v125
	v_mov_b32_e32 v110, v103
	v_pk_mul_f32 v[154:155], v[102:103], v[138:139]
	v_pk_mul_f32 v[102:103], v[110:111], v[138:139]
	v_mov_b32_e32 v137, v154
	v_mov_b32_e32 v151, v155
	v_mov_b32_e32 v125, v102
	v_mov_b32_e32 v153, v103
	v_pk_fma_f32 v[108:109], v[108:109], v[122:123], v[118:119] neg_lo:[0,0,1] neg_hi:[0,0,1]
	v_pk_add_f32 v[118:119], v[136:137], v[150:151] neg_lo:[0,1] neg_hi:[0,1]
	v_pk_fma_f32 v[100:101], v[100:101], v[122:123], v[148:149]
	v_pk_add_f32 v[102:103], v[124:125], v[152:153]
	global_load_dwordx4 v[122:125], v[126:127], off offset:64
	global_load_dwordx4 v[136:139], v[146:147], off offset:64
	s_waitcnt vmcnt(0)
	v_pk_mul_f32 v[110:111], v[104:105], v[136:137]
	v_pk_mul_f32 v[126:127], v[96:97], v[136:137]
	v_mul_f32_e32 v136, v106, v124
	v_mul_f32_e32 v146, v98, v138
	v_mul_f32_e32 v148, v106, v138
	v_mul_f32_e32 v124, v98, v124
	v_mov_b32_e32 v98, v107
	v_mov_b32_e32 v138, v125
	v_pk_mul_f32 v[150:151], v[98:99], v[138:139]
	v_mov_b32_e32 v106, v99
	v_mov_b32_e32 v137, v150
	v_mov_b32_e32 v147, v151
	v_pk_mul_f32 v[98:99], v[106:107], v[138:139]
	v_pk_fma_f32 v[104:105], v[104:105], v[122:123], v[126:127] neg_lo:[0,0,1] neg_hi:[0,0,1]
	v_pk_add_f32 v[126:127], v[136:137], v[146:147] neg_lo:[0,1] neg_hi:[0,1]
	v_mov_b32_e32 v125, v98
	v_mov_b32_e32 v149, v99
	v_pk_fma_f32 v[96:97], v[96:97], v[122:123], v[110:111]
	v_pk_add_f32 v[98:99], v[124:125], v[148:149]
	v_mov_b32_e32 v106, v126
	v_mov_b32_e32 v107, v127
	v_mov_b32_e32 v110, v118
	v_mov_b32_e32 v111, v119
.LBB0_405:
	s_or_b64 exec, exec, s[0:1]
	s_waitcnt vmcnt(0)
	v_add_f32_e32 v112, 0, v112
	v_add_f32_e32 v112, v112, v113
	v_add_f32_e32 v112, v112, v114
	v_add_f32_e32 v112, v112, v115
	v_add_f32_e32 v112, v112, v116
	v_add_f32_e32 v112, v112, v117
	v_fmamk_f32 v112, v112, 0x3b2aaaab, v252
	v_mul_f32_e32 v113, 0x4b800000, v112
	v_cmp_gt_f32_e64 s[0:1], s25, v112
	v_lshlrev_b32_e32 v115, 4, v140
	s_nop 0
	v_cndmask_b32_e64 v112, v112, v113, s[0:1]
	v_rsq_f32_e32 v114, v112
	v_mov_b64_e32 v[112:113], s[22:23]
	v_mul_f32_e32 v116, 0x45800000, v114
	v_cndmask_b32_e64 v114, v114, v116, s[0:1]
	v_mul_f32_e32 v114, 0x3dd53b94, v114
	v_pk_mul_f32 v[108:109], v[114:115], v[108:109] op_sel_hi:[0,1]
	v_pk_mul_f32 v[104:105], v[114:115], v[104:105] op_sel_hi:[0,1]
	v_pk_mul_f32 v[110:111], v[114:115], v[110:111] op_sel_hi:[0,1]
	v_pk_mul_f32 v[106:107], v[114:115], v[106:107] op_sel_hi:[0,1]
	v_mad_i64_i32 v[112:113], s[0:1], v120, s8, v[112:113]
	s_waitcnt lgkmcnt(0)
	s_nop 1
	v_permlane16_swap_b32_e32 v108, v104
	s_waitcnt lgkmcnt(0)
	s_nop 1
	v_permlane16_swap_b32_e32 v109, v105
	v_lshl_add_u64 v[112:113], v[112:113], 0, v[128:129]
	s_waitcnt lgkmcnt(0)
	v_mov_b32_e32 v116, v106
	s_nop 1
	v_permlane16_swap_b32_e32 v110, v116
	s_waitcnt lgkmcnt(0)
	v_cvt_pk_bf16_f32 v106, v108, v109
	v_cvt_pk_bf16_f32 v108, v104, v105
	v_lshlrev_b32_e32 v104, 1, v115
	v_mov_b32_e32 v105, v177
	v_mov_b32_e32 v117, v107
	s_nop 1
	v_permlane16_swap_b32_e32 v111, v117
	v_cvt_pk_bf16_f32 v107, v110, v111
	v_lshl_add_u64 v[110:111], v[112:113], 0, v[104:105]
	v_cvt_pk_bf16_f32 v109, v116, v117
	v_lshl_add_u64 v[110:111], v[110:111], 0, v[176:177]
	v_pk_mul_f32 v[102:103], v[114:115], v[102:103] op_sel_hi:[0,1]
	v_pk_mul_f32 v[100:101], v[114:115], v[100:101] op_sel_hi:[0,1]
	v_pk_mul_f32 v[98:99], v[114:115], v[98:99] op_sel_hi:[0,1]
	v_pk_mul_f32 v[96:97], v[114:115], v[96:97] op_sel_hi:[0,1]
	global_store_dwordx4 v[110:111], v[106:109], off
	v_cndmask_b32_e32 v111, v103, v99, vcc
	ds_bpermute_b32 v111, v130, v111
	v_mov_b64_e32 v[106:107], s[34:35]
	v_mad_i64_i32 v[106:107], s[0:1], v120, s8, v[106:107]
	v_lshl_add_u64 v[106:107], v[106:107], 0, v[128:129]
	s_waitcnt lgkmcnt(1)
	v_mov_b32_e32 v108, v96
	s_nop 1
	v_permlane16_swap_b32_e32 v100, v108
	s_waitcnt lgkmcnt(1)
	v_mov_b32_e32 v96, v101
	v_mov_b32_e32 v101, v97
	s_nop 1
	v_permlane16_swap_b32_e32 v96, v101
	s_waitcnt lgkmcnt(1)
	v_mov_b32_e32 v97, v102
	v_mov_b32_e32 v102, v98
	s_nop 1
	v_permlane16_swap_b32_e32 v97, v102
	s_waitcnt lgkmcnt(0)
	v_cndmask_b32_e32 v98, v111, v103, vcc
	v_cvt_pk_bf16_f32 v96, v100, v96
	v_cvt_pk_bf16_f32 v97, v97, v98
	v_cvt_pk_bf16_f32 v98, v108, v101
	v_lshl_add_u64 v[100:101], v[106:107], 0, v[104:105]
	v_cndmask_b32_e32 v99, v99, v111, vcc
	v_lshl_add_u64 v[100:101], v[100:101], 0, v[176:177]
	s_mov_b32 s0, 0x3900000
	v_cvt_pk_bf16_f32 v99, v102, v99
	v_add_co_u32_e64 v100, s[0:1], s0, v100
	v_or_b32_e32 v102, 32, v143
	s_nop 0
	v_addc_co_u32_e64 v101, s[0:1], 0, v101, s[0:1]
	v_or_b32_e32 v106, v144, v102
	global_store_dwordx4 v[100:101], v[96:99], off offset:64
	s_nop 1
	v_lshlrev_b32_e32 v96, 3, v106
	v_ashrrev_i32_e32 v97, 31, v96
	v_lshl_add_u64 v[96:97], v[96:97], 2, s[4:5]
	global_load_dwordx2 v[100:101], v[96:97], off offset:16
	s_nop 0
	global_load_dwordx4 v[96:99], v[96:97], off
	s_and_saveexec_b64 s[0:1], s[40:41]
	s_cbranch_execz .LBB0_407
	v_or_b32_e32 v102, v142, v102
	v_lshlrev_b32_e32 v102, 7, v102
	v_mov_b32_e32 v103, v177
	v_lshl_add_u64 v[116:117], v[134:135], 0, v[102:103]
	v_lshl_add_u64 v[118:119], v[132:133], 0, v[102:103]
	global_load_dwordx4 v[108:111], v[116:117], off
	global_load_dwordx4 v[112:115], v[118:119], off
	s_waitcnt vmcnt(0)
	v_pk_mul_f32 v[120:121], v[92:93], v[112:113]
	v_pk_mul_f32 v[102:103], v[84:85], v[112:113]
	v_mul_f32_e32 v112, v94, v110
	v_mul_f32_e32 v122, v86, v114
	v_mul_f32_e32 v124, v94, v114
	v_mul_f32_e32 v110, v86, v110
	v_mov_b32_e32 v86, v95
	v_mov_b32_e32 v114, v111
	v_mov_b32_e32 v94, v87
	v_pk_mul_f32 v[126:127], v[86:87], v[114:115]
	v_pk_mul_f32 v[86:87], v[94:95], v[114:115]
	v_mov_b32_e32 v113, v126
	v_mov_b32_e32 v123, v127
	v_mov_b32_e32 v111, v86
	v_mov_b32_e32 v125, v87
	v_pk_fma_f32 v[92:93], v[92:93], v[108:109], v[102:103] neg_lo:[0,0,1] neg_hi:[0,0,1]
	v_pk_add_f32 v[102:103], v[112:113], v[122:123] neg_lo:[0,1] neg_hi:[0,1]
	v_pk_fma_f32 v[84:85], v[84:85], v[108:109], v[120:121]
	v_pk_add_f32 v[86:87], v[110:111], v[124:125]
	global_load_dwordx4 v[108:111], v[116:117], off offset:64
	global_load_dwordx4 v[112:115], v[118:119], off offset:64
	s_waitcnt vmcnt(1)
	v_mul_f32_e32 v116, v90, v110
	s_waitcnt vmcnt(0)
	v_mul_f32_e32 v118, v82, v114
	v_mul_f32_e32 v120, v90, v114
	v_mul_f32_e32 v110, v82, v110
	v_mov_b32_e32 v82, v91
	v_mov_b32_e32 v114, v111
	v_pk_mul_f32 v[122:123], v[82:83], v[114:115]
	v_mov_b32_e32 v90, v83
	v_pk_mul_f32 v[94:95], v[88:89], v[112:113]
	v_pk_mul_f32 v[112:113], v[80:81], v[112:113]
	v_mov_b32_e32 v117, v122
	v_mov_b32_e32 v119, v123
	v_pk_mul_f32 v[82:83], v[90:91], v[114:115]
	v_pk_fma_f32 v[88:89], v[88:89], v[108:109], v[112:113] neg_lo:[0,0,1] neg_hi:[0,0,1]
	v_pk_add_f32 v[112:113], v[116:117], v[118:119] neg_lo:[0,1] neg_hi:[0,1]
	v_mov_b32_e32 v111, v82
	v_mov_b32_e32 v121, v83
	v_pk_fma_f32 v[80:81], v[80:81], v[108:109], v[94:95]
	v_pk_add_f32 v[82:83], v[110:111], v[120:121]
	v_mov_b32_e32 v90, v112
	v_mov_b32_e32 v91, v113
	v_mov_b32_e32 v94, v102
	v_mov_b32_e32 v95, v103
.LBB0_407:
	s_or_b64 exec, exec, s[0:1]
	s_waitcnt vmcnt(0)
	v_add_f32_e32 v96, 0, v96
	v_add_f32_e32 v96, v96, v97
	v_add_f32_e32 v96, v96, v98
	v_add_f32_e32 v96, v96, v99
	v_add_f32_e32 v96, v96, v100
	v_add_f32_e32 v96, v96, v101
	v_fmamk_f32 v96, v96, 0x3b2aaaab, v252
	v_mul_f32_e32 v97, 0x4b800000, v96
	v_cmp_gt_f32_e64 s[0:1], s25, v96
	s_nop 1
	v_cndmask_b32_e64 v96, v96, v97, s[0:1]
	v_rsq_f32_e32 v98, v96
	v_mov_b64_e32 v[96:97], s[22:23]
	v_mul_f32_e32 v99, 0x45800000, v98
	v_cndmask_b32_e64 v98, v98, v99, s[0:1]
	v_mul_f32_e32 v98, 0x3dd53b94, v98
	v_pk_mul_f32 v[94:95], v[98:99], v[94:95] op_sel_hi:[0,1]
	v_pk_mul_f32 v[92:93], v[98:99], v[92:93] op_sel_hi:[0,1]
	v_pk_mul_f32 v[90:91], v[98:99], v[90:91] op_sel_hi:[0,1]
	v_pk_mul_f32 v[88:89], v[98:99], v[88:89] op_sel_hi:[0,1]
	v_mad_i64_i32 v[96:97], s[0:1], v106, s8, v[96:97]
	v_lshl_add_u64 v[96:97], v[96:97], 0, v[128:129]
	s_waitcnt lgkmcnt(0)
	v_mov_b32_e32 v99, v88
	s_nop 1
	v_permlane16_swap_b32_e32 v92, v99
	s_waitcnt lgkmcnt(0)
	v_mov_b32_e32 v88, v93
	v_mov_b32_e32 v93, v89
	s_nop 1
	v_permlane16_swap_b32_e32 v88, v93
	s_waitcnt lgkmcnt(0)
	v_mov_b32_e32 v89, v94
	v_mov_b32_e32 v94, v90
	s_nop 1
	v_permlane16_swap_b32_e32 v89, v94
	s_waitcnt lgkmcnt(0)
	v_mov_b32_e32 v90, v95
	s_nop 1
	v_permlane16_swap_b32_e32 v90, v91
	v_cvt_pk_bf16_f32 v88, v92, v88
	v_cvt_pk_bf16_f32 v89, v89, v90
	v_cvt_pk_bf16_f32 v90, v99, v93
	v_lshl_add_u64 v[92:93], v[96:97], 0, v[104:105]
	v_cvt_pk_bf16_f32 v91, v94, v91
	v_lshl_add_u64 v[92:93], v[92:93], 0, v[176:177]
	v_pk_mul_f32 v[86:87], v[98:99], v[86:87] op_sel_hi:[0,1]
	v_pk_mul_f32 v[84:85], v[98:99], v[84:85] op_sel_hi:[0,1]
	v_pk_mul_f32 v[82:83], v[98:99], v[82:83] op_sel_hi:[0,1]
	v_pk_mul_f32 v[80:81], v[98:99], v[80:81] op_sel_hi:[0,1]
	global_store_dwordx4 v[92:93], v[88:91], off
	v_cndmask_b32_e32 v93, v87, v83, vcc
	ds_bpermute_b32 v93, v130, v93
	v_mov_b64_e32 v[88:89], s[34:35]
	v_mad_i64_i32 v[88:89], s[0:1], v106, s8, v[88:89]
	v_lshl_add_u64 v[88:89], v[88:89], 0, v[128:129]
	s_waitcnt lgkmcnt(1)
	v_mov_b32_e32 v90, v80
	s_nop 1
	v_permlane16_swap_b32_e32 v84, v90
	s_waitcnt lgkmcnt(1)
	v_mov_b32_e32 v80, v85
	v_mov_b32_e32 v85, v81
	s_nop 1
	v_permlane16_swap_b32_e32 v80, v85
	s_waitcnt lgkmcnt(1)
	v_mov_b32_e32 v81, v86
	v_mov_b32_e32 v86, v82
	s_nop 1
	v_permlane16_swap_b32_e32 v81, v86
	s_waitcnt lgkmcnt(0)
	v_cndmask_b32_e32 v82, v93, v87, vcc
	v_cvt_pk_bf16_f32 v80, v84, v80
	v_cvt_pk_bf16_f32 v81, v81, v82
	v_cvt_pk_bf16_f32 v82, v90, v85
	v_lshl_add_u64 v[84:85], v[88:89], 0, v[104:105]
	v_cndmask_b32_e32 v83, v83, v93, vcc
	v_lshl_add_u64 v[84:85], v[84:85], 0, v[176:177]
	s_mov_b32 s0, 0x3900000
	v_cvt_pk_bf16_f32 v83, v86, v83
	v_add_co_u32_e64 v84, s[0:1], s0, v84
	v_or_b32_e32 v86, 48, v143
	s_nop 0
	v_addc_co_u32_e64 v85, s[0:1], 0, v85, s[0:1]
	v_or_b32_e32 v88, v144, v86
	global_store_dwordx4 v[84:85], v[80:83], off offset:64
	s_nop 1
	v_lshlrev_b32_e32 v80, 3, v88
	v_ashrrev_i32_e32 v81, 31, v80
	v_lshl_add_u64 v[80:81], v[80:81], 2, s[4:5]
	global_load_dwordx2 v[84:85], v[80:81], off offset:16
	s_nop 0
	global_load_dwordx4 v[80:83], v[80:81], off
	s_and_saveexec_b64 s[0:1], s[40:41]
	s_cbranch_execz .LBB0_409
	v_or_b32_e32 v86, v142, v86
	v_lshlrev_b32_e32 v86, 7, v86
	v_mov_b32_e32 v87, v177
	v_lshl_add_u64 v[98:99], v[134:135], 0, v[86:87]
	v_lshl_add_u64 v[100:101], v[132:133], 0, v[86:87]
	global_load_dwordx4 v[90:93], v[98:99], off
	global_load_dwordx4 v[94:97], v[100:101], off
	s_waitcnt vmcnt(0)
	v_pk_mul_f32 v[102:103], v[76:77], v[94:95]
	v_pk_mul_f32 v[86:87], v[68:69], v[94:95]
	v_mul_f32_e32 v94, v78, v92
	v_mul_f32_e32 v106, v70, v96
	v_mul_f32_e32 v108, v78, v96
	v_mul_f32_e32 v92, v70, v92
	v_mov_b32_e32 v70, v79
	v_mov_b32_e32 v96, v93
	v_mov_b32_e32 v78, v71
	v_pk_mul_f32 v[110:111], v[70:71], v[96:97]
	v_pk_mul_f32 v[70:71], v[78:79], v[96:97]
	v_mov_b32_e32 v95, v110
	v_mov_b32_e32 v107, v111
	v_mov_b32_e32 v93, v70
	v_mov_b32_e32 v109, v71
	v_pk_fma_f32 v[76:77], v[76:77], v[90:91], v[86:87] neg_lo:[0,0,1] neg_hi:[0,0,1]
	v_pk_add_f32 v[86:87], v[94:95], v[106:107] neg_lo:[0,1] neg_hi:[0,1]
	v_pk_fma_f32 v[68:69], v[68:69], v[90:91], v[102:103]
	v_pk_add_f32 v[70:71], v[92:93], v[108:109]
	global_load_dwordx4 v[90:93], v[98:99], off offset:64
	global_load_dwordx4 v[94:97], v[100:101], off offset:64
	s_waitcnt vmcnt(1)
	v_mul_f32_e32 v98, v74, v92
	s_waitcnt vmcnt(0)
	v_mul_f32_e32 v100, v66, v96
	v_mul_f32_e32 v102, v74, v96
	v_mul_f32_e32 v92, v66, v92
	v_mov_b32_e32 v66, v75
	v_mov_b32_e32 v96, v93
	v_pk_mul_f32 v[106:107], v[66:67], v[96:97]
	v_mov_b32_e32 v74, v67
	v_pk_mul_f32 v[78:79], v[72:73], v[94:95]
	v_pk_mul_f32 v[94:95], v[64:65], v[94:95]
	v_mov_b32_e32 v99, v106
	v_mov_b32_e32 v101, v107
	v_pk_mul_f32 v[66:67], v[74:75], v[96:97]
	v_pk_fma_f32 v[72:73], v[72:73], v[90:91], v[94:95] neg_lo:[0,0,1] neg_hi:[0,0,1]
	v_pk_add_f32 v[94:95], v[98:99], v[100:101] neg_lo:[0,1] neg_hi:[0,1]
	v_mov_b32_e32 v93, v66
	v_mov_b32_e32 v103, v67
	v_pk_fma_f32 v[64:65], v[64:65], v[90:91], v[78:79]
	v_pk_add_f32 v[66:67], v[92:93], v[102:103]
	v_mov_b32_e32 v74, v94
	v_mov_b32_e32 v75, v95
	v_mov_b32_e32 v78, v86
	v_mov_b32_e32 v79, v87
.LBB0_409:
	s_or_b64 exec, exec, s[0:1]
	s_waitcnt vmcnt(0)
	v_add_f32_e32 v80, 0, v80
	v_add_f32_e32 v80, v80, v81
	v_add_f32_e32 v80, v80, v82
	v_add_f32_e32 v80, v80, v83
	v_add_f32_e32 v80, v80, v84
	v_add_f32_e32 v80, v80, v85
	v_fmamk_f32 v80, v80, 0x3b2aaaab, v252
	v_mul_f32_e32 v81, 0x4b800000, v80
	v_cmp_gt_f32_e64 s[0:1], s25, v80
	v_mov_b32_e32 v105, v177
	s_nop 0
	v_cndmask_b32_e64 v80, v80, v81, s[0:1]
	v_rsq_f32_e32 v82, v80
	v_mov_b64_e32 v[80:81], s[22:23]
	v_mul_f32_e32 v83, 0x45800000, v82
	v_cndmask_b32_e64 v82, v82, v83, s[0:1]
	v_mul_f32_e32 v82, 0x3dd53b94, v82
	v_pk_mul_f32 v[78:79], v[82:83], v[78:79] op_sel_hi:[0,1]
	v_pk_mul_f32 v[76:77], v[82:83], v[76:77] op_sel_hi:[0,1]
	v_pk_mul_f32 v[74:75], v[82:83], v[74:75] op_sel_hi:[0,1]
	v_pk_mul_f32 v[72:73], v[82:83], v[72:73] op_sel_hi:[0,1]
	v_mad_i64_i32 v[80:81], s[0:1], v88, s8, v[80:81]
	v_lshl_add_u64 v[80:81], v[80:81], 0, v[128:129]
	s_waitcnt lgkmcnt(0)
	v_mov_b32_e32 v83, v72
	s_nop 1
	v_permlane16_swap_b32_e32 v76, v83
	s_waitcnt lgkmcnt(0)
	v_mov_b32_e32 v72, v77
	v_mov_b32_e32 v77, v73
	s_nop 1
	v_permlane16_swap_b32_e32 v72, v77
	s_waitcnt lgkmcnt(0)
	v_mov_b32_e32 v73, v78
	v_mov_b32_e32 v78, v74
	s_nop 1
	v_permlane16_swap_b32_e32 v73, v78
	s_waitcnt lgkmcnt(0)
	v_mov_b32_e32 v74, v79
	s_nop 1
	v_permlane16_swap_b32_e32 v74, v75
	v_cvt_pk_bf16_f32 v72, v76, v72
	v_cvt_pk_bf16_f32 v73, v73, v74
	v_cvt_pk_bf16_f32 v74, v83, v77
	v_lshl_add_u64 v[76:77], v[80:81], 0, v[104:105]
	v_cvt_pk_bf16_f32 v75, v78, v75
	v_lshl_add_u64 v[76:77], v[76:77], 0, v[176:177]
	v_pk_mul_f32 v[70:71], v[82:83], v[70:71] op_sel_hi:[0,1]
	v_pk_mul_f32 v[68:69], v[82:83], v[68:69] op_sel_hi:[0,1]
	v_pk_mul_f32 v[66:67], v[82:83], v[66:67] op_sel_hi:[0,1]
	v_pk_mul_f32 v[64:65], v[82:83], v[64:65] op_sel_hi:[0,1]
	global_store_dwordx4 v[76:77], v[72:75], off
	v_cndmask_b32_e32 v77, v71, v67, vcc
	ds_bpermute_b32 v77, v130, v77
	v_mov_b64_e32 v[72:73], s[34:35]
	v_mad_i64_i32 v[72:73], s[0:1], v88, s8, v[72:73]
	v_lshl_add_u64 v[72:73], v[72:73], 0, v[128:129]
	s_waitcnt lgkmcnt(1)
	v_mov_b32_e32 v74, v64
	s_nop 1
	v_permlane16_swap_b32_e32 v68, v74
	s_waitcnt lgkmcnt(1)
	v_mov_b32_e32 v64, v69
	v_mov_b32_e32 v69, v65
	s_nop 1
	v_permlane16_swap_b32_e32 v64, v69
	s_waitcnt lgkmcnt(1)
	v_mov_b32_e32 v65, v70
	v_mov_b32_e32 v70, v66
	s_nop 1
	v_permlane16_swap_b32_e32 v65, v70
	s_waitcnt lgkmcnt(0)
	v_cndmask_b32_e32 v66, v77, v71, vcc
	v_cvt_pk_bf16_f32 v64, v68, v64
	v_cvt_pk_bf16_f32 v65, v65, v66
	v_cvt_pk_bf16_f32 v66, v74, v69
	v_lshl_add_u64 v[68:69], v[72:73], 0, v[104:105]
	v_cndmask_b32_e32 v67, v67, v77, vcc
	v_lshl_add_u64 v[68:69], v[68:69], 0, v[176:177]
	s_mov_b32 s0, 0x3900000
	v_cvt_pk_bf16_f32 v67, v70, v67
	v_add_co_u32_e64 v68, s[0:1], s0, v68
	v_or_b32_e32 v70, 64, v143
	s_nop 0
	v_addc_co_u32_e64 v69, s[0:1], 0, v69, s[0:1]
	v_or_b32_e32 v72, v144, v70
	global_store_dwordx4 v[68:69], v[64:67], off offset:64
	s_nop 1
	v_lshlrev_b32_e32 v64, 3, v72
	v_ashrrev_i32_e32 v65, 31, v64
	v_lshl_add_u64 v[64:65], v[64:65], 2, s[4:5]
	global_load_dwordx2 v[68:69], v[64:65], off offset:16
	s_nop 0
	global_load_dwordx4 v[64:67], v[64:65], off
	s_and_saveexec_b64 s[0:1], s[40:41]
	s_cbranch_execz .LBB0_411
	v_or_b32_e32 v70, v142, v70
	v_lshlrev_b32_e32 v70, 7, v70
	v_mov_b32_e32 v71, v177
	v_lshl_add_u64 v[82:83], v[134:135], 0, v[70:71]
	v_lshl_add_u64 v[84:85], v[132:133], 0, v[70:71]
	global_load_dwordx4 v[74:77], v[82:83], off
	global_load_dwordx4 v[78:81], v[84:85], off
	s_waitcnt vmcnt(0)
	v_pk_mul_f32 v[86:87], v[60:61], v[78:79]
	v_pk_mul_f32 v[70:71], v[52:53], v[78:79]
	v_mul_f32_e32 v78, v62, v76
	v_mul_f32_e32 v88, v54, v80
	v_mul_f32_e32 v90, v62, v80
	v_mul_f32_e32 v76, v54, v76
	v_mov_b32_e32 v54, v63
	v_mov_b32_e32 v80, v77
	v_mov_b32_e32 v62, v55
	v_pk_mul_f32 v[92:93], v[54:55], v[80:81]
	v_pk_mul_f32 v[54:55], v[62:63], v[80:81]
	v_mov_b32_e32 v79, v92
	v_mov_b32_e32 v89, v93
	v_mov_b32_e32 v77, v54
	v_mov_b32_e32 v91, v55
	v_pk_fma_f32 v[60:61], v[60:61], v[74:75], v[70:71] neg_lo:[0,0,1] neg_hi:[0,0,1]
	v_pk_add_f32 v[70:71], v[78:79], v[88:89] neg_lo:[0,1] neg_hi:[0,1]
	v_pk_fma_f32 v[52:53], v[52:53], v[74:75], v[86:87]
	v_pk_add_f32 v[54:55], v[76:77], v[90:91]
	global_load_dwordx4 v[74:77], v[82:83], off offset:64
	global_load_dwordx4 v[78:81], v[84:85], off offset:64
	s_waitcnt vmcnt(1)
	v_mul_f32_e32 v82, v58, v76
	s_waitcnt vmcnt(0)
	v_mul_f32_e32 v84, v50, v80
	v_mul_f32_e32 v86, v58, v80
	v_mul_f32_e32 v76, v50, v76
	v_mov_b32_e32 v50, v59
	v_mov_b32_e32 v80, v77
	v_pk_mul_f32 v[88:89], v[50:51], v[80:81]
	v_mov_b32_e32 v58, v51
	v_pk_mul_f32 v[62:63], v[56:57], v[78:79]
	v_pk_mul_f32 v[78:79], v[48:49], v[78:79]
	v_mov_b32_e32 v83, v88
	v_mov_b32_e32 v85, v89
	v_pk_mul_f32 v[50:51], v[58:59], v[80:81]
	v_pk_fma_f32 v[56:57], v[56:57], v[74:75], v[78:79] neg_lo:[0,0,1] neg_hi:[0,0,1]
	v_pk_add_f32 v[78:79], v[82:83], v[84:85] neg_lo:[0,1] neg_hi:[0,1]
	v_mov_b32_e32 v77, v50
	v_mov_b32_e32 v87, v51
	v_pk_fma_f32 v[48:49], v[48:49], v[74:75], v[62:63]
	v_pk_add_f32 v[50:51], v[76:77], v[86:87]
	v_mov_b32_e32 v58, v78
	v_mov_b32_e32 v59, v79
	v_mov_b32_e32 v62, v70
	v_mov_b32_e32 v63, v71
.LBB0_411:
	s_or_b64 exec, exec, s[0:1]
	s_waitcnt vmcnt(0)
	v_add_f32_e32 v64, 0, v64
	v_add_f32_e32 v64, v64, v65
	v_add_f32_e32 v64, v64, v66
	v_add_f32_e32 v64, v64, v67
	v_add_f32_e32 v64, v64, v68
	v_add_f32_e32 v64, v64, v69
	v_fmamk_f32 v64, v64, 0x3b2aaaab, v252
	v_mul_f32_e32 v65, 0x4b800000, v64
	v_cmp_gt_f32_e64 s[0:1], s25, v64
	s_nop 1
	v_cndmask_b32_e64 v64, v64, v65, s[0:1]
	v_rsq_f32_e32 v66, v64
	v_mov_b64_e32 v[64:65], s[22:23]
	v_mul_f32_e32 v67, 0x45800000, v66
	v_cndmask_b32_e64 v66, v66, v67, s[0:1]
	v_mul_f32_e32 v66, 0x3dd53b94, v66
	v_pk_mul_f32 v[62:63], v[66:67], v[62:63] op_sel_hi:[0,1]
	v_pk_mul_f32 v[60:61], v[66:67], v[60:61] op_sel_hi:[0,1]
	v_pk_mul_f32 v[58:59], v[66:67], v[58:59] op_sel_hi:[0,1]
	v_pk_mul_f32 v[56:57], v[66:67], v[56:57] op_sel_hi:[0,1]
	v_mad_i64_i32 v[64:65], s[0:1], v72, s8, v[64:65]
	v_lshl_add_u64 v[64:65], v[64:65], 0, v[128:129]
	s_waitcnt lgkmcnt(0)
	v_mov_b32_e32 v67, v56
	s_nop 1
	v_permlane16_swap_b32_e32 v60, v67
	s_waitcnt lgkmcnt(0)
	v_mov_b32_e32 v56, v61
	v_mov_b32_e32 v61, v57
	s_nop 1
	v_permlane16_swap_b32_e32 v56, v61
	s_waitcnt lgkmcnt(0)
	v_mov_b32_e32 v57, v62
	v_mov_b32_e32 v62, v58
	s_nop 1
	v_permlane16_swap_b32_e32 v57, v62
	s_waitcnt lgkmcnt(0)
	v_mov_b32_e32 v58, v63
	s_nop 1
	v_permlane16_swap_b32_e32 v58, v59
	v_cvt_pk_bf16_f32 v56, v60, v56
	v_cvt_pk_bf16_f32 v57, v57, v58
	v_cvt_pk_bf16_f32 v58, v67, v61
	v_lshl_add_u64 v[60:61], v[64:65], 0, v[104:105]
	v_cvt_pk_bf16_f32 v59, v62, v59
	v_lshl_add_u64 v[60:61], v[60:61], 0, v[176:177]
	v_pk_mul_f32 v[54:55], v[66:67], v[54:55] op_sel_hi:[0,1]
	v_pk_mul_f32 v[52:53], v[66:67], v[52:53] op_sel_hi:[0,1]
	v_pk_mul_f32 v[50:51], v[66:67], v[50:51] op_sel_hi:[0,1]
	v_pk_mul_f32 v[48:49], v[66:67], v[48:49] op_sel_hi:[0,1]
	global_store_dwordx4 v[60:61], v[56:59], off
	v_cndmask_b32_e32 v61, v55, v51, vcc
	ds_bpermute_b32 v61, v130, v61
	v_mov_b64_e32 v[56:57], s[34:35]
	v_mad_i64_i32 v[56:57], s[0:1], v72, s8, v[56:57]
	v_lshl_add_u64 v[56:57], v[56:57], 0, v[128:129]
	s_waitcnt lgkmcnt(1)
	v_mov_b32_e32 v58, v48
	s_nop 1
	v_permlane16_swap_b32_e32 v52, v58
	s_waitcnt lgkmcnt(1)
	v_mov_b32_e32 v48, v53
	v_mov_b32_e32 v53, v49
	s_nop 1
	v_permlane16_swap_b32_e32 v48, v53
	s_waitcnt lgkmcnt(1)
	v_mov_b32_e32 v49, v54
	v_mov_b32_e32 v54, v50
	s_nop 1
	v_permlane16_swap_b32_e32 v49, v54
	s_waitcnt lgkmcnt(0)
	v_cndmask_b32_e32 v50, v61, v55, vcc
	v_cvt_pk_bf16_f32 v48, v52, v48
	v_cvt_pk_bf16_f32 v49, v49, v50
	v_cvt_pk_bf16_f32 v50, v58, v53
	v_lshl_add_u64 v[52:53], v[56:57], 0, v[104:105]
	v_cndmask_b32_e32 v51, v51, v61, vcc
	v_lshl_add_u64 v[52:53], v[52:53], 0, v[176:177]
	s_mov_b32 s0, 0x3900000
	v_cvt_pk_bf16_f32 v51, v54, v51
	v_add_co_u32_e64 v52, s[0:1], s0, v52
	v_or_b32_e32 v54, 0x50, v143
	s_nop 0
	v_addc_co_u32_e64 v53, s[0:1], 0, v53, s[0:1]
	v_or_b32_e32 v56, v144, v54
	global_store_dwordx4 v[52:53], v[48:51], off offset:64
	s_nop 1
	v_lshlrev_b32_e32 v48, 3, v56
	v_ashrrev_i32_e32 v49, 31, v48
	v_lshl_add_u64 v[48:49], v[48:49], 2, s[4:5]
	global_load_dwordx2 v[52:53], v[48:49], off offset:16
	s_nop 0
	global_load_dwordx4 v[48:51], v[48:49], off
	s_and_saveexec_b64 s[0:1], s[40:41]
	s_cbranch_execz .LBB0_413
	v_or_b32_e32 v54, v142, v54
	v_lshlrev_b32_e32 v54, 7, v54
	v_mov_b32_e32 v55, v177
	v_lshl_add_u64 v[66:67], v[134:135], 0, v[54:55]
	v_lshl_add_u64 v[68:69], v[132:133], 0, v[54:55]
	global_load_dwordx4 v[58:61], v[66:67], off
	global_load_dwordx4 v[62:65], v[68:69], off
	s_waitcnt vmcnt(0)
	v_pk_mul_f32 v[70:71], v[44:45], v[62:63]
	v_pk_mul_f32 v[54:55], v[32:33], v[62:63]
	v_mul_f32_e32 v62, v46, v60
	v_mul_f32_e32 v72, v34, v64
	v_mul_f32_e32 v74, v46, v64
	v_mul_f32_e32 v60, v34, v60
	v_mov_b32_e32 v34, v47
	v_mov_b32_e32 v64, v61
	v_mov_b32_e32 v46, v35
	v_pk_mul_f32 v[76:77], v[34:35], v[64:65]
	v_pk_mul_f32 v[34:35], v[46:47], v[64:65]
	v_mov_b32_e32 v63, v76
	v_mov_b32_e32 v73, v77
	v_mov_b32_e32 v61, v34
	v_mov_b32_e32 v75, v35
	v_pk_fma_f32 v[44:45], v[44:45], v[58:59], v[54:55] neg_lo:[0,0,1] neg_hi:[0,0,1]
	v_pk_add_f32 v[54:55], v[62:63], v[72:73] neg_lo:[0,1] neg_hi:[0,1]
	v_pk_fma_f32 v[32:33], v[32:33], v[58:59], v[70:71]
	v_pk_add_f32 v[34:35], v[60:61], v[74:75]
	global_load_dwordx4 v[58:61], v[66:67], off offset:64
	global_load_dwordx4 v[62:65], v[68:69], off offset:64
	s_waitcnt vmcnt(1)
	v_mul_f32_e32 v66, v42, v60
	s_waitcnt vmcnt(0)
	v_mul_f32_e32 v68, v38, v64
	v_mul_f32_e32 v70, v42, v64
	v_mul_f32_e32 v60, v38, v60
	v_mov_b32_e32 v38, v43
	v_mov_b32_e32 v64, v61
	v_pk_mul_f32 v[72:73], v[38:39], v[64:65]
	v_mov_b32_e32 v42, v39
	v_pk_mul_f32 v[46:47], v[40:41], v[62:63]
	v_pk_mul_f32 v[62:63], v[36:37], v[62:63]
	v_mov_b32_e32 v67, v72
	v_mov_b32_e32 v69, v73
	v_pk_mul_f32 v[38:39], v[42:43], v[64:65]
	v_pk_fma_f32 v[40:41], v[40:41], v[58:59], v[62:63] neg_lo:[0,0,1] neg_hi:[0,0,1]
	v_pk_add_f32 v[62:63], v[66:67], v[68:69] neg_lo:[0,1] neg_hi:[0,1]
	v_mov_b32_e32 v61, v38
	v_mov_b32_e32 v71, v39
	v_pk_fma_f32 v[36:37], v[36:37], v[58:59], v[46:47]
	v_pk_add_f32 v[38:39], v[60:61], v[70:71]
	v_mov_b32_e32 v42, v62
	v_mov_b32_e32 v43, v63
	v_mov_b32_e32 v46, v54
	v_mov_b32_e32 v47, v55
.LBB0_413:
	s_or_b64 exec, exec, s[0:1]
	s_waitcnt vmcnt(0)
	v_add_f32_e32 v48, 0, v48
	v_add_f32_e32 v48, v48, v49
	v_add_f32_e32 v48, v48, v50
	v_add_f32_e32 v48, v48, v51
	v_add_f32_e32 v48, v48, v52
	v_add_f32_e32 v48, v48, v53
	v_fmamk_f32 v48, v48, 0x3b2aaaab, v252
	v_mul_f32_e32 v49, 0x4b800000, v48
	v_cmp_gt_f32_e64 s[0:1], s25, v48
	v_mov_b32_e32 v105, v177
	s_nop 0
	v_cndmask_b32_e64 v48, v48, v49, s[0:1]
	v_rsq_f32_e32 v50, v48
	v_mov_b64_e32 v[48:49], s[22:23]
	v_mul_f32_e32 v51, 0x45800000, v50
	v_cndmask_b32_e64 v50, v50, v51, s[0:1]
	v_mul_f32_e32 v50, 0x3dd53b94, v50
	v_pk_mul_f32 v[46:47], v[50:51], v[46:47] op_sel_hi:[0,1]
	v_pk_mul_f32 v[44:45], v[50:51], v[44:45] op_sel_hi:[0,1]
	v_pk_mul_f32 v[42:43], v[50:51], v[42:43] op_sel_hi:[0,1]
	v_pk_mul_f32 v[40:41], v[50:51], v[40:41] op_sel_hi:[0,1]
	v_mad_i64_i32 v[48:49], s[0:1], v56, s8, v[48:49]
	v_lshl_add_u64 v[48:49], v[48:49], 0, v[128:129]
	s_waitcnt lgkmcnt(0)
	v_mov_b32_e32 v51, v40
	s_nop 1
	v_permlane16_swap_b32_e32 v44, v51
	s_waitcnt lgkmcnt(0)
	v_mov_b32_e32 v40, v45
	v_mov_b32_e32 v45, v41
	s_nop 1
	v_permlane16_swap_b32_e32 v40, v45
	s_waitcnt lgkmcnt(0)
	v_mov_b32_e32 v41, v46
	v_mov_b32_e32 v46, v42
	s_nop 1
	v_permlane16_swap_b32_e32 v41, v46
	s_waitcnt lgkmcnt(0)
	v_mov_b32_e32 v42, v47
	s_nop 1
	v_permlane16_swap_b32_e32 v42, v43
	v_cvt_pk_bf16_f32 v40, v44, v40
	v_cvt_pk_bf16_f32 v41, v41, v42
	v_cvt_pk_bf16_f32 v42, v51, v45
	v_lshl_add_u64 v[44:45], v[48:49], 0, v[104:105]
	v_cvt_pk_bf16_f32 v43, v46, v43
	v_lshl_add_u64 v[44:45], v[44:45], 0, v[176:177]
	v_pk_mul_f32 v[34:35], v[50:51], v[34:35] op_sel_hi:[0,1]
	v_pk_mul_f32 v[32:33], v[50:51], v[32:33] op_sel_hi:[0,1]
	v_pk_mul_f32 v[38:39], v[50:51], v[38:39] op_sel_hi:[0,1]
	v_pk_mul_f32 v[36:37], v[50:51], v[36:37] op_sel_hi:[0,1]
	global_store_dwordx4 v[44:45], v[40:43], off
	v_cndmask_b32_e32 v44, v34, v38, vcc
	v_cndmask_b32_e32 v45, v35, v39, vcc
	ds_bpermute_b32 v44, v130, v44
	ds_bpermute_b32 v45, v130, v45
	v_mov_b64_e32 v[40:41], s[34:35]
	v_mad_i64_i32 v[40:41], s[0:1], v56, s8, v[40:41]
	v_lshl_add_u64 v[40:41], v[40:41], 0, v[128:129]
	s_waitcnt lgkmcnt(2)
	s_nop 1
	v_permlane16_swap_b32_e32 v32, v36
	s_waitcnt lgkmcnt(2)
	s_nop 1
	v_permlane16_swap_b32_e32 v33, v37
	s_waitcnt lgkmcnt(1)
	v_cndmask_b32_e32 v34, v44, v34, vcc
	s_waitcnt lgkmcnt(0)
	v_cndmask_b32_e32 v35, v45, v35, vcc
	v_cvt_pk_bf16_f32 v32, v32, v33
	v_cvt_pk_bf16_f32 v33, v34, v35
	v_cvt_pk_bf16_f32 v34, v36, v37
	v_lshl_add_u64 v[36:37], v[40:41], 0, v[104:105]
	v_cndmask_b32_e32 v38, v38, v44, vcc
	v_cndmask_b32_e32 v39, v39, v45, vcc
	v_lshl_add_u64 v[36:37], v[36:37], 0, v[176:177]
	s_mov_b32 s0, 0x3900000
	v_cvt_pk_bf16_f32 v35, v38, v39
	v_add_co_u32_e64 v36, s[0:1], s0, v36
	v_or_b32_e32 v38, 0x60, v143
	s_nop 0
	v_addc_co_u32_e64 v37, s[0:1], 0, v37, s[0:1]
	v_or_b32_e32 v40, v144, v38
	global_store_dwordx4 v[36:37], v[32:35], off offset:64
	s_nop 1
	v_lshlrev_b32_e32 v32, 3, v40
	v_ashrrev_i32_e32 v33, 31, v32
	v_lshl_add_u64 v[32:33], v[32:33], 2, s[4:5]
	global_load_dwordx2 v[36:37], v[32:33], off offset:16
	s_nop 0
	global_load_dwordx4 v[32:35], v[32:33], off
	s_and_saveexec_b64 s[0:1], s[40:41]
	s_cbranch_execz .LBB0_415
	v_or_b32_e32 v38, v142, v38
	v_lshlrev_b32_e32 v38, 7, v38
	v_mov_b32_e32 v39, v177
	v_lshl_add_u64 v[50:51], v[134:135], 0, v[38:39]
	v_lshl_add_u64 v[52:53], v[132:133], 0, v[38:39]
	global_load_dwordx4 v[42:45], v[50:51], off
	global_load_dwordx4 v[46:49], v[52:53], off
	s_waitcnt vmcnt(0)
	v_pk_mul_f32 v[54:55], v[24:25], v[46:47]
	v_pk_mul_f32 v[38:39], v[20:21], v[46:47]
	v_mul_f32_e32 v46, v26, v44
	v_mul_f32_e32 v56, v22, v48
	v_mul_f32_e32 v58, v26, v48
	v_mul_f32_e32 v44, v22, v44
	v_mov_b32_e32 v22, v27
	v_mov_b32_e32 v48, v45
	v_mov_b32_e32 v26, v23
	v_pk_mul_f32 v[60:61], v[22:23], v[48:49]
	v_pk_mul_f32 v[22:23], v[26:27], v[48:49]
	v_mov_b32_e32 v47, v60
	v_mov_b32_e32 v57, v61
	v_mov_b32_e32 v45, v22
	v_mov_b32_e32 v59, v23
	v_pk_fma_f32 v[24:25], v[24:25], v[42:43], v[38:39] neg_lo:[0,0,1] neg_hi:[0,0,1]
	v_pk_add_f32 v[38:39], v[46:47], v[56:57] neg_lo:[0,1] neg_hi:[0,1]
	v_pk_fma_f32 v[20:21], v[20:21], v[42:43], v[54:55]
	v_pk_add_f32 v[22:23], v[44:45], v[58:59]
	global_load_dwordx4 v[42:45], v[50:51], off offset:64
	global_load_dwordx4 v[46:49], v[52:53], off offset:64
	s_waitcnt vmcnt(1)
	v_mul_f32_e32 v50, v30, v44
	s_waitcnt vmcnt(0)
	v_mul_f32_e32 v52, v18, v48
	v_mul_f32_e32 v54, v30, v48
	v_mul_f32_e32 v44, v18, v44
	v_mov_b32_e32 v18, v31
	v_mov_b32_e32 v48, v45
	v_pk_mul_f32 v[56:57], v[18:19], v[48:49]
	v_mov_b32_e32 v30, v19
	v_pk_mul_f32 v[26:27], v[28:29], v[46:47]
	v_pk_mul_f32 v[46:47], v[16:17], v[46:47]
	v_mov_b32_e32 v51, v56
	v_mov_b32_e32 v53, v57
	v_pk_mul_f32 v[18:19], v[30:31], v[48:49]
	v_pk_fma_f32 v[28:29], v[28:29], v[42:43], v[46:47] neg_lo:[0,0,1] neg_hi:[0,0,1]
	v_pk_add_f32 v[46:47], v[50:51], v[52:53] neg_lo:[0,1] neg_hi:[0,1]
	v_mov_b32_e32 v45, v18
	v_mov_b32_e32 v55, v19
	v_pk_fma_f32 v[16:17], v[16:17], v[42:43], v[26:27]
	v_pk_add_f32 v[18:19], v[44:45], v[54:55]
	v_mov_b32_e32 v30, v46
	v_mov_b32_e32 v31, v47
	v_mov_b32_e32 v26, v38
	v_mov_b32_e32 v27, v39
.LBB0_415:
	s_or_b64 exec, exec, s[0:1]
	s_waitcnt vmcnt(0)
	v_add_f32_e32 v32, 0, v32
	v_add_f32_e32 v32, v32, v33
	v_add_f32_e32 v32, v32, v34
	v_add_f32_e32 v32, v32, v35
	v_add_f32_e32 v32, v32, v36
	v_add_f32_e32 v32, v32, v37
	v_fmamk_f32 v32, v32, 0x3b2aaaab, v252
	v_mul_f32_e32 v33, 0x4b800000, v32
	v_cmp_gt_f32_e64 s[0:1], s25, v32
	s_nop 1
	v_cndmask_b32_e64 v32, v32, v33, s[0:1]
	v_rsq_f32_e32 v34, v32
	v_mov_b64_e32 v[32:33], s[22:23]
	v_mul_f32_e32 v35, 0x45800000, v34
	v_cndmask_b32_e64 v34, v34, v35, s[0:1]
	v_mul_f32_e32 v34, 0x3dd53b94, v34
	v_pk_mul_f32 v[26:27], v[34:35], v[26:27] op_sel_hi:[0,1]
	v_pk_mul_f32 v[24:25], v[34:35], v[24:25] op_sel_hi:[0,1]
	v_pk_mul_f32 v[30:31], v[34:35], v[30:31] op_sel_hi:[0,1]
	v_pk_mul_f32 v[28:29], v[34:35], v[28:29] op_sel_hi:[0,1]
	v_cndmask_b32_e32 v35, v24, v28, vcc
	ds_bpermute_b32 v35, v130, v35
	v_mad_i64_i32 v[32:33], s[0:1], v40, s8, v[32:33]
	v_lshl_add_u64 v[32:33], v[32:33], 0, v[128:129]
	s_waitcnt lgkmcnt(0)
	v_cndmask_b32_e32 v24, v35, v24, vcc
	v_cndmask_b32_e32 v28, v28, v35, vcc
	s_waitcnt lgkmcnt(0)
	s_nop 1
	v_permlane16_swap_b32_e32 v25, v29
	s_waitcnt lgkmcnt(0)
	s_waitcnt lgkmcnt(0)
	s_nop 1
	v_permlane16_swap_b32_e32 v26, v30
	s_nop 1
	v_permlane16_swap_b32_e32 v27, v31
	v_cvt_pk_bf16_f32 v24, v24, v25
	v_cvt_pk_bf16_f32 v25, v26, v27
	v_cvt_pk_bf16_f32 v26, v28, v29
	v_lshl_add_u64 v[28:29], v[32:33], 0, v[104:105]
	v_cvt_pk_bf16_f32 v27, v30, v31
	v_lshl_add_u64 v[28:29], v[28:29], 0, v[176:177]
	v_pk_mul_f32 v[22:23], v[34:35], v[22:23] op_sel_hi:[0,1]
	v_pk_mul_f32 v[20:21], v[34:35], v[20:21] op_sel_hi:[0,1]
	v_pk_mul_f32 v[18:19], v[34:35], v[18:19] op_sel_hi:[0,1]
	v_pk_mul_f32 v[16:17], v[34:35], v[16:17] op_sel_hi:[0,1]
	global_store_dwordx4 v[28:29], v[24:27], off
	v_cndmask_b32_e32 v29, v23, v19, vcc
	ds_bpermute_b32 v29, v130, v29
	v_mov_b64_e32 v[24:25], s[34:35]
	v_mad_i64_i32 v[24:25], s[0:1], v40, s8, v[24:25]
	v_lshl_add_u64 v[24:25], v[24:25], 0, v[128:129]
	s_waitcnt lgkmcnt(1)
	v_mov_b32_e32 v26, v16
	s_nop 1
	v_permlane16_swap_b32_e32 v20, v26
	s_waitcnt lgkmcnt(1)
	v_mov_b32_e32 v16, v21
	v_mov_b32_e32 v21, v17
	s_nop 1
	v_permlane16_swap_b32_e32 v16, v21
	s_waitcnt lgkmcnt(1)
	v_mov_b32_e32 v17, v22
	v_mov_b32_e32 v22, v18
	s_nop 1
	v_permlane16_swap_b32_e32 v17, v22
	s_waitcnt lgkmcnt(0)
	v_cndmask_b32_e32 v18, v29, v23, vcc
	v_cvt_pk_bf16_f32 v16, v20, v16
	v_cvt_pk_bf16_f32 v17, v17, v18
	v_cvt_pk_bf16_f32 v18, v26, v21
	v_lshl_add_u64 v[20:21], v[24:25], 0, v[104:105]
	v_cndmask_b32_e32 v19, v19, v29, vcc
	v_lshl_add_u64 v[20:21], v[20:21], 0, v[176:177]
	s_mov_b32 s0, 0x3900000
	v_cvt_pk_bf16_f32 v19, v22, v19
	v_add_co_u32_e64 v20, s[0:1], s0, v20
	v_or_b32_e32 v22, 0x70, v143
	s_nop 0
	v_addc_co_u32_e64 v21, s[0:1], 0, v21, s[0:1]
	v_or_b32_e32 v24, v144, v22
	global_store_dwordx4 v[20:21], v[16:19], off offset:64
	s_nop 1
	v_lshlrev_b32_e32 v16, 3, v24
	v_ashrrev_i32_e32 v17, 31, v16
	v_lshl_add_u64 v[16:17], v[16:17], 2, s[4:5]
	global_load_dwordx2 v[20:21], v[16:17], off offset:16
	s_nop 0
	global_load_dwordx4 v[16:19], v[16:17], off
	s_and_saveexec_b64 s[0:1], s[40:41]
	s_cbranch_execz .LBB0_417
	v_or_b32_e32 v22, v142, v22
	v_lshlrev_b32_e32 v22, 7, v22
	v_mov_b32_e32 v23, v177
	v_lshl_add_u64 v[34:35], v[134:135], 0, v[22:23]
	v_lshl_add_u64 v[36:37], v[132:133], 0, v[22:23]
	global_load_dwordx4 v[26:29], v[34:35], off
	global_load_dwordx4 v[30:33], v[36:37], off
	s_waitcnt vmcnt(0)
	v_pk_mul_f32 v[38:39], v[8:9], v[30:31]
	v_pk_mul_f32 v[22:23], v[0:1], v[30:31]
	v_mul_f32_e32 v30, v10, v28
	v_mul_f32_e32 v40, v2, v32
	v_mul_f32_e32 v42, v10, v32
	v_mul_f32_e32 v28, v2, v28
	v_mov_b32_e32 v2, v11
	v_mov_b32_e32 v32, v29
	v_mov_b32_e32 v10, v3
	v_pk_mul_f32 v[44:45], v[2:3], v[32:33]
	v_pk_mul_f32 v[2:3], v[10:11], v[32:33]
	v_mov_b32_e32 v31, v44
	v_mov_b32_e32 v41, v45
	v_mov_b32_e32 v29, v2
	v_mov_b32_e32 v43, v3
	v_pk_fma_f32 v[8:9], v[8:9], v[26:27], v[22:23] neg_lo:[0,0,1] neg_hi:[0,0,1]
	v_pk_add_f32 v[22:23], v[30:31], v[40:41] neg_lo:[0,1] neg_hi:[0,1]
	v_pk_fma_f32 v[0:1], v[0:1], v[26:27], v[38:39]
	v_pk_add_f32 v[2:3], v[28:29], v[42:43]
	global_load_dwordx4 v[26:29], v[34:35], off offset:64
	global_load_dwordx4 v[30:33], v[36:37], off offset:64
	s_waitcnt vmcnt(1)
	v_mul_f32_e32 v34, v14, v28
	s_waitcnt vmcnt(0)
	v_mul_f32_e32 v36, v6, v32
	v_mul_f32_e32 v38, v14, v32
	v_mul_f32_e32 v28, v6, v28
	v_mov_b32_e32 v6, v15
	v_mov_b32_e32 v32, v29
	v_pk_mul_f32 v[40:41], v[6:7], v[32:33]
	v_mov_b32_e32 v14, v7
	v_pk_mul_f32 v[10:11], v[12:13], v[30:31]
	v_pk_mul_f32 v[30:31], v[4:5], v[30:31]
	v_mov_b32_e32 v35, v40
	v_mov_b32_e32 v37, v41
	v_pk_mul_f32 v[6:7], v[14:15], v[32:33]
	v_pk_fma_f32 v[12:13], v[12:13], v[26:27], v[30:31] neg_lo:[0,0,1] neg_hi:[0,0,1]
	v_pk_add_f32 v[30:31], v[34:35], v[36:37] neg_lo:[0,1] neg_hi:[0,1]
	v_mov_b32_e32 v29, v6
	v_mov_b32_e32 v39, v7
	v_pk_fma_f32 v[4:5], v[4:5], v[26:27], v[10:11]
	v_pk_add_f32 v[6:7], v[28:29], v[38:39]
	v_mov_b32_e32 v14, v30
	v_mov_b32_e32 v15, v31
	v_mov_b32_e32 v10, v22
	v_mov_b32_e32 v11, v23
.LBB0_417:
	s_or_b64 exec, exec, s[0:1]
	s_waitcnt vmcnt(0)
	v_add_f32_e32 v16, 0, v16
	v_add_f32_e32 v16, v16, v17
	v_add_f32_e32 v16, v16, v18
	v_add_f32_e32 v16, v16, v19
	v_add_f32_e32 v16, v16, v20
	v_add_f32_e32 v16, v16, v21
	v_fmamk_f32 v16, v16, 0x3b2aaaab, v252
	v_mul_f32_e32 v17, 0x4b800000, v16
	v_cmp_gt_f32_e64 s[0:1], s25, v16
	v_mov_b32_e32 v105, v177
	s_nop 0
	v_cndmask_b32_e64 v16, v16, v17, s[0:1]
	v_rsq_f32_e32 v18, v16
	v_mov_b64_e32 v[16:17], s[22:23]
	v_mul_f32_e32 v19, 0x45800000, v18
	v_cndmask_b32_e64 v18, v18, v19, s[0:1]
	v_mul_f32_e32 v18, 0x3dd53b94, v18
	v_pk_mul_f32 v[10:11], v[18:19], v[10:11] op_sel_hi:[0,1]
	v_pk_mul_f32 v[8:9], v[18:19], v[8:9] op_sel_hi:[0,1]
	v_pk_mul_f32 v[14:15], v[18:19], v[14:15] op_sel_hi:[0,1]
	v_pk_mul_f32 v[12:13], v[18:19], v[12:13] op_sel_hi:[0,1]
	v_cndmask_b32_e32 v19, v8, v12, vcc
	ds_bpermute_b32 v19, v130, v19
	v_mad_i64_i32 v[16:17], s[0:1], v24, s8, v[16:17]
	v_lshl_add_u64 v[16:17], v[16:17], 0, v[128:129]
	s_waitcnt lgkmcnt(0)
	v_cndmask_b32_e32 v8, v19, v8, vcc
	v_cndmask_b32_e32 v12, v12, v19, vcc
	s_waitcnt lgkmcnt(0)
	s_nop 1
	v_permlane16_swap_b32_e32 v9, v13
	s_waitcnt lgkmcnt(0)
	s_waitcnt lgkmcnt(0)
	s_nop 1
	v_permlane16_swap_b32_e32 v10, v14
	s_nop 1
	v_permlane16_swap_b32_e32 v11, v15
	v_cvt_pk_bf16_f32 v8, v8, v9
	v_cvt_pk_bf16_f32 v9, v10, v11
	v_cvt_pk_bf16_f32 v10, v12, v13
	v_lshl_add_u64 v[12:13], v[16:17], 0, v[104:105]
	v_cvt_pk_bf16_f32 v11, v14, v15
	v_lshl_add_u64 v[12:13], v[12:13], 0, v[176:177]
	v_pk_mul_f32 v[2:3], v[18:19], v[2:3] op_sel_hi:[0,1]
	v_pk_mul_f32 v[0:1], v[18:19], v[0:1] op_sel_hi:[0,1]
	v_pk_mul_f32 v[6:7], v[18:19], v[6:7] op_sel_hi:[0,1]
	v_pk_mul_f32 v[4:5], v[18:19], v[4:5] op_sel_hi:[0,1]
	global_store_dwordx4 v[12:13], v[8:11], off
	v_cndmask_b32_e32 v12, v2, v6, vcc
	v_cndmask_b32_e32 v13, v3, v7, vcc
	ds_bpermute_b32 v12, v130, v12
	ds_bpermute_b32 v13, v130, v13
	v_mov_b64_e32 v[8:9], s[34:35]
	v_mad_i64_i32 v[8:9], s[0:1], v24, s8, v[8:9]
	v_lshl_add_u64 v[8:9], v[8:9], 0, v[128:129]
	s_waitcnt lgkmcnt(2)
	s_nop 1
	v_permlane16_swap_b32_e32 v0, v4
	s_waitcnt lgkmcnt(2)
	s_nop 1
	v_permlane16_swap_b32_e32 v1, v5
	s_waitcnt lgkmcnt(1)
	v_cndmask_b32_e32 v2, v12, v2, vcc
	s_waitcnt lgkmcnt(0)
	v_cndmask_b32_e32 v3, v13, v3, vcc
	v_cvt_pk_bf16_f32 v0, v0, v1
	v_cvt_pk_bf16_f32 v1, v2, v3
	v_cvt_pk_bf16_f32 v2, v4, v5
	v_lshl_add_u64 v[4:5], v[8:9], 0, v[104:105]
	v_lshl_add_u64 v[4:5], v[4:5], 0, v[176:177]
	v_cndmask_b32_e32 v6, v6, v12, vcc
	v_cndmask_b32_e32 v7, v7, v13, vcc
	v_add_co_u32_e32 v4, vcc, 0x3900000, v4
	v_cvt_pk_bf16_f32 v3, v6, v7
	s_nop 0
	v_addc_co_u32_e32 v5, vcc, 0, v5, vcc
	global_store_dwordx4 v[4:5], v[0:3], off offset:64

.LBB0_456:
	v_lshl_add_u32 v52, v147, 3, s9
	v_cmp_lt_i32_e32 vcc, v189, v202
	v_mad_u64_u32 v[128:129], s[0:1], v52, s8, v[128:129]
	v_lshlrev_b32_e32 v176, 7, v149
	v_bfe_u32 v133, v146, 4, 1
	v_cndmask_b32_e32 v54, v203, v189, vcc
	v_lshl_add_u64 v[52:53], s[94:95], 0, v[176:177]
	v_lshlrev_b32_e32 v129, 2, v54
	v_lshlrev_b32_e32 v176, 5, v133
	v_lshlrev_b32_e32 v54, 3, v148
	v_lshl_add_u64 v[52:53], v[52:53], 0, v[176:177]
	v_and_b32_e32 v176, 16, v54
	v_lshl_add_u64 v[130:131], v[52:53], 0, v[176:177]
	v_add_u32_e32 v52, v128, v145
	v_mad_i64_i32 v[56:57], s[0:1], v52, s18, v[130:131]
	v_pk_mul_f32 v[52:53], v[126:127], v[134:135] op_sel_hi:[1,0]
	v_pk_mul_f32 v[54:55], v[124:125], v[134:135] op_sel_hi:[1,0]
	v_pk_mul_f32 v[58:59], v[122:123], v[134:135] op_sel_hi:[1,0]
	v_pk_mul_f32 v[120:121], v[120:121], v[134:135] op_sel_hi:[1,0]
	v_cmp_eq_u32_e64 s[40:41], 0, v133
	v_pk_mul_f32 v[112:113], v[112:113], v[134:135] op_sel_hi:[1,0]
	s_and_b64 vcc, exec, s[42:43]
	s_waitcnt lgkmcnt(0)
	s_nop 1
	v_permlane16_swap_b32_e32 v54, v120
	s_waitcnt lgkmcnt(0)
	s_nop 1
	v_permlane16_swap_b32_e32 v55, v121
	s_waitcnt lgkmcnt(0)
	v_mov_b32_e32 v122, v52
	s_nop 1
	v_permlane16_swap_b32_e32 v122, v58
	s_waitcnt lgkmcnt(0)
	s_nop 1
	v_permlane16_swap_b32_e32 v53, v59
	v_cvt_pk_bf16_f32 v52, v54, v55
	v_cvt_pk_bf16_f32 v53, v122, v53
	v_cvt_pk_bf16_f32 v54, v120, v121
	v_cvt_pk_bf16_f32 v55, v58, v59
	global_store_dwordx4 v[56:57], v[52:55], off
	v_pk_mul_f32 v[58:59], v[114:115], v[134:135] op_sel_hi:[1,0]
	s_nop 0
	v_pk_mul_f32 v[52:53], v[118:119], v[134:135] op_sel_hi:[1,0]
	v_pk_mul_f32 v[54:55], v[116:117], v[134:135] op_sel_hi:[1,0]
	s_waitcnt lgkmcnt(0)
	s_nop 1
	v_permlane16_swap_b32_e32 v54, v112
	s_waitcnt lgkmcnt(0)
	s_nop 1
	v_permlane16_swap_b32_e32 v55, v113
	s_waitcnt lgkmcnt(0)
	v_mov_b32_e32 v114, v52
	s_nop 1
	v_permlane16_swap_b32_e32 v114, v58
	s_waitcnt lgkmcnt(0)
	s_nop 1
	v_permlane16_swap_b32_e32 v53, v59
	v_cvt_pk_bf16_f32 v52, v54, v55
	v_cvt_pk_bf16_f32 v53, v114, v53
	v_cvt_pk_bf16_f32 v54, v112, v113
	v_cvt_pk_bf16_f32 v55, v58, v59
	v_or_b32_e32 v112, 16, v145
	global_store_dwordx4 v[56:57], v[52:55], off offset:64
	s_cbranch_vccnz .LBB0_458
	s_nop 0
	v_add_u32_e32 v52, v144, v112
	v_ashrrev_i32_e32 v53, 31, v52
	v_lshl_add_u64 v[52:53], v[52:53], 4, s[2:3]
	global_load_dwordx4 v[52:55], v[52:53], off
	s_waitcnt vmcnt(0)
	v_add_f32_e32 v52, v52, v53
	v_add_f32_e32 v52, v52, v54
	v_add_f32_e32 v52, v52, v55
	v_fmamk_f32 v52, v52, 0x3b800000, v252
	v_mul_f32_e32 v53, 0x4b800000, v52
	v_cmp_gt_f32_e32 vcc, s25, v52
	s_nop 1
	v_cndmask_b32_e32 v52, v52, v53, vcc
	v_rsq_f32_e32 v52, v52
	s_nop 0
	v_mul_f32_e32 v53, 0x45800000, v52
	v_cndmask_b32_e32 v132, v52, v53, vcc
.LBB0_458:
	s_nop 0
	v_add_u32_e32 v52, v128, v112
	v_mad_i64_i32 v[56:57], s[0:1], v52, s18, v[130:131]
	v_pk_mul_f32 v[52:53], v[110:111], v[132:133] op_sel_hi:[1,0]
	v_pk_mul_f32 v[54:55], v[108:109], v[132:133] op_sel_hi:[1,0]
	v_pk_mul_f32 v[58:59], v[106:107], v[132:133] op_sel_hi:[1,0]
	v_pk_mul_f32 v[104:105], v[104:105], v[132:133] op_sel_hi:[1,0]
	v_pk_mul_f32 v[96:97], v[96:97], v[132:133] op_sel_hi:[1,0]
	s_waitcnt lgkmcnt(0)
	s_nop 1
	v_permlane16_swap_b32_e32 v54, v104
	s_waitcnt lgkmcnt(0)
	s_nop 1
	v_permlane16_swap_b32_e32 v55, v105
	s_waitcnt lgkmcnt(0)
	v_mov_b32_e32 v106, v52
	s_nop 1
	v_permlane16_swap_b32_e32 v106, v58
	s_waitcnt lgkmcnt(0)
	s_nop 1
	v_permlane16_swap_b32_e32 v53, v59
	v_cvt_pk_bf16_f32 v52, v54, v55
	v_cvt_pk_bf16_f32 v53, v106, v53
	v_cvt_pk_bf16_f32 v54, v104, v105
	v_cvt_pk_bf16_f32 v55, v58, v59
	global_store_dwordx4 v[56:57], v[52:55], off
	v_pk_mul_f32 v[58:59], v[98:99], v[132:133] op_sel_hi:[1,0]
	s_and_b64 vcc, exec, s[42:43]
	v_pk_mul_f32 v[52:53], v[102:103], v[132:133] op_sel_hi:[1,0]
	v_pk_mul_f32 v[54:55], v[100:101], v[132:133] op_sel_hi:[1,0]
	s_waitcnt lgkmcnt(0)
	s_nop 1
	v_permlane16_swap_b32_e32 v54, v96
	s_waitcnt lgkmcnt(0)
	s_nop 1
	v_permlane16_swap_b32_e32 v55, v97
	s_waitcnt lgkmcnt(0)
	v_mov_b32_e32 v98, v52
	s_nop 1
	v_permlane16_swap_b32_e32 v98, v58
	s_waitcnt lgkmcnt(0)
	s_nop 1
	v_permlane16_swap_b32_e32 v53, v59
	v_cvt_pk_bf16_f32 v52, v54, v55
	v_cvt_pk_bf16_f32 v53, v98, v53
	v_cvt_pk_bf16_f32 v54, v96, v97
	v_cvt_pk_bf16_f32 v55, v58, v59
	v_or_b32_e32 v97, 32, v145
	v_mov_b32_e32 v96, 1.0
	v_mov_b32_e32 v98, 1.0
	global_store_dwordx4 v[56:57], v[52:55], off offset:64
	s_cbranch_vccnz .LBB0_460
	s_nop 0
	v_add_u32_e32 v52, v144, v97
	v_ashrrev_i32_e32 v53, 31, v52
	v_lshl_add_u64 v[52:53], v[52:53], 4, s[2:3]
	global_load_dwordx4 v[52:55], v[52:53], off
	s_waitcnt vmcnt(0)
	v_add_f32_e32 v52, v52, v53
	v_add_f32_e32 v52, v52, v54
	v_add_f32_e32 v52, v52, v55
	v_fmamk_f32 v52, v52, 0x3b800000, v252
	v_mul_f32_e32 v53, 0x4b800000, v52
	v_cmp_gt_f32_e32 vcc, s25, v52
	s_nop 1
	v_cndmask_b32_e32 v52, v52, v53, vcc
	v_rsq_f32_e32 v52, v52
	s_nop 0
	v_mul_f32_e32 v53, 0x45800000, v52
	v_cndmask_b32_e32 v98, v52, v53, vcc
.LBB0_460:
	s_nop 0
	v_add_u32_e32 v52, v128, v97
	v_mad_i64_i32 v[56:57], s[0:1], v52, s18, v[130:131]
	v_pk_mul_f32 v[52:53], v[94:95], v[98:99] op_sel_hi:[1,0]
	v_pk_mul_f32 v[54:55], v[92:93], v[98:99] op_sel_hi:[1,0]
	v_pk_mul_f32 v[58:59], v[90:91], v[98:99] op_sel_hi:[1,0]
	v_pk_mul_f32 v[88:89], v[88:89], v[98:99] op_sel_hi:[1,0]
	v_pk_mul_f32 v[80:81], v[80:81], v[98:99] op_sel_hi:[1,0]
	s_waitcnt lgkmcnt(0)
	s_nop 1
	v_permlane16_swap_b32_e32 v54, v88
	s_waitcnt lgkmcnt(0)
	s_nop 1
	v_permlane16_swap_b32_e32 v55, v89
	s_waitcnt lgkmcnt(0)
	v_mov_b32_e32 v90, v52
	s_nop 1
	v_permlane16_swap_b32_e32 v90, v58
	s_waitcnt lgkmcnt(0)
	s_nop 1
	v_permlane16_swap_b32_e32 v53, v59
	v_cvt_pk_bf16_f32 v52, v54, v55
	v_cvt_pk_bf16_f32 v53, v90, v53
	v_cvt_pk_bf16_f32 v54, v88, v89
	v_cvt_pk_bf16_f32 v55, v58, v59
	global_store_dwordx4 v[56:57], v[52:55], off
	v_pk_mul_f32 v[58:59], v[82:83], v[98:99] op_sel_hi:[1,0]
	s_and_b64 vcc, exec, s[42:43]
	v_pk_mul_f32 v[52:53], v[86:87], v[98:99] op_sel_hi:[1,0]
	v_pk_mul_f32 v[54:55], v[84:85], v[98:99] op_sel_hi:[1,0]
	s_waitcnt lgkmcnt(0)
	s_nop 1
	v_permlane16_swap_b32_e32 v54, v80
	s_waitcnt lgkmcnt(0)
	s_nop 1
	v_permlane16_swap_b32_e32 v55, v81
	s_waitcnt lgkmcnt(0)
	v_mov_b32_e32 v82, v52
	s_nop 1
	v_permlane16_swap_b32_e32 v82, v58
	s_waitcnt lgkmcnt(0)
	s_nop 1
	v_permlane16_swap_b32_e32 v53, v59
	v_cvt_pk_bf16_f32 v52, v54, v55
	v_cvt_pk_bf16_f32 v53, v82, v53
	v_cvt_pk_bf16_f32 v54, v80, v81
	v_cvt_pk_bf16_f32 v55, v58, v59
	v_or_b32_e32 v80, 48, v145
	global_store_dwordx4 v[56:57], v[52:55], off offset:64
	s_cbranch_vccnz .LBB0_462
	s_nop 0
	v_add_u32_e32 v52, v144, v80
	v_ashrrev_i32_e32 v53, 31, v52
	v_lshl_add_u64 v[52:53], v[52:53], 4, s[2:3]
	global_load_dwordx4 v[52:55], v[52:53], off
	s_waitcnt vmcnt(0)
	v_add_f32_e32 v52, v52, v53
	v_add_f32_e32 v52, v52, v54
	v_add_f32_e32 v52, v52, v55
	v_fmamk_f32 v52, v52, 0x3b800000, v252
	v_mul_f32_e32 v53, 0x4b800000, v52
	v_cmp_gt_f32_e32 vcc, s25, v52
	s_nop 1
	v_cndmask_b32_e32 v52, v52, v53, vcc
	v_rsq_f32_e32 v52, v52
	s_nop 0
	v_mul_f32_e32 v53, 0x45800000, v52
	v_cndmask_b32_e32 v96, v52, v53, vcc
.LBB0_462:
	s_nop 0
	v_add_u32_e32 v52, v128, v80
	v_mad_i64_i32 v[56:57], s[0:1], v52, s18, v[130:131]
	v_pk_mul_f32 v[52:53], v[78:79], v[96:97] op_sel_hi:[1,0]
	v_pk_mul_f32 v[54:55], v[76:77], v[96:97] op_sel_hi:[1,0]
	v_pk_mul_f32 v[58:59], v[74:75], v[96:97] op_sel_hi:[1,0]
	v_pk_mul_f32 v[72:73], v[72:73], v[96:97] op_sel_hi:[1,0]
	v_pk_mul_f32 v[64:65], v[64:65], v[96:97] op_sel_hi:[1,0]
	s_waitcnt lgkmcnt(0)
	s_nop 1
	v_permlane16_swap_b32_e32 v54, v72
	s_waitcnt lgkmcnt(0)
	s_nop 1
	v_permlane16_swap_b32_e32 v55, v73
	s_waitcnt lgkmcnt(0)
	v_mov_b32_e32 v74, v52
	s_nop 1
	v_permlane16_swap_b32_e32 v74, v58
	s_waitcnt lgkmcnt(0)
	s_nop 1
	v_permlane16_swap_b32_e32 v53, v59
	v_cvt_pk_bf16_f32 v52, v54, v55
	v_cvt_pk_bf16_f32 v53, v74, v53
	v_cvt_pk_bf16_f32 v54, v72, v73
	v_cvt_pk_bf16_f32 v55, v58, v59
	global_store_dwordx4 v[56:57], v[52:55], off
	v_pk_mul_f32 v[58:59], v[66:67], v[96:97] op_sel_hi:[1,0]
	s_and_b64 vcc, exec, s[42:43]
	v_pk_mul_f32 v[52:53], v[70:71], v[96:97] op_sel_hi:[1,0]
	v_pk_mul_f32 v[54:55], v[68:69], v[96:97] op_sel_hi:[1,0]
	s_waitcnt lgkmcnt(0)
	s_nop 1
	v_permlane16_swap_b32_e32 v54, v64
	s_waitcnt lgkmcnt(0)
	s_nop 1
	v_permlane16_swap_b32_e32 v55, v65
	s_waitcnt lgkmcnt(0)
	v_mov_b32_e32 v66, v52
	s_nop 1
	v_permlane16_swap_b32_e32 v66, v58
	s_waitcnt lgkmcnt(0)
	s_nop 1
	v_permlane16_swap_b32_e32 v53, v59
	v_cvt_pk_bf16_f32 v52, v54, v55
	v_cvt_pk_bf16_f32 v53, v66, v53
	v_cvt_pk_bf16_f32 v54, v64, v65
	v_cvt_pk_bf16_f32 v55, v58, v59
	v_or_b32_e32 v65, 64, v145
	v_mov_b32_e32 v64, 1.0
	v_mov_b32_e32 v66, 1.0
	global_store_dwordx4 v[56:57], v[52:55], off offset:64
	s_cbranch_vccnz .LBB0_464
	s_nop 0
	v_add_u32_e32 v52, v144, v65
	v_ashrrev_i32_e32 v53, 31, v52
	v_lshl_add_u64 v[52:53], v[52:53], 4, s[2:3]
	global_load_dwordx4 v[52:55], v[52:53], off
	s_waitcnt vmcnt(0)
	v_add_f32_e32 v52, v52, v53
	v_add_f32_e32 v52, v52, v54
	v_add_f32_e32 v52, v52, v55
	v_fmamk_f32 v52, v52, 0x3b800000, v252
	v_mul_f32_e32 v53, 0x4b800000, v52
	v_cmp_gt_f32_e32 vcc, s25, v52
	s_nop 1
	v_cndmask_b32_e32 v52, v52, v53, vcc
	v_rsq_f32_e32 v52, v52
	s_nop 0
	v_mul_f32_e32 v53, 0x45800000, v52
	v_cndmask_b32_e32 v66, v52, v53, vcc
.LBB0_464:
	s_nop 0
	v_add_u32_e32 v52, v128, v65
	v_mad_i64_i32 v[56:57], s[0:1], v52, s18, v[130:131]
	v_pk_mul_f32 v[52:53], v[62:63], v[66:67] op_sel_hi:[1,0]
	v_pk_mul_f32 v[54:55], v[60:61], v[66:67] op_sel_hi:[1,0]
	v_pk_mul_f32 v[58:59], v[158:159], v[66:67] op_sel_hi:[1,0]
	v_pk_mul_f32 v[60:61], v[156:157], v[66:67] op_sel_hi:[1,0]
	v_cndmask_b32_e64 v67, v53, v59, s[40:41]
	ds_bpermute_b32 v67, v129, v67
	s_and_b64 vcc, exec, s[42:43]
	s_waitcnt lgkmcnt(1)
	s_nop 1
	v_permlane16_swap_b32_e32 v54, v60
	s_waitcnt lgkmcnt(1)
	s_nop 1
	v_permlane16_swap_b32_e32 v55, v61
	s_waitcnt lgkmcnt(1)
	v_mov_b32_e32 v62, v52
	s_nop 1
	v_permlane16_swap_b32_e32 v62, v58
	s_waitcnt lgkmcnt(0)
	v_cndmask_b32_e64 v53, v67, v53, s[40:41]
	v_cndmask_b32_e64 v59, v59, v67, s[40:41]
	v_cvt_pk_bf16_f32 v52, v54, v55
	v_cvt_pk_bf16_f32 v53, v62, v53
	v_cvt_pk_bf16_f32 v54, v60, v61
	v_cvt_pk_bf16_f32 v55, v58, v59
	global_store_dwordx4 v[56:57], v[52:55], off
	v_pk_mul_f32 v[50:51], v[50:51], v[66:67] op_sel_hi:[1,0]
	v_pk_mul_f32 v[48:49], v[48:49], v[66:67] op_sel_hi:[1,0]
	v_pk_mul_f32 v[52:53], v[154:155], v[66:67] op_sel_hi:[1,0]
	v_pk_mul_f32 v[54:55], v[152:153], v[66:67] op_sel_hi:[1,0]
	s_waitcnt lgkmcnt(0)
	v_mov_b32_e32 v58, v48
	s_nop 1
	v_permlane16_swap_b32_e32 v54, v58
	s_waitcnt lgkmcnt(0)
	v_mov_b32_e32 v48, v55
	v_mov_b32_e32 v55, v49
	s_nop 1
	v_permlane16_swap_b32_e32 v48, v55
	s_waitcnt lgkmcnt(0)
	v_mov_b32_e32 v49, v52
	v_mov_b32_e32 v52, v50
	s_nop 1
	v_permlane16_swap_b32_e32 v49, v52
	s_waitcnt lgkmcnt(0)
	v_mov_b32_e32 v50, v53
	s_nop 1
	v_permlane16_swap_b32_e32 v50, v51
	v_cvt_pk_bf16_f32 v48, v54, v48
	v_cvt_pk_bf16_f32 v49, v49, v50
	v_cvt_pk_bf16_f32 v50, v58, v55
	v_cvt_pk_bf16_f32 v51, v52, v51
	global_store_dwordx4 v[56:57], v[48:51], off offset:64
	s_nop 1
	v_or_b32_e32 v48, 0x50, v145
	s_cbranch_vccnz .LBB0_466
	v_add_u32_e32 v50, v144, v48
	v_ashrrev_i32_e32 v51, 31, v50
	v_lshl_add_u64 v[50:51], v[50:51], 4, s[2:3]
	global_load_dwordx4 v[50:53], v[50:51], off
	s_waitcnt vmcnt(0)
	v_add_f32_e32 v49, v50, v51
	v_add_f32_e32 v49, v49, v52
	v_add_f32_e32 v49, v49, v53
	v_fmamk_f32 v49, v49, 0x3b800000, v252
	v_mul_f32_e32 v50, 0x4b800000, v49
	v_cmp_gt_f32_e32 vcc, s25, v49
	s_nop 1
	v_cndmask_b32_e32 v49, v49, v50, vcc
	v_rsq_f32_e32 v49, v49
	s_nop 0
	v_mul_f32_e32 v50, 0x45800000, v49
	v_cndmask_b32_e32 v64, v49, v50, vcc
.LBB0_466:
	v_pk_mul_f32 v[46:47], v[46:47], v[64:65] op_sel_hi:[1,0]
	v_pk_mul_f32 v[44:45], v[44:45], v[64:65] op_sel_hi:[1,0]
	v_pk_mul_f32 v[42:43], v[42:43], v[64:65] op_sel_hi:[1,0]
	v_pk_mul_f32 v[40:41], v[40:41], v[64:65] op_sel_hi:[1,0]
	v_add_u32_e32 v48, v128, v48
	s_waitcnt lgkmcnt(0)
	v_mov_b32_e32 v50, v40
	s_nop 1
	v_permlane16_swap_b32_e32 v44, v50
	s_waitcnt lgkmcnt(0)
	v_mov_b32_e32 v40, v45
	v_mov_b32_e32 v45, v41
	s_nop 1
	v_permlane16_swap_b32_e32 v40, v45
	s_waitcnt lgkmcnt(0)
	v_mov_b32_e32 v41, v46
	v_mov_b32_e32 v46, v42
	s_nop 1
	v_permlane16_swap_b32_e32 v41, v46
	s_waitcnt lgkmcnt(0)
	v_mov_b32_e32 v42, v47
	s_nop 1
	v_permlane16_swap_b32_e32 v42, v43
	v_mad_i64_i32 v[48:49], s[0:1], v48, s18, v[130:131]
	v_cvt_pk_bf16_f32 v40, v44, v40
	v_cvt_pk_bf16_f32 v41, v41, v42
	v_cvt_pk_bf16_f32 v42, v50, v45
	v_cvt_pk_bf16_f32 v43, v46, v43
	v_pk_mul_f32 v[38:39], v[38:39], v[64:65] op_sel_hi:[1,0]
	v_pk_mul_f32 v[36:37], v[36:37], v[64:65] op_sel_hi:[1,0]
	v_pk_mul_f32 v[34:35], v[34:35], v[64:65] op_sel_hi:[1,0]
	v_pk_mul_f32 v[32:33], v[32:33], v[64:65] op_sel_hi:[1,0]
	global_store_dwordx4 v[48:49], v[40:43], off
	s_and_b64 vcc, exec, s[42:43]
	s_nop 0
	s_waitcnt lgkmcnt(0)
	v_mov_b32_e32 v40, v32
	s_nop 1
	v_permlane16_swap_b32_e32 v36, v40
	s_waitcnt lgkmcnt(0)
	v_mov_b32_e32 v32, v37
	v_mov_b32_e32 v37, v33
	s_nop 1
	v_permlane16_swap_b32_e32 v32, v37
	s_waitcnt lgkmcnt(0)
	v_mov_b32_e32 v33, v38
	v_mov_b32_e32 v38, v34
	s_nop 1
	v_permlane16_swap_b32_e32 v33, v38
	s_waitcnt lgkmcnt(0)
	v_mov_b32_e32 v34, v39
	s_nop 1
	v_permlane16_swap_b32_e32 v34, v35
	v_cvt_pk_bf16_f32 v32, v36, v32
	v_cvt_pk_bf16_f32 v33, v33, v34
	v_cvt_pk_bf16_f32 v34, v40, v37
	v_cvt_pk_bf16_f32 v35, v38, v35
	global_store_dwordx4 v[48:49], v[32:35], off offset:64
	s_nop 1
	v_or_b32_e32 v33, 0x60, v145
	v_mov_b32_e32 v32, 1.0
	v_mov_b32_e32 v34, 1.0
	s_cbranch_vccnz .LBB0_468
	v_add_u32_e32 v34, v144, v33
	v_ashrrev_i32_e32 v35, 31, v34
	v_lshl_add_u64 v[34:35], v[34:35], 4, s[2:3]
	global_load_dwordx4 v[34:37], v[34:35], off
	s_waitcnt vmcnt(0)
	v_add_f32_e32 v34, v34, v35
	v_add_f32_e32 v34, v34, v36
	v_add_f32_e32 v34, v34, v37
	v_fmamk_f32 v34, v34, 0x3b800000, v252
	v_mul_f32_e32 v35, 0x4b800000, v34
	v_cmp_gt_f32_e32 vcc, s25, v34
	s_nop 1
	v_cndmask_b32_e32 v34, v34, v35, vcc
	v_rsq_f32_e32 v34, v34
	s_nop 0
	v_mul_f32_e32 v35, 0x45800000, v34
	v_cndmask_b32_e32 v34, v34, v35, vcc
.LBB0_468:
	v_add_u32_e32 v33, v128, v33
	v_pk_mul_f32 v[30:31], v[30:31], v[34:35] op_sel_hi:[1,0]
	v_pk_mul_f32 v[28:29], v[28:29], v[34:35] op_sel_hi:[1,0]
	v_pk_mul_f32 v[26:27], v[26:27], v[34:35] op_sel_hi:[1,0]
	v_pk_mul_f32 v[24:25], v[24:25], v[34:35] op_sel_hi:[1,0]
	v_mad_i64_i32 v[36:37], s[0:1], v33, s18, v[130:131]
	v_cndmask_b32_e64 v35, v29, v25, s[40:41]
	ds_bpermute_b32 v35, v129, v35
	s_and_b64 vcc, exec, s[42:43]
	s_waitcnt lgkmcnt(1)
	v_mov_b32_e32 v33, v24
	s_nop 1
	v_permlane16_swap_b32_e32 v28, v33
	s_waitcnt lgkmcnt(0)
	v_cndmask_b32_e64 v24, v35, v29, s[40:41]
	v_cndmask_b32_e64 v29, v25, v35, s[40:41]
	s_waitcnt lgkmcnt(0)
	v_mov_b32_e32 v25, v30
	v_mov_b32_e32 v30, v26
	s_nop 1
	v_permlane16_swap_b32_e32 v25, v30
	s_waitcnt lgkmcnt(0)
	v_mov_b32_e32 v26, v31
	s_nop 1
	v_permlane16_swap_b32_e32 v26, v27
	v_cvt_pk_bf16_f32 v24, v28, v24
	v_cvt_pk_bf16_f32 v25, v25, v26
	v_cvt_pk_bf16_f32 v26, v33, v29
	v_cvt_pk_bf16_f32 v27, v30, v27
	v_pk_mul_f32 v[22:23], v[22:23], v[34:35] op_sel_hi:[1,0]
	v_pk_mul_f32 v[20:21], v[20:21], v[34:35] op_sel_hi:[1,0]
	v_pk_mul_f32 v[18:19], v[18:19], v[34:35] op_sel_hi:[1,0]
	v_pk_mul_f32 v[16:17], v[16:17], v[34:35] op_sel_hi:[1,0]
	global_store_dwordx4 v[36:37], v[24:27], off
	s_nop 1
	s_waitcnt lgkmcnt(0)
	v_mov_b32_e32 v24, v16
	s_nop 1
	v_permlane16_swap_b32_e32 v20, v24
	s_waitcnt lgkmcnt(0)
	v_mov_b32_e32 v16, v21
	v_mov_b32_e32 v21, v17
	s_nop 1
	v_permlane16_swap_b32_e32 v16, v21
	s_waitcnt lgkmcnt(0)
	v_mov_b32_e32 v17, v22
	v_mov_b32_e32 v22, v18
	s_nop 1
	v_permlane16_swap_b32_e32 v17, v22
	s_waitcnt lgkmcnt(0)
	v_mov_b32_e32 v18, v23
	s_nop 1
	v_permlane16_swap_b32_e32 v18, v19
	v_cvt_pk_bf16_f32 v16, v20, v16
	v_cvt_pk_bf16_f32 v17, v17, v18
	v_cvt_pk_bf16_f32 v18, v24, v21
	v_cvt_pk_bf16_f32 v19, v22, v19
	global_store_dwordx4 v[36:37], v[16:19], off offset:64
	s_nop 1
	v_or_b32_e32 v16, 0x70, v145
	s_cbranch_vccnz .LBB0_390
	v_add_u32_e32 v18, v144, v16
	v_ashrrev_i32_e32 v19, 31, v18
	v_lshl_add_u64 v[18:19], v[18:19], 4, s[2:3]
	global_load_dwordx4 v[18:21], v[18:19], off
	s_waitcnt vmcnt(0)
	v_add_f32_e32 v17, v18, v19
	v_add_f32_e32 v17, v17, v20
	v_add_f32_e32 v17, v17, v21
	v_fmamk_f32 v17, v17, 0x3b800000, v252
	v_mul_f32_e32 v18, 0x4b800000, v17
	v_cmp_gt_f32_e32 vcc, s25, v17
	s_nop 1
	v_cndmask_b32_e32 v17, v17, v18, vcc
	v_rsq_f32_e32 v17, v17
	s_nop 0
	v_mul_f32_e32 v18, 0x45800000, v17
	v_cndmask_b32_e32 v32, v17, v18, vcc
	s_branch .LBB0_390

.LBB0_484:
	s_or_b64 exec, exec, s[30:31]
	v_mov_b64_e32 v[20:21], s[4:5]
	s_movk_i32 s42, 0x300
	v_mad_i64_i32 v[20:21], s[30:31], v16, s42, v[20:21]
	v_lshlrev_b64 v[22:23], 1, v[134:135]
	v_lshl_add_u64 v[20:21], v[20:21], 0, v[22:23]
	s_waitcnt lgkmcnt(0)
	v_mov_b32_e32 v17, v8
	s_nop 1
	v_permlane16_swap_b32_e32 v12, v17
	s_waitcnt lgkmcnt(0)
	v_mov_b32_e32 v8, v13
	v_mov_b32_e32 v13, v9
	s_nop 1
	v_permlane16_swap_b32_e32 v8, v13
	s_waitcnt lgkmcnt(0)
	v_mov_b32_e32 v9, v14
	v_mov_b32_e32 v14, v10
	s_nop 1
	v_permlane16_swap_b32_e32 v9, v14
	s_waitcnt lgkmcnt(0)
	v_mov_b32_e32 v10, v15
	s_nop 1
	v_permlane16_swap_b32_e32 v10, v11
	v_lshlrev_b32_e32 v176, 1, v180
	v_cvt_pk_bf16_f32 v8, v12, v8
	v_cvt_pk_bf16_f32 v9, v9, v10
	v_cvt_pk_bf16_f32 v10, v17, v13
	v_cvt_pk_bf16_f32 v11, v14, v11
	v_lshl_add_u64 v[12:13], v[20:21], 0, v[176:177]
	v_lshlrev_b32_e32 v14, 1, v179
	v_mov_b32_e32 v15, v177
	v_lshl_add_u64 v[12:13], v[12:13], 0, v[14:15]
	global_store_dwordx4 v[12:13], v[8:11], off
	v_cndmask_b32_e64 v13, v7, v3, s[40:41]
	ds_bpermute_b32 v13, v18, v13
	v_mov_b64_e32 v[8:9], s[34:35]
	v_mad_i64_i32 v[8:9], s[30:31], v16, s42, v[8:9]
	v_lshl_add_u64 v[8:9], v[8:9], 0, v[22:23]
	s_waitcnt lgkmcnt(1)
	v_mov_b32_e32 v10, v0
	s_nop 1
	v_permlane16_swap_b32_e32 v4, v10
	s_waitcnt lgkmcnt(1)
	v_mov_b32_e32 v0, v5
	v_mov_b32_e32 v5, v1
	s_nop 1
	v_permlane16_swap_b32_e32 v0, v5
	s_waitcnt lgkmcnt(1)
	v_mov_b32_e32 v1, v6
	v_mov_b32_e32 v6, v2
	s_nop 1
	v_permlane16_swap_b32_e32 v1, v6
	s_waitcnt lgkmcnt(0)
	v_cndmask_b32_e64 v2, v13, v7, s[40:41]
	v_cvt_pk_bf16_f32 v0, v4, v0
	v_cvt_pk_bf16_f32 v1, v1, v2
	v_cvt_pk_bf16_f32 v2, v10, v5
	v_lshl_add_u64 v[4:5], v[8:9], 0, v[176:177]
	v_lshl_add_u64 v[4:5], v[4:5], 0, v[14:15]
	v_cndmask_b32_e64 v3, v3, v13, s[40:41]
	v_add_co_u32_e32 v4, vcc, 0xa700000, v4
	v_cvt_pk_bf16_f32 v3, v6, v3
	s_nop 0
	v_addc_co_u32_e32 v5, vcc, 0, v5, vcc
	global_store_dwordx4 v[4:5], v[0:3], off offset:64

.LBB0_487:
	s_waitcnt lgkmcnt(0)
	s_barrier
	ds_read_b128 v[224:227], v184
	ds_read_b128 v[228:231], v184 offset:1024
	ds_read_b128 v[232:235], v184 offset:2048
	ds_read_b128 v[236:239], v184 offset:3072
	ds_read_b128 v[190:193], v185
	ds_read_b128 v[194:197], v185 offset:1024
	ds_read_b128 v[198:201], v185 offset:2048
	ds_read_b128 v[204:207], v185 offset:3072
	ds_read_b128 v[208:211], v185 offset:4096
	ds_read_b128 v[212:215], v185 offset:5120
	ds_read_b128 v[216:219], v185 offset:6144
	ds_read_b128 v[220:223], v185 offset:7168
	s_movk_i32 vcc_lo, 0x6000
	s_cmp_eq_u32 m0, 2
	s_cselect_b32 vcc_lo, 0xffff4000, vcc_lo
	s_add_u32 m0, m0, 1
	s_cmp_eq_u32 m0, 3
	s_cselect_b32 m0, 0, m0
	v_add_u32_e32 v185, vcc_lo, v185
	v_add_u32_e32 v184, vcc_lo, v184
	v_xor_b32_e32 v185, 64, v185
	v_xor_b32_e32 v184, 64, v184
	s_waitcnt lgkmcnt(7)
	v_mfma_f32_16x16x32_bf16 v[172:175], v[224:227], v[190:193], v[172:175]
	v_mfma_f32_16x16x32_bf16 v[168:171], v[228:231], v[190:193], v[168:171]
	v_mfma_f32_16x16x32_bf16 v[164:167], v[232:235], v[190:193], v[164:167]
	v_mfma_f32_16x16x32_bf16 v[156:159], v[236:239], v[190:193], v[156:159]
	ds_read_b128 v[190:193], v185
	s_waitcnt lgkmcnt(7)
	v_mfma_f32_16x16x32_bf16 v[144:147], v[224:227], v[194:197], v[144:147]
	v_mfma_f32_16x16x32_bf16 v[136:139], v[228:231], v[194:197], v[136:139]
	v_mfma_f32_16x16x32_bf16 v[132:135], v[232:235], v[194:197], v[132:135]
	v_mfma_f32_16x16x32_bf16 v[120:123], v[236:239], v[194:197], v[120:123]
	ds_read_b128 v[194:197], v185 offset:1024
	s_waitcnt lgkmcnt(7)
	v_mfma_f32_16x16x32_bf16 v[112:115], v[224:227], v[198:201], v[112:115]
	v_mfma_f32_16x16x32_bf16 v[108:111], v[228:231], v[198:201], v[108:111]
	v_mfma_f32_16x16x32_bf16 v[96:99], v[232:235], v[198:201], v[96:99]
	v_mfma_f32_16x16x32_bf16 v[92:95], v[236:239], v[198:201], v[92:95]
	ds_read_b128 v[198:201], v185 offset:2048
	s_waitcnt lgkmcnt(7)
	v_mfma_f32_16x16x32_bf16 v[88:91], v[224:227], v[204:207], v[88:91]
	v_mfma_f32_16x16x32_bf16 v[80:83], v[228:231], v[204:207], v[80:83]
	v_mfma_f32_16x16x32_bf16 v[72:75], v[232:235], v[204:207], v[72:75]
	v_mfma_f32_16x16x32_bf16 v[68:71], v[236:239], v[204:207], v[68:71]
	ds_read_b128 v[204:207], v185 offset:3072
	s_waitcnt lgkmcnt(7)
	v_mfma_f32_16x16x32_bf16 v[60:63], v[224:227], v[208:211], v[60:63]
	v_mfma_f32_16x16x32_bf16 v[52:55], v[228:231], v[208:211], v[52:55]
	v_mfma_f32_16x16x32_bf16 v[48:51], v[232:235], v[208:211], v[48:51]
	v_mfma_f32_16x16x32_bf16 v[44:47], v[236:239], v[208:211], v[44:47]
	ds_read_b128 v[208:211], v185 offset:4096
	s_waitcnt lgkmcnt(7)
	v_mfma_f32_16x16x32_bf16 v[40:43], v[224:227], v[212:215], v[40:43]
	v_mfma_f32_16x16x32_bf16 v[36:39], v[228:231], v[212:215], v[36:39]
	v_mfma_f32_16x16x32_bf16 v[32:35], v[232:235], v[212:215], v[32:35]
	v_mfma_f32_16x16x32_bf16 v[28:31], v[236:239], v[212:215], v[28:31]
	ds_read_b128 v[212:215], v185 offset:5120
	s_waitcnt lgkmcnt(7)
	v_mfma_f32_16x16x32_bf16 v[24:27], v[224:227], v[216:219], v[24:27]
	v_mfma_f32_16x16x32_bf16 v[20:23], v[228:231], v[216:219], v[20:23]
	v_mfma_f32_16x16x32_bf16 v[16:19], v[232:235], v[216:219], v[16:19]
	v_mfma_f32_16x16x32_bf16 v[12:15], v[236:239], v[216:219], v[12:15]
	ds_read_b128 v[216:219], v185 offset:6144
	s_waitcnt lgkmcnt(7)
	v_mfma_f32_16x16x32_bf16 v[8:11], v[224:227], v[220:223], v[8:11]
	v_mfma_f32_16x16x32_bf16 v[4:7], v[228:231], v[220:223], v[4:7]
	v_mfma_f32_16x16x32_bf16 v[0:3], v[232:235], v[220:223], v[0:3]
	v_mfma_f32_16x16x32_bf16 v[116:119], v[236:239], v[220:223], v[116:119]
	ds_read_b128 v[220:223], v185 offset:7168
	ds_read_b128 v[224:227], v184
	ds_read_b128 v[228:231], v184 offset:1024
	ds_read_b128 v[232:235], v184 offset:2048
	ds_read_b128 v[236:239], v184 offset:3072
	s_movk_i32 vcc_lo, 0x6000
	s_cmp_eq_u32 m0, 2
	s_cselect_b32 vcc_lo, 0xffff4000, vcc_lo
	s_add_u32 m0, m0, 1
	s_cmp_eq_u32 m0, 3
	s_cselect_b32 m0, 0, m0
	v_add_u32_e32 v185, vcc_lo, v185
	v_add_u32_e32 v184, vcc_lo, v184
	v_xor_b32_e32 v185, 64, v185
	v_xor_b32_e32 v184, 64, v184
	s_sub_u32 vcc_lo, s30, s98
	v_add_u32_e32 v186, vcc_lo, v178
	v_add_u32_e32 v187, vcc_lo, v180
	s_barrier
	s_waitcnt lgkmcnt(0)
	v_mfma_f32_16x16x32_bf16 v[172:175], v[224:227], v[190:193], v[172:175]
	s_waitcnt vmcnt(11)
	v_mfma_f32_16x16x32_bf16 v[168:171], v[228:231], v[190:193], v[168:171]
	ds_write_b128 v183, v[160:163]
	v_add_u32_e32 v160, s26, v186
	v_mfma_f32_16x16x32_bf16 v[164:167], v[232:235], v[190:193], v[164:167]
	global_load_dwordx4 v[160:163], v160, s[98:99] offset:128
	v_mfma_f32_16x16x32_bf16 v[156:159], v[236:239], v[190:193], v[156:159]
	s_waitcnt vmcnt(11)
	ds_write_b128 v183, v[152:155] offset:2048
	v_mfma_f32_16x16x32_bf16 v[144:147], v[224:227], v[194:197], v[144:147]
	v_add_u32_e32 v152, s27, v186
	v_mfma_f32_16x16x32_bf16 v[136:139], v[228:231], v[194:197], v[136:139]
	global_load_dwordx4 v[152:155], v152, s[98:99] offset:128
	s_waitcnt vmcnt(11)
	v_mfma_f32_16x16x32_bf16 v[132:135], v[232:235], v[194:197], v[132:135]
	ds_write_b128 v183, v[148:151] offset:4096
	v_mfma_f32_16x16x32_bf16 v[120:123], v[236:239], v[194:197], v[120:123]
	v_add_u32_e32 v148, s20, v186
	global_load_dwordx4 v[148:151], v148, s[98:99] offset:128
	v_mfma_f32_16x16x32_bf16 v[112:115], v[224:227], v[198:201], v[112:115]
	s_waitcnt vmcnt(11)
	v_mfma_f32_16x16x32_bf16 v[108:111], v[228:231], v[198:201], v[108:111]
	ds_write_b128 v183, v[128:131] offset:6144
	v_add_u32_e32 v128, s21, v186
	v_mfma_f32_16x16x32_bf16 v[96:99], v[232:235], v[198:201], v[96:99]
	global_load_dwordx4 v[128:131], v128, s[98:99] offset:128
	v_mfma_f32_16x16x32_bf16 v[92:95], v[236:239], v[198:201], v[92:95]
	s_waitcnt vmcnt(11)
	ds_write_b128 v183, v[124:127] offset:8192
	v_mfma_f32_16x16x32_bf16 v[88:91], v[224:227], v[204:207], v[88:91]
	v_add_u32_e32 v124, s56, v186
	v_mfma_f32_16x16x32_bf16 v[80:83], v[228:231], v[204:207], v[80:83]
	global_load_dwordx4 v[124:127], v124, s[98:99] offset:128
	s_waitcnt vmcnt(11)
	v_mfma_f32_16x16x32_bf16 v[72:75], v[232:235], v[204:207], v[72:75]
	ds_write_b128 v183, v[104:107] offset:10240
	v_mfma_f32_16x16x32_bf16 v[68:71], v[236:239], v[204:207], v[68:71]
	v_add_u32_e32 v104, s57, v186
	global_load_dwordx4 v[104:107], v104, s[98:99] offset:128
	v_mfma_f32_16x16x32_bf16 v[60:63], v[224:227], v[208:211], v[60:63]
	s_waitcnt vmcnt(11)
	v_mfma_f32_16x16x32_bf16 v[52:55], v[228:231], v[208:211], v[52:55]
	ds_write_b128 v183, v[100:103] offset:12288
	v_add_u32_e32 v100, s24, v186
	v_mfma_f32_16x16x32_bf16 v[48:51], v[232:235], v[208:211], v[48:51]
	global_load_dwordx4 v[100:103], v100, s[98:99] offset:128
	v_mfma_f32_16x16x32_bf16 v[44:47], v[236:239], v[208:211], v[44:47]
	s_waitcnt vmcnt(11)
	ds_write_b128 v183, v[84:87] offset:14336
	v_mfma_f32_16x16x32_bf16 v[40:43], v[224:227], v[212:215], v[40:43]
	v_add_u32_e32 v84, s96, v186
	v_mfma_f32_16x16x32_bf16 v[36:39], v[228:231], v[212:215], v[36:39]
	global_load_dwordx4 v[84:87], v84, s[98:99] offset:128
	s_waitcnt vmcnt(11)
	v_mfma_f32_16x16x32_bf16 v[32:35], v[232:235], v[212:215], v[32:35]
	ds_write_b128 v183, v[140:143] offset:16384
	v_mfma_f32_16x16x32_bf16 v[28:31], v[236:239], v[212:215], v[28:31]
	v_add_u32_e32 v140, 0x1800000, v187
	global_load_dwordx4 v[140:143], v140, s[98:99] offset:128
	v_mfma_f32_16x16x32_bf16 v[24:27], v[224:227], v[216:219], v[24:27]
	s_waitcnt vmcnt(11)
	v_mfma_f32_16x16x32_bf16 v[20:23], v[228:231], v[216:219], v[20:23]
	ds_write_b128 v183, v[76:79] offset:18432
	v_add_u32_e32 v76, 0x1810000, v187
	v_mfma_f32_16x16x32_bf16 v[16:19], v[232:235], v[216:219], v[16:19]
	global_load_dwordx4 v[76:79], v76, s[98:99] offset:128
	v_mfma_f32_16x16x32_bf16 v[12:15], v[236:239], v[216:219], v[12:15]
	s_waitcnt vmcnt(11)
	ds_write_b128 v183, v[64:67] offset:20480
	v_mfma_f32_16x16x32_bf16 v[8:11], v[224:227], v[220:223], v[8:11]
	v_add_u32_e32 v64, 0x1820000, v187
	v_mfma_f32_16x16x32_bf16 v[4:7], v[228:231], v[220:223], v[4:7]
	global_load_dwordx4 v[64:67], v64, s[98:99] offset:128
	s_waitcnt vmcnt(11)
	v_mfma_f32_16x16x32_bf16 v[0:3], v[232:235], v[220:223], v[0:3]
	ds_write_b128 v183, v[56:59] offset:22528
	v_mfma_f32_16x16x32_bf16 v[116:119], v[236:239], v[220:223], v[116:119]
	v_add_u32_e32 v56, 0x1830000, v187
	global_load_dwordx4 v[56:59], v56, s[98:99] offset:128
	v_cmp_gt_u32_e32 vcc, 0x6000, v183
	v_add_u32_e32 v182, 0xc000, v183
	v_add_u32_e32 v183, 0xffffa000, v183
	s_nop 0
	v_cndmask_b32_e32 v183, v183, v182, vcc
	s_add_u32 s30, s30, 0x80
	s_addc_u32 s31, s31, 0
	s_cmpk_lg_i32 s30, 0x780
	s_cbranch_scc1 .LBB0_487
	s_waitcnt lgkmcnt(0)
	s_barrier
	ds_read_b128 v[224:227], v184
	ds_read_b128 v[228:231], v184 offset:1024
	ds_read_b128 v[232:235], v184 offset:2048
	ds_read_b128 v[236:239], v184 offset:3072
	ds_read_b128 v[190:193], v185
	ds_read_b128 v[194:197], v185 offset:1024
	ds_read_b128 v[198:201], v185 offset:2048
	ds_read_b128 v[204:207], v185 offset:3072
	ds_read_b128 v[208:211], v185 offset:4096
	ds_read_b128 v[212:215], v185 offset:5120
	ds_read_b128 v[216:219], v185 offset:6144
	ds_read_b128 v[220:223], v185 offset:7168
	s_movk_i32 vcc_lo, 0x6000
	s_cmp_eq_u32 m0, 2
	s_cselect_b32 vcc_lo, 0xffff4000, vcc_lo
	s_add_u32 m0, m0, 1
	s_cmp_eq_u32 m0, 3
	s_cselect_b32 m0, 0, m0
	v_add_u32_e32 v185, vcc_lo, v185
	v_add_u32_e32 v184, vcc_lo, v184
	v_xor_b32_e32 v185, 64, v185
	v_xor_b32_e32 v184, 64, v184
	s_waitcnt lgkmcnt(7)
	v_mfma_f32_16x16x32_bf16 v[172:175], v[224:227], v[190:193], v[172:175]
	v_mfma_f32_16x16x32_bf16 v[168:171], v[228:231], v[190:193], v[168:171]
	v_mfma_f32_16x16x32_bf16 v[164:167], v[232:235], v[190:193], v[164:167]
	v_mfma_f32_16x16x32_bf16 v[156:159], v[236:239], v[190:193], v[156:159]
	ds_read_b128 v[190:193], v185
	s_waitcnt lgkmcnt(7)
	v_mfma_f32_16x16x32_bf16 v[144:147], v[224:227], v[194:197], v[144:147]
	v_mfma_f32_16x16x32_bf16 v[136:139], v[228:231], v[194:197], v[136:139]
	v_mfma_f32_16x16x32_bf16 v[132:135], v[232:235], v[194:197], v[132:135]
	v_mfma_f32_16x16x32_bf16 v[120:123], v[236:239], v[194:197], v[120:123]
	ds_read_b128 v[194:197], v185 offset:1024
	s_waitcnt lgkmcnt(7)
	v_mfma_f32_16x16x32_bf16 v[112:115], v[224:227], v[198:201], v[112:115]
	v_mfma_f32_16x16x32_bf16 v[108:111], v[228:231], v[198:201], v[108:111]
	v_mfma_f32_16x16x32_bf16 v[96:99], v[232:235], v[198:201], v[96:99]
	v_mfma_f32_16x16x32_bf16 v[92:95], v[236:239], v[198:201], v[92:95]
	ds_read_b128 v[198:201], v185 offset:2048
	s_waitcnt lgkmcnt(7)
	v_mfma_f32_16x16x32_bf16 v[88:91], v[224:227], v[204:207], v[88:91]
	v_mfma_f32_16x16x32_bf16 v[80:83], v[228:231], v[204:207], v[80:83]
	v_mfma_f32_16x16x32_bf16 v[72:75], v[232:235], v[204:207], v[72:75]
	v_mfma_f32_16x16x32_bf16 v[68:71], v[236:239], v[204:207], v[68:71]
	ds_read_b128 v[204:207], v185 offset:3072
	s_waitcnt lgkmcnt(7)
	v_mfma_f32_16x16x32_bf16 v[60:63], v[224:227], v[208:211], v[60:63]
	v_mfma_f32_16x16x32_bf16 v[52:55], v[228:231], v[208:211], v[52:55]
	v_mfma_f32_16x16x32_bf16 v[48:51], v[232:235], v[208:211], v[48:51]
	v_mfma_f32_16x16x32_bf16 v[44:47], v[236:239], v[208:211], v[44:47]
	ds_read_b128 v[208:211], v185 offset:4096
	s_waitcnt lgkmcnt(7)
	v_mfma_f32_16x16x32_bf16 v[40:43], v[224:227], v[212:215], v[40:43]
	v_mfma_f32_16x16x32_bf16 v[36:39], v[228:231], v[212:215], v[36:39]
	v_mfma_f32_16x16x32_bf16 v[32:35], v[232:235], v[212:215], v[32:35]
	v_mfma_f32_16x16x32_bf16 v[28:31], v[236:239], v[212:215], v[28:31]
	ds_read_b128 v[212:215], v185 offset:5120
	s_waitcnt lgkmcnt(7)
	v_mfma_f32_16x16x32_bf16 v[24:27], v[224:227], v[216:219], v[24:27]
	v_mfma_f32_16x16x32_bf16 v[20:23], v[228:231], v[216:219], v[20:23]
	v_mfma_f32_16x16x32_bf16 v[16:19], v[232:235], v[216:219], v[16:19]
	v_mfma_f32_16x16x32_bf16 v[12:15], v[236:239], v[216:219], v[12:15]
	ds_read_b128 v[216:219], v185 offset:6144
	s_waitcnt lgkmcnt(7)
	v_mfma_f32_16x16x32_bf16 v[8:11], v[224:227], v[220:223], v[8:11]
	v_mfma_f32_16x16x32_bf16 v[4:7], v[228:231], v[220:223], v[4:7]
	v_mfma_f32_16x16x32_bf16 v[0:3], v[232:235], v[220:223], v[0:3]
	v_mfma_f32_16x16x32_bf16 v[116:119], v[236:239], v[220:223], v[116:119]
	ds_read_b128 v[220:223], v185 offset:7168
	ds_read_b128 v[224:227], v184
	ds_read_b128 v[228:231], v184 offset:1024
	ds_read_b128 v[232:235], v184 offset:2048
	ds_read_b128 v[236:239], v184 offset:3072
	s_movk_i32 vcc_lo, 0x6000
	s_cmp_eq_u32 m0, 2
	s_cselect_b32 vcc_lo, 0xffff4000, vcc_lo
	s_add_u32 m0, m0, 1
	s_cmp_eq_u32 m0, 3
	s_cselect_b32 m0, 0, m0
	v_add_u32_e32 v185, vcc_lo, v185
	v_add_u32_e32 v184, vcc_lo, v184
	v_xor_b32_e32 v185, 64, v185
	v_xor_b32_e32 v184, 64, v184
	s_waitcnt lgkmcnt(0)
	v_mfma_f32_16x16x32_bf16 v[172:175], v[224:227], v[190:193], v[172:175]
	v_mfma_f32_16x16x32_bf16 v[168:171], v[228:231], v[190:193], v[168:171]
	v_mfma_f32_16x16x32_bf16 v[164:167], v[232:235], v[190:193], v[164:167]
	v_mfma_f32_16x16x32_bf16 v[156:159], v[236:239], v[190:193], v[156:159]
	v_mfma_f32_16x16x32_bf16 v[144:147], v[224:227], v[194:197], v[144:147]
	v_mfma_f32_16x16x32_bf16 v[136:139], v[228:231], v[194:197], v[136:139]
	v_mfma_f32_16x16x32_bf16 v[132:135], v[232:235], v[194:197], v[132:135]
	v_mfma_f32_16x16x32_bf16 v[120:123], v[236:239], v[194:197], v[120:123]
	v_mfma_f32_16x16x32_bf16 v[112:115], v[224:227], v[198:201], v[112:115]
	v_mfma_f32_16x16x32_bf16 v[108:111], v[228:231], v[198:201], v[108:111]
	v_mfma_f32_16x16x32_bf16 v[96:99], v[232:235], v[198:201], v[96:99]
	v_mfma_f32_16x16x32_bf16 v[92:95], v[236:239], v[198:201], v[92:95]
	v_mfma_f32_16x16x32_bf16 v[88:91], v[224:227], v[204:207], v[88:91]
	v_mfma_f32_16x16x32_bf16 v[80:83], v[228:231], v[204:207], v[80:83]
	v_mfma_f32_16x16x32_bf16 v[72:75], v[232:235], v[204:207], v[72:75]
	v_mfma_f32_16x16x32_bf16 v[68:71], v[236:239], v[204:207], v[68:71]
	v_mfma_f32_16x16x32_bf16 v[60:63], v[224:227], v[208:211], v[60:63]
	v_mfma_f32_16x16x32_bf16 v[52:55], v[228:231], v[208:211], v[52:55]
	v_mfma_f32_16x16x32_bf16 v[48:51], v[232:235], v[208:211], v[48:51]
	v_mfma_f32_16x16x32_bf16 v[44:47], v[236:239], v[208:211], v[44:47]
	v_mfma_f32_16x16x32_bf16 v[40:43], v[224:227], v[212:215], v[40:43]
	v_mfma_f32_16x16x32_bf16 v[36:39], v[228:231], v[212:215], v[36:39]
	v_mfma_f32_16x16x32_bf16 v[32:35], v[232:235], v[212:215], v[32:35]
	v_mfma_f32_16x16x32_bf16 v[28:31], v[236:239], v[212:215], v[28:31]
	v_mfma_f32_16x16x32_bf16 v[24:27], v[224:227], v[216:219], v[24:27]
	v_mfma_f32_16x16x32_bf16 v[20:23], v[228:231], v[216:219], v[20:23]
	v_mfma_f32_16x16x32_bf16 v[16:19], v[232:235], v[216:219], v[16:19]
	v_mfma_f32_16x16x32_bf16 v[12:15], v[236:239], v[216:219], v[12:15]
	v_mfma_f32_16x16x32_bf16 v[8:11], v[224:227], v[220:223], v[8:11]
	v_mfma_f32_16x16x32_bf16 v[4:7], v[228:231], v[220:223], v[4:7]
	v_mfma_f32_16x16x32_bf16 v[0:3], v[232:235], v[220:223], v[0:3]
	v_mfma_f32_16x16x32_bf16 v[116:119], v[236:239], v[220:223], v[116:119]
	v_lshrrev_b32_e32 v224, 4, v188
	v_and_b32_e32 v225, 7, v188
	v_bitop3_b32 v226, v224, v225, 3 bitop3:0x6c
	v_lshlrev_b32_e32 v227, 7, v188
	v_bfe_u32 v228, v188, 4, 2
	v_and_b32_e32 v229, 0xffffc780, v227
	v_and_b32_e32 v227, 0x2780, v227
	v_bitop3_b32 v228, v228, v225, 4 bitop3:0x36
	v_lshlrev_b32_e32 v226, 4, v226
	v_lshlrev_b32_e32 v228, 4, v228
	v_or_b32_e32 v185, v229, v226
	v_or_b32_e32 v184, v227, v226
	v_or_b32_e32 v183, v229, v228
	v_or_b32_e32 v182, v227, v228
	s_waitcnt vmcnt(0)
	s_barrier
	s_waitcnt vmcnt(11)
	ds_write_b128 v176, v[160:163]
	s_waitcnt vmcnt(10)
	ds_write_b128 v176, v[152:155] offset:4096
	s_waitcnt vmcnt(9)
	ds_write_b128 v176, v[148:151] offset:8192
	s_waitcnt vmcnt(8)
	ds_write_b128 v176, v[128:131] offset:12288
	s_waitcnt vmcnt(7)
	ds_write_b128 v176, v[124:127] offset:16384
	s_waitcnt vmcnt(6)
	ds_write_b128 v176, v[104:107] offset:20480
	s_waitcnt vmcnt(5)
	ds_write_b128 v176, v[100:103] offset:24576
	s_waitcnt vmcnt(4)
	ds_write_b128 v176, v[84:87] offset:28672
	s_waitcnt vmcnt(3)
	ds_write_b128 v176, v[140:143] offset:32768
	s_waitcnt vmcnt(2)
	ds_write_b128 v176, v[76:79] offset:36864
	s_waitcnt vmcnt(1)
	ds_write_b128 v176, v[64:67] offset:40960
	s_waitcnt vmcnt(0)
	ds_write_b128 v176, v[56:59] offset:45056
	s_waitcnt lgkmcnt(0)
	s_barrier
	ds_read_b128 v[56:59], v185
	ds_read_b128 v[64:67], v185 offset:2048
	ds_read_b128 v[76:79], v185 offset:4096
	ds_read_b128 v[84:87], v185 offset:6144
	ds_read_b128 v[100:103], v185 offset:8192
	ds_read_b128 v[104:107], v185 offset:10240
	ds_read_b128 v[124:127], v185 offset:12288
	ds_read_b128 v[128:131], v185 offset:14336
	ds_read_b128 v[140:143], v184 offset:32768
	ds_read_b128 v[148:151], v184 offset:34816
	ds_read_b128 v[152:155], v184 offset:36864
	ds_read_b128 v[160:163], v184 offset:38912
	s_waitcnt lgkmcnt(3)
	v_mfma_f32_16x16x32_bf16 v[172:175], v[140:143], v[56:59], v[172:175]
	s_waitcnt lgkmcnt(2)
	v_mfma_f32_16x16x32_bf16 v[168:171], v[148:151], v[56:59], v[168:171]
	s_waitcnt lgkmcnt(1)
	v_mfma_f32_16x16x32_bf16 v[164:167], v[152:155], v[56:59], v[164:167]
	s_waitcnt lgkmcnt(0)
	v_mfma_f32_16x16x32_bf16 v[56:59], v[160:163], v[56:59], v[156:159]
	v_mfma_f32_16x16x32_bf16 v[144:147], v[140:143], v[64:67], v[144:147]
	v_mfma_f32_16x16x32_bf16 v[136:139], v[148:151], v[64:67], v[136:139]
	v_mfma_f32_16x16x32_bf16 v[132:135], v[152:155], v[64:67], v[132:135]
	v_mfma_f32_16x16x32_bf16 v[64:67], v[160:163], v[64:67], v[120:123]
	v_mfma_f32_16x16x32_bf16 v[156:159], v[140:143], v[76:79], v[112:115]
	v_mfma_f32_16x16x32_bf16 v[178:181], v[148:151], v[76:79], v[108:111]
	v_mfma_f32_16x16x32_bf16 v[184:187], v[152:155], v[76:79], v[96:99]
	v_mfma_f32_16x16x32_bf16 v[76:79], v[160:163], v[76:79], v[92:95]
	v_mfma_f32_16x16x32_bf16 v[60:63], v[140:143], v[100:103], v[60:63]
	v_mfma_f32_16x16x32_bf16 v[52:55], v[148:151], v[100:103], v[52:55]
	v_mfma_f32_16x16x32_bf16 v[48:51], v[152:155], v[100:103], v[48:51]
	v_mfma_f32_16x16x32_bf16 v[44:47], v[160:163], v[100:103], v[44:47]
	v_mfma_f32_16x16x32_bf16 v[40:43], v[140:143], v[104:107], v[40:43]
	v_mfma_f32_16x16x32_bf16 v[36:39], v[148:151], v[104:107], v[36:39]
	v_mfma_f32_16x16x32_bf16 v[32:35], v[152:155], v[104:107], v[32:35]
	v_mfma_f32_16x16x32_bf16 v[28:31], v[160:163], v[104:107], v[28:31]
	v_mfma_f32_16x16x32_bf16 v[24:27], v[140:143], v[124:127], v[24:27]
	v_mfma_f32_16x16x32_bf16 v[20:23], v[148:151], v[124:127], v[20:23]
	v_mfma_f32_16x16x32_bf16 v[16:19], v[152:155], v[124:127], v[16:19]
	v_mfma_f32_16x16x32_bf16 v[12:15], v[160:163], v[124:127], v[12:15]
	v_mfma_f32_16x16x32_bf16 v[8:11], v[140:143], v[128:131], v[8:11]
	v_mfma_f32_16x16x32_bf16 v[4:7], v[148:151], v[128:131], v[4:7]
	v_mfma_f32_16x16x32_bf16 v[0:3], v[152:155], v[128:131], v[0:3]
	v_mfma_f32_16x16x32_bf16 v[190:193], v[140:143], v[84:87], v[88:91]
	v_mfma_f32_16x16x32_bf16 v[194:197], v[148:151], v[84:87], v[80:83]
	v_mfma_f32_16x16x32_bf16 v[198:201], v[152:155], v[84:87], v[72:75]
	v_mfma_f32_16x16x32_bf16 v[204:207], v[160:163], v[84:87], v[68:71]
	v_mfma_f32_16x16x32_bf16 v[140:143], v[160:163], v[128:131], v[116:119]
	s_nop 1
	ds_read_b128 v[68:71], v183
	ds_read_b128 v[72:75], v183 offset:2048
	ds_read_b128 v[80:83], v183 offset:4096
	ds_read_b128 v[128:131], v183 offset:6144
	ds_read_b128 v[148:151], v183 offset:8192
	ds_read_b128 v[152:155], v183 offset:10240
	ds_read_b128 v[160:163], v183 offset:12288
	ds_read_b128 v[208:211], v183 offset:14336
	ds_read_b128 v[212:215], v182 offset:32768
	ds_read_b128 v[216:219], v182 offset:34816
	ds_read_b128 v[220:223], v182 offset:36864
	ds_read_b128 v[224:227], v182 offset:38912
	s_waitcnt lgkmcnt(3)
	v_mfma_f32_16x16x32_bf16 v[124:127], v[212:215], v[68:71], v[172:175]
	s_movk_i32 s30, 0x6c0
	s_waitcnt lgkmcnt(2)
	v_mfma_f32_16x16x32_bf16 v[120:123], v[216:219], v[68:71], v[168:171]
	s_waitcnt lgkmcnt(1)
	v_mfma_f32_16x16x32_bf16 v[116:119], v[220:223], v[68:71], v[164:167]
	s_waitcnt lgkmcnt(0)
	v_mfma_f32_16x16x32_bf16 v[112:115], v[224:227], v[68:71], v[56:59]
	v_mfma_f32_16x16x32_bf16 v[108:111], v[212:215], v[72:75], v[144:147]
	v_mfma_f32_16x16x32_bf16 v[104:107], v[216:219], v[72:75], v[136:139]
	v_mfma_f32_16x16x32_bf16 v[100:103], v[220:223], v[72:75], v[132:135]
	v_mfma_f32_16x16x32_bf16 v[96:99], v[224:227], v[72:75], v[64:67]
	v_mfma_f32_16x16x32_bf16 v[92:95], v[212:215], v[80:83], v[156:159]
	v_mfma_f32_16x16x32_bf16 v[88:91], v[216:219], v[80:83], v[178:181]
	v_mfma_f32_16x16x32_bf16 v[84:87], v[220:223], v[80:83], v[184:187]
	v_mfma_f32_16x16x32_bf16 v[80:83], v[224:227], v[80:83], v[76:79]
	v_mfma_f32_16x16x32_bf16 v[76:79], v[212:215], v[128:131], v[190:193]
	v_mfma_f32_16x16x32_bf16 v[72:75], v[216:219], v[128:131], v[194:197]
	v_mfma_f32_16x16x32_bf16 v[68:71], v[220:223], v[128:131], v[198:201]
	v_mfma_f32_16x16x32_bf16 v[64:67], v[224:227], v[128:131], v[204:207]
	v_mov_b32_e32 v128, v188
	v_mov_b32_e32 v129, v188
	v_mfma_f32_16x16x32_bf16 v[60:63], v[212:215], v[148:151], v[60:63]
	s_nop 0
	v_and_or_b32 v134, v129, 64, s41
	v_mfma_f32_16x16x32_bf16 v[56:59], v[216:219], v[148:151], v[52:55]
	v_cmp_gt_i32_e32 vcc, s30, v134
	v_mfma_f32_16x16x32_bf16 v[52:55], v[220:223], v[148:151], v[48:51]
	v_mfma_f32_16x16x32_bf16 v[48:51], v[224:227], v[148:151], v[44:47]
	v_mfma_f32_16x16x32_bf16 v[44:47], v[212:215], v[152:155], v[40:43]
	v_mfma_f32_16x16x32_bf16 v[40:43], v[216:219], v[152:155], v[36:39]
	v_mfma_f32_16x16x32_bf16 v[36:39], v[220:223], v[152:155], v[32:35]
	v_mfma_f32_16x16x32_bf16 v[32:35], v[224:227], v[152:155], v[28:31]
	v_mfma_f32_16x16x32_bf16 v[28:31], v[212:215], v[160:163], v[24:27]
	v_mfma_f32_16x16x32_bf16 v[24:27], v[216:219], v[160:163], v[20:23]
	v_mfma_f32_16x16x32_bf16 v[20:23], v[220:223], v[160:163], v[16:19]
	v_mfma_f32_16x16x32_bf16 v[16:19], v[224:227], v[160:163], v[12:15]
	v_mfma_f32_16x16x32_bf16 v[12:15], v[212:215], v[208:211], v[8:11]
	v_mfma_f32_16x16x32_bf16 v[8:11], v[216:219], v[208:211], v[4:7]
	v_mfma_f32_16x16x32_bf16 v[4:7], v[220:223], v[208:211], v[0:3]
	v_mfma_f32_16x16x32_bf16 v[0:3], v[224:227], v[208:211], v[140:143]
	s_and_saveexec_b64 s[92:93], vcc
	s_cbranch_execz .LBB0_485
	v_and_b32_e32 v130, 0xffffff80, v129
	v_add_u32_e32 v183, s40, v130
	s_movk_i32 s30, 0xfff
	v_cmp_lt_i32_e64 s[48:49], s30, v183
	s_movk_i32 s30, 0x1000
	v_cmp_gt_i32_e64 s[44:45], s30, v183
	v_add_u32_e32 v130, 0xfffff000, v183
	v_bfe_u32 v141, v128, 4, 2
	s_movk_i32 s30, 0x27f
	v_ashrrev_i32_e32 v135, 10, v130
	v_ashrrev_i32_e32 v132, 8, v183
	v_cmp_lt_i32_e64 s[52:53], s30, v134
	s_movk_i32 s30, 0x280
	v_lshlrev_b32_e32 v130, 4, v141
	v_mov_b32_e32 v131, v177
	v_and_b32_e32 v140, 0x80, v129
	v_cmp_ne_u32_e64 s[50:51], s30, v134
	v_lshl_add_u64 v[138:139], s[84:85], 0, v[130:131]
	v_lshl_add_u64 v[136:137], s[82:83], 0, v[130:131]
	v_lshlrev_b32_e32 v130, 9, v132
	v_readlane_b32 s30, v255, 49
	v_and_b32_e32 v182, 15, v128
	v_and_b32_e32 v181, 0x380, v183
	v_or3_b32 v178, v130, s30, v140
	v_lshlrev_b32_e32 v130, 3, v132
	v_ashrrev_i32_e32 v131, 31, v130
	v_lshlrev_b64 v[132:133], 8, v[130:131]
	v_lshlrev_b32_e32 v130, 3, v135
	s_movk_i32 s30, 0x500
	v_bfe_u32 v129, v128, 4, 1
	v_lshrrev_b32_e32 v128, 2, v128
	v_mad_i64_i32 v[130:131], s[30:31], v130, s30, 0
	v_mov_b32_e32 v176, v134
	v_cmp_eq_u32_e64 s[40:41], 0, v129
	v_lshlrev_b32_e32 v180, 4, v129
	v_and_b32_e32 v179, 8, v128
	v_lshlrev_b32_e32 v128, 2, v141
	v_mov_b32_e32 v129, v177
	v_or_b32_e32 v132, v132, v140
	v_or_b32_e32 v130, v130, v181
	v_cmp_lt_i32_e64 s[46:47], s97, v134
	v_cmp_eq_u32_e64 s[42:43], 0, v141
	v_or_b32_e32 v140, v183, v182
	s_and_saveexec_b64 s[30:31], s[52:53]
	s_xor_b64 s[94:95], exec, s[30:31]
	s_cbranch_execz .LBB0_513
	s_and_saveexec_b64 s[30:31], s[50:51]
	s_xor_b64 s[30:31], exec, s[30:31]
	s_cbranch_execz .LBB0_492
	v_mul_f32_e32 v142, 0xbfb8aa3b, v124
	v_mul_f32_e32 v144, 0xbfb8aa3b, v120
	v_mul_f32_e32 v145, 0xbfb8aa3b, v125
	v_exp_f32_e32 v142, v142
	v_exp_f32_e32 v144, v144
	v_exp_f32_e32 v145, v145
	v_mul_f32_e32 v146, 0xbfb8aa3b, v121
	v_add_f32_e32 v142, 1.0, v142
	v_add_f32_e32 v144, 1.0, v144
	v_add_f32_e32 v145, 1.0, v145
	v_rcp_f32_e32 v142, v142
	v_rcp_f32_e32 v144, v144
	v_rcp_f32_e32 v145, v145
	v_exp_f32_e32 v146, v146
	v_mul_f32_e32 v142, v124, v142
	v_mul_f32_e32 v144, v120, v144
	v_mul_f32_e32 v145, v125, v145
	v_add_f32_e32 v120, 1.0, v146
	v_mul_f32_e32 v124, 0xbfb8aa3b, v126
	v_mul_f32_e32 v125, 0xbfb8aa3b, v122
	v_rcp_f32_e32 v120, v120
	v_exp_f32_e32 v124, v124
	v_exp_f32_e32 v125, v125
	v_ashrrev_i32_e32 v141, 31, v140
	v_mul_f32_e32 v146, v121, v120
	v_add_f32_e32 v120, 1.0, v124
	v_add_f32_e32 v121, 1.0, v125
	v_mul_f32_e32 v124, 0xbfb8aa3b, v127
	v_mul_f32_e32 v125, 0xbfb8aa3b, v123
	v_exp_f32_e32 v124, v124
	v_exp_f32_e32 v125, v125
	v_rcp_f32_e32 v120, v120
	v_rcp_f32_e32 v121, v121
	v_add_f32_e32 v124, 1.0, v124
	v_add_f32_e32 v125, 1.0, v125
	v_rcp_f32_e32 v124, v124
	v_rcp_f32_e32 v125, v125
	v_lshlrev_b64 v[140:141], 11, v[140:141]
	v_cmp_lt_i32_e32 vcc, v189, v202
	v_mul_f32_e32 v126, v126, v120
	v_mul_f32_e32 v122, v122, v121
	v_cndmask_b32_e32 v143, v203, v189, vcc
	v_mul_f32_e32 v127, v127, v124
	v_mul_f32_e32 v123, v123, v125
	v_lshl_add_u64 v[120:121], s[34:35], 0, v[140:141]
	v_lshlrev_b32_e32 v143, 2, v143
	v_lshl_add_u64 v[124:125], v[176:177], 1, v[120:121]
	s_mov_b32 s58, 0x96ff000
	s_waitcnt lgkmcnt(0)
	s_nop 1
	v_permlane16_swap_b32_e32 v142, v144
	s_waitcnt lgkmcnt(0)
	v_mov_b32_e32 v120, v145
	v_mov_b32_e32 v145, v146
	s_nop 1
	v_permlane16_swap_b32_e32 v120, v145
	s_waitcnt lgkmcnt(0)
	v_mov_b32_e32 v121, v126
	v_mov_b32_e32 v126, v122
	s_nop 1
	v_permlane16_swap_b32_e32 v121, v126
	s_waitcnt lgkmcnt(0)
	v_mov_b32_e32 v122, v127
	s_nop 1
	v_permlane16_swap_b32_e32 v122, v123
	v_cvt_pk_bf16_f32 v123, v126, v123
	v_lshlrev_b32_e32 v126, 1, v180
	v_mov_b32_e32 v127, v177
	v_lshlrev_b32_e32 v140, 1, v179
	v_mov_b32_e32 v141, v177
	v_lshl_add_u64 v[124:125], v[124:125], 0, v[126:127]
	v_lshl_add_u64 v[124:125], v[124:125], 0, v[140:141]
	v_add_co_u32_e32 v124, vcc, s58, v124
	v_cvt_pk_bf16_f32 v120, v142, v120
	v_cvt_pk_bf16_f32 v121, v121, v122
	v_cvt_pk_bf16_f32 v122, v144, v145
	v_addc_co_u32_e32 v125, vcc, 0, v125, vcc
	v_mul_f32_e32 v126, 0xbfb8aa3b, v116
	global_store_dwordx4 v[124:125], v[120:123], off offset:2688
	v_exp_f32_e32 v126, v126
	s_nop 0
	v_mul_f32_e32 v121, 0xbfb8aa3b, v112
	v_mul_f32_e32 v122, 0xbfb8aa3b, v117
	v_exp_f32_e32 v121, v121
	v_exp_f32_e32 v122, v122
	v_add_f32_e32 v120, 1.0, v126
	v_mul_f32_e32 v123, 0xbfb8aa3b, v113
	v_add_f32_e32 v121, 1.0, v121
	v_add_f32_e32 v122, 1.0, v122
	v_rcp_f32_e32 v120, v120
	v_rcp_f32_e32 v121, v121
	v_rcp_f32_e32 v122, v122
	v_exp_f32_e32 v123, v123
	v_mul_f32_e32 v116, v116, v120
	v_mul_f32_e32 v112, v112, v121
	v_mul_f32_e32 v117, v117, v122
	v_add_f32_e32 v120, 1.0, v123
	v_mul_f32_e32 v121, 0xbfb8aa3b, v118
	v_mul_f32_e32 v122, 0xbfb8aa3b, v114
	v_rcp_f32_e32 v120, v120
	v_exp_f32_e32 v121, v121
	v_exp_f32_e32 v122, v122
	v_mul_f32_e32 v123, 0xbfb8aa3b, v115
	v_mul_f32_e32 v113, v113, v120
	v_add_f32_e32 v120, 1.0, v121
	v_add_f32_e32 v121, 1.0, v122
	v_mul_f32_e32 v122, 0xbfb8aa3b, v119
	v_exp_f32_e32 v122, v122
	v_exp_f32_e32 v123, v123
	v_rcp_f32_e32 v120, v120
	v_rcp_f32_e32 v121, v121
	v_add_f32_e32 v122, 1.0, v122
	v_add_f32_e32 v123, 1.0, v123
	v_rcp_f32_e32 v122, v122
	v_rcp_f32_e32 v123, v123
	v_mul_f32_e32 v118, v118, v120
	v_mul_f32_e32 v114, v114, v121
	v_mul_f32_e32 v119, v119, v122
	v_mul_f32_e32 v115, v115, v123
	s_waitcnt lgkmcnt(0)
	v_mov_b32_e32 v120, v112
	s_nop 1
	v_permlane16_swap_b32_e32 v116, v120
	s_waitcnt lgkmcnt(0)
	v_mov_b32_e32 v112, v117
	v_mov_b32_e32 v117, v113
	s_nop 1
	v_permlane16_swap_b32_e32 v112, v117
	s_waitcnt lgkmcnt(0)
	v_mov_b32_e32 v113, v118
	v_mov_b32_e32 v118, v114
	s_nop 1
	v_permlane16_swap_b32_e32 v113, v118
	s_waitcnt lgkmcnt(0)
	v_mov_b32_e32 v114, v119
	s_nop 1
	v_permlane16_swap_b32_e32 v114, v115
	v_cvt_pk_bf16_f32 v112, v116, v112
	v_cvt_pk_bf16_f32 v113, v113, v114
	v_cvt_pk_bf16_f32 v114, v120, v117
	v_cvt_pk_bf16_f32 v115, v118, v115
	global_store_dwordx4 v[124:125], v[112:115], off offset:2752

.LBB0_499:
	s_or_b64 exec, exec, vcc
	v_lshlrev_b32_e32 v184, 1, v128
	v_mov_b32_e32 v185, v177
	v_lshl_add_u64 v[152:153], v[152:153], 0, v[184:185]
	v_cvt_pk_bf16_f32 v124, v124, v125
	v_cvt_pk_bf16_f32 v125, v126, v127
	v_lshl_add_u64 v[126:127], v[152:153], 0, v[174:175]
	v_lshl_add_u64 v[126:127], v[152:153], 0, v[172:173]
	v_lshl_add_u64 v[126:127], v[152:153], 0, v[170:171]
	v_lshl_add_u64 v[126:127], v[152:153], 0, v[168:169]
	v_lshl_add_u64 v[126:127], v[152:153], 0, v[166:167]
	v_lshl_add_u64 v[126:127], v[152:153], 0, v[164:165]
	v_lshl_add_u64 v[126:127], v[152:153], 0, v[162:163]
	v_lshl_add_u64 v[126:127], v[152:153], 0, v[160:161]
	v_lshl_add_u64 v[126:127], v[152:153], 0, v[158:159]
	v_lshl_add_u64 v[126:127], v[152:153], 0, v[156:157]
	v_lshl_add_u64 v[126:127], v[152:153], 0, v[154:155]
	v_lshl_add_u64 v[126:127], v[152:153], 0, v[150:151]
	v_lshl_add_u64 v[126:127], v[152:153], 0, v[148:149]
	global_store_dwordx2 v[152:153], v[124:125], off
	v_lshl_add_u64 v[126:127], v[152:153], 0, v[146:147]
	v_or_b32_e32 v124, 16, v128
	v_lshlrev_b32_e32 v126, 1, v124
	v_cvt_pk_bf16_f32 v124, v120, v121
	v_cvt_pk_bf16_f32 v125, v122, v123
	s_and_saveexec_b64 s[58:59], s[44:45]
	s_xor_b64 s[58:59], exec, s[58:59]
	s_cbranch_execz .LBB0_501
	v_lshlrev_b32_e32 v146, 2, v128
	v_mov_b32_e32 v147, v177
	v_lshl_add_u64 v[146:147], v[142:143], 0, v[146:147]
	v_mov_b32_e32 v127, v177
	global_store_dwordx4 v[146:147], v[120:123], off offset:64
	s_nop 1
	v_lshl_add_u64 v[120:121], v[140:141], 0, v[126:127]
	v_add_co_u32_e32 v122, vcc, 0x5100000, v120
	s_nop 1
	v_addc_co_u32_e32 v123, vcc, 0, v121, vcc
	global_store_dwordx2 v[122:123], v[124:125], off offset:256
	v_add_co_u32_e32 v122, vcc, 0x5118000, v120
	s_nop 1
	v_addc_co_u32_e32 v123, vcc, 0, v121, vcc
	v_add_co_u32_e32 v122, vcc, 0x5130000, v120
	s_nop 1
	v_addc_co_u32_e32 v123, vcc, 0, v121, vcc
	v_add_co_u32_e32 v122, vcc, 0x5148000, v120
	s_nop 1
	v_addc_co_u32_e32 v123, vcc, 0, v121, vcc
	v_add_co_u32_e32 v122, vcc, 0x5160000, v120
	s_nop 1
	v_addc_co_u32_e32 v123, vcc, 0, v121, vcc
	v_add_co_u32_e32 v122, vcc, 0x5178000, v120
	s_nop 1
	v_addc_co_u32_e32 v123, vcc, 0, v121, vcc
	v_add_co_u32_e32 v122, vcc, 0x5190000, v120
	s_nop 1
	v_addc_co_u32_e32 v123, vcc, 0, v121, vcc
	v_add_co_u32_e32 v120, vcc, 0x51a8000, v120
	s_nop 0
	s_nop 0
	v_addc_co_u32_e32 v121, vcc, 0, v121, vcc
.LBB0_501:
	s_andn2_saveexec_b64 s[58:59], s[58:59]
	s_cbranch_execz .LBB0_503
	v_mov_b32_e32 v127, v177
	v_lshl_add_u64 v[120:121], v[144:145], 0, v[126:127]
	v_add_co_u32_e32 v122, vcc, 0xb900000, v120
	s_nop 1
	v_addc_co_u32_e32 v123, vcc, 0, v121, vcc
	global_store_dwordx2 v[122:123], v[124:125], off offset:256
	v_add_co_u32_e32 v122, vcc, 0xb978000, v120
	s_nop 1
	v_addc_co_u32_e32 v123, vcc, 0, v121, vcc
	v_add_co_u32_e32 v122, vcc, 0xb9f0000, v120
	s_nop 1
	v_addc_co_u32_e32 v123, vcc, 0, v121, vcc
	v_add_co_u32_e32 v122, vcc, 0xba68000, v120
	s_nop 1
	v_addc_co_u32_e32 v123, vcc, 0, v121, vcc
	v_add_co_u32_e32 v122, vcc, 0xbae0000, v120
	s_nop 1
	v_addc_co_u32_e32 v123, vcc, 0, v121, vcc
	v_add_co_u32_e32 v122, vcc, 0xbb58000, v120
	s_nop 1
	v_addc_co_u32_e32 v123, vcc, 0, v121, vcc
	v_add_co_u32_e32 v122, vcc, 0xbbd0000, v120
	s_nop 1
	v_addc_co_u32_e32 v123, vcc, 0, v121, vcc
	v_add_co_u32_e32 v120, vcc, 0xbc48000, v120
	s_nop 0
	s_nop 0
	v_addc_co_u32_e32 v121, vcc, 0, v121, vcc
.LBB0_503:
	s_or_b64 exec, exec, s[58:59]
	v_or_b32_e32 v120, 32, v128
	v_lshlrev_b32_e32 v122, 1, v120
	v_cvt_pk_bf16_f32 v120, v116, v117
	v_cvt_pk_bf16_f32 v121, v118, v119
	s_and_saveexec_b64 s[58:59], s[44:45]
	s_xor_b64 s[58:59], exec, s[58:59]
	s_cbranch_execz .LBB0_505
	v_lshlrev_b32_e32 v124, 2, v128
	v_mov_b32_e32 v125, v177
	v_lshl_add_u64 v[124:125], v[142:143], 0, v[124:125]
	v_mov_b32_e32 v123, v177
	global_store_dwordx4 v[124:125], v[116:119], off offset:128
	s_nop 1
	v_lshl_add_u64 v[116:117], v[140:141], 0, v[122:123]
	v_add_co_u32_e32 v118, vcc, 0x5100000, v116
	s_nop 1
	v_addc_co_u32_e32 v119, vcc, 0, v117, vcc
	global_store_dwordx2 v[118:119], v[120:121], off offset:256
	v_add_co_u32_e32 v118, vcc, 0x5118000, v116
	s_nop 1
	v_addc_co_u32_e32 v119, vcc, 0, v117, vcc
	v_add_co_u32_e32 v118, vcc, 0x5130000, v116
	s_nop 1
	v_addc_co_u32_e32 v119, vcc, 0, v117, vcc
	v_add_co_u32_e32 v118, vcc, 0x5148000, v116
	s_nop 1
	v_addc_co_u32_e32 v119, vcc, 0, v117, vcc
	v_add_co_u32_e32 v118, vcc, 0x5160000, v116
	s_nop 1
	v_addc_co_u32_e32 v119, vcc, 0, v117, vcc
	v_add_co_u32_e32 v118, vcc, 0x5178000, v116
	s_nop 1
	v_addc_co_u32_e32 v119, vcc, 0, v117, vcc
	v_add_co_u32_e32 v118, vcc, 0x5190000, v116
	s_nop 1
	v_addc_co_u32_e32 v119, vcc, 0, v117, vcc
	v_add_co_u32_e32 v116, vcc, 0x51a8000, v116
	s_nop 0
	s_nop 0
	v_addc_co_u32_e32 v117, vcc, 0, v117, vcc
.LBB0_505:
	s_andn2_saveexec_b64 s[58:59], s[58:59]
	s_cbranch_execz .LBB0_507
	v_mov_b32_e32 v123, v177
	v_lshl_add_u64 v[116:117], v[144:145], 0, v[122:123]
	v_add_co_u32_e32 v118, vcc, 0xb900000, v116
	s_nop 1
	v_addc_co_u32_e32 v119, vcc, 0, v117, vcc
	global_store_dwordx2 v[118:119], v[120:121], off offset:256
	v_add_co_u32_e32 v118, vcc, 0xb978000, v116
	s_nop 1
	v_addc_co_u32_e32 v119, vcc, 0, v117, vcc
	v_add_co_u32_e32 v118, vcc, 0xb9f0000, v116
	s_nop 1
	v_addc_co_u32_e32 v119, vcc, 0, v117, vcc
	v_add_co_u32_e32 v118, vcc, 0xba68000, v116
	s_nop 1
	v_addc_co_u32_e32 v119, vcc, 0, v117, vcc
	v_add_co_u32_e32 v118, vcc, 0xbae0000, v116
	s_nop 1
	v_addc_co_u32_e32 v119, vcc, 0, v117, vcc
	v_add_co_u32_e32 v118, vcc, 0xbb58000, v116
	s_nop 1
	v_addc_co_u32_e32 v119, vcc, 0, v117, vcc
	v_add_co_u32_e32 v118, vcc, 0xbbd0000, v116
	s_nop 1
	v_addc_co_u32_e32 v119, vcc, 0, v117, vcc
	v_add_co_u32_e32 v116, vcc, 0xbc48000, v116
	s_nop 0
	s_nop 0
	v_addc_co_u32_e32 v117, vcc, 0, v117, vcc
.LBB0_507:
	s_or_b64 exec, exec, s[58:59]
	v_or_b32_e32 v116, 48, v128
	v_lshlrev_b32_e32 v118, 1, v116
	v_cvt_pk_bf16_f32 v116, v112, v113
	v_cvt_pk_bf16_f32 v117, v114, v115
	s_and_saveexec_b64 s[58:59], s[44:45]
	s_xor_b64 s[58:59], exec, s[58:59]
	s_cbranch_execz .LBB0_509
	v_lshlrev_b32_e32 v120, 2, v128
	v_mov_b32_e32 v121, v177
	v_lshl_add_u64 v[120:121], v[142:143], 0, v[120:121]
	v_mov_b32_e32 v119, v177
	global_store_dwordx4 v[120:121], v[112:115], off offset:192
	s_nop 1
	v_lshl_add_u64 v[112:113], v[140:141], 0, v[118:119]
	v_add_co_u32_e32 v114, vcc, 0x5100000, v112
	s_nop 1
	v_addc_co_u32_e32 v115, vcc, 0, v113, vcc
	global_store_dwordx2 v[114:115], v[116:117], off offset:256
	v_add_co_u32_e32 v114, vcc, 0x5118000, v112
	s_nop 1
	v_addc_co_u32_e32 v115, vcc, 0, v113, vcc
	v_add_co_u32_e32 v114, vcc, 0x5130000, v112
	s_nop 1
	v_addc_co_u32_e32 v115, vcc, 0, v113, vcc
	v_add_co_u32_e32 v114, vcc, 0x5148000, v112
	s_nop 1
	v_addc_co_u32_e32 v115, vcc, 0, v113, vcc
	v_add_co_u32_e32 v114, vcc, 0x5160000, v112
	s_nop 1
	v_addc_co_u32_e32 v115, vcc, 0, v113, vcc
	v_add_co_u32_e32 v114, vcc, 0x5178000, v112
	s_nop 1
	v_addc_co_u32_e32 v115, vcc, 0, v113, vcc
	v_add_co_u32_e32 v114, vcc, 0x5190000, v112
	s_nop 1
	v_addc_co_u32_e32 v115, vcc, 0, v113, vcc
	v_add_co_u32_e32 v112, vcc, 0x51a8000, v112
	s_nop 0
	s_nop 0
	v_addc_co_u32_e32 v113, vcc, 0, v113, vcc
.LBB0_509:
	s_andn2_saveexec_b64 s[58:59], s[58:59]
	s_cbranch_execz .LBB0_511
	v_mov_b32_e32 v119, v177
	v_lshl_add_u64 v[112:113], v[144:145], 0, v[118:119]
	v_add_co_u32_e32 v114, vcc, 0xb900000, v112
	s_nop 1
	v_addc_co_u32_e32 v115, vcc, 0, v113, vcc
	global_store_dwordx2 v[114:115], v[116:117], off offset:256
	v_add_co_u32_e32 v114, vcc, 0xb978000, v112
	s_nop 1
	v_addc_co_u32_e32 v115, vcc, 0, v113, vcc
	v_add_co_u32_e32 v114, vcc, 0xb9f0000, v112
	s_nop 1
	v_addc_co_u32_e32 v115, vcc, 0, v113, vcc
	v_add_co_u32_e32 v114, vcc, 0xba68000, v112
	s_nop 1
	v_addc_co_u32_e32 v115, vcc, 0, v113, vcc
	v_add_co_u32_e32 v114, vcc, 0xbae0000, v112
	s_nop 1
	v_addc_co_u32_e32 v115, vcc, 0, v113, vcc
	v_add_co_u32_e32 v114, vcc, 0xbb58000, v112
	s_nop 1
	v_addc_co_u32_e32 v115, vcc, 0, v113, vcc
	v_add_co_u32_e32 v114, vcc, 0xbbd0000, v112
	s_nop 1
	v_addc_co_u32_e32 v115, vcc, 0, v113, vcc
	v_add_co_u32_e32 v112, vcc, 0xbc48000, v112
	s_nop 0
	s_nop 0
	v_addc_co_u32_e32 v113, vcc, 0, v113, vcc

.LBB0_519:
	s_or_b64 exec, exec, s[58:59]
	v_lshlrev_b64 v[140:141], 9, v[140:141]
	v_lshl_add_u64 v[140:141], s[14:15], 0, v[140:141]
	s_waitcnt lgkmcnt(0)
	v_mov_b32_e32 v143, v120
	s_nop 1
	v_permlane16_swap_b32_e32 v124, v143
	s_waitcnt lgkmcnt(0)
	v_mov_b32_e32 v120, v125
	v_mov_b32_e32 v125, v121
	s_nop 1
	v_permlane16_swap_b32_e32 v120, v125
	s_waitcnt lgkmcnt(0)
	v_mov_b32_e32 v121, v126
	v_mov_b32_e32 v126, v122
	s_nop 1
	v_permlane16_swap_b32_e32 v121, v126
	s_waitcnt lgkmcnt(0)
	v_lshl_add_u64 v[140:141], v[176:177], 1, v[140:141]
	v_mov_b32_e32 v122, v127
	s_nop 1
	v_permlane16_swap_b32_e32 v122, v123
	v_cvt_pk_bf16_f32 v120, v124, v120
	v_cvt_pk_bf16_f32 v121, v121, v122
	v_cvt_pk_bf16_f32 v122, v143, v125
	v_lshlrev_b32_e32 v124, 1, v180
	v_mov_b32_e32 v125, v177
	v_cvt_pk_bf16_f32 v123, v126, v123
	v_lshlrev_b32_e32 v126, 1, v179
	v_mov_b32_e32 v127, v177
	v_lshl_add_u64 v[124:125], v[140:141], 0, v[124:125]
	v_lshl_add_u64 v[124:125], v[124:125], 0, v[126:127]
	s_mov_b32 s58, 0xacff000
	v_add_co_u32_e32 v124, vcc, s58, v124
	s_nop 1
	v_addc_co_u32_e32 v125, vcc, 0, v125, vcc
	global_store_dwordx4 v[124:125], v[120:123], off offset:3328
	s_nop 1
	s_waitcnt lgkmcnt(0)
	v_mov_b32_e32 v120, v112
	s_nop 1
	v_permlane16_swap_b32_e32 v116, v120
	s_waitcnt lgkmcnt(0)
	v_mov_b32_e32 v112, v117
	v_mov_b32_e32 v117, v113
	s_nop 1
	v_permlane16_swap_b32_e32 v112, v117
	s_waitcnt lgkmcnt(0)
	v_mov_b32_e32 v113, v118
	v_mov_b32_e32 v118, v114
	s_nop 1
	v_permlane16_swap_b32_e32 v113, v118
	s_waitcnt lgkmcnt(0)
	v_mov_b32_e32 v114, v119
	s_nop 1
	v_permlane16_swap_b32_e32 v114, v115
	v_cvt_pk_bf16_f32 v112, v116, v112
	v_cvt_pk_bf16_f32 v113, v113, v114
	v_cvt_pk_bf16_f32 v114, v120, v117
	v_cvt_pk_bf16_f32 v115, v118, v115
	global_store_dwordx4 v[124:125], v[112:115], off offset:3392

.LBB0_523:
	s_or_b64 exec, exec, s[58:59]
	v_mov_b64_e32 v[144:145], s[4:5]
	s_movk_i32 vcc_lo, 0x300
	v_mad_i64_i32 v[144:145], s[58:59], v140, vcc_lo, v[144:145]
	v_lshlrev_b64 v[146:147], 1, v[134:135]
	s_waitcnt lgkmcnt(0)
	v_mov_b32_e32 v141, v120
	s_nop 1
	v_permlane16_swap_b32_e32 v124, v141
	s_waitcnt lgkmcnt(0)
	v_mov_b32_e32 v120, v125
	v_mov_b32_e32 v125, v121
	s_nop 1
	v_permlane16_swap_b32_e32 v120, v125
	s_waitcnt lgkmcnt(0)
	v_mov_b32_e32 v121, v126
	v_mov_b32_e32 v126, v122
	s_nop 1
	v_permlane16_swap_b32_e32 v121, v126
	s_waitcnt lgkmcnt(0)
	v_lshl_add_u64 v[144:145], v[144:145], 0, v[146:147]
	v_mov_b32_e32 v122, v127
	s_nop 1
	v_permlane16_swap_b32_e32 v122, v123
	v_cvt_pk_bf16_f32 v120, v124, v120
	v_cvt_pk_bf16_f32 v121, v121, v122
	v_cvt_pk_bf16_f32 v122, v141, v125
	v_lshlrev_b32_e32 v124, 1, v180
	v_mov_b32_e32 v125, v177
	v_cvt_pk_bf16_f32 v123, v126, v123
	v_lshl_add_u64 v[126:127], v[144:145], 0, v[124:125]
	v_lshlrev_b32_e32 v144, 1, v179
	v_mov_b32_e32 v145, v177
	v_lshl_add_u64 v[126:127], v[126:127], 0, v[144:145]
	global_store_dwordx4 v[126:127], v[120:123], off
	v_cndmask_b32_e64 v127, v119, v115, s[40:41]
	ds_bpermute_b32 v127, v142, v127
	v_mov_b64_e32 v[120:121], s[34:35]
	v_mad_i64_i32 v[120:121], s[58:59], v140, vcc_lo, v[120:121]
	v_lshl_add_u64 v[120:121], v[120:121], 0, v[146:147]
	s_waitcnt lgkmcnt(1)
	v_mov_b32_e32 v122, v112
	s_nop 1
	v_permlane16_swap_b32_e32 v116, v122
	s_waitcnt lgkmcnt(1)
	v_mov_b32_e32 v112, v117
	v_mov_b32_e32 v117, v113
	s_nop 1
	v_permlane16_swap_b32_e32 v112, v117
	s_waitcnt lgkmcnt(1)
	v_mov_b32_e32 v113, v118
	v_mov_b32_e32 v118, v114
	s_nop 1
	v_permlane16_swap_b32_e32 v113, v118
	s_waitcnt lgkmcnt(0)
	v_cndmask_b32_e64 v114, v127, v119, s[40:41]
	v_cvt_pk_bf16_f32 v112, v116, v112
	v_cvt_pk_bf16_f32 v113, v113, v114
	v_cvt_pk_bf16_f32 v114, v122, v117
	v_lshl_add_u64 v[116:117], v[120:121], 0, v[124:125]
	v_lshl_add_u64 v[116:117], v[116:117], 0, v[144:145]
	v_cndmask_b32_e64 v115, v115, v127, s[40:41]
	v_add_co_u32_e32 v116, vcc, 0xa700000, v116
	v_cvt_pk_bf16_f32 v115, v118, v115
	s_nop 0
	v_addc_co_u32_e32 v117, vcc, 0, v117, vcc
	global_store_dwordx4 v[116:117], v[112:115], off offset:64

.LBB0_525:
	s_or_b64 exec, exec, s[30:31]
	v_or_b32_e32 v116, 16, v182
	v_or_b32_e32 v112, v183, v116
	s_and_saveexec_b64 s[30:31], s[52:53]
	s_xor_b64 s[94:95], exec, s[30:31]
	s_cbranch_execz .LBB0_549
	s_and_saveexec_b64 s[30:31], s[50:51]
	s_xor_b64 s[30:31], exec, s[30:31]
	s_cbranch_execz .LBB0_528
	v_mul_f32_e32 v114, 0xbfb8aa3b, v108
	v_mul_f32_e32 v116, 0xbfb8aa3b, v104
	v_mul_f32_e32 v117, 0xbfb8aa3b, v109
	v_exp_f32_e32 v114, v114
	v_exp_f32_e32 v116, v116
	v_exp_f32_e32 v117, v117
	v_mul_f32_e32 v118, 0xbfb8aa3b, v105
	v_add_f32_e32 v114, 1.0, v114
	v_add_f32_e32 v116, 1.0, v116
	v_add_f32_e32 v117, 1.0, v117
	v_rcp_f32_e32 v114, v114
	v_rcp_f32_e32 v116, v116
	v_rcp_f32_e32 v117, v117
	v_exp_f32_e32 v118, v118
	v_mul_f32_e32 v114, v108, v114
	v_mul_f32_e32 v116, v104, v116
	v_mul_f32_e32 v117, v109, v117
	v_add_f32_e32 v104, 1.0, v118
	v_mul_f32_e32 v108, 0xbfb8aa3b, v110
	v_mul_f32_e32 v109, 0xbfb8aa3b, v106
	v_rcp_f32_e32 v104, v104
	v_exp_f32_e32 v108, v108
	v_exp_f32_e32 v109, v109
	v_ashrrev_i32_e32 v113, 31, v112
	v_mul_f32_e32 v118, v105, v104
	v_add_f32_e32 v104, 1.0, v108
	v_add_f32_e32 v105, 1.0, v109
	v_mul_f32_e32 v108, 0xbfb8aa3b, v111
	v_mul_f32_e32 v109, 0xbfb8aa3b, v107
	v_exp_f32_e32 v108, v108
	v_exp_f32_e32 v109, v109
	v_rcp_f32_e32 v104, v104
	v_rcp_f32_e32 v105, v105
	v_add_f32_e32 v108, 1.0, v108
	v_add_f32_e32 v109, 1.0, v109
	v_rcp_f32_e32 v108, v108
	v_rcp_f32_e32 v109, v109
	v_lshlrev_b64 v[112:113], 11, v[112:113]
	v_cmp_lt_i32_e32 vcc, v189, v202
	v_mul_f32_e32 v110, v110, v104
	v_mul_f32_e32 v106, v106, v105
	v_cndmask_b32_e32 v115, v203, v189, vcc
	v_mul_f32_e32 v111, v111, v108
	v_mul_f32_e32 v107, v107, v109
	v_lshl_add_u64 v[104:105], s[34:35], 0, v[112:113]
	v_lshlrev_b32_e32 v115, 2, v115
	v_lshl_add_u64 v[108:109], v[176:177], 1, v[104:105]
	s_mov_b32 s58, 0x96ff000
	s_waitcnt lgkmcnt(0)
	s_nop 1
	v_permlane16_swap_b32_e32 v114, v116
	s_waitcnt lgkmcnt(0)
	v_mov_b32_e32 v104, v117
	v_mov_b32_e32 v117, v118
	s_nop 1
	v_permlane16_swap_b32_e32 v104, v117
	s_waitcnt lgkmcnt(0)
	v_mov_b32_e32 v105, v110
	v_mov_b32_e32 v110, v106
	s_nop 1
	v_permlane16_swap_b32_e32 v105, v110
	s_waitcnt lgkmcnt(0)
	v_mov_b32_e32 v106, v111
	s_nop 1
	v_permlane16_swap_b32_e32 v106, v107
	v_cvt_pk_bf16_f32 v107, v110, v107
	v_lshlrev_b32_e32 v110, 1, v180
	v_mov_b32_e32 v111, v177
	v_lshlrev_b32_e32 v112, 1, v179
	v_mov_b32_e32 v113, v177
	v_lshl_add_u64 v[108:109], v[108:109], 0, v[110:111]
	v_lshl_add_u64 v[108:109], v[108:109], 0, v[112:113]
	v_add_co_u32_e32 v108, vcc, s58, v108
	v_cvt_pk_bf16_f32 v104, v114, v104
	v_cvt_pk_bf16_f32 v105, v105, v106
	v_cvt_pk_bf16_f32 v106, v116, v117
	v_addc_co_u32_e32 v109, vcc, 0, v109, vcc
	v_mul_f32_e32 v110, 0xbfb8aa3b, v100
	global_store_dwordx4 v[108:109], v[104:107], off offset:2688
	v_exp_f32_e32 v110, v110
	s_nop 0
	v_mul_f32_e32 v105, 0xbfb8aa3b, v96
	v_mul_f32_e32 v106, 0xbfb8aa3b, v101
	v_exp_f32_e32 v105, v105
	v_exp_f32_e32 v106, v106
	v_add_f32_e32 v104, 1.0, v110
	v_mul_f32_e32 v107, 0xbfb8aa3b, v97
	v_add_f32_e32 v105, 1.0, v105
	v_add_f32_e32 v106, 1.0, v106
	v_rcp_f32_e32 v104, v104
	v_rcp_f32_e32 v105, v105
	v_rcp_f32_e32 v106, v106
	v_exp_f32_e32 v107, v107
	v_mul_f32_e32 v100, v100, v104
	v_mul_f32_e32 v96, v96, v105
	v_mul_f32_e32 v101, v101, v106
	v_add_f32_e32 v104, 1.0, v107
	v_mul_f32_e32 v105, 0xbfb8aa3b, v102
	v_mul_f32_e32 v106, 0xbfb8aa3b, v98
	v_rcp_f32_e32 v104, v104
	v_exp_f32_e32 v105, v105
	v_exp_f32_e32 v106, v106
	v_mul_f32_e32 v107, 0xbfb8aa3b, v99
	v_mul_f32_e32 v97, v97, v104
	v_add_f32_e32 v104, 1.0, v105
	v_add_f32_e32 v105, 1.0, v106
	v_mul_f32_e32 v106, 0xbfb8aa3b, v103
	v_exp_f32_e32 v106, v106
	v_exp_f32_e32 v107, v107
	v_rcp_f32_e32 v104, v104
	v_rcp_f32_e32 v105, v105
	v_add_f32_e32 v106, 1.0, v106
	v_add_f32_e32 v107, 1.0, v107
	v_rcp_f32_e32 v106, v106
	v_rcp_f32_e32 v107, v107
	v_mul_f32_e32 v102, v102, v104
	v_mul_f32_e32 v98, v98, v105
	v_mul_f32_e32 v103, v103, v106
	v_mul_f32_e32 v99, v99, v107
	s_waitcnt lgkmcnt(0)
	v_mov_b32_e32 v104, v96
	s_nop 1
	v_permlane16_swap_b32_e32 v100, v104
	s_waitcnt lgkmcnt(0)
	v_mov_b32_e32 v96, v101
	v_mov_b32_e32 v101, v97
	s_nop 1
	v_permlane16_swap_b32_e32 v96, v101
	s_waitcnt lgkmcnt(0)
	v_mov_b32_e32 v97, v102
	v_mov_b32_e32 v102, v98
	s_nop 1
	v_permlane16_swap_b32_e32 v97, v102
	s_waitcnt lgkmcnt(0)
	v_mov_b32_e32 v98, v103
	s_nop 1
	v_permlane16_swap_b32_e32 v98, v99
	v_cvt_pk_bf16_f32 v96, v100, v96
	v_cvt_pk_bf16_f32 v97, v97, v98
	v_cvt_pk_bf16_f32 v98, v104, v101
	v_cvt_pk_bf16_f32 v99, v102, v99
	global_store_dwordx4 v[108:109], v[96:99], off offset:2752

.LBB0_535:
	s_or_b64 exec, exec, vcc
	v_lshlrev_b32_e32 v164, 1, v128
	v_mov_b32_e32 v165, v177
	v_lshl_add_u64 v[124:125], v[124:125], 0, v[164:165]
	v_cvt_pk_bf16_f32 v108, v108, v109
	v_cvt_pk_bf16_f32 v109, v110, v111
	v_lshl_add_u64 v[110:111], v[124:125], 0, v[158:159]
	v_lshl_add_u64 v[110:111], v[124:125], 0, v[156:157]
	v_lshl_add_u64 v[110:111], v[124:125], 0, v[154:155]
	v_lshl_add_u64 v[110:111], v[124:125], 0, v[152:153]
	v_lshl_add_u64 v[110:111], v[124:125], 0, v[150:151]
	v_lshl_add_u64 v[110:111], v[124:125], 0, v[148:149]
	v_lshl_add_u64 v[110:111], v[124:125], 0, v[146:147]
	v_lshl_add_u64 v[110:111], v[124:125], 0, v[144:145]
	v_lshl_add_u64 v[110:111], v[124:125], 0, v[142:143]
	v_lshl_add_u64 v[110:111], v[124:125], 0, v[140:141]
	v_lshl_add_u64 v[110:111], v[124:125], 0, v[126:127]
	v_lshl_add_u64 v[110:111], v[124:125], 0, v[122:123]
	v_lshl_add_u64 v[110:111], v[124:125], 0, v[120:121]
	global_store_dwordx2 v[124:125], v[108:109], off
	v_lshl_add_u64 v[110:111], v[124:125], 0, v[118:119]
	v_or_b32_e32 v108, 16, v128
	v_lshlrev_b32_e32 v110, 1, v108
	v_cvt_pk_bf16_f32 v108, v104, v105
	v_cvt_pk_bf16_f32 v109, v106, v107
	s_and_saveexec_b64 s[58:59], s[44:45]
	s_xor_b64 s[58:59], exec, s[58:59]
	s_cbranch_execz .LBB0_537
	v_lshlrev_b32_e32 v118, 2, v128
	v_mov_b32_e32 v119, v177
	v_lshl_add_u64 v[118:119], v[114:115], 0, v[118:119]
	v_mov_b32_e32 v111, v177
	global_store_dwordx4 v[118:119], v[104:107], off offset:64
	s_nop 1
	v_lshl_add_u64 v[104:105], v[112:113], 0, v[110:111]
	v_add_co_u32_e32 v106, vcc, 0x5100000, v104
	s_nop 1
	v_addc_co_u32_e32 v107, vcc, 0, v105, vcc
	global_store_dwordx2 v[106:107], v[108:109], off offset:256
	v_add_co_u32_e32 v106, vcc, 0x5118000, v104
	s_nop 1
	v_addc_co_u32_e32 v107, vcc, 0, v105, vcc
	v_add_co_u32_e32 v106, vcc, 0x5130000, v104
	s_nop 1
	v_addc_co_u32_e32 v107, vcc, 0, v105, vcc
	v_add_co_u32_e32 v106, vcc, 0x5148000, v104
	s_nop 1
	v_addc_co_u32_e32 v107, vcc, 0, v105, vcc
	v_add_co_u32_e32 v106, vcc, 0x5160000, v104
	s_nop 1
	v_addc_co_u32_e32 v107, vcc, 0, v105, vcc
	v_add_co_u32_e32 v106, vcc, 0x5178000, v104
	s_nop 1
	v_addc_co_u32_e32 v107, vcc, 0, v105, vcc
	v_add_co_u32_e32 v106, vcc, 0x5190000, v104
	s_nop 1
	v_addc_co_u32_e32 v107, vcc, 0, v105, vcc
	v_add_co_u32_e32 v104, vcc, 0x51a8000, v104
	s_nop 0
	s_nop 0
	v_addc_co_u32_e32 v105, vcc, 0, v105, vcc
.LBB0_537:
	s_andn2_saveexec_b64 s[58:59], s[58:59]
	s_cbranch_execz .LBB0_539
	v_mov_b32_e32 v111, v177
	v_lshl_add_u64 v[104:105], v[116:117], 0, v[110:111]
	v_add_co_u32_e32 v106, vcc, 0xb900000, v104
	s_nop 1
	v_addc_co_u32_e32 v107, vcc, 0, v105, vcc
	global_store_dwordx2 v[106:107], v[108:109], off offset:256
	v_add_co_u32_e32 v106, vcc, 0xb978000, v104
	s_nop 1
	v_addc_co_u32_e32 v107, vcc, 0, v105, vcc
	v_add_co_u32_e32 v106, vcc, 0xb9f0000, v104
	s_nop 1
	v_addc_co_u32_e32 v107, vcc, 0, v105, vcc
	v_add_co_u32_e32 v106, vcc, 0xba68000, v104
	s_nop 1
	v_addc_co_u32_e32 v107, vcc, 0, v105, vcc
	v_add_co_u32_e32 v106, vcc, 0xbae0000, v104
	s_nop 1
	v_addc_co_u32_e32 v107, vcc, 0, v105, vcc
	v_add_co_u32_e32 v106, vcc, 0xbb58000, v104
	s_nop 1
	v_addc_co_u32_e32 v107, vcc, 0, v105, vcc
	v_add_co_u32_e32 v106, vcc, 0xbbd0000, v104
	s_nop 1
	v_addc_co_u32_e32 v107, vcc, 0, v105, vcc
	v_add_co_u32_e32 v104, vcc, 0xbc48000, v104
	s_nop 0
	s_nop 0
	v_addc_co_u32_e32 v105, vcc, 0, v105, vcc
.LBB0_539:
	s_or_b64 exec, exec, s[58:59]
	v_or_b32_e32 v104, 32, v128
	v_lshlrev_b32_e32 v106, 1, v104
	v_cvt_pk_bf16_f32 v104, v100, v101
	v_cvt_pk_bf16_f32 v105, v102, v103
	s_and_saveexec_b64 s[58:59], s[44:45]
	s_xor_b64 s[58:59], exec, s[58:59]
	s_cbranch_execz .LBB0_541
	v_lshlrev_b32_e32 v108, 2, v128
	v_mov_b32_e32 v109, v177
	v_lshl_add_u64 v[108:109], v[114:115], 0, v[108:109]
	v_mov_b32_e32 v107, v177
	global_store_dwordx4 v[108:109], v[100:103], off offset:128
	s_nop 1
	v_lshl_add_u64 v[100:101], v[112:113], 0, v[106:107]
	v_add_co_u32_e32 v102, vcc, 0x5100000, v100
	s_nop 1
	v_addc_co_u32_e32 v103, vcc, 0, v101, vcc
	global_store_dwordx2 v[102:103], v[104:105], off offset:256
	v_add_co_u32_e32 v102, vcc, 0x5118000, v100
	s_nop 1
	v_addc_co_u32_e32 v103, vcc, 0, v101, vcc
	v_add_co_u32_e32 v102, vcc, 0x5130000, v100
	s_nop 1
	v_addc_co_u32_e32 v103, vcc, 0, v101, vcc
	v_add_co_u32_e32 v102, vcc, 0x5148000, v100
	s_nop 1
	v_addc_co_u32_e32 v103, vcc, 0, v101, vcc
	v_add_co_u32_e32 v102, vcc, 0x5160000, v100
	s_nop 1
	v_addc_co_u32_e32 v103, vcc, 0, v101, vcc
	v_add_co_u32_e32 v102, vcc, 0x5178000, v100
	s_nop 1
	v_addc_co_u32_e32 v103, vcc, 0, v101, vcc
	v_add_co_u32_e32 v102, vcc, 0x5190000, v100
	s_nop 1
	v_addc_co_u32_e32 v103, vcc, 0, v101, vcc
	v_add_co_u32_e32 v100, vcc, 0x51a8000, v100
	s_nop 0
	s_nop 0
	v_addc_co_u32_e32 v101, vcc, 0, v101, vcc
.LBB0_541:
	s_andn2_saveexec_b64 s[58:59], s[58:59]
	s_cbranch_execz .LBB0_543
	v_mov_b32_e32 v107, v177
	v_lshl_add_u64 v[100:101], v[116:117], 0, v[106:107]
	v_add_co_u32_e32 v102, vcc, 0xb900000, v100
	s_nop 1
	v_addc_co_u32_e32 v103, vcc, 0, v101, vcc
	global_store_dwordx2 v[102:103], v[104:105], off offset:256
	v_add_co_u32_e32 v102, vcc, 0xb978000, v100
	s_nop 1
	v_addc_co_u32_e32 v103, vcc, 0, v101, vcc
	v_add_co_u32_e32 v102, vcc, 0xb9f0000, v100
	s_nop 1
	v_addc_co_u32_e32 v103, vcc, 0, v101, vcc
	v_add_co_u32_e32 v102, vcc, 0xba68000, v100
	s_nop 1
	v_addc_co_u32_e32 v103, vcc, 0, v101, vcc
	v_add_co_u32_e32 v102, vcc, 0xbae0000, v100
	s_nop 1
	v_addc_co_u32_e32 v103, vcc, 0, v101, vcc
	v_add_co_u32_e32 v102, vcc, 0xbb58000, v100
	s_nop 1
	v_addc_co_u32_e32 v103, vcc, 0, v101, vcc
	v_add_co_u32_e32 v102, vcc, 0xbbd0000, v100
	s_nop 1
	v_addc_co_u32_e32 v103, vcc, 0, v101, vcc
	v_add_co_u32_e32 v100, vcc, 0xbc48000, v100
	s_nop 0
	s_nop 0
	v_addc_co_u32_e32 v101, vcc, 0, v101, vcc
.LBB0_543:
	s_or_b64 exec, exec, s[58:59]
	v_or_b32_e32 v100, 48, v128
	v_lshlrev_b32_e32 v102, 1, v100
	v_cvt_pk_bf16_f32 v100, v96, v97
	v_cvt_pk_bf16_f32 v101, v98, v99
	s_and_saveexec_b64 s[58:59], s[44:45]
	s_xor_b64 s[58:59], exec, s[58:59]
	s_cbranch_execz .LBB0_545
	v_lshlrev_b32_e32 v104, 2, v128
	v_mov_b32_e32 v105, v177
	v_lshl_add_u64 v[104:105], v[114:115], 0, v[104:105]
	v_mov_b32_e32 v103, v177
	global_store_dwordx4 v[104:105], v[96:99], off offset:192
	s_nop 1
	v_lshl_add_u64 v[96:97], v[112:113], 0, v[102:103]
	v_add_co_u32_e32 v98, vcc, 0x5100000, v96
	s_nop 1
	v_addc_co_u32_e32 v99, vcc, 0, v97, vcc
	global_store_dwordx2 v[98:99], v[100:101], off offset:256
	v_add_co_u32_e32 v98, vcc, 0x5118000, v96
	s_nop 1
	v_addc_co_u32_e32 v99, vcc, 0, v97, vcc
	v_add_co_u32_e32 v98, vcc, 0x5130000, v96
	s_nop 1
	v_addc_co_u32_e32 v99, vcc, 0, v97, vcc
	v_add_co_u32_e32 v98, vcc, 0x5148000, v96
	s_nop 1
	v_addc_co_u32_e32 v99, vcc, 0, v97, vcc
	v_add_co_u32_e32 v98, vcc, 0x5160000, v96
	s_nop 1
	v_addc_co_u32_e32 v99, vcc, 0, v97, vcc
	v_add_co_u32_e32 v98, vcc, 0x5178000, v96
	s_nop 1
	v_addc_co_u32_e32 v99, vcc, 0, v97, vcc
	v_add_co_u32_e32 v98, vcc, 0x5190000, v96
	s_nop 1
	v_addc_co_u32_e32 v99, vcc, 0, v97, vcc
	v_add_co_u32_e32 v96, vcc, 0x51a8000, v96
	s_nop 0
	s_nop 0
	v_addc_co_u32_e32 v97, vcc, 0, v97, vcc
.LBB0_545:
	s_andn2_saveexec_b64 s[58:59], s[58:59]
	s_cbranch_execz .LBB0_547
	v_mov_b32_e32 v103, v177
	v_lshl_add_u64 v[96:97], v[116:117], 0, v[102:103]
	v_add_co_u32_e32 v98, vcc, 0xb900000, v96
	s_nop 1
	v_addc_co_u32_e32 v99, vcc, 0, v97, vcc
	global_store_dwordx2 v[98:99], v[100:101], off offset:256
	v_add_co_u32_e32 v98, vcc, 0xb978000, v96
	s_nop 1
	v_addc_co_u32_e32 v99, vcc, 0, v97, vcc
	v_add_co_u32_e32 v98, vcc, 0xb9f0000, v96
	s_nop 1
	v_addc_co_u32_e32 v99, vcc, 0, v97, vcc
	v_add_co_u32_e32 v98, vcc, 0xba68000, v96
	s_nop 1
	v_addc_co_u32_e32 v99, vcc, 0, v97, vcc
	v_add_co_u32_e32 v98, vcc, 0xbae0000, v96
	s_nop 1
	v_addc_co_u32_e32 v99, vcc, 0, v97, vcc
	v_add_co_u32_e32 v98, vcc, 0xbb58000, v96
	s_nop 1
	v_addc_co_u32_e32 v99, vcc, 0, v97, vcc
	v_add_co_u32_e32 v98, vcc, 0xbbd0000, v96
	s_nop 1
	v_addc_co_u32_e32 v99, vcc, 0, v97, vcc
	v_add_co_u32_e32 v96, vcc, 0xbc48000, v96
	s_nop 0
	s_nop 0
	v_addc_co_u32_e32 v97, vcc, 0, v97, vcc

.LBB0_555:
	s_or_b64 exec, exec, s[58:59]
	v_lshlrev_b64 v[112:113], 9, v[112:113]
	v_lshl_add_u64 v[112:113], s[14:15], 0, v[112:113]
	s_waitcnt lgkmcnt(0)
	v_mov_b32_e32 v115, v104
	s_nop 1
	v_permlane16_swap_b32_e32 v108, v115
	s_waitcnt lgkmcnt(0)
	v_mov_b32_e32 v104, v109
	v_mov_b32_e32 v109, v105
	s_nop 1
	v_permlane16_swap_b32_e32 v104, v109
	s_waitcnt lgkmcnt(0)
	v_mov_b32_e32 v105, v110
	v_mov_b32_e32 v110, v106
	s_nop 1
	v_permlane16_swap_b32_e32 v105, v110
	s_waitcnt lgkmcnt(0)
	v_lshl_add_u64 v[112:113], v[176:177], 1, v[112:113]
	v_mov_b32_e32 v106, v111
	s_nop 1
	v_permlane16_swap_b32_e32 v106, v107
	v_cvt_pk_bf16_f32 v104, v108, v104
	v_cvt_pk_bf16_f32 v105, v105, v106
	v_cvt_pk_bf16_f32 v106, v115, v109
	v_lshlrev_b32_e32 v108, 1, v180
	v_mov_b32_e32 v109, v177
	v_cvt_pk_bf16_f32 v107, v110, v107
	v_lshlrev_b32_e32 v110, 1, v179
	v_mov_b32_e32 v111, v177
	v_lshl_add_u64 v[108:109], v[112:113], 0, v[108:109]
	v_lshl_add_u64 v[108:109], v[108:109], 0, v[110:111]
	s_mov_b32 s58, 0xacff000
	v_add_co_u32_e32 v108, vcc, s58, v108
	s_nop 1
	v_addc_co_u32_e32 v109, vcc, 0, v109, vcc
	global_store_dwordx4 v[108:109], v[104:107], off offset:3328
	s_nop 1
	s_waitcnt lgkmcnt(0)
	v_mov_b32_e32 v104, v96
	s_nop 1
	v_permlane16_swap_b32_e32 v100, v104
	s_waitcnt lgkmcnt(0)
	v_mov_b32_e32 v96, v101
	v_mov_b32_e32 v101, v97
	s_nop 1
	v_permlane16_swap_b32_e32 v96, v101
	s_waitcnt lgkmcnt(0)
	v_mov_b32_e32 v97, v102
	v_mov_b32_e32 v102, v98
	s_nop 1
	v_permlane16_swap_b32_e32 v97, v102
	s_waitcnt lgkmcnt(0)
	v_mov_b32_e32 v98, v103
	s_nop 1
	v_permlane16_swap_b32_e32 v98, v99
	v_cvt_pk_bf16_f32 v96, v100, v96
	v_cvt_pk_bf16_f32 v97, v97, v98
	v_cvt_pk_bf16_f32 v98, v104, v101
	v_cvt_pk_bf16_f32 v99, v102, v99
	global_store_dwordx4 v[108:109], v[96:99], off offset:3392

.LBB0_559:
	s_or_b64 exec, exec, s[58:59]
	v_mov_b64_e32 v[116:117], s[4:5]
	s_movk_i32 vcc_lo, 0x300
	v_mad_i64_i32 v[116:117], s[58:59], v112, vcc_lo, v[116:117]
	v_lshlrev_b64 v[118:119], 1, v[134:135]
	s_waitcnt lgkmcnt(0)
	v_mov_b32_e32 v113, v104
	s_nop 1
	v_permlane16_swap_b32_e32 v108, v113
	s_waitcnt lgkmcnt(0)
	v_mov_b32_e32 v104, v109
	v_mov_b32_e32 v109, v105
	s_nop 1
	v_permlane16_swap_b32_e32 v104, v109
	s_waitcnt lgkmcnt(0)
	v_mov_b32_e32 v105, v110
	v_mov_b32_e32 v110, v106
	s_nop 1
	v_permlane16_swap_b32_e32 v105, v110
	s_waitcnt lgkmcnt(0)
	v_lshl_add_u64 v[116:117], v[116:117], 0, v[118:119]
	v_mov_b32_e32 v106, v111
	s_nop 1
	v_permlane16_swap_b32_e32 v106, v107
	v_cvt_pk_bf16_f32 v104, v108, v104
	v_cvt_pk_bf16_f32 v105, v105, v106
	v_cvt_pk_bf16_f32 v106, v113, v109
	v_lshlrev_b32_e32 v108, 1, v180
	v_mov_b32_e32 v109, v177
	v_cvt_pk_bf16_f32 v107, v110, v107
	v_lshl_add_u64 v[110:111], v[116:117], 0, v[108:109]
	v_lshlrev_b32_e32 v116, 1, v179
	v_mov_b32_e32 v117, v177
	v_lshl_add_u64 v[110:111], v[110:111], 0, v[116:117]
	global_store_dwordx4 v[110:111], v[104:107], off
	v_cndmask_b32_e64 v111, v103, v99, s[40:41]
	ds_bpermute_b32 v111, v114, v111
	v_mov_b64_e32 v[104:105], s[34:35]
	v_mad_i64_i32 v[104:105], s[58:59], v112, vcc_lo, v[104:105]
	v_lshl_add_u64 v[104:105], v[104:105], 0, v[118:119]
	s_waitcnt lgkmcnt(1)
	v_mov_b32_e32 v106, v96
	s_nop 1
	v_permlane16_swap_b32_e32 v100, v106
	s_waitcnt lgkmcnt(1)
	v_mov_b32_e32 v96, v101
	v_mov_b32_e32 v101, v97
	s_nop 1
	v_permlane16_swap_b32_e32 v96, v101
	s_waitcnt lgkmcnt(1)
	v_mov_b32_e32 v97, v102
	v_mov_b32_e32 v102, v98
	s_nop 1
	v_permlane16_swap_b32_e32 v97, v102
	s_waitcnt lgkmcnt(0)
	v_cndmask_b32_e64 v98, v111, v103, s[40:41]
	v_cvt_pk_bf16_f32 v96, v100, v96
	v_cvt_pk_bf16_f32 v97, v97, v98
	v_cvt_pk_bf16_f32 v98, v106, v101
	v_lshl_add_u64 v[100:101], v[104:105], 0, v[108:109]
	v_lshl_add_u64 v[100:101], v[100:101], 0, v[116:117]
	v_cndmask_b32_e64 v99, v99, v111, s[40:41]
	v_add_co_u32_e32 v100, vcc, 0xa700000, v100
	v_cvt_pk_bf16_f32 v99, v102, v99
	s_nop 0
	v_addc_co_u32_e32 v101, vcc, 0, v101, vcc
	global_store_dwordx4 v[100:101], v[96:99], off offset:64

.LBB0_561:
	s_or_b64 exec, exec, s[30:31]
	v_or_b32_e32 v100, 32, v182
	v_or_b32_e32 v96, v183, v100
	s_and_saveexec_b64 s[30:31], s[52:53]
	s_xor_b64 s[94:95], exec, s[30:31]
	s_cbranch_execz .LBB0_585
	s_and_saveexec_b64 s[30:31], s[50:51]
	s_xor_b64 s[30:31], exec, s[30:31]
	s_cbranch_execz .LBB0_564
	v_mul_f32_e32 v98, 0xbfb8aa3b, v92
	v_mul_f32_e32 v100, 0xbfb8aa3b, v88
	v_mul_f32_e32 v101, 0xbfb8aa3b, v93
	v_exp_f32_e32 v98, v98
	v_exp_f32_e32 v100, v100
	v_exp_f32_e32 v101, v101
	v_mul_f32_e32 v102, 0xbfb8aa3b, v89
	v_add_f32_e32 v98, 1.0, v98
	v_add_f32_e32 v100, 1.0, v100
	v_add_f32_e32 v101, 1.0, v101
	v_rcp_f32_e32 v98, v98
	v_rcp_f32_e32 v100, v100
	v_rcp_f32_e32 v101, v101
	v_exp_f32_e32 v102, v102
	v_mul_f32_e32 v98, v92, v98
	v_mul_f32_e32 v100, v88, v100
	v_mul_f32_e32 v101, v93, v101
	v_add_f32_e32 v88, 1.0, v102
	v_mul_f32_e32 v92, 0xbfb8aa3b, v94
	v_mul_f32_e32 v93, 0xbfb8aa3b, v90
	v_rcp_f32_e32 v88, v88
	v_exp_f32_e32 v92, v92
	v_exp_f32_e32 v93, v93
	v_ashrrev_i32_e32 v97, 31, v96
	v_mul_f32_e32 v102, v89, v88
	v_add_f32_e32 v88, 1.0, v92
	v_add_f32_e32 v89, 1.0, v93
	v_mul_f32_e32 v92, 0xbfb8aa3b, v95
	v_mul_f32_e32 v93, 0xbfb8aa3b, v91
	v_exp_f32_e32 v92, v92
	v_exp_f32_e32 v93, v93
	v_rcp_f32_e32 v88, v88
	v_rcp_f32_e32 v89, v89
	v_add_f32_e32 v92, 1.0, v92
	v_add_f32_e32 v93, 1.0, v93
	v_rcp_f32_e32 v92, v92
	v_rcp_f32_e32 v93, v93
	v_lshlrev_b64 v[96:97], 11, v[96:97]
	v_cmp_lt_i32_e32 vcc, v189, v202
	v_mul_f32_e32 v94, v94, v88
	v_mul_f32_e32 v90, v90, v89
	v_cndmask_b32_e32 v99, v203, v189, vcc
	v_mul_f32_e32 v95, v95, v92
	v_mul_f32_e32 v91, v91, v93
	v_lshl_add_u64 v[88:89], s[34:35], 0, v[96:97]
	v_lshlrev_b32_e32 v99, 2, v99
	v_lshl_add_u64 v[92:93], v[176:177], 1, v[88:89]
	s_mov_b32 s58, 0x96ff000
	s_waitcnt lgkmcnt(0)
	s_nop 1
	v_permlane16_swap_b32_e32 v98, v100
	s_waitcnt lgkmcnt(0)
	v_mov_b32_e32 v88, v101
	v_mov_b32_e32 v101, v102
	s_nop 1
	v_permlane16_swap_b32_e32 v88, v101
	s_waitcnt lgkmcnt(0)
	v_mov_b32_e32 v89, v94
	v_mov_b32_e32 v94, v90
	s_nop 1
	v_permlane16_swap_b32_e32 v89, v94
	s_waitcnt lgkmcnt(0)
	v_mov_b32_e32 v90, v95
	s_nop 1
	v_permlane16_swap_b32_e32 v90, v91
	v_cvt_pk_bf16_f32 v91, v94, v91
	v_lshlrev_b32_e32 v94, 1, v180
	v_mov_b32_e32 v95, v177
	v_lshlrev_b32_e32 v96, 1, v179
	v_mov_b32_e32 v97, v177
	v_lshl_add_u64 v[92:93], v[92:93], 0, v[94:95]
	v_lshl_add_u64 v[92:93], v[92:93], 0, v[96:97]
	v_add_co_u32_e32 v92, vcc, s58, v92
	v_cvt_pk_bf16_f32 v88, v98, v88
	v_cvt_pk_bf16_f32 v89, v89, v90
	v_cvt_pk_bf16_f32 v90, v100, v101
	v_addc_co_u32_e32 v93, vcc, 0, v93, vcc
	v_mul_f32_e32 v94, 0xbfb8aa3b, v84
	global_store_dwordx4 v[92:93], v[88:91], off offset:2688
	v_exp_f32_e32 v94, v94
	s_nop 0
	v_mul_f32_e32 v89, 0xbfb8aa3b, v80
	v_mul_f32_e32 v90, 0xbfb8aa3b, v85
	v_exp_f32_e32 v89, v89
	v_exp_f32_e32 v90, v90
	v_add_f32_e32 v88, 1.0, v94
	v_mul_f32_e32 v91, 0xbfb8aa3b, v81
	v_add_f32_e32 v89, 1.0, v89
	v_add_f32_e32 v90, 1.0, v90
	v_rcp_f32_e32 v88, v88
	v_rcp_f32_e32 v89, v89
	v_rcp_f32_e32 v90, v90
	v_exp_f32_e32 v91, v91
	v_mul_f32_e32 v84, v84, v88
	v_mul_f32_e32 v80, v80, v89
	v_mul_f32_e32 v85, v85, v90
	v_add_f32_e32 v88, 1.0, v91
	v_mul_f32_e32 v89, 0xbfb8aa3b, v86
	v_mul_f32_e32 v90, 0xbfb8aa3b, v82
	v_rcp_f32_e32 v88, v88
	v_exp_f32_e32 v89, v89
	v_exp_f32_e32 v90, v90
	v_mul_f32_e32 v91, 0xbfb8aa3b, v83
	v_mul_f32_e32 v81, v81, v88
	v_add_f32_e32 v88, 1.0, v89
	v_add_f32_e32 v89, 1.0, v90
	v_mul_f32_e32 v90, 0xbfb8aa3b, v87
	v_exp_f32_e32 v90, v90
	v_exp_f32_e32 v91, v91
	v_rcp_f32_e32 v88, v88
	v_rcp_f32_e32 v89, v89
	v_add_f32_e32 v90, 1.0, v90
	v_add_f32_e32 v91, 1.0, v91
	v_rcp_f32_e32 v90, v90
	v_rcp_f32_e32 v91, v91
	v_mul_f32_e32 v86, v86, v88
	v_mul_f32_e32 v82, v82, v89
	v_mul_f32_e32 v87, v87, v90
	v_mul_f32_e32 v83, v83, v91
	s_waitcnt lgkmcnt(0)
	v_mov_b32_e32 v88, v80
	s_nop 1
	v_permlane16_swap_b32_e32 v84, v88
	s_waitcnt lgkmcnt(0)
	v_mov_b32_e32 v80, v85
	v_mov_b32_e32 v85, v81
	s_nop 1
	v_permlane16_swap_b32_e32 v80, v85
	s_waitcnt lgkmcnt(0)
	v_mov_b32_e32 v81, v86
	v_mov_b32_e32 v86, v82
	s_nop 1
	v_permlane16_swap_b32_e32 v81, v86
	s_waitcnt lgkmcnt(0)
	v_mov_b32_e32 v82, v87
	s_nop 1
	v_permlane16_swap_b32_e32 v82, v83
	v_cvt_pk_bf16_f32 v80, v84, v80
	v_cvt_pk_bf16_f32 v81, v81, v82
	v_cvt_pk_bf16_f32 v82, v88, v85
	v_cvt_pk_bf16_f32 v83, v86, v83
	global_store_dwordx4 v[92:93], v[80:83], off offset:2752

.LBB0_571:
	s_or_b64 exec, exec, vcc
	v_lshlrev_b32_e32 v144, 1, v128
	v_mov_b32_e32 v145, v177
	v_lshl_add_u64 v[108:109], v[108:109], 0, v[144:145]
	v_cvt_pk_bf16_f32 v92, v92, v93
	v_cvt_pk_bf16_f32 v93, v94, v95
	v_lshl_add_u64 v[94:95], v[108:109], 0, v[142:143]
	v_lshl_add_u64 v[94:95], v[108:109], 0, v[140:141]
	v_lshl_add_u64 v[94:95], v[108:109], 0, v[126:127]
	v_lshl_add_u64 v[94:95], v[108:109], 0, v[124:125]
	v_lshl_add_u64 v[94:95], v[108:109], 0, v[122:123]
	v_lshl_add_u64 v[94:95], v[108:109], 0, v[120:121]
	v_lshl_add_u64 v[94:95], v[108:109], 0, v[118:119]
	v_lshl_add_u64 v[94:95], v[108:109], 0, v[116:117]
	v_lshl_add_u64 v[94:95], v[108:109], 0, v[114:115]
	v_lshl_add_u64 v[94:95], v[108:109], 0, v[112:113]
	v_lshl_add_u64 v[94:95], v[108:109], 0, v[110:111]
	v_lshl_add_u64 v[94:95], v[108:109], 0, v[106:107]
	v_lshl_add_u64 v[94:95], v[108:109], 0, v[104:105]
	global_store_dwordx2 v[108:109], v[92:93], off
	v_lshl_add_u64 v[94:95], v[108:109], 0, v[102:103]
	v_or_b32_e32 v92, 16, v128
	v_lshlrev_b32_e32 v94, 1, v92
	v_cvt_pk_bf16_f32 v92, v88, v89
	v_cvt_pk_bf16_f32 v93, v90, v91
	s_and_saveexec_b64 s[58:59], s[44:45]
	s_xor_b64 s[58:59], exec, s[58:59]
	s_cbranch_execz .LBB0_573
	v_lshlrev_b32_e32 v102, 2, v128
	v_mov_b32_e32 v103, v177
	v_lshl_add_u64 v[102:103], v[98:99], 0, v[102:103]
	v_mov_b32_e32 v95, v177
	global_store_dwordx4 v[102:103], v[88:91], off offset:64
	s_nop 1
	v_lshl_add_u64 v[88:89], v[96:97], 0, v[94:95]
	v_add_co_u32_e32 v90, vcc, 0x5100000, v88
	s_nop 1
	v_addc_co_u32_e32 v91, vcc, 0, v89, vcc
	global_store_dwordx2 v[90:91], v[92:93], off offset:256
	v_add_co_u32_e32 v90, vcc, 0x5118000, v88
	s_nop 1
	v_addc_co_u32_e32 v91, vcc, 0, v89, vcc
	v_add_co_u32_e32 v90, vcc, 0x5130000, v88
	s_nop 1
	v_addc_co_u32_e32 v91, vcc, 0, v89, vcc
	v_add_co_u32_e32 v90, vcc, 0x5148000, v88
	s_nop 1
	v_addc_co_u32_e32 v91, vcc, 0, v89, vcc
	v_add_co_u32_e32 v90, vcc, 0x5160000, v88
	s_nop 1
	v_addc_co_u32_e32 v91, vcc, 0, v89, vcc
	v_add_co_u32_e32 v90, vcc, 0x5178000, v88
	s_nop 1
	v_addc_co_u32_e32 v91, vcc, 0, v89, vcc
	v_add_co_u32_e32 v90, vcc, 0x5190000, v88
	s_nop 1
	v_addc_co_u32_e32 v91, vcc, 0, v89, vcc
	v_add_co_u32_e32 v88, vcc, 0x51a8000, v88
	s_nop 0
	s_nop 0
	v_addc_co_u32_e32 v89, vcc, 0, v89, vcc
.LBB0_573:
	s_andn2_saveexec_b64 s[58:59], s[58:59]
	s_cbranch_execz .LBB0_575
	v_mov_b32_e32 v95, v177
	v_lshl_add_u64 v[88:89], v[100:101], 0, v[94:95]
	v_add_co_u32_e32 v90, vcc, 0xb900000, v88
	s_nop 1
	v_addc_co_u32_e32 v91, vcc, 0, v89, vcc
	global_store_dwordx2 v[90:91], v[92:93], off offset:256
	v_add_co_u32_e32 v90, vcc, 0xb978000, v88
	s_nop 1
	v_addc_co_u32_e32 v91, vcc, 0, v89, vcc
	v_add_co_u32_e32 v90, vcc, 0xb9f0000, v88
	s_nop 1
	v_addc_co_u32_e32 v91, vcc, 0, v89, vcc
	v_add_co_u32_e32 v90, vcc, 0xba68000, v88
	s_nop 1
	v_addc_co_u32_e32 v91, vcc, 0, v89, vcc
	v_add_co_u32_e32 v90, vcc, 0xbae0000, v88
	s_nop 1
	v_addc_co_u32_e32 v91, vcc, 0, v89, vcc
	v_add_co_u32_e32 v90, vcc, 0xbb58000, v88
	s_nop 1
	v_addc_co_u32_e32 v91, vcc, 0, v89, vcc
	v_add_co_u32_e32 v90, vcc, 0xbbd0000, v88
	s_nop 1
	v_addc_co_u32_e32 v91, vcc, 0, v89, vcc
	v_add_co_u32_e32 v88, vcc, 0xbc48000, v88
	s_nop 0
	s_nop 0
	v_addc_co_u32_e32 v89, vcc, 0, v89, vcc
.LBB0_575:
	s_or_b64 exec, exec, s[58:59]
	v_or_b32_e32 v88, 32, v128
	v_lshlrev_b32_e32 v90, 1, v88
	v_cvt_pk_bf16_f32 v88, v84, v85
	v_cvt_pk_bf16_f32 v89, v86, v87
	s_and_saveexec_b64 s[58:59], s[44:45]
	s_xor_b64 s[58:59], exec, s[58:59]
	s_cbranch_execz .LBB0_577
	v_lshlrev_b32_e32 v92, 2, v128
	v_mov_b32_e32 v93, v177
	v_lshl_add_u64 v[92:93], v[98:99], 0, v[92:93]
	v_mov_b32_e32 v91, v177
	global_store_dwordx4 v[92:93], v[84:87], off offset:128
	s_nop 1
	v_lshl_add_u64 v[84:85], v[96:97], 0, v[90:91]
	v_add_co_u32_e32 v86, vcc, 0x5100000, v84
	s_nop 1
	v_addc_co_u32_e32 v87, vcc, 0, v85, vcc
	global_store_dwordx2 v[86:87], v[88:89], off offset:256
	v_add_co_u32_e32 v86, vcc, 0x5118000, v84
	s_nop 1
	v_addc_co_u32_e32 v87, vcc, 0, v85, vcc
	v_add_co_u32_e32 v86, vcc, 0x5130000, v84
	s_nop 1
	v_addc_co_u32_e32 v87, vcc, 0, v85, vcc
	v_add_co_u32_e32 v86, vcc, 0x5148000, v84
	s_nop 1
	v_addc_co_u32_e32 v87, vcc, 0, v85, vcc
	v_add_co_u32_e32 v86, vcc, 0x5160000, v84
	s_nop 1
	v_addc_co_u32_e32 v87, vcc, 0, v85, vcc
	v_add_co_u32_e32 v86, vcc, 0x5178000, v84
	s_nop 1
	v_addc_co_u32_e32 v87, vcc, 0, v85, vcc
	v_add_co_u32_e32 v86, vcc, 0x5190000, v84
	s_nop 1
	v_addc_co_u32_e32 v87, vcc, 0, v85, vcc
	v_add_co_u32_e32 v84, vcc, 0x51a8000, v84
	s_nop 0
	s_nop 0
	v_addc_co_u32_e32 v85, vcc, 0, v85, vcc
.LBB0_577:
	s_andn2_saveexec_b64 s[58:59], s[58:59]
	s_cbranch_execz .LBB0_579
	v_mov_b32_e32 v91, v177
	v_lshl_add_u64 v[84:85], v[100:101], 0, v[90:91]
	v_add_co_u32_e32 v86, vcc, 0xb900000, v84
	s_nop 1
	v_addc_co_u32_e32 v87, vcc, 0, v85, vcc
	global_store_dwordx2 v[86:87], v[88:89], off offset:256
	v_add_co_u32_e32 v86, vcc, 0xb978000, v84
	s_nop 1
	v_addc_co_u32_e32 v87, vcc, 0, v85, vcc
	v_add_co_u32_e32 v86, vcc, 0xb9f0000, v84
	s_nop 1
	v_addc_co_u32_e32 v87, vcc, 0, v85, vcc
	v_add_co_u32_e32 v86, vcc, 0xba68000, v84
	s_nop 1
	v_addc_co_u32_e32 v87, vcc, 0, v85, vcc
	v_add_co_u32_e32 v86, vcc, 0xbae0000, v84
	s_nop 1
	v_addc_co_u32_e32 v87, vcc, 0, v85, vcc
	v_add_co_u32_e32 v86, vcc, 0xbb58000, v84
	s_nop 1
	v_addc_co_u32_e32 v87, vcc, 0, v85, vcc
	v_add_co_u32_e32 v86, vcc, 0xbbd0000, v84
	s_nop 1
	v_addc_co_u32_e32 v87, vcc, 0, v85, vcc
	v_add_co_u32_e32 v84, vcc, 0xbc48000, v84
	s_nop 0
	s_nop 0
	v_addc_co_u32_e32 v85, vcc, 0, v85, vcc
.LBB0_579:
	s_or_b64 exec, exec, s[58:59]
	v_or_b32_e32 v84, 48, v128
	v_lshlrev_b32_e32 v86, 1, v84
	v_cvt_pk_bf16_f32 v84, v80, v81
	v_cvt_pk_bf16_f32 v85, v82, v83
	s_and_saveexec_b64 s[58:59], s[44:45]
	s_xor_b64 s[58:59], exec, s[58:59]
	s_cbranch_execz .LBB0_581
	v_lshlrev_b32_e32 v88, 2, v128
	v_mov_b32_e32 v89, v177
	v_lshl_add_u64 v[88:89], v[98:99], 0, v[88:89]
	v_mov_b32_e32 v87, v177
	global_store_dwordx4 v[88:89], v[80:83], off offset:192
	s_nop 1
	v_lshl_add_u64 v[80:81], v[96:97], 0, v[86:87]
	v_add_co_u32_e32 v82, vcc, 0x5100000, v80
	s_nop 1
	v_addc_co_u32_e32 v83, vcc, 0, v81, vcc
	global_store_dwordx2 v[82:83], v[84:85], off offset:256
	v_add_co_u32_e32 v82, vcc, 0x5118000, v80
	s_nop 1
	v_addc_co_u32_e32 v83, vcc, 0, v81, vcc
	v_add_co_u32_e32 v82, vcc, 0x5130000, v80
	s_nop 1
	v_addc_co_u32_e32 v83, vcc, 0, v81, vcc
	v_add_co_u32_e32 v82, vcc, 0x5148000, v80
	s_nop 1
	v_addc_co_u32_e32 v83, vcc, 0, v81, vcc
	v_add_co_u32_e32 v82, vcc, 0x5160000, v80
	s_nop 1
	v_addc_co_u32_e32 v83, vcc, 0, v81, vcc
	v_add_co_u32_e32 v82, vcc, 0x5178000, v80
	s_nop 1
	v_addc_co_u32_e32 v83, vcc, 0, v81, vcc
	v_add_co_u32_e32 v82, vcc, 0x5190000, v80
	s_nop 1
	v_addc_co_u32_e32 v83, vcc, 0, v81, vcc
	v_add_co_u32_e32 v80, vcc, 0x51a8000, v80
	s_nop 0
	s_nop 0
	v_addc_co_u32_e32 v81, vcc, 0, v81, vcc
.LBB0_581:
	s_andn2_saveexec_b64 s[58:59], s[58:59]
	s_cbranch_execz .LBB0_583
	v_mov_b32_e32 v87, v177
	v_lshl_add_u64 v[80:81], v[100:101], 0, v[86:87]
	v_add_co_u32_e32 v82, vcc, 0xb900000, v80
	s_nop 1
	v_addc_co_u32_e32 v83, vcc, 0, v81, vcc
	global_store_dwordx2 v[82:83], v[84:85], off offset:256
	v_add_co_u32_e32 v82, vcc, 0xb978000, v80
	s_nop 1
	v_addc_co_u32_e32 v83, vcc, 0, v81, vcc
	v_add_co_u32_e32 v82, vcc, 0xb9f0000, v80
	s_nop 1
	v_addc_co_u32_e32 v83, vcc, 0, v81, vcc
	v_add_co_u32_e32 v82, vcc, 0xba68000, v80
	s_nop 1
	v_addc_co_u32_e32 v83, vcc, 0, v81, vcc
	v_add_co_u32_e32 v82, vcc, 0xbae0000, v80
	s_nop 1
	v_addc_co_u32_e32 v83, vcc, 0, v81, vcc
	v_add_co_u32_e32 v82, vcc, 0xbb58000, v80
	s_nop 1
	v_addc_co_u32_e32 v83, vcc, 0, v81, vcc
	v_add_co_u32_e32 v82, vcc, 0xbbd0000, v80
	s_nop 1
	v_addc_co_u32_e32 v83, vcc, 0, v81, vcc
	v_add_co_u32_e32 v80, vcc, 0xbc48000, v80
	s_nop 0
	s_nop 0
	v_addc_co_u32_e32 v81, vcc, 0, v81, vcc

.LBB0_591:
	s_or_b64 exec, exec, s[58:59]
	v_lshlrev_b64 v[96:97], 9, v[96:97]
	v_lshl_add_u64 v[96:97], s[14:15], 0, v[96:97]
	s_waitcnt lgkmcnt(0)
	v_mov_b32_e32 v99, v88
	s_nop 1
	v_permlane16_swap_b32_e32 v92, v99
	s_waitcnt lgkmcnt(0)
	v_mov_b32_e32 v88, v93
	v_mov_b32_e32 v93, v89
	s_nop 1
	v_permlane16_swap_b32_e32 v88, v93
	s_waitcnt lgkmcnt(0)
	v_mov_b32_e32 v89, v94
	v_mov_b32_e32 v94, v90
	s_nop 1
	v_permlane16_swap_b32_e32 v89, v94
	s_waitcnt lgkmcnt(0)
	v_lshl_add_u64 v[96:97], v[176:177], 1, v[96:97]
	v_mov_b32_e32 v90, v95
	s_nop 1
	v_permlane16_swap_b32_e32 v90, v91
	v_cvt_pk_bf16_f32 v88, v92, v88
	v_cvt_pk_bf16_f32 v89, v89, v90
	v_cvt_pk_bf16_f32 v90, v99, v93
	v_lshlrev_b32_e32 v92, 1, v180
	v_mov_b32_e32 v93, v177
	v_cvt_pk_bf16_f32 v91, v94, v91
	v_lshlrev_b32_e32 v94, 1, v179
	v_mov_b32_e32 v95, v177
	v_lshl_add_u64 v[92:93], v[96:97], 0, v[92:93]
	v_lshl_add_u64 v[92:93], v[92:93], 0, v[94:95]
	s_mov_b32 s58, 0xacff000
	v_add_co_u32_e32 v92, vcc, s58, v92
	s_nop 1
	v_addc_co_u32_e32 v93, vcc, 0, v93, vcc
	global_store_dwordx4 v[92:93], v[88:91], off offset:3328
	s_nop 1
	s_waitcnt lgkmcnt(0)
	v_mov_b32_e32 v88, v80
	s_nop 1
	v_permlane16_swap_b32_e32 v84, v88
	s_waitcnt lgkmcnt(0)
	v_mov_b32_e32 v80, v85
	v_mov_b32_e32 v85, v81
	s_nop 1
	v_permlane16_swap_b32_e32 v80, v85
	s_waitcnt lgkmcnt(0)
	v_mov_b32_e32 v81, v86
	v_mov_b32_e32 v86, v82
	s_nop 1
	v_permlane16_swap_b32_e32 v81, v86
	s_waitcnt lgkmcnt(0)
	v_mov_b32_e32 v82, v87
	s_nop 1
	v_permlane16_swap_b32_e32 v82, v83
	v_cvt_pk_bf16_f32 v80, v84, v80
	v_cvt_pk_bf16_f32 v81, v81, v82
	v_cvt_pk_bf16_f32 v82, v88, v85
	v_cvt_pk_bf16_f32 v83, v86, v83
	global_store_dwordx4 v[92:93], v[80:83], off offset:3392

.LBB0_595:
	s_or_b64 exec, exec, s[58:59]
	v_mov_b64_e32 v[100:101], s[4:5]
	s_movk_i32 vcc_lo, 0x300
	v_mad_i64_i32 v[100:101], s[58:59], v96, vcc_lo, v[100:101]
	v_lshlrev_b64 v[102:103], 1, v[134:135]
	s_waitcnt lgkmcnt(0)
	v_mov_b32_e32 v97, v88
	s_nop 1
	v_permlane16_swap_b32_e32 v92, v97
	s_waitcnt lgkmcnt(0)
	v_mov_b32_e32 v88, v93
	v_mov_b32_e32 v93, v89
	s_nop 1
	v_permlane16_swap_b32_e32 v88, v93
	s_waitcnt lgkmcnt(0)
	v_mov_b32_e32 v89, v94
	v_mov_b32_e32 v94, v90
	s_nop 1
	v_permlane16_swap_b32_e32 v89, v94
	s_waitcnt lgkmcnt(0)
	v_lshl_add_u64 v[100:101], v[100:101], 0, v[102:103]
	v_mov_b32_e32 v90, v95
	s_nop 1
	v_permlane16_swap_b32_e32 v90, v91
	v_cvt_pk_bf16_f32 v88, v92, v88
	v_cvt_pk_bf16_f32 v89, v89, v90
	v_cvt_pk_bf16_f32 v90, v97, v93
	v_lshlrev_b32_e32 v92, 1, v180
	v_mov_b32_e32 v93, v177
	v_cvt_pk_bf16_f32 v91, v94, v91
	v_lshl_add_u64 v[94:95], v[100:101], 0, v[92:93]
	v_lshlrev_b32_e32 v100, 1, v179
	v_mov_b32_e32 v101, v177
	v_lshl_add_u64 v[94:95], v[94:95], 0, v[100:101]
	global_store_dwordx4 v[94:95], v[88:91], off
	v_cndmask_b32_e64 v95, v87, v83, s[40:41]
	ds_bpermute_b32 v95, v98, v95
	v_mov_b64_e32 v[88:89], s[34:35]
	v_mad_i64_i32 v[88:89], s[58:59], v96, vcc_lo, v[88:89]
	v_lshl_add_u64 v[88:89], v[88:89], 0, v[102:103]
	s_waitcnt lgkmcnt(1)
	v_mov_b32_e32 v90, v80
	s_nop 1
	v_permlane16_swap_b32_e32 v84, v90
	s_waitcnt lgkmcnt(1)
	v_mov_b32_e32 v80, v85
	v_mov_b32_e32 v85, v81
	s_nop 1
	v_permlane16_swap_b32_e32 v80, v85
	s_waitcnt lgkmcnt(1)
	v_mov_b32_e32 v81, v86
	v_mov_b32_e32 v86, v82
	s_nop 1
	v_permlane16_swap_b32_e32 v81, v86
	s_waitcnt lgkmcnt(0)
	v_cndmask_b32_e64 v82, v95, v87, s[40:41]
	v_cvt_pk_bf16_f32 v80, v84, v80
	v_cvt_pk_bf16_f32 v81, v81, v82
	v_cvt_pk_bf16_f32 v82, v90, v85
	v_lshl_add_u64 v[84:85], v[88:89], 0, v[92:93]
	v_lshl_add_u64 v[84:85], v[84:85], 0, v[100:101]
	v_cndmask_b32_e64 v83, v83, v95, s[40:41]
	v_add_co_u32_e32 v84, vcc, 0xa700000, v84
	v_cvt_pk_bf16_f32 v83, v86, v83
	s_nop 0
	v_addc_co_u32_e32 v85, vcc, 0, v85, vcc
	global_store_dwordx4 v[84:85], v[80:83], off offset:64

.LBB0_597:
	s_or_b64 exec, exec, s[30:31]
	v_or_b32_e32 v84, 48, v182
	v_or_b32_e32 v80, v183, v84
	s_and_saveexec_b64 s[30:31], s[52:53]
	s_xor_b64 s[94:95], exec, s[30:31]
	s_cbranch_execz .LBB0_621
	s_and_saveexec_b64 s[30:31], s[50:51]
	s_xor_b64 s[30:31], exec, s[30:31]
	s_cbranch_execz .LBB0_600
	v_mul_f32_e32 v82, 0xbfb8aa3b, v76
	v_mul_f32_e32 v84, 0xbfb8aa3b, v72
	v_mul_f32_e32 v85, 0xbfb8aa3b, v77
	v_exp_f32_e32 v82, v82
	v_exp_f32_e32 v84, v84
	v_exp_f32_e32 v85, v85
	v_mul_f32_e32 v86, 0xbfb8aa3b, v73
	v_add_f32_e32 v82, 1.0, v82
	v_add_f32_e32 v84, 1.0, v84
	v_add_f32_e32 v85, 1.0, v85
	v_rcp_f32_e32 v82, v82
	v_rcp_f32_e32 v84, v84
	v_rcp_f32_e32 v85, v85
	v_exp_f32_e32 v86, v86
	v_mul_f32_e32 v82, v76, v82
	v_mul_f32_e32 v84, v72, v84
	v_mul_f32_e32 v85, v77, v85
	v_add_f32_e32 v72, 1.0, v86
	v_mul_f32_e32 v76, 0xbfb8aa3b, v78
	v_mul_f32_e32 v77, 0xbfb8aa3b, v74
	v_rcp_f32_e32 v72, v72
	v_exp_f32_e32 v76, v76
	v_exp_f32_e32 v77, v77
	v_ashrrev_i32_e32 v81, 31, v80
	v_mul_f32_e32 v86, v73, v72
	v_add_f32_e32 v72, 1.0, v76
	v_add_f32_e32 v73, 1.0, v77
	v_mul_f32_e32 v76, 0xbfb8aa3b, v79
	v_mul_f32_e32 v77, 0xbfb8aa3b, v75
	v_exp_f32_e32 v76, v76
	v_exp_f32_e32 v77, v77
	v_rcp_f32_e32 v72, v72
	v_rcp_f32_e32 v73, v73
	v_add_f32_e32 v76, 1.0, v76
	v_add_f32_e32 v77, 1.0, v77
	v_rcp_f32_e32 v76, v76
	v_rcp_f32_e32 v77, v77
	v_lshlrev_b64 v[80:81], 11, v[80:81]
	v_cmp_lt_i32_e32 vcc, v189, v202
	v_mul_f32_e32 v78, v78, v72
	v_mul_f32_e32 v74, v74, v73
	v_cndmask_b32_e32 v83, v203, v189, vcc
	v_mul_f32_e32 v79, v79, v76
	v_mul_f32_e32 v75, v75, v77
	v_lshl_add_u64 v[72:73], s[34:35], 0, v[80:81]
	v_lshlrev_b32_e32 v83, 2, v83
	v_lshl_add_u64 v[76:77], v[176:177], 1, v[72:73]
	s_mov_b32 s58, 0x96ff000
	s_waitcnt lgkmcnt(0)
	s_nop 1
	v_permlane16_swap_b32_e32 v82, v84
	s_waitcnt lgkmcnt(0)
	v_mov_b32_e32 v72, v85
	v_mov_b32_e32 v85, v86
	s_nop 1
	v_permlane16_swap_b32_e32 v72, v85
	s_waitcnt lgkmcnt(0)
	v_mov_b32_e32 v73, v78
	v_mov_b32_e32 v78, v74
	s_nop 1
	v_permlane16_swap_b32_e32 v73, v78
	s_waitcnt lgkmcnt(0)
	v_mov_b32_e32 v74, v79
	s_nop 1
	v_permlane16_swap_b32_e32 v74, v75
	v_cvt_pk_bf16_f32 v75, v78, v75
	v_lshlrev_b32_e32 v78, 1, v180
	v_mov_b32_e32 v79, v177
	v_lshlrev_b32_e32 v80, 1, v179
	v_mov_b32_e32 v81, v177
	v_lshl_add_u64 v[76:77], v[76:77], 0, v[78:79]
	v_lshl_add_u64 v[76:77], v[76:77], 0, v[80:81]
	v_add_co_u32_e32 v76, vcc, s58, v76
	v_cvt_pk_bf16_f32 v72, v82, v72
	v_cvt_pk_bf16_f32 v73, v73, v74
	v_cvt_pk_bf16_f32 v74, v84, v85
	v_addc_co_u32_e32 v77, vcc, 0, v77, vcc
	v_mul_f32_e32 v78, 0xbfb8aa3b, v68
	global_store_dwordx4 v[76:77], v[72:75], off offset:2688
	v_exp_f32_e32 v78, v78
	s_nop 0
	v_mul_f32_e32 v73, 0xbfb8aa3b, v64
	v_mul_f32_e32 v74, 0xbfb8aa3b, v69
	v_exp_f32_e32 v73, v73
	v_exp_f32_e32 v74, v74
	v_add_f32_e32 v72, 1.0, v78
	v_mul_f32_e32 v75, 0xbfb8aa3b, v65
	v_add_f32_e32 v73, 1.0, v73
	v_add_f32_e32 v74, 1.0, v74
	v_rcp_f32_e32 v72, v72
	v_rcp_f32_e32 v73, v73
	v_rcp_f32_e32 v74, v74
	v_exp_f32_e32 v75, v75
	v_mul_f32_e32 v68, v68, v72
	v_mul_f32_e32 v64, v64, v73
	v_mul_f32_e32 v69, v69, v74
	v_add_f32_e32 v72, 1.0, v75
	v_mul_f32_e32 v73, 0xbfb8aa3b, v70
	v_mul_f32_e32 v74, 0xbfb8aa3b, v66
	v_rcp_f32_e32 v72, v72
	v_exp_f32_e32 v73, v73
	v_exp_f32_e32 v74, v74
	v_mul_f32_e32 v75, 0xbfb8aa3b, v67
	v_mul_f32_e32 v65, v65, v72
	v_add_f32_e32 v72, 1.0, v73
	v_add_f32_e32 v73, 1.0, v74
	v_mul_f32_e32 v74, 0xbfb8aa3b, v71
	v_exp_f32_e32 v74, v74
	v_exp_f32_e32 v75, v75
	v_rcp_f32_e32 v72, v72
	v_rcp_f32_e32 v73, v73
	v_add_f32_e32 v74, 1.0, v74
	v_add_f32_e32 v75, 1.0, v75
	v_rcp_f32_e32 v74, v74
	v_rcp_f32_e32 v75, v75
	v_mul_f32_e32 v70, v70, v72
	v_mul_f32_e32 v66, v66, v73
	v_mul_f32_e32 v71, v71, v74
	v_mul_f32_e32 v67, v67, v75
	s_waitcnt lgkmcnt(0)
	v_mov_b32_e32 v72, v64
	s_nop 1
	v_permlane16_swap_b32_e32 v68, v72
	s_waitcnt lgkmcnt(0)
	v_mov_b32_e32 v64, v69
	v_mov_b32_e32 v69, v65
	s_nop 1
	v_permlane16_swap_b32_e32 v64, v69
	s_waitcnt lgkmcnt(0)
	v_mov_b32_e32 v65, v70
	v_mov_b32_e32 v70, v66
	s_nop 1
	v_permlane16_swap_b32_e32 v65, v70
	s_waitcnt lgkmcnt(0)
	v_mov_b32_e32 v66, v71
	s_nop 1
	v_permlane16_swap_b32_e32 v66, v67
	v_cvt_pk_bf16_f32 v64, v68, v64
	v_cvt_pk_bf16_f32 v65, v65, v66
	v_cvt_pk_bf16_f32 v66, v72, v69
	v_cvt_pk_bf16_f32 v67, v70, v67
	global_store_dwordx4 v[76:77], v[64:67], off offset:2752

.LBB0_607:
	s_or_b64 exec, exec, vcc
	v_lshlrev_b32_e32 v116, 1, v128
	v_mov_b32_e32 v117, v177
	v_lshl_add_u64 v[92:93], v[92:93], 0, v[116:117]
	v_cvt_pk_bf16_f32 v76, v76, v77
	v_cvt_pk_bf16_f32 v77, v78, v79
	v_lshl_add_u64 v[78:79], v[92:93], 0, v[114:115]
	v_lshl_add_u64 v[78:79], v[92:93], 0, v[112:113]
	v_lshl_add_u64 v[78:79], v[92:93], 0, v[110:111]
	v_lshl_add_u64 v[78:79], v[92:93], 0, v[108:109]
	v_lshl_add_u64 v[78:79], v[92:93], 0, v[106:107]
	v_lshl_add_u64 v[78:79], v[92:93], 0, v[104:105]
	v_lshl_add_u64 v[78:79], v[92:93], 0, v[102:103]
	v_lshl_add_u64 v[78:79], v[92:93], 0, v[100:101]
	v_lshl_add_u64 v[78:79], v[92:93], 0, v[98:99]
	v_lshl_add_u64 v[78:79], v[92:93], 0, v[96:97]
	v_lshl_add_u64 v[78:79], v[92:93], 0, v[94:95]
	v_lshl_add_u64 v[78:79], v[92:93], 0, v[90:91]
	v_lshl_add_u64 v[78:79], v[92:93], 0, v[88:89]
	global_store_dwordx2 v[92:93], v[76:77], off
	v_lshl_add_u64 v[78:79], v[92:93], 0, v[86:87]
	v_or_b32_e32 v76, 16, v128
	v_lshlrev_b32_e32 v78, 1, v76
	v_cvt_pk_bf16_f32 v76, v72, v73
	v_cvt_pk_bf16_f32 v77, v74, v75
	s_and_saveexec_b64 s[58:59], s[44:45]
	s_xor_b64 s[58:59], exec, s[58:59]
	s_cbranch_execz .LBB0_609
	v_lshlrev_b32_e32 v86, 2, v128
	v_mov_b32_e32 v87, v177
	v_lshl_add_u64 v[86:87], v[82:83], 0, v[86:87]
	v_mov_b32_e32 v79, v177
	global_store_dwordx4 v[86:87], v[72:75], off offset:64
	s_nop 1
	v_lshl_add_u64 v[72:73], v[80:81], 0, v[78:79]
	v_add_co_u32_e32 v74, vcc, 0x5100000, v72
	s_nop 1
	v_addc_co_u32_e32 v75, vcc, 0, v73, vcc
	global_store_dwordx2 v[74:75], v[76:77], off offset:256
	v_add_co_u32_e32 v74, vcc, 0x5118000, v72
	s_nop 1
	v_addc_co_u32_e32 v75, vcc, 0, v73, vcc
	v_add_co_u32_e32 v74, vcc, 0x5130000, v72
	s_nop 1
	v_addc_co_u32_e32 v75, vcc, 0, v73, vcc
	v_add_co_u32_e32 v74, vcc, 0x5148000, v72
	s_nop 1
	v_addc_co_u32_e32 v75, vcc, 0, v73, vcc
	v_add_co_u32_e32 v74, vcc, 0x5160000, v72
	s_nop 1
	v_addc_co_u32_e32 v75, vcc, 0, v73, vcc
	v_add_co_u32_e32 v74, vcc, 0x5178000, v72
	s_nop 1
	v_addc_co_u32_e32 v75, vcc, 0, v73, vcc
	v_add_co_u32_e32 v74, vcc, 0x5190000, v72
	s_nop 1
	v_addc_co_u32_e32 v75, vcc, 0, v73, vcc
	v_add_co_u32_e32 v72, vcc, 0x51a8000, v72
	s_nop 0
	s_nop 0
	v_addc_co_u32_e32 v73, vcc, 0, v73, vcc
.LBB0_609:
	s_andn2_saveexec_b64 s[58:59], s[58:59]
	s_cbranch_execz .LBB0_611
	v_mov_b32_e32 v79, v177
	v_lshl_add_u64 v[72:73], v[84:85], 0, v[78:79]
	v_add_co_u32_e32 v74, vcc, 0xb900000, v72
	s_nop 1
	v_addc_co_u32_e32 v75, vcc, 0, v73, vcc
	global_store_dwordx2 v[74:75], v[76:77], off offset:256
	v_add_co_u32_e32 v74, vcc, 0xb978000, v72
	s_nop 1
	v_addc_co_u32_e32 v75, vcc, 0, v73, vcc
	v_add_co_u32_e32 v74, vcc, 0xb9f0000, v72
	s_nop 1
	v_addc_co_u32_e32 v75, vcc, 0, v73, vcc
	v_add_co_u32_e32 v74, vcc, 0xba68000, v72
	s_nop 1
	v_addc_co_u32_e32 v75, vcc, 0, v73, vcc
	v_add_co_u32_e32 v74, vcc, 0xbae0000, v72
	s_nop 1
	v_addc_co_u32_e32 v75, vcc, 0, v73, vcc
	v_add_co_u32_e32 v74, vcc, 0xbb58000, v72
	s_nop 1
	v_addc_co_u32_e32 v75, vcc, 0, v73, vcc
	v_add_co_u32_e32 v74, vcc, 0xbbd0000, v72
	s_nop 1
	v_addc_co_u32_e32 v75, vcc, 0, v73, vcc
	v_add_co_u32_e32 v72, vcc, 0xbc48000, v72
	s_nop 0
	s_nop 0
	v_addc_co_u32_e32 v73, vcc, 0, v73, vcc
.LBB0_611:
	s_or_b64 exec, exec, s[58:59]
	v_or_b32_e32 v72, 32, v128
	v_lshlrev_b32_e32 v74, 1, v72
	v_cvt_pk_bf16_f32 v72, v68, v69
	v_cvt_pk_bf16_f32 v73, v70, v71
	s_and_saveexec_b64 s[58:59], s[44:45]
	s_xor_b64 s[58:59], exec, s[58:59]
	s_cbranch_execz .LBB0_613
	v_lshlrev_b32_e32 v76, 2, v128
	v_mov_b32_e32 v77, v177
	v_lshl_add_u64 v[76:77], v[82:83], 0, v[76:77]
	v_mov_b32_e32 v75, v177
	global_store_dwordx4 v[76:77], v[68:71], off offset:128
	s_nop 1
	v_lshl_add_u64 v[68:69], v[80:81], 0, v[74:75]
	v_add_co_u32_e32 v70, vcc, 0x5100000, v68
	s_nop 1
	v_addc_co_u32_e32 v71, vcc, 0, v69, vcc
	global_store_dwordx2 v[70:71], v[72:73], off offset:256
	v_add_co_u32_e32 v70, vcc, 0x5118000, v68
	s_nop 1
	v_addc_co_u32_e32 v71, vcc, 0, v69, vcc
	v_add_co_u32_e32 v70, vcc, 0x5130000, v68
	s_nop 1
	v_addc_co_u32_e32 v71, vcc, 0, v69, vcc
	v_add_co_u32_e32 v70, vcc, 0x5148000, v68
	s_nop 1
	v_addc_co_u32_e32 v71, vcc, 0, v69, vcc
	v_add_co_u32_e32 v70, vcc, 0x5160000, v68
	s_nop 1
	v_addc_co_u32_e32 v71, vcc, 0, v69, vcc
	v_add_co_u32_e32 v70, vcc, 0x5178000, v68
	s_nop 1
	v_addc_co_u32_e32 v71, vcc, 0, v69, vcc
	v_add_co_u32_e32 v70, vcc, 0x5190000, v68
	s_nop 1
	v_addc_co_u32_e32 v71, vcc, 0, v69, vcc
	v_add_co_u32_e32 v68, vcc, 0x51a8000, v68
	s_nop 0
	s_nop 0
	v_addc_co_u32_e32 v69, vcc, 0, v69, vcc
.LBB0_613:
	s_andn2_saveexec_b64 s[58:59], s[58:59]
	s_cbranch_execz .LBB0_615
	v_mov_b32_e32 v75, v177
	v_lshl_add_u64 v[68:69], v[84:85], 0, v[74:75]
	v_add_co_u32_e32 v70, vcc, 0xb900000, v68
	s_nop 1
	v_addc_co_u32_e32 v71, vcc, 0, v69, vcc
	global_store_dwordx2 v[70:71], v[72:73], off offset:256
	v_add_co_u32_e32 v70, vcc, 0xb978000, v68
	s_nop 1
	v_addc_co_u32_e32 v71, vcc, 0, v69, vcc
	v_add_co_u32_e32 v70, vcc, 0xb9f0000, v68
	s_nop 1
	v_addc_co_u32_e32 v71, vcc, 0, v69, vcc
	v_add_co_u32_e32 v70, vcc, 0xba68000, v68
	s_nop 1
	v_addc_co_u32_e32 v71, vcc, 0, v69, vcc
	v_add_co_u32_e32 v70, vcc, 0xbae0000, v68
	s_nop 1
	v_addc_co_u32_e32 v71, vcc, 0, v69, vcc
	v_add_co_u32_e32 v70, vcc, 0xbb58000, v68
	s_nop 1
	v_addc_co_u32_e32 v71, vcc, 0, v69, vcc
	v_add_co_u32_e32 v70, vcc, 0xbbd0000, v68
	s_nop 1
	v_addc_co_u32_e32 v71, vcc, 0, v69, vcc
	v_add_co_u32_e32 v68, vcc, 0xbc48000, v68
	s_nop 0
	s_nop 0
	v_addc_co_u32_e32 v69, vcc, 0, v69, vcc
.LBB0_615:
	s_or_b64 exec, exec, s[58:59]
	v_or_b32_e32 v68, 48, v128
	v_lshlrev_b32_e32 v70, 1, v68
	v_cvt_pk_bf16_f32 v68, v64, v65
	v_cvt_pk_bf16_f32 v69, v66, v67
	s_and_saveexec_b64 s[58:59], s[44:45]
	s_xor_b64 s[58:59], exec, s[58:59]
	s_cbranch_execz .LBB0_617
	v_lshlrev_b32_e32 v72, 2, v128
	v_mov_b32_e32 v73, v177
	v_lshl_add_u64 v[72:73], v[82:83], 0, v[72:73]
	v_mov_b32_e32 v71, v177
	global_store_dwordx4 v[72:73], v[64:67], off offset:192
	s_nop 1
	v_lshl_add_u64 v[64:65], v[80:81], 0, v[70:71]
	v_add_co_u32_e32 v66, vcc, 0x5100000, v64
	s_nop 1
	v_addc_co_u32_e32 v67, vcc, 0, v65, vcc
	global_store_dwordx2 v[66:67], v[68:69], off offset:256
	v_add_co_u32_e32 v66, vcc, 0x5118000, v64
	s_nop 1
	v_addc_co_u32_e32 v67, vcc, 0, v65, vcc
	v_add_co_u32_e32 v66, vcc, 0x5130000, v64
	s_nop 1
	v_addc_co_u32_e32 v67, vcc, 0, v65, vcc
	v_add_co_u32_e32 v66, vcc, 0x5148000, v64
	s_nop 1
	v_addc_co_u32_e32 v67, vcc, 0, v65, vcc
	v_add_co_u32_e32 v66, vcc, 0x5160000, v64
	s_nop 1
	v_addc_co_u32_e32 v67, vcc, 0, v65, vcc
	v_add_co_u32_e32 v66, vcc, 0x5178000, v64
	s_nop 1
	v_addc_co_u32_e32 v67, vcc, 0, v65, vcc
	v_add_co_u32_e32 v66, vcc, 0x5190000, v64
	s_nop 1
	v_addc_co_u32_e32 v67, vcc, 0, v65, vcc
	v_add_co_u32_e32 v64, vcc, 0x51a8000, v64
	s_nop 0
	s_nop 0
	v_addc_co_u32_e32 v65, vcc, 0, v65, vcc
.LBB0_617:
	s_andn2_saveexec_b64 s[58:59], s[58:59]
	s_cbranch_execz .LBB0_619
	v_mov_b32_e32 v71, v177
	v_lshl_add_u64 v[64:65], v[84:85], 0, v[70:71]
	v_add_co_u32_e32 v66, vcc, 0xb900000, v64
	s_nop 1
	v_addc_co_u32_e32 v67, vcc, 0, v65, vcc
	global_store_dwordx2 v[66:67], v[68:69], off offset:256
	v_add_co_u32_e32 v66, vcc, 0xb978000, v64
	s_nop 1
	v_addc_co_u32_e32 v67, vcc, 0, v65, vcc
	v_add_co_u32_e32 v66, vcc, 0xb9f0000, v64
	s_nop 1
	v_addc_co_u32_e32 v67, vcc, 0, v65, vcc
	v_add_co_u32_e32 v66, vcc, 0xba68000, v64
	s_nop 1
	v_addc_co_u32_e32 v67, vcc, 0, v65, vcc
	v_add_co_u32_e32 v66, vcc, 0xbae0000, v64
	s_nop 1
	v_addc_co_u32_e32 v67, vcc, 0, v65, vcc
	v_add_co_u32_e32 v66, vcc, 0xbb58000, v64
	s_nop 1
	v_addc_co_u32_e32 v67, vcc, 0, v65, vcc
	v_add_co_u32_e32 v66, vcc, 0xbbd0000, v64
	s_nop 1
	v_addc_co_u32_e32 v67, vcc, 0, v65, vcc
	v_add_co_u32_e32 v64, vcc, 0xbc48000, v64
	s_nop 0
	s_nop 0
	v_addc_co_u32_e32 v65, vcc, 0, v65, vcc

.LBB0_627:
	s_or_b64 exec, exec, s[58:59]
	v_lshlrev_b64 v[80:81], 9, v[80:81]
	v_lshl_add_u64 v[80:81], s[14:15], 0, v[80:81]
	s_waitcnt lgkmcnt(0)
	v_mov_b32_e32 v83, v72
	s_nop 1
	v_permlane16_swap_b32_e32 v76, v83
	s_waitcnt lgkmcnt(0)
	v_mov_b32_e32 v72, v77
	v_mov_b32_e32 v77, v73
	s_nop 1
	v_permlane16_swap_b32_e32 v72, v77
	s_waitcnt lgkmcnt(0)
	v_mov_b32_e32 v73, v78
	v_mov_b32_e32 v78, v74
	s_nop 1
	v_permlane16_swap_b32_e32 v73, v78
	s_waitcnt lgkmcnt(0)
	v_lshl_add_u64 v[80:81], v[176:177], 1, v[80:81]
	v_mov_b32_e32 v74, v79
	s_nop 1
	v_permlane16_swap_b32_e32 v74, v75
	v_cvt_pk_bf16_f32 v72, v76, v72
	v_cvt_pk_bf16_f32 v73, v73, v74
	v_cvt_pk_bf16_f32 v74, v83, v77
	v_lshlrev_b32_e32 v76, 1, v180
	v_mov_b32_e32 v77, v177
	v_cvt_pk_bf16_f32 v75, v78, v75
	v_lshlrev_b32_e32 v78, 1, v179
	v_mov_b32_e32 v79, v177
	v_lshl_add_u64 v[76:77], v[80:81], 0, v[76:77]
	v_lshl_add_u64 v[76:77], v[76:77], 0, v[78:79]
	s_mov_b32 s58, 0xacff000
	v_add_co_u32_e32 v76, vcc, s58, v76
	s_nop 1
	v_addc_co_u32_e32 v77, vcc, 0, v77, vcc
	global_store_dwordx4 v[76:77], v[72:75], off offset:3328
	s_nop 1
	s_waitcnt lgkmcnt(0)
	v_mov_b32_e32 v72, v64
	s_nop 1
	v_permlane16_swap_b32_e32 v68, v72
	s_waitcnt lgkmcnt(0)
	v_mov_b32_e32 v64, v69
	v_mov_b32_e32 v69, v65
	s_nop 1
	v_permlane16_swap_b32_e32 v64, v69
	s_waitcnt lgkmcnt(0)
	v_mov_b32_e32 v65, v70
	v_mov_b32_e32 v70, v66
	s_nop 1
	v_permlane16_swap_b32_e32 v65, v70
	s_waitcnt lgkmcnt(0)
	v_mov_b32_e32 v66, v71
	s_nop 1
	v_permlane16_swap_b32_e32 v66, v67
	v_cvt_pk_bf16_f32 v64, v68, v64
	v_cvt_pk_bf16_f32 v65, v65, v66
	v_cvt_pk_bf16_f32 v66, v72, v69
	v_cvt_pk_bf16_f32 v67, v70, v67
	global_store_dwordx4 v[76:77], v[64:67], off offset:3392

.LBB0_631:
	s_or_b64 exec, exec, s[58:59]
	v_mov_b64_e32 v[84:85], s[4:5]
	s_movk_i32 vcc_lo, 0x300
	v_mad_i64_i32 v[84:85], s[58:59], v80, vcc_lo, v[84:85]
	v_lshlrev_b64 v[86:87], 1, v[134:135]
	s_waitcnt lgkmcnt(0)
	v_mov_b32_e32 v81, v72
	s_nop 1
	v_permlane16_swap_b32_e32 v76, v81
	s_waitcnt lgkmcnt(0)
	v_mov_b32_e32 v72, v77
	v_mov_b32_e32 v77, v73
	s_nop 1
	v_permlane16_swap_b32_e32 v72, v77
	s_waitcnt lgkmcnt(0)
	v_mov_b32_e32 v73, v78
	v_mov_b32_e32 v78, v74
	s_nop 1
	v_permlane16_swap_b32_e32 v73, v78
	s_waitcnt lgkmcnt(0)
	v_lshl_add_u64 v[84:85], v[84:85], 0, v[86:87]
	v_mov_b32_e32 v74, v79
	s_nop 1
	v_permlane16_swap_b32_e32 v74, v75
	v_cvt_pk_bf16_f32 v72, v76, v72
	v_cvt_pk_bf16_f32 v73, v73, v74
	v_cvt_pk_bf16_f32 v74, v81, v77
	v_lshlrev_b32_e32 v76, 1, v180
	v_mov_b32_e32 v77, v177
	v_cvt_pk_bf16_f32 v75, v78, v75
	v_lshl_add_u64 v[78:79], v[84:85], 0, v[76:77]
	v_lshlrev_b32_e32 v84, 1, v179
	v_mov_b32_e32 v85, v177
	v_lshl_add_u64 v[78:79], v[78:79], 0, v[84:85]
	global_store_dwordx4 v[78:79], v[72:75], off
	v_cndmask_b32_e64 v79, v71, v67, s[40:41]
	ds_bpermute_b32 v79, v82, v79
	v_mov_b64_e32 v[72:73], s[34:35]
	v_mad_i64_i32 v[72:73], s[58:59], v80, vcc_lo, v[72:73]
	v_lshl_add_u64 v[72:73], v[72:73], 0, v[86:87]
	s_waitcnt lgkmcnt(1)
	v_mov_b32_e32 v74, v64
	s_nop 1
	v_permlane16_swap_b32_e32 v68, v74
	s_waitcnt lgkmcnt(1)
	v_mov_b32_e32 v64, v69
	v_mov_b32_e32 v69, v65
	s_nop 1
	v_permlane16_swap_b32_e32 v64, v69
	s_waitcnt lgkmcnt(1)
	v_mov_b32_e32 v65, v70
	v_mov_b32_e32 v70, v66
	s_nop 1
	v_permlane16_swap_b32_e32 v65, v70
	s_waitcnt lgkmcnt(0)
	v_cndmask_b32_e64 v66, v79, v71, s[40:41]
	v_cvt_pk_bf16_f32 v64, v68, v64
	v_cvt_pk_bf16_f32 v65, v65, v66
	v_cvt_pk_bf16_f32 v66, v74, v69
	v_lshl_add_u64 v[68:69], v[72:73], 0, v[76:77]
	v_lshl_add_u64 v[68:69], v[68:69], 0, v[84:85]
	v_cndmask_b32_e64 v67, v67, v79, s[40:41]
	v_add_co_u32_e32 v68, vcc, 0xa700000, v68
	v_cvt_pk_bf16_f32 v67, v70, v67
	s_nop 0
	v_addc_co_u32_e32 v69, vcc, 0, v69, vcc
	global_store_dwordx4 v[68:69], v[64:67], off offset:64

.LBB0_633:
	s_or_b64 exec, exec, s[30:31]
	v_or_b32_e32 v68, 64, v182
	v_or_b32_e32 v64, v183, v68
	s_and_saveexec_b64 s[30:31], s[52:53]
	s_xor_b64 s[94:95], exec, s[30:31]
	s_cbranch_execz .LBB0_657
	s_and_saveexec_b64 s[30:31], s[50:51]
	s_xor_b64 s[30:31], exec, s[30:31]
	s_cbranch_execz .LBB0_636
	v_mul_f32_e32 v66, 0xbfb8aa3b, v60
	v_mul_f32_e32 v68, 0xbfb8aa3b, v56
	v_mul_f32_e32 v69, 0xbfb8aa3b, v61
	v_exp_f32_e32 v66, v66
	v_exp_f32_e32 v68, v68
	v_exp_f32_e32 v69, v69
	v_mul_f32_e32 v70, 0xbfb8aa3b, v57
	v_add_f32_e32 v66, 1.0, v66
	v_add_f32_e32 v68, 1.0, v68
	v_add_f32_e32 v69, 1.0, v69
	v_rcp_f32_e32 v66, v66
	v_rcp_f32_e32 v68, v68
	v_rcp_f32_e32 v69, v69
	v_exp_f32_e32 v70, v70
	v_mul_f32_e32 v66, v60, v66
	v_mul_f32_e32 v68, v56, v68
	v_mul_f32_e32 v69, v61, v69
	v_add_f32_e32 v56, 1.0, v70
	v_mul_f32_e32 v60, 0xbfb8aa3b, v62
	v_mul_f32_e32 v61, 0xbfb8aa3b, v58
	v_rcp_f32_e32 v56, v56
	v_exp_f32_e32 v60, v60
	v_exp_f32_e32 v61, v61
	v_ashrrev_i32_e32 v65, 31, v64
	v_mul_f32_e32 v70, v57, v56
	v_add_f32_e32 v56, 1.0, v60
	v_add_f32_e32 v57, 1.0, v61
	v_mul_f32_e32 v60, 0xbfb8aa3b, v63
	v_mul_f32_e32 v61, 0xbfb8aa3b, v59
	v_exp_f32_e32 v60, v60
	v_exp_f32_e32 v61, v61
	v_rcp_f32_e32 v56, v56
	v_rcp_f32_e32 v57, v57
	v_add_f32_e32 v60, 1.0, v60
	v_add_f32_e32 v61, 1.0, v61
	v_rcp_f32_e32 v60, v60
	v_rcp_f32_e32 v61, v61
	v_lshlrev_b64 v[64:65], 11, v[64:65]
	v_cmp_lt_i32_e32 vcc, v189, v202
	v_mul_f32_e32 v62, v62, v56
	v_mul_f32_e32 v58, v58, v57
	v_cndmask_b32_e32 v67, v203, v189, vcc
	v_mul_f32_e32 v63, v63, v60
	v_mul_f32_e32 v59, v59, v61
	v_lshl_add_u64 v[56:57], s[34:35], 0, v[64:65]
	v_lshlrev_b32_e32 v67, 2, v67
	v_lshl_add_u64 v[60:61], v[176:177], 1, v[56:57]
	s_mov_b32 s58, 0x96ff000
	s_waitcnt lgkmcnt(0)
	s_nop 1
	v_permlane16_swap_b32_e32 v66, v68
	s_waitcnt lgkmcnt(0)
	v_mov_b32_e32 v56, v69
	v_mov_b32_e32 v69, v70
	s_nop 1
	v_permlane16_swap_b32_e32 v56, v69
	s_waitcnt lgkmcnt(0)
	v_mov_b32_e32 v57, v62
	v_mov_b32_e32 v62, v58
	s_nop 1
	v_permlane16_swap_b32_e32 v57, v62
	s_waitcnt lgkmcnt(0)
	v_mov_b32_e32 v58, v63
	s_nop 1
	v_permlane16_swap_b32_e32 v58, v59
	v_cvt_pk_bf16_f32 v59, v62, v59
	v_lshlrev_b32_e32 v62, 1, v180
	v_mov_b32_e32 v63, v177
	v_lshlrev_b32_e32 v64, 1, v179
	v_mov_b32_e32 v65, v177
	v_lshl_add_u64 v[60:61], v[60:61], 0, v[62:63]
	v_lshl_add_u64 v[60:61], v[60:61], 0, v[64:65]
	v_add_co_u32_e32 v60, vcc, s58, v60
	v_cvt_pk_bf16_f32 v56, v66, v56
	v_cvt_pk_bf16_f32 v57, v57, v58
	v_cvt_pk_bf16_f32 v58, v68, v69
	v_addc_co_u32_e32 v61, vcc, 0, v61, vcc
	v_mul_f32_e32 v62, 0xbfb8aa3b, v52
	global_store_dwordx4 v[60:61], v[56:59], off offset:2688
	v_exp_f32_e32 v62, v62
	s_nop 0
	v_mul_f32_e32 v57, 0xbfb8aa3b, v48
	v_mul_f32_e32 v58, 0xbfb8aa3b, v53
	v_exp_f32_e32 v57, v57
	v_exp_f32_e32 v58, v58
	v_add_f32_e32 v56, 1.0, v62
	v_mul_f32_e32 v59, 0xbfb8aa3b, v49
	v_add_f32_e32 v57, 1.0, v57
	v_add_f32_e32 v58, 1.0, v58
	v_rcp_f32_e32 v56, v56
	v_rcp_f32_e32 v57, v57
	v_rcp_f32_e32 v58, v58
	v_exp_f32_e32 v59, v59
	v_mul_f32_e32 v52, v52, v56
	v_mul_f32_e32 v48, v48, v57
	v_mul_f32_e32 v53, v53, v58
	v_add_f32_e32 v56, 1.0, v59
	v_mul_f32_e32 v57, 0xbfb8aa3b, v54
	v_mul_f32_e32 v58, 0xbfb8aa3b, v50
	v_rcp_f32_e32 v56, v56
	v_exp_f32_e32 v57, v57
	v_exp_f32_e32 v58, v58
	v_mul_f32_e32 v59, 0xbfb8aa3b, v51
	v_mul_f32_e32 v49, v49, v56
	v_add_f32_e32 v56, 1.0, v57
	v_add_f32_e32 v57, 1.0, v58
	v_mul_f32_e32 v58, 0xbfb8aa3b, v55
	v_exp_f32_e32 v58, v58
	v_exp_f32_e32 v59, v59
	v_rcp_f32_e32 v56, v56
	v_rcp_f32_e32 v57, v57
	v_add_f32_e32 v58, 1.0, v58
	v_add_f32_e32 v59, 1.0, v59
	v_rcp_f32_e32 v58, v58
	v_rcp_f32_e32 v59, v59
	v_mul_f32_e32 v54, v54, v56
	v_mul_f32_e32 v50, v50, v57
	v_mul_f32_e32 v55, v55, v58
	v_mul_f32_e32 v51, v51, v59
	s_waitcnt lgkmcnt(0)
	v_mov_b32_e32 v56, v48
	s_nop 1
	v_permlane16_swap_b32_e32 v52, v56
	s_waitcnt lgkmcnt(0)
	v_mov_b32_e32 v48, v53
	v_mov_b32_e32 v53, v49
	s_nop 1
	v_permlane16_swap_b32_e32 v48, v53
	s_waitcnt lgkmcnt(0)
	v_mov_b32_e32 v49, v54
	v_mov_b32_e32 v54, v50
	s_nop 1
	v_permlane16_swap_b32_e32 v49, v54
	s_waitcnt lgkmcnt(0)
	v_mov_b32_e32 v50, v55
	s_nop 1
	v_permlane16_swap_b32_e32 v50, v51
	v_cvt_pk_bf16_f32 v48, v52, v48
	v_cvt_pk_bf16_f32 v49, v49, v50
	v_cvt_pk_bf16_f32 v50, v56, v53
	v_cvt_pk_bf16_f32 v51, v54, v51
	global_store_dwordx4 v[60:61], v[48:51], off offset:2752

.LBB0_643:
	s_or_b64 exec, exec, vcc
	v_lshlrev_b32_e32 v100, 1, v128
	v_mov_b32_e32 v101, v177
	v_lshl_add_u64 v[76:77], v[76:77], 0, v[100:101]
	v_cvt_pk_bf16_f32 v60, v60, v61
	v_cvt_pk_bf16_f32 v61, v62, v63
	v_lshl_add_u64 v[62:63], v[76:77], 0, v[98:99]
	v_lshl_add_u64 v[62:63], v[76:77], 0, v[96:97]
	v_lshl_add_u64 v[62:63], v[76:77], 0, v[94:95]
	v_lshl_add_u64 v[62:63], v[76:77], 0, v[92:93]
	v_lshl_add_u64 v[62:63], v[76:77], 0, v[90:91]
	v_lshl_add_u64 v[62:63], v[76:77], 0, v[88:89]
	v_lshl_add_u64 v[62:63], v[76:77], 0, v[86:87]
	v_lshl_add_u64 v[62:63], v[76:77], 0, v[84:85]
	v_lshl_add_u64 v[62:63], v[76:77], 0, v[82:83]
	v_lshl_add_u64 v[62:63], v[76:77], 0, v[80:81]
	v_lshl_add_u64 v[62:63], v[76:77], 0, v[78:79]
	v_lshl_add_u64 v[62:63], v[76:77], 0, v[74:75]
	v_lshl_add_u64 v[62:63], v[76:77], 0, v[72:73]
	global_store_dwordx2 v[76:77], v[60:61], off
	v_lshl_add_u64 v[62:63], v[76:77], 0, v[70:71]
	v_or_b32_e32 v60, 16, v128
	v_lshlrev_b32_e32 v62, 1, v60
	v_cvt_pk_bf16_f32 v60, v56, v57
	v_cvt_pk_bf16_f32 v61, v58, v59
	s_and_saveexec_b64 s[58:59], s[44:45]
	s_xor_b64 s[58:59], exec, s[58:59]
	s_cbranch_execz .LBB0_645
	v_lshlrev_b32_e32 v70, 2, v128
	v_mov_b32_e32 v71, v177
	v_lshl_add_u64 v[70:71], v[66:67], 0, v[70:71]
	v_mov_b32_e32 v63, v177
	global_store_dwordx4 v[70:71], v[56:59], off offset:64
	s_nop 1
	v_lshl_add_u64 v[56:57], v[64:65], 0, v[62:63]
	v_add_co_u32_e32 v58, vcc, 0x5100000, v56
	s_nop 1
	v_addc_co_u32_e32 v59, vcc, 0, v57, vcc
	global_store_dwordx2 v[58:59], v[60:61], off offset:256
	v_add_co_u32_e32 v58, vcc, 0x5118000, v56
	s_nop 1
	v_addc_co_u32_e32 v59, vcc, 0, v57, vcc
	v_add_co_u32_e32 v58, vcc, 0x5130000, v56
	s_nop 1
	v_addc_co_u32_e32 v59, vcc, 0, v57, vcc
	v_add_co_u32_e32 v58, vcc, 0x5148000, v56
	s_nop 1
	v_addc_co_u32_e32 v59, vcc, 0, v57, vcc
	v_add_co_u32_e32 v58, vcc, 0x5160000, v56
	s_nop 1
	v_addc_co_u32_e32 v59, vcc, 0, v57, vcc
	v_add_co_u32_e32 v58, vcc, 0x5178000, v56
	s_nop 1
	v_addc_co_u32_e32 v59, vcc, 0, v57, vcc
	v_add_co_u32_e32 v58, vcc, 0x5190000, v56
	s_nop 1
	v_addc_co_u32_e32 v59, vcc, 0, v57, vcc
	v_add_co_u32_e32 v56, vcc, 0x51a8000, v56
	s_nop 0
	s_nop 0
	v_addc_co_u32_e32 v57, vcc, 0, v57, vcc
.LBB0_645:
	s_andn2_saveexec_b64 s[58:59], s[58:59]
	s_cbranch_execz .LBB0_647
	v_mov_b32_e32 v63, v177
	v_lshl_add_u64 v[56:57], v[68:69], 0, v[62:63]
	v_add_co_u32_e32 v58, vcc, 0xb900000, v56
	s_nop 1
	v_addc_co_u32_e32 v59, vcc, 0, v57, vcc
	global_store_dwordx2 v[58:59], v[60:61], off offset:256
	v_add_co_u32_e32 v58, vcc, 0xb978000, v56
	s_nop 1
	v_addc_co_u32_e32 v59, vcc, 0, v57, vcc
	v_add_co_u32_e32 v58, vcc, 0xb9f0000, v56
	s_nop 1
	v_addc_co_u32_e32 v59, vcc, 0, v57, vcc
	v_add_co_u32_e32 v58, vcc, 0xba68000, v56
	s_nop 1
	v_addc_co_u32_e32 v59, vcc, 0, v57, vcc
	v_add_co_u32_e32 v58, vcc, 0xbae0000, v56
	s_nop 1
	v_addc_co_u32_e32 v59, vcc, 0, v57, vcc
	v_add_co_u32_e32 v58, vcc, 0xbb58000, v56
	s_nop 1
	v_addc_co_u32_e32 v59, vcc, 0, v57, vcc
	v_add_co_u32_e32 v58, vcc, 0xbbd0000, v56
	s_nop 1
	v_addc_co_u32_e32 v59, vcc, 0, v57, vcc
	v_add_co_u32_e32 v56, vcc, 0xbc48000, v56
	s_nop 0
	s_nop 0
	v_addc_co_u32_e32 v57, vcc, 0, v57, vcc
.LBB0_647:
	s_or_b64 exec, exec, s[58:59]
	v_or_b32_e32 v56, 32, v128
	v_lshlrev_b32_e32 v58, 1, v56
	v_cvt_pk_bf16_f32 v56, v52, v53
	v_cvt_pk_bf16_f32 v57, v54, v55
	s_and_saveexec_b64 s[58:59], s[44:45]
	s_xor_b64 s[58:59], exec, s[58:59]
	s_cbranch_execz .LBB0_649
	v_lshlrev_b32_e32 v60, 2, v128
	v_mov_b32_e32 v61, v177
	v_lshl_add_u64 v[60:61], v[66:67], 0, v[60:61]
	v_mov_b32_e32 v59, v177
	global_store_dwordx4 v[60:61], v[52:55], off offset:128
	s_nop 1
	v_lshl_add_u64 v[52:53], v[64:65], 0, v[58:59]
	v_add_co_u32_e32 v54, vcc, 0x5100000, v52
	s_nop 1
	v_addc_co_u32_e32 v55, vcc, 0, v53, vcc
	global_store_dwordx2 v[54:55], v[56:57], off offset:256
	v_add_co_u32_e32 v54, vcc, 0x5118000, v52
	s_nop 1
	v_addc_co_u32_e32 v55, vcc, 0, v53, vcc
	v_add_co_u32_e32 v54, vcc, 0x5130000, v52
	s_nop 1
	v_addc_co_u32_e32 v55, vcc, 0, v53, vcc
	v_add_co_u32_e32 v54, vcc, 0x5148000, v52
	s_nop 1
	v_addc_co_u32_e32 v55, vcc, 0, v53, vcc
	v_add_co_u32_e32 v54, vcc, 0x5160000, v52
	s_nop 1
	v_addc_co_u32_e32 v55, vcc, 0, v53, vcc
	v_add_co_u32_e32 v54, vcc, 0x5178000, v52
	s_nop 1
	v_addc_co_u32_e32 v55, vcc, 0, v53, vcc
	v_add_co_u32_e32 v54, vcc, 0x5190000, v52
	s_nop 1
	v_addc_co_u32_e32 v55, vcc, 0, v53, vcc
	v_add_co_u32_e32 v52, vcc, 0x51a8000, v52
	s_nop 0
	s_nop 0
	v_addc_co_u32_e32 v53, vcc, 0, v53, vcc
.LBB0_649:
	s_andn2_saveexec_b64 s[58:59], s[58:59]
	s_cbranch_execz .LBB0_651
	v_mov_b32_e32 v59, v177
	v_lshl_add_u64 v[52:53], v[68:69], 0, v[58:59]
	v_add_co_u32_e32 v54, vcc, 0xb900000, v52
	s_nop 1
	v_addc_co_u32_e32 v55, vcc, 0, v53, vcc
	global_store_dwordx2 v[54:55], v[56:57], off offset:256
	v_add_co_u32_e32 v54, vcc, 0xb978000, v52
	s_nop 1
	v_addc_co_u32_e32 v55, vcc, 0, v53, vcc
	v_add_co_u32_e32 v54, vcc, 0xb9f0000, v52
	s_nop 1
	v_addc_co_u32_e32 v55, vcc, 0, v53, vcc
	v_add_co_u32_e32 v54, vcc, 0xba68000, v52
	s_nop 1
	v_addc_co_u32_e32 v55, vcc, 0, v53, vcc
	v_add_co_u32_e32 v54, vcc, 0xbae0000, v52
	s_nop 1
	v_addc_co_u32_e32 v55, vcc, 0, v53, vcc
	v_add_co_u32_e32 v54, vcc, 0xbb58000, v52
	s_nop 1
	v_addc_co_u32_e32 v55, vcc, 0, v53, vcc
	v_add_co_u32_e32 v54, vcc, 0xbbd0000, v52
	s_nop 1
	v_addc_co_u32_e32 v55, vcc, 0, v53, vcc
	v_add_co_u32_e32 v52, vcc, 0xbc48000, v52
	s_nop 0
	s_nop 0
	v_addc_co_u32_e32 v53, vcc, 0, v53, vcc
.LBB0_651:
	s_or_b64 exec, exec, s[58:59]
	v_or_b32_e32 v52, 48, v128
	v_lshlrev_b32_e32 v54, 1, v52
	v_cvt_pk_bf16_f32 v52, v48, v49
	v_cvt_pk_bf16_f32 v53, v50, v51
	s_and_saveexec_b64 s[58:59], s[44:45]
	s_xor_b64 s[58:59], exec, s[58:59]
	s_cbranch_execz .LBB0_653
	v_lshlrev_b32_e32 v56, 2, v128
	v_mov_b32_e32 v57, v177
	v_lshl_add_u64 v[56:57], v[66:67], 0, v[56:57]
	v_mov_b32_e32 v55, v177
	global_store_dwordx4 v[56:57], v[48:51], off offset:192
	s_nop 1
	v_lshl_add_u64 v[48:49], v[64:65], 0, v[54:55]
	v_add_co_u32_e32 v50, vcc, 0x5100000, v48
	s_nop 1
	v_addc_co_u32_e32 v51, vcc, 0, v49, vcc
	global_store_dwordx2 v[50:51], v[52:53], off offset:256
	v_add_co_u32_e32 v50, vcc, 0x5118000, v48
	s_nop 1
	v_addc_co_u32_e32 v51, vcc, 0, v49, vcc
	v_add_co_u32_e32 v50, vcc, 0x5130000, v48
	s_nop 1
	v_addc_co_u32_e32 v51, vcc, 0, v49, vcc
	v_add_co_u32_e32 v50, vcc, 0x5148000, v48
	s_nop 1
	v_addc_co_u32_e32 v51, vcc, 0, v49, vcc
	v_add_co_u32_e32 v50, vcc, 0x5160000, v48
	s_nop 1
	v_addc_co_u32_e32 v51, vcc, 0, v49, vcc
	v_add_co_u32_e32 v50, vcc, 0x5178000, v48
	s_nop 1
	v_addc_co_u32_e32 v51, vcc, 0, v49, vcc
	v_add_co_u32_e32 v50, vcc, 0x5190000, v48
	s_nop 1
	v_addc_co_u32_e32 v51, vcc, 0, v49, vcc
	v_add_co_u32_e32 v48, vcc, 0x51a8000, v48
	s_nop 0
	s_nop 0
	v_addc_co_u32_e32 v49, vcc, 0, v49, vcc
.LBB0_653:
	s_andn2_saveexec_b64 s[58:59], s[58:59]
	s_cbranch_execz .LBB0_655
	v_mov_b32_e32 v55, v177
	v_lshl_add_u64 v[48:49], v[68:69], 0, v[54:55]
	v_add_co_u32_e32 v50, vcc, 0xb900000, v48
	s_nop 1
	v_addc_co_u32_e32 v51, vcc, 0, v49, vcc
	global_store_dwordx2 v[50:51], v[52:53], off offset:256
	v_add_co_u32_e32 v50, vcc, 0xb978000, v48
	s_nop 1
	v_addc_co_u32_e32 v51, vcc, 0, v49, vcc
	v_add_co_u32_e32 v50, vcc, 0xb9f0000, v48
	s_nop 1
	v_addc_co_u32_e32 v51, vcc, 0, v49, vcc
	v_add_co_u32_e32 v50, vcc, 0xba68000, v48
	s_nop 1
	v_addc_co_u32_e32 v51, vcc, 0, v49, vcc
	v_add_co_u32_e32 v50, vcc, 0xbae0000, v48
	s_nop 1
	v_addc_co_u32_e32 v51, vcc, 0, v49, vcc
	v_add_co_u32_e32 v50, vcc, 0xbb58000, v48
	s_nop 1
	v_addc_co_u32_e32 v51, vcc, 0, v49, vcc
	v_add_co_u32_e32 v50, vcc, 0xbbd0000, v48
	s_nop 1
	v_addc_co_u32_e32 v51, vcc, 0, v49, vcc
	v_add_co_u32_e32 v48, vcc, 0xbc48000, v48
	s_nop 0
	s_nop 0
	v_addc_co_u32_e32 v49, vcc, 0, v49, vcc

.LBB0_663:
	s_or_b64 exec, exec, s[58:59]
	v_lshlrev_b64 v[64:65], 9, v[64:65]
	v_lshl_add_u64 v[64:65], s[14:15], 0, v[64:65]
	s_waitcnt lgkmcnt(0)
	v_mov_b32_e32 v67, v56
	s_nop 1
	v_permlane16_swap_b32_e32 v60, v67
	s_waitcnt lgkmcnt(0)
	v_mov_b32_e32 v56, v61
	v_mov_b32_e32 v61, v57
	s_nop 1
	v_permlane16_swap_b32_e32 v56, v61
	s_waitcnt lgkmcnt(0)
	v_mov_b32_e32 v57, v62
	v_mov_b32_e32 v62, v58
	s_nop 1
	v_permlane16_swap_b32_e32 v57, v62
	s_waitcnt lgkmcnt(0)
	v_lshl_add_u64 v[64:65], v[176:177], 1, v[64:65]
	v_mov_b32_e32 v58, v63
	s_nop 1
	v_permlane16_swap_b32_e32 v58, v59
	v_cvt_pk_bf16_f32 v56, v60, v56
	v_cvt_pk_bf16_f32 v57, v57, v58
	v_cvt_pk_bf16_f32 v58, v67, v61
	v_lshlrev_b32_e32 v60, 1, v180
	v_mov_b32_e32 v61, v177
	v_cvt_pk_bf16_f32 v59, v62, v59
	v_lshlrev_b32_e32 v62, 1, v179
	v_mov_b32_e32 v63, v177
	v_lshl_add_u64 v[60:61], v[64:65], 0, v[60:61]
	v_lshl_add_u64 v[60:61], v[60:61], 0, v[62:63]
	s_mov_b32 s58, 0xacff000
	v_add_co_u32_e32 v60, vcc, s58, v60
	s_nop 1
	v_addc_co_u32_e32 v61, vcc, 0, v61, vcc
	global_store_dwordx4 v[60:61], v[56:59], off offset:3328
	s_nop 1
	s_waitcnt lgkmcnt(0)
	v_mov_b32_e32 v56, v48
	s_nop 1
	v_permlane16_swap_b32_e32 v52, v56
	s_waitcnt lgkmcnt(0)
	v_mov_b32_e32 v48, v53
	v_mov_b32_e32 v53, v49
	s_nop 1
	v_permlane16_swap_b32_e32 v48, v53
	s_waitcnt lgkmcnt(0)
	v_mov_b32_e32 v49, v54
	v_mov_b32_e32 v54, v50
	s_nop 1
	v_permlane16_swap_b32_e32 v49, v54
	s_waitcnt lgkmcnt(0)
	v_mov_b32_e32 v50, v55
	s_nop 1
	v_permlane16_swap_b32_e32 v50, v51
	v_cvt_pk_bf16_f32 v48, v52, v48
	v_cvt_pk_bf16_f32 v49, v49, v50
	v_cvt_pk_bf16_f32 v50, v56, v53
	v_cvt_pk_bf16_f32 v51, v54, v51
	global_store_dwordx4 v[60:61], v[48:51], off offset:3392

.LBB0_667:
	s_or_b64 exec, exec, s[58:59]
	v_mov_b64_e32 v[68:69], s[4:5]
	s_movk_i32 vcc_lo, 0x300
	v_mad_i64_i32 v[68:69], s[58:59], v64, vcc_lo, v[68:69]
	v_lshlrev_b64 v[70:71], 1, v[134:135]
	s_waitcnt lgkmcnt(0)
	v_mov_b32_e32 v65, v56
	s_nop 1
	v_permlane16_swap_b32_e32 v60, v65
	s_waitcnt lgkmcnt(0)
	v_mov_b32_e32 v56, v61
	v_mov_b32_e32 v61, v57
	s_nop 1
	v_permlane16_swap_b32_e32 v56, v61
	s_waitcnt lgkmcnt(0)
	v_mov_b32_e32 v57, v62
	v_mov_b32_e32 v62, v58
	s_nop 1
	v_permlane16_swap_b32_e32 v57, v62
	s_waitcnt lgkmcnt(0)
	v_lshl_add_u64 v[68:69], v[68:69], 0, v[70:71]
	v_mov_b32_e32 v58, v63
	s_nop 1
	v_permlane16_swap_b32_e32 v58, v59
	v_cvt_pk_bf16_f32 v56, v60, v56
	v_cvt_pk_bf16_f32 v57, v57, v58
	v_cvt_pk_bf16_f32 v58, v65, v61
	v_lshlrev_b32_e32 v60, 1, v180
	v_mov_b32_e32 v61, v177
	v_cvt_pk_bf16_f32 v59, v62, v59
	v_lshl_add_u64 v[62:63], v[68:69], 0, v[60:61]
	v_lshlrev_b32_e32 v68, 1, v179
	v_mov_b32_e32 v69, v177
	v_lshl_add_u64 v[62:63], v[62:63], 0, v[68:69]
	global_store_dwordx4 v[62:63], v[56:59], off
	v_cndmask_b32_e64 v63, v55, v51, s[40:41]
	ds_bpermute_b32 v63, v66, v63
	v_mov_b64_e32 v[56:57], s[34:35]
	v_mad_i64_i32 v[56:57], s[58:59], v64, vcc_lo, v[56:57]
	v_lshl_add_u64 v[56:57], v[56:57], 0, v[70:71]
	s_waitcnt lgkmcnt(1)
	v_mov_b32_e32 v58, v48
	s_nop 1
	v_permlane16_swap_b32_e32 v52, v58
	s_waitcnt lgkmcnt(1)
	v_mov_b32_e32 v48, v53
	v_mov_b32_e32 v53, v49
	s_nop 1
	v_permlane16_swap_b32_e32 v48, v53
	s_waitcnt lgkmcnt(1)
	v_mov_b32_e32 v49, v54
	v_mov_b32_e32 v54, v50
	s_nop 1
	v_permlane16_swap_b32_e32 v49, v54
	s_waitcnt lgkmcnt(0)
	v_cndmask_b32_e64 v50, v63, v55, s[40:41]
	v_cvt_pk_bf16_f32 v48, v52, v48
	v_cvt_pk_bf16_f32 v49, v49, v50
	v_cvt_pk_bf16_f32 v50, v58, v53
	v_lshl_add_u64 v[52:53], v[56:57], 0, v[60:61]
	v_lshl_add_u64 v[52:53], v[52:53], 0, v[68:69]
	v_cndmask_b32_e64 v51, v51, v63, s[40:41]
	v_add_co_u32_e32 v52, vcc, 0xa700000, v52
	v_cvt_pk_bf16_f32 v51, v54, v51
	s_nop 0
	v_addc_co_u32_e32 v53, vcc, 0, v53, vcc
	global_store_dwordx4 v[52:53], v[48:51], off offset:64

.LBB0_669:
	s_or_b64 exec, exec, s[30:31]
	v_or_b32_e32 v52, 0x50, v182
	v_or_b32_e32 v48, v183, v52
	s_and_saveexec_b64 s[30:31], s[52:53]
	s_xor_b64 s[94:95], exec, s[30:31]
	s_cbranch_execz .LBB0_693
	s_and_saveexec_b64 s[30:31], s[50:51]
	s_xor_b64 s[30:31], exec, s[30:31]
	s_cbranch_execz .LBB0_672
	v_mul_f32_e32 v50, 0xbfb8aa3b, v44
	v_mul_f32_e32 v52, 0xbfb8aa3b, v40
	v_mul_f32_e32 v53, 0xbfb8aa3b, v45
	v_exp_f32_e32 v50, v50
	v_exp_f32_e32 v52, v52
	v_exp_f32_e32 v53, v53
	v_mul_f32_e32 v54, 0xbfb8aa3b, v41
	v_add_f32_e32 v50, 1.0, v50
	v_add_f32_e32 v52, 1.0, v52
	v_add_f32_e32 v53, 1.0, v53
	v_rcp_f32_e32 v50, v50
	v_rcp_f32_e32 v52, v52
	v_rcp_f32_e32 v53, v53
	v_exp_f32_e32 v54, v54
	v_mul_f32_e32 v50, v44, v50
	v_mul_f32_e32 v52, v40, v52
	v_mul_f32_e32 v53, v45, v53
	v_add_f32_e32 v40, 1.0, v54
	v_mul_f32_e32 v44, 0xbfb8aa3b, v46
	v_mul_f32_e32 v45, 0xbfb8aa3b, v42
	v_rcp_f32_e32 v40, v40
	v_exp_f32_e32 v44, v44
	v_exp_f32_e32 v45, v45
	v_ashrrev_i32_e32 v49, 31, v48
	v_mul_f32_e32 v54, v41, v40
	v_add_f32_e32 v40, 1.0, v44
	v_add_f32_e32 v41, 1.0, v45
	v_mul_f32_e32 v44, 0xbfb8aa3b, v47
	v_mul_f32_e32 v45, 0xbfb8aa3b, v43
	v_exp_f32_e32 v44, v44
	v_exp_f32_e32 v45, v45
	v_rcp_f32_e32 v40, v40
	v_rcp_f32_e32 v41, v41
	v_add_f32_e32 v44, 1.0, v44
	v_add_f32_e32 v45, 1.0, v45
	v_rcp_f32_e32 v44, v44
	v_rcp_f32_e32 v45, v45
	v_lshlrev_b64 v[48:49], 11, v[48:49]
	v_cmp_lt_i32_e32 vcc, v189, v202
	v_mul_f32_e32 v46, v46, v40
	v_mul_f32_e32 v42, v42, v41
	v_cndmask_b32_e32 v51, v203, v189, vcc
	v_mul_f32_e32 v47, v47, v44
	v_mul_f32_e32 v43, v43, v45
	v_lshl_add_u64 v[40:41], s[34:35], 0, v[48:49]
	v_lshlrev_b32_e32 v51, 2, v51
	v_lshl_add_u64 v[44:45], v[176:177], 1, v[40:41]
	s_mov_b32 s58, 0x96ff000
	s_waitcnt lgkmcnt(0)
	s_nop 1
	v_permlane16_swap_b32_e32 v50, v52
	s_waitcnt lgkmcnt(0)
	v_mov_b32_e32 v40, v53
	v_mov_b32_e32 v53, v54
	s_nop 1
	v_permlane16_swap_b32_e32 v40, v53
	s_waitcnt lgkmcnt(0)
	v_mov_b32_e32 v41, v46
	v_mov_b32_e32 v46, v42
	s_nop 1
	v_permlane16_swap_b32_e32 v41, v46
	s_waitcnt lgkmcnt(0)
	v_mov_b32_e32 v42, v47
	s_nop 1
	v_permlane16_swap_b32_e32 v42, v43
	v_cvt_pk_bf16_f32 v43, v46, v43
	v_lshlrev_b32_e32 v46, 1, v180
	v_mov_b32_e32 v47, v177
	v_lshlrev_b32_e32 v48, 1, v179
	v_mov_b32_e32 v49, v177
	v_lshl_add_u64 v[44:45], v[44:45], 0, v[46:47]
	v_lshl_add_u64 v[44:45], v[44:45], 0, v[48:49]
	v_add_co_u32_e32 v44, vcc, s58, v44
	v_cvt_pk_bf16_f32 v40, v50, v40
	v_cvt_pk_bf16_f32 v41, v41, v42
	v_cvt_pk_bf16_f32 v42, v52, v53
	v_addc_co_u32_e32 v45, vcc, 0, v45, vcc
	v_mul_f32_e32 v46, 0xbfb8aa3b, v36
	global_store_dwordx4 v[44:45], v[40:43], off offset:2688
	v_exp_f32_e32 v46, v46
	s_nop 0
	v_mul_f32_e32 v41, 0xbfb8aa3b, v32
	v_mul_f32_e32 v42, 0xbfb8aa3b, v37
	v_exp_f32_e32 v41, v41
	v_exp_f32_e32 v42, v42
	v_add_f32_e32 v40, 1.0, v46
	v_mul_f32_e32 v43, 0xbfb8aa3b, v33
	v_add_f32_e32 v41, 1.0, v41
	v_add_f32_e32 v42, 1.0, v42
	v_rcp_f32_e32 v40, v40
	v_rcp_f32_e32 v41, v41
	v_rcp_f32_e32 v42, v42
	v_exp_f32_e32 v43, v43
	v_mul_f32_e32 v36, v36, v40
	v_mul_f32_e32 v32, v32, v41
	v_mul_f32_e32 v37, v37, v42
	v_add_f32_e32 v40, 1.0, v43
	v_mul_f32_e32 v41, 0xbfb8aa3b, v38
	v_mul_f32_e32 v42, 0xbfb8aa3b, v34
	v_rcp_f32_e32 v40, v40
	v_exp_f32_e32 v41, v41
	v_exp_f32_e32 v42, v42
	v_mul_f32_e32 v43, 0xbfb8aa3b, v35
	v_mul_f32_e32 v33, v33, v40
	v_add_f32_e32 v40, 1.0, v41
	v_add_f32_e32 v41, 1.0, v42
	v_mul_f32_e32 v42, 0xbfb8aa3b, v39
	v_exp_f32_e32 v42, v42
	v_exp_f32_e32 v43, v43
	v_rcp_f32_e32 v40, v40
	v_rcp_f32_e32 v41, v41
	v_add_f32_e32 v42, 1.0, v42
	v_add_f32_e32 v43, 1.0, v43
	v_rcp_f32_e32 v42, v42
	v_rcp_f32_e32 v43, v43
	v_mul_f32_e32 v38, v38, v40
	v_mul_f32_e32 v34, v34, v41
	v_mul_f32_e32 v39, v39, v42
	v_mul_f32_e32 v35, v35, v43
	s_waitcnt lgkmcnt(0)
	v_mov_b32_e32 v40, v32
	s_nop 1
	v_permlane16_swap_b32_e32 v36, v40
	s_waitcnt lgkmcnt(0)
	v_mov_b32_e32 v32, v37
	v_mov_b32_e32 v37, v33
	s_nop 1
	v_permlane16_swap_b32_e32 v32, v37
	s_waitcnt lgkmcnt(0)
	v_mov_b32_e32 v33, v38
	v_mov_b32_e32 v38, v34
	s_nop 1
	v_permlane16_swap_b32_e32 v33, v38
	s_waitcnt lgkmcnt(0)
	v_mov_b32_e32 v34, v39
	s_nop 1
	v_permlane16_swap_b32_e32 v34, v35
	v_cvt_pk_bf16_f32 v32, v36, v32
	v_cvt_pk_bf16_f32 v33, v33, v34
	v_cvt_pk_bf16_f32 v34, v40, v37
	v_cvt_pk_bf16_f32 v35, v38, v35
	global_store_dwordx4 v[44:45], v[32:35], off offset:2752

.LBB0_679:
	s_or_b64 exec, exec, vcc
	v_lshlrev_b32_e32 v84, 1, v128
	v_mov_b32_e32 v85, v177
	v_lshl_add_u64 v[60:61], v[60:61], 0, v[84:85]
	v_cvt_pk_bf16_f32 v44, v44, v45
	v_cvt_pk_bf16_f32 v45, v46, v47
	v_lshl_add_u64 v[46:47], v[60:61], 0, v[82:83]
	v_lshl_add_u64 v[46:47], v[60:61], 0, v[80:81]
	v_lshl_add_u64 v[46:47], v[60:61], 0, v[78:79]
	v_lshl_add_u64 v[46:47], v[60:61], 0, v[76:77]
	v_lshl_add_u64 v[46:47], v[60:61], 0, v[74:75]
	v_lshl_add_u64 v[46:47], v[60:61], 0, v[72:73]
	v_lshl_add_u64 v[46:47], v[60:61], 0, v[70:71]
	v_lshl_add_u64 v[46:47], v[60:61], 0, v[68:69]
	v_lshl_add_u64 v[46:47], v[60:61], 0, v[66:67]
	v_lshl_add_u64 v[46:47], v[60:61], 0, v[64:65]
	v_lshl_add_u64 v[46:47], v[60:61], 0, v[62:63]
	v_lshl_add_u64 v[46:47], v[60:61], 0, v[58:59]
	v_lshl_add_u64 v[46:47], v[60:61], 0, v[56:57]
	global_store_dwordx2 v[60:61], v[44:45], off
	v_lshl_add_u64 v[46:47], v[60:61], 0, v[54:55]
	v_or_b32_e32 v44, 16, v128
	v_lshlrev_b32_e32 v46, 1, v44
	v_cvt_pk_bf16_f32 v44, v40, v41
	v_cvt_pk_bf16_f32 v45, v42, v43
	s_and_saveexec_b64 s[58:59], s[44:45]
	s_xor_b64 s[58:59], exec, s[58:59]
	s_cbranch_execz .LBB0_681
	v_lshlrev_b32_e32 v54, 2, v128
	v_mov_b32_e32 v55, v177
	v_lshl_add_u64 v[54:55], v[50:51], 0, v[54:55]
	v_mov_b32_e32 v47, v177
	global_store_dwordx4 v[54:55], v[40:43], off offset:64
	s_nop 1
	v_lshl_add_u64 v[40:41], v[48:49], 0, v[46:47]
	v_add_co_u32_e32 v42, vcc, 0x5100000, v40
	s_nop 1
	v_addc_co_u32_e32 v43, vcc, 0, v41, vcc
	global_store_dwordx2 v[42:43], v[44:45], off offset:256
	v_add_co_u32_e32 v42, vcc, 0x5118000, v40
	s_nop 1
	v_addc_co_u32_e32 v43, vcc, 0, v41, vcc
	v_add_co_u32_e32 v42, vcc, 0x5130000, v40
	s_nop 1
	v_addc_co_u32_e32 v43, vcc, 0, v41, vcc
	v_add_co_u32_e32 v42, vcc, 0x5148000, v40
	s_nop 1
	v_addc_co_u32_e32 v43, vcc, 0, v41, vcc
	v_add_co_u32_e32 v42, vcc, 0x5160000, v40
	s_nop 1
	v_addc_co_u32_e32 v43, vcc, 0, v41, vcc
	v_add_co_u32_e32 v42, vcc, 0x5178000, v40
	s_nop 1
	v_addc_co_u32_e32 v43, vcc, 0, v41, vcc
	v_add_co_u32_e32 v42, vcc, 0x5190000, v40
	s_nop 1
	v_addc_co_u32_e32 v43, vcc, 0, v41, vcc
	v_add_co_u32_e32 v40, vcc, 0x51a8000, v40
	s_nop 0
	s_nop 0
	v_addc_co_u32_e32 v41, vcc, 0, v41, vcc
.LBB0_681:
	s_andn2_saveexec_b64 s[58:59], s[58:59]
	s_cbranch_execz .LBB0_683
	v_mov_b32_e32 v47, v177
	v_lshl_add_u64 v[40:41], v[52:53], 0, v[46:47]
	v_add_co_u32_e32 v42, vcc, 0xb900000, v40
	s_nop 1
	v_addc_co_u32_e32 v43, vcc, 0, v41, vcc
	global_store_dwordx2 v[42:43], v[44:45], off offset:256
	v_add_co_u32_e32 v42, vcc, 0xb978000, v40
	s_nop 1
	v_addc_co_u32_e32 v43, vcc, 0, v41, vcc
	v_add_co_u32_e32 v42, vcc, 0xb9f0000, v40
	s_nop 1
	v_addc_co_u32_e32 v43, vcc, 0, v41, vcc
	v_add_co_u32_e32 v42, vcc, 0xba68000, v40
	s_nop 1
	v_addc_co_u32_e32 v43, vcc, 0, v41, vcc
	v_add_co_u32_e32 v42, vcc, 0xbae0000, v40
	s_nop 1
	v_addc_co_u32_e32 v43, vcc, 0, v41, vcc
	v_add_co_u32_e32 v42, vcc, 0xbb58000, v40
	s_nop 1
	v_addc_co_u32_e32 v43, vcc, 0, v41, vcc
	v_add_co_u32_e32 v42, vcc, 0xbbd0000, v40
	s_nop 1
	v_addc_co_u32_e32 v43, vcc, 0, v41, vcc
	v_add_co_u32_e32 v40, vcc, 0xbc48000, v40
	s_nop 0
	s_nop 0
	v_addc_co_u32_e32 v41, vcc, 0, v41, vcc
.LBB0_683:
	s_or_b64 exec, exec, s[58:59]
	v_or_b32_e32 v40, 32, v128
	v_lshlrev_b32_e32 v42, 1, v40
	v_cvt_pk_bf16_f32 v40, v36, v37
	v_cvt_pk_bf16_f32 v41, v38, v39
	s_and_saveexec_b64 s[58:59], s[44:45]
	s_xor_b64 s[58:59], exec, s[58:59]
	s_cbranch_execz .LBB0_685
	v_lshlrev_b32_e32 v44, 2, v128
	v_mov_b32_e32 v45, v177
	v_lshl_add_u64 v[44:45], v[50:51], 0, v[44:45]
	v_mov_b32_e32 v43, v177
	global_store_dwordx4 v[44:45], v[36:39], off offset:128
	s_nop 1
	v_lshl_add_u64 v[36:37], v[48:49], 0, v[42:43]
	v_add_co_u32_e32 v38, vcc, 0x5100000, v36
	s_nop 1
	v_addc_co_u32_e32 v39, vcc, 0, v37, vcc
	global_store_dwordx2 v[38:39], v[40:41], off offset:256
	v_add_co_u32_e32 v38, vcc, 0x5118000, v36
	s_nop 1
	v_addc_co_u32_e32 v39, vcc, 0, v37, vcc
	v_add_co_u32_e32 v38, vcc, 0x5130000, v36
	s_nop 1
	v_addc_co_u32_e32 v39, vcc, 0, v37, vcc
	v_add_co_u32_e32 v38, vcc, 0x5148000, v36
	s_nop 1
	v_addc_co_u32_e32 v39, vcc, 0, v37, vcc
	v_add_co_u32_e32 v38, vcc, 0x5160000, v36
	s_nop 1
	v_addc_co_u32_e32 v39, vcc, 0, v37, vcc
	v_add_co_u32_e32 v38, vcc, 0x5178000, v36
	s_nop 1
	v_addc_co_u32_e32 v39, vcc, 0, v37, vcc
	v_add_co_u32_e32 v38, vcc, 0x5190000, v36
	s_nop 1
	v_addc_co_u32_e32 v39, vcc, 0, v37, vcc
	v_add_co_u32_e32 v36, vcc, 0x51a8000, v36
	s_nop 0
	s_nop 0
	v_addc_co_u32_e32 v37, vcc, 0, v37, vcc
.LBB0_685:
	s_andn2_saveexec_b64 s[58:59], s[58:59]
	s_cbranch_execz .LBB0_687
	v_mov_b32_e32 v43, v177
	v_lshl_add_u64 v[36:37], v[52:53], 0, v[42:43]
	v_add_co_u32_e32 v38, vcc, 0xb900000, v36
	s_nop 1
	v_addc_co_u32_e32 v39, vcc, 0, v37, vcc
	global_store_dwordx2 v[38:39], v[40:41], off offset:256
	v_add_co_u32_e32 v38, vcc, 0xb978000, v36
	s_nop 1
	v_addc_co_u32_e32 v39, vcc, 0, v37, vcc
	v_add_co_u32_e32 v38, vcc, 0xb9f0000, v36
	s_nop 1
	v_addc_co_u32_e32 v39, vcc, 0, v37, vcc
	v_add_co_u32_e32 v38, vcc, 0xba68000, v36
	s_nop 1
	v_addc_co_u32_e32 v39, vcc, 0, v37, vcc
	v_add_co_u32_e32 v38, vcc, 0xbae0000, v36
	s_nop 1
	v_addc_co_u32_e32 v39, vcc, 0, v37, vcc
	v_add_co_u32_e32 v38, vcc, 0xbb58000, v36
	s_nop 1
	v_addc_co_u32_e32 v39, vcc, 0, v37, vcc
	v_add_co_u32_e32 v38, vcc, 0xbbd0000, v36
	s_nop 1
	v_addc_co_u32_e32 v39, vcc, 0, v37, vcc
	v_add_co_u32_e32 v36, vcc, 0xbc48000, v36
	s_nop 0
	s_nop 0
	v_addc_co_u32_e32 v37, vcc, 0, v37, vcc
.LBB0_687:
	s_or_b64 exec, exec, s[58:59]
	v_or_b32_e32 v36, 48, v128
	v_lshlrev_b32_e32 v38, 1, v36
	v_cvt_pk_bf16_f32 v36, v32, v33
	v_cvt_pk_bf16_f32 v37, v34, v35
	s_and_saveexec_b64 s[58:59], s[44:45]
	s_xor_b64 s[58:59], exec, s[58:59]
	s_cbranch_execz .LBB0_689
	v_lshlrev_b32_e32 v40, 2, v128
	v_mov_b32_e32 v41, v177
	v_lshl_add_u64 v[40:41], v[50:51], 0, v[40:41]
	v_mov_b32_e32 v39, v177
	global_store_dwordx4 v[40:41], v[32:35], off offset:192
	s_nop 1
	v_lshl_add_u64 v[32:33], v[48:49], 0, v[38:39]
	v_add_co_u32_e32 v34, vcc, 0x5100000, v32
	s_nop 1
	v_addc_co_u32_e32 v35, vcc, 0, v33, vcc
	global_store_dwordx2 v[34:35], v[36:37], off offset:256
	v_add_co_u32_e32 v34, vcc, 0x5118000, v32
	s_nop 1
	v_addc_co_u32_e32 v35, vcc, 0, v33, vcc
	v_add_co_u32_e32 v34, vcc, 0x5130000, v32
	s_nop 1
	v_addc_co_u32_e32 v35, vcc, 0, v33, vcc
	v_add_co_u32_e32 v34, vcc, 0x5148000, v32
	s_nop 1
	v_addc_co_u32_e32 v35, vcc, 0, v33, vcc
	v_add_co_u32_e32 v34, vcc, 0x5160000, v32
	s_nop 1
	v_addc_co_u32_e32 v35, vcc, 0, v33, vcc
	v_add_co_u32_e32 v34, vcc, 0x5178000, v32
	s_nop 1
	v_addc_co_u32_e32 v35, vcc, 0, v33, vcc
	v_add_co_u32_e32 v34, vcc, 0x5190000, v32
	s_nop 1
	v_addc_co_u32_e32 v35, vcc, 0, v33, vcc
	v_add_co_u32_e32 v32, vcc, 0x51a8000, v32
	s_nop 0
	s_nop 0
	v_addc_co_u32_e32 v33, vcc, 0, v33, vcc
.LBB0_689:
	s_andn2_saveexec_b64 s[58:59], s[58:59]
	s_cbranch_execz .LBB0_691
	v_mov_b32_e32 v39, v177
	v_lshl_add_u64 v[32:33], v[52:53], 0, v[38:39]
	v_add_co_u32_e32 v34, vcc, 0xb900000, v32
	s_nop 1
	v_addc_co_u32_e32 v35, vcc, 0, v33, vcc
	global_store_dwordx2 v[34:35], v[36:37], off offset:256
	v_add_co_u32_e32 v34, vcc, 0xb978000, v32
	s_nop 1
	v_addc_co_u32_e32 v35, vcc, 0, v33, vcc
	v_add_co_u32_e32 v34, vcc, 0xb9f0000, v32
	s_nop 1
	v_addc_co_u32_e32 v35, vcc, 0, v33, vcc
	v_add_co_u32_e32 v34, vcc, 0xba68000, v32
	s_nop 1
	v_addc_co_u32_e32 v35, vcc, 0, v33, vcc
	v_add_co_u32_e32 v34, vcc, 0xbae0000, v32
	s_nop 1
	v_addc_co_u32_e32 v35, vcc, 0, v33, vcc
	v_add_co_u32_e32 v34, vcc, 0xbb58000, v32
	s_nop 1
	v_addc_co_u32_e32 v35, vcc, 0, v33, vcc
	v_add_co_u32_e32 v34, vcc, 0xbbd0000, v32
	s_nop 1
	v_addc_co_u32_e32 v35, vcc, 0, v33, vcc
	v_add_co_u32_e32 v32, vcc, 0xbc48000, v32
	s_nop 0
	s_nop 0
	v_addc_co_u32_e32 v33, vcc, 0, v33, vcc

.LBB0_699:
	s_or_b64 exec, exec, s[58:59]
	v_lshlrev_b64 v[48:49], 9, v[48:49]
	v_lshl_add_u64 v[48:49], s[14:15], 0, v[48:49]
	s_waitcnt lgkmcnt(0)
	v_mov_b32_e32 v51, v40
	s_nop 1
	v_permlane16_swap_b32_e32 v44, v51
	s_waitcnt lgkmcnt(0)
	v_mov_b32_e32 v40, v45
	v_mov_b32_e32 v45, v41
	s_nop 1
	v_permlane16_swap_b32_e32 v40, v45
	s_waitcnt lgkmcnt(0)
	v_mov_b32_e32 v41, v46
	v_mov_b32_e32 v46, v42
	s_nop 1
	v_permlane16_swap_b32_e32 v41, v46
	s_waitcnt lgkmcnt(0)
	v_lshl_add_u64 v[48:49], v[176:177], 1, v[48:49]
	v_mov_b32_e32 v42, v47
	s_nop 1
	v_permlane16_swap_b32_e32 v42, v43
	v_cvt_pk_bf16_f32 v40, v44, v40
	v_cvt_pk_bf16_f32 v41, v41, v42
	v_cvt_pk_bf16_f32 v42, v51, v45
	v_lshlrev_b32_e32 v44, 1, v180
	v_mov_b32_e32 v45, v177
	v_cvt_pk_bf16_f32 v43, v46, v43
	v_lshlrev_b32_e32 v46, 1, v179
	v_mov_b32_e32 v47, v177
	v_lshl_add_u64 v[44:45], v[48:49], 0, v[44:45]
	v_lshl_add_u64 v[44:45], v[44:45], 0, v[46:47]
	s_mov_b32 s58, 0xacff000
	v_add_co_u32_e32 v44, vcc, s58, v44
	s_nop 1
	v_addc_co_u32_e32 v45, vcc, 0, v45, vcc
	global_store_dwordx4 v[44:45], v[40:43], off offset:3328
	s_nop 1
	s_waitcnt lgkmcnt(0)
	v_mov_b32_e32 v40, v32
	s_nop 1
	v_permlane16_swap_b32_e32 v36, v40
	s_waitcnt lgkmcnt(0)
	v_mov_b32_e32 v32, v37
	v_mov_b32_e32 v37, v33
	s_nop 1
	v_permlane16_swap_b32_e32 v32, v37
	s_waitcnt lgkmcnt(0)
	v_mov_b32_e32 v33, v38
	v_mov_b32_e32 v38, v34
	s_nop 1
	v_permlane16_swap_b32_e32 v33, v38
	s_waitcnt lgkmcnt(0)
	v_mov_b32_e32 v34, v39
	s_nop 1
	v_permlane16_swap_b32_e32 v34, v35
	v_cvt_pk_bf16_f32 v32, v36, v32
	v_cvt_pk_bf16_f32 v33, v33, v34
	v_cvt_pk_bf16_f32 v34, v40, v37
	v_cvt_pk_bf16_f32 v35, v38, v35
	global_store_dwordx4 v[44:45], v[32:35], off offset:3392

.LBB0_703:
	s_or_b64 exec, exec, s[58:59]
	v_mov_b64_e32 v[52:53], s[4:5]
	s_movk_i32 vcc_lo, 0x300
	v_mad_i64_i32 v[52:53], s[58:59], v48, vcc_lo, v[52:53]
	v_lshlrev_b64 v[54:55], 1, v[134:135]
	s_waitcnt lgkmcnt(0)
	v_mov_b32_e32 v49, v40
	s_nop 1
	v_permlane16_swap_b32_e32 v44, v49
	s_waitcnt lgkmcnt(0)
	v_mov_b32_e32 v40, v45
	v_mov_b32_e32 v45, v41
	s_nop 1
	v_permlane16_swap_b32_e32 v40, v45
	s_waitcnt lgkmcnt(0)
	v_mov_b32_e32 v41, v46
	v_mov_b32_e32 v46, v42
	s_nop 1
	v_permlane16_swap_b32_e32 v41, v46
	s_waitcnt lgkmcnt(0)
	v_lshl_add_u64 v[52:53], v[52:53], 0, v[54:55]
	v_mov_b32_e32 v42, v47
	s_nop 1
	v_permlane16_swap_b32_e32 v42, v43
	v_cvt_pk_bf16_f32 v40, v44, v40
	v_cvt_pk_bf16_f32 v41, v41, v42
	v_cvt_pk_bf16_f32 v42, v49, v45
	v_lshlrev_b32_e32 v44, 1, v180
	v_mov_b32_e32 v45, v177
	v_cvt_pk_bf16_f32 v43, v46, v43
	v_lshl_add_u64 v[46:47], v[52:53], 0, v[44:45]
	v_lshlrev_b32_e32 v52, 1, v179
	v_mov_b32_e32 v53, v177
	v_lshl_add_u64 v[46:47], v[46:47], 0, v[52:53]
	global_store_dwordx4 v[46:47], v[40:43], off
	v_cndmask_b32_e64 v47, v39, v35, s[40:41]
	ds_bpermute_b32 v47, v50, v47
	v_mov_b64_e32 v[40:41], s[34:35]
	v_mad_i64_i32 v[40:41], s[58:59], v48, vcc_lo, v[40:41]
	v_lshl_add_u64 v[40:41], v[40:41], 0, v[54:55]
	s_waitcnt lgkmcnt(1)
	v_mov_b32_e32 v42, v32
	s_nop 1
	v_permlane16_swap_b32_e32 v36, v42
	s_waitcnt lgkmcnt(1)
	v_mov_b32_e32 v32, v37
	v_mov_b32_e32 v37, v33
	s_nop 1
	v_permlane16_swap_b32_e32 v32, v37
	s_waitcnt lgkmcnt(1)
	v_mov_b32_e32 v33, v38
	v_mov_b32_e32 v38, v34
	s_nop 1
	v_permlane16_swap_b32_e32 v33, v38
	s_waitcnt lgkmcnt(0)
	v_cndmask_b32_e64 v34, v47, v39, s[40:41]
	v_cvt_pk_bf16_f32 v32, v36, v32
	v_cvt_pk_bf16_f32 v33, v33, v34
	v_cvt_pk_bf16_f32 v34, v42, v37
	v_lshl_add_u64 v[36:37], v[40:41], 0, v[44:45]
	v_lshl_add_u64 v[36:37], v[36:37], 0, v[52:53]
	v_cndmask_b32_e64 v35, v35, v47, s[40:41]
	v_add_co_u32_e32 v36, vcc, 0xa700000, v36
	v_cvt_pk_bf16_f32 v35, v38, v35
	s_nop 0
	v_addc_co_u32_e32 v37, vcc, 0, v37, vcc
	global_store_dwordx4 v[36:37], v[32:35], off offset:64

.LBB0_705:
	s_or_b64 exec, exec, s[30:31]
	v_or_b32_e32 v36, 0x60, v182
	v_or_b32_e32 v32, v183, v36
	s_and_saveexec_b64 s[30:31], s[52:53]
	s_xor_b64 s[94:95], exec, s[30:31]
	s_cbranch_execz .LBB0_729
	s_and_saveexec_b64 s[30:31], s[50:51]
	s_xor_b64 s[30:31], exec, s[30:31]
	s_cbranch_execz .LBB0_708
	v_mul_f32_e32 v34, 0xbfb8aa3b, v28
	v_mul_f32_e32 v36, 0xbfb8aa3b, v24
	v_mul_f32_e32 v37, 0xbfb8aa3b, v29
	v_exp_f32_e32 v34, v34
	v_exp_f32_e32 v36, v36
	v_exp_f32_e32 v37, v37
	v_mul_f32_e32 v38, 0xbfb8aa3b, v25
	v_add_f32_e32 v34, 1.0, v34
	v_add_f32_e32 v36, 1.0, v36
	v_add_f32_e32 v37, 1.0, v37
	v_rcp_f32_e32 v34, v34
	v_rcp_f32_e32 v36, v36
	v_rcp_f32_e32 v37, v37
	v_exp_f32_e32 v38, v38
	v_mul_f32_e32 v34, v28, v34
	v_mul_f32_e32 v36, v24, v36
	v_mul_f32_e32 v37, v29, v37
	v_add_f32_e32 v24, 1.0, v38
	v_mul_f32_e32 v28, 0xbfb8aa3b, v30
	v_mul_f32_e32 v29, 0xbfb8aa3b, v26
	v_rcp_f32_e32 v24, v24
	v_exp_f32_e32 v28, v28
	v_exp_f32_e32 v29, v29
	v_ashrrev_i32_e32 v33, 31, v32
	v_mul_f32_e32 v38, v25, v24
	v_add_f32_e32 v24, 1.0, v28
	v_add_f32_e32 v25, 1.0, v29
	v_mul_f32_e32 v28, 0xbfb8aa3b, v31
	v_mul_f32_e32 v29, 0xbfb8aa3b, v27
	v_exp_f32_e32 v28, v28
	v_exp_f32_e32 v29, v29
	v_rcp_f32_e32 v24, v24
	v_rcp_f32_e32 v25, v25
	v_add_f32_e32 v28, 1.0, v28
	v_add_f32_e32 v29, 1.0, v29
	v_rcp_f32_e32 v28, v28
	v_rcp_f32_e32 v29, v29
	v_lshlrev_b64 v[32:33], 11, v[32:33]
	v_cmp_lt_i32_e32 vcc, v189, v202
	v_mul_f32_e32 v30, v30, v24
	v_mul_f32_e32 v26, v26, v25
	v_cndmask_b32_e32 v35, v203, v189, vcc
	v_mul_f32_e32 v31, v31, v28
	v_mul_f32_e32 v27, v27, v29
	v_lshl_add_u64 v[24:25], s[34:35], 0, v[32:33]
	v_lshlrev_b32_e32 v35, 2, v35
	v_lshl_add_u64 v[28:29], v[176:177], 1, v[24:25]
	s_mov_b32 s58, 0x96ff000
	s_waitcnt lgkmcnt(0)
	s_nop 1
	v_permlane16_swap_b32_e32 v34, v36
	s_waitcnt lgkmcnt(0)
	v_mov_b32_e32 v24, v37
	v_mov_b32_e32 v37, v38
	s_nop 1
	v_permlane16_swap_b32_e32 v24, v37
	s_waitcnt lgkmcnt(0)
	v_mov_b32_e32 v25, v30
	v_mov_b32_e32 v30, v26
	s_nop 1
	v_permlane16_swap_b32_e32 v25, v30
	s_waitcnt lgkmcnt(0)
	v_mov_b32_e32 v26, v31
	s_nop 1
	v_permlane16_swap_b32_e32 v26, v27
	v_cvt_pk_bf16_f32 v27, v30, v27
	v_lshlrev_b32_e32 v30, 1, v180
	v_mov_b32_e32 v31, v177
	v_lshlrev_b32_e32 v32, 1, v179
	v_mov_b32_e32 v33, v177
	v_lshl_add_u64 v[28:29], v[28:29], 0, v[30:31]
	v_lshl_add_u64 v[28:29], v[28:29], 0, v[32:33]
	v_add_co_u32_e32 v28, vcc, s58, v28
	v_cvt_pk_bf16_f32 v24, v34, v24
	v_cvt_pk_bf16_f32 v25, v25, v26
	v_cvt_pk_bf16_f32 v26, v36, v37
	v_addc_co_u32_e32 v29, vcc, 0, v29, vcc
	v_mul_f32_e32 v30, 0xbfb8aa3b, v20
	global_store_dwordx4 v[28:29], v[24:27], off offset:2688
	v_exp_f32_e32 v30, v30
	s_nop 0
	v_mul_f32_e32 v25, 0xbfb8aa3b, v16
	v_mul_f32_e32 v26, 0xbfb8aa3b, v21
	v_exp_f32_e32 v25, v25
	v_exp_f32_e32 v26, v26
	v_add_f32_e32 v24, 1.0, v30
	v_mul_f32_e32 v27, 0xbfb8aa3b, v17
	v_add_f32_e32 v25, 1.0, v25
	v_add_f32_e32 v26, 1.0, v26
	v_rcp_f32_e32 v24, v24
	v_rcp_f32_e32 v25, v25
	v_rcp_f32_e32 v26, v26
	v_exp_f32_e32 v27, v27
	v_mul_f32_e32 v20, v20, v24
	v_mul_f32_e32 v16, v16, v25
	v_mul_f32_e32 v21, v21, v26
	v_add_f32_e32 v24, 1.0, v27
	v_mul_f32_e32 v25, 0xbfb8aa3b, v22
	v_mul_f32_e32 v26, 0xbfb8aa3b, v18
	v_rcp_f32_e32 v24, v24
	v_exp_f32_e32 v25, v25
	v_exp_f32_e32 v26, v26
	v_mul_f32_e32 v27, 0xbfb8aa3b, v19
	v_mul_f32_e32 v17, v17, v24
	v_add_f32_e32 v24, 1.0, v25
	v_add_f32_e32 v25, 1.0, v26
	v_mul_f32_e32 v26, 0xbfb8aa3b, v23
	v_exp_f32_e32 v26, v26
	v_exp_f32_e32 v27, v27
	v_rcp_f32_e32 v24, v24
	v_rcp_f32_e32 v25, v25
	v_add_f32_e32 v26, 1.0, v26
	v_add_f32_e32 v27, 1.0, v27
	v_rcp_f32_e32 v26, v26
	v_rcp_f32_e32 v27, v27
	v_mul_f32_e32 v22, v22, v24
	v_mul_f32_e32 v18, v18, v25
	v_mul_f32_e32 v23, v23, v26
	v_mul_f32_e32 v19, v19, v27
	s_waitcnt lgkmcnt(0)
	v_mov_b32_e32 v24, v16
	s_nop 1
	v_permlane16_swap_b32_e32 v20, v24
	s_waitcnt lgkmcnt(0)
	v_mov_b32_e32 v16, v21
	v_mov_b32_e32 v21, v17
	s_nop 1
	v_permlane16_swap_b32_e32 v16, v21
	s_waitcnt lgkmcnt(0)
	v_mov_b32_e32 v17, v22
	v_mov_b32_e32 v22, v18
	s_nop 1
	v_permlane16_swap_b32_e32 v17, v22
	s_waitcnt lgkmcnt(0)
	v_mov_b32_e32 v18, v23
	s_nop 1
	v_permlane16_swap_b32_e32 v18, v19
	v_cvt_pk_bf16_f32 v16, v20, v16
	v_cvt_pk_bf16_f32 v17, v17, v18
	v_cvt_pk_bf16_f32 v18, v24, v21
	v_cvt_pk_bf16_f32 v19, v22, v19
	global_store_dwordx4 v[28:29], v[16:19], off offset:2752

.LBB0_715:
	s_or_b64 exec, exec, vcc
	v_lshlrev_b32_e32 v68, 1, v128
	v_mov_b32_e32 v69, v177
	v_lshl_add_u64 v[44:45], v[44:45], 0, v[68:69]
	v_cvt_pk_bf16_f32 v28, v28, v29
	v_cvt_pk_bf16_f32 v29, v30, v31
	v_lshl_add_u64 v[30:31], v[44:45], 0, v[66:67]
	v_lshl_add_u64 v[30:31], v[44:45], 0, v[64:65]
	v_lshl_add_u64 v[30:31], v[44:45], 0, v[62:63]
	v_lshl_add_u64 v[30:31], v[44:45], 0, v[60:61]
	v_lshl_add_u64 v[30:31], v[44:45], 0, v[58:59]
	v_lshl_add_u64 v[30:31], v[44:45], 0, v[56:57]
	v_lshl_add_u64 v[30:31], v[44:45], 0, v[54:55]
	v_lshl_add_u64 v[30:31], v[44:45], 0, v[52:53]
	v_lshl_add_u64 v[30:31], v[44:45], 0, v[50:51]
	v_lshl_add_u64 v[30:31], v[44:45], 0, v[48:49]
	v_lshl_add_u64 v[30:31], v[44:45], 0, v[46:47]
	v_lshl_add_u64 v[30:31], v[44:45], 0, v[42:43]
	v_lshl_add_u64 v[30:31], v[44:45], 0, v[40:41]
	global_store_dwordx2 v[44:45], v[28:29], off
	v_lshl_add_u64 v[30:31], v[44:45], 0, v[38:39]
	v_or_b32_e32 v28, 16, v128
	v_lshlrev_b32_e32 v30, 1, v28
	v_cvt_pk_bf16_f32 v28, v24, v25
	v_cvt_pk_bf16_f32 v29, v26, v27
	s_and_saveexec_b64 s[58:59], s[44:45]
	s_xor_b64 s[58:59], exec, s[58:59]
	s_cbranch_execz .LBB0_717
	v_lshlrev_b32_e32 v38, 2, v128
	v_mov_b32_e32 v39, v177
	v_lshl_add_u64 v[38:39], v[34:35], 0, v[38:39]
	v_mov_b32_e32 v31, v177
	global_store_dwordx4 v[38:39], v[24:27], off offset:64
	s_nop 1
	v_lshl_add_u64 v[24:25], v[32:33], 0, v[30:31]
	v_add_co_u32_e32 v26, vcc, 0x5100000, v24
	s_nop 1
	v_addc_co_u32_e32 v27, vcc, 0, v25, vcc
	global_store_dwordx2 v[26:27], v[28:29], off offset:256
	v_add_co_u32_e32 v26, vcc, 0x5118000, v24
	s_nop 1
	v_addc_co_u32_e32 v27, vcc, 0, v25, vcc
	v_add_co_u32_e32 v26, vcc, 0x5130000, v24
	s_nop 1
	v_addc_co_u32_e32 v27, vcc, 0, v25, vcc
	v_add_co_u32_e32 v26, vcc, 0x5148000, v24
	s_nop 1
	v_addc_co_u32_e32 v27, vcc, 0, v25, vcc
	v_add_co_u32_e32 v26, vcc, 0x5160000, v24
	s_nop 1
	v_addc_co_u32_e32 v27, vcc, 0, v25, vcc
	v_add_co_u32_e32 v26, vcc, 0x5178000, v24
	s_nop 1
	v_addc_co_u32_e32 v27, vcc, 0, v25, vcc
	v_add_co_u32_e32 v26, vcc, 0x5190000, v24
	s_nop 1
	v_addc_co_u32_e32 v27, vcc, 0, v25, vcc
	v_add_co_u32_e32 v24, vcc, 0x51a8000, v24
	s_nop 0
	s_nop 0
	v_addc_co_u32_e32 v25, vcc, 0, v25, vcc
.LBB0_717:
	s_andn2_saveexec_b64 s[58:59], s[58:59]
	s_cbranch_execz .LBB0_719
	v_mov_b32_e32 v31, v177
	v_lshl_add_u64 v[24:25], v[36:37], 0, v[30:31]
	v_add_co_u32_e32 v26, vcc, 0xb900000, v24
	s_nop 1
	v_addc_co_u32_e32 v27, vcc, 0, v25, vcc
	global_store_dwordx2 v[26:27], v[28:29], off offset:256
	v_add_co_u32_e32 v26, vcc, 0xb978000, v24
	s_nop 1
	v_addc_co_u32_e32 v27, vcc, 0, v25, vcc
	v_add_co_u32_e32 v26, vcc, 0xb9f0000, v24
	s_nop 1
	v_addc_co_u32_e32 v27, vcc, 0, v25, vcc
	v_add_co_u32_e32 v26, vcc, 0xba68000, v24
	s_nop 1
	v_addc_co_u32_e32 v27, vcc, 0, v25, vcc
	v_add_co_u32_e32 v26, vcc, 0xbae0000, v24
	s_nop 1
	v_addc_co_u32_e32 v27, vcc, 0, v25, vcc
	v_add_co_u32_e32 v26, vcc, 0xbb58000, v24
	s_nop 1
	v_addc_co_u32_e32 v27, vcc, 0, v25, vcc
	v_add_co_u32_e32 v26, vcc, 0xbbd0000, v24
	s_nop 1
	v_addc_co_u32_e32 v27, vcc, 0, v25, vcc
	v_add_co_u32_e32 v24, vcc, 0xbc48000, v24
	s_nop 0
	s_nop 0
	v_addc_co_u32_e32 v25, vcc, 0, v25, vcc
.LBB0_719:
	s_or_b64 exec, exec, s[58:59]
	v_or_b32_e32 v24, 32, v128
	v_lshlrev_b32_e32 v26, 1, v24
	v_cvt_pk_bf16_f32 v24, v20, v21
	v_cvt_pk_bf16_f32 v25, v22, v23
	s_and_saveexec_b64 s[58:59], s[44:45]
	s_xor_b64 s[58:59], exec, s[58:59]
	s_cbranch_execz .LBB0_721
	v_lshlrev_b32_e32 v28, 2, v128
	v_mov_b32_e32 v29, v177
	v_lshl_add_u64 v[28:29], v[34:35], 0, v[28:29]
	v_mov_b32_e32 v27, v177
	global_store_dwordx4 v[28:29], v[20:23], off offset:128
	s_nop 1
	v_lshl_add_u64 v[20:21], v[32:33], 0, v[26:27]
	v_add_co_u32_e32 v22, vcc, 0x5100000, v20
	s_nop 1
	v_addc_co_u32_e32 v23, vcc, 0, v21, vcc
	global_store_dwordx2 v[22:23], v[24:25], off offset:256
	v_add_co_u32_e32 v22, vcc, 0x5118000, v20
	s_nop 1
	v_addc_co_u32_e32 v23, vcc, 0, v21, vcc
	v_add_co_u32_e32 v22, vcc, 0x5130000, v20
	s_nop 1
	v_addc_co_u32_e32 v23, vcc, 0, v21, vcc
	v_add_co_u32_e32 v22, vcc, 0x5148000, v20
	s_nop 1
	v_addc_co_u32_e32 v23, vcc, 0, v21, vcc
	v_add_co_u32_e32 v22, vcc, 0x5160000, v20
	s_nop 1
	v_addc_co_u32_e32 v23, vcc, 0, v21, vcc
	v_add_co_u32_e32 v22, vcc, 0x5178000, v20
	s_nop 1
	v_addc_co_u32_e32 v23, vcc, 0, v21, vcc
	v_add_co_u32_e32 v22, vcc, 0x5190000, v20
	s_nop 1
	v_addc_co_u32_e32 v23, vcc, 0, v21, vcc
	v_add_co_u32_e32 v20, vcc, 0x51a8000, v20
	s_nop 0
	s_nop 0
	v_addc_co_u32_e32 v21, vcc, 0, v21, vcc
.LBB0_721:
	s_andn2_saveexec_b64 s[58:59], s[58:59]
	s_cbranch_execz .LBB0_723
	v_mov_b32_e32 v27, v177
	v_lshl_add_u64 v[20:21], v[36:37], 0, v[26:27]
	v_add_co_u32_e32 v22, vcc, 0xb900000, v20
	s_nop 1
	v_addc_co_u32_e32 v23, vcc, 0, v21, vcc
	global_store_dwordx2 v[22:23], v[24:25], off offset:256
	v_add_co_u32_e32 v22, vcc, 0xb978000, v20
	s_nop 1
	v_addc_co_u32_e32 v23, vcc, 0, v21, vcc
	v_add_co_u32_e32 v22, vcc, 0xb9f0000, v20
	s_nop 1
	v_addc_co_u32_e32 v23, vcc, 0, v21, vcc
	v_add_co_u32_e32 v22, vcc, 0xba68000, v20
	s_nop 1
	v_addc_co_u32_e32 v23, vcc, 0, v21, vcc
	v_add_co_u32_e32 v22, vcc, 0xbae0000, v20
	s_nop 1
	v_addc_co_u32_e32 v23, vcc, 0, v21, vcc
	v_add_co_u32_e32 v22, vcc, 0xbb58000, v20
	s_nop 1
	v_addc_co_u32_e32 v23, vcc, 0, v21, vcc
	v_add_co_u32_e32 v22, vcc, 0xbbd0000, v20
	s_nop 1
	v_addc_co_u32_e32 v23, vcc, 0, v21, vcc
	v_add_co_u32_e32 v20, vcc, 0xbc48000, v20
	s_nop 0
	s_nop 0
	v_addc_co_u32_e32 v21, vcc, 0, v21, vcc
.LBB0_723:
	s_or_b64 exec, exec, s[58:59]
	v_or_b32_e32 v20, 48, v128
	v_lshlrev_b32_e32 v22, 1, v20
	v_cvt_pk_bf16_f32 v20, v16, v17
	v_cvt_pk_bf16_f32 v21, v18, v19
	s_and_saveexec_b64 s[58:59], s[44:45]
	s_xor_b64 s[58:59], exec, s[58:59]
	s_cbranch_execz .LBB0_725
	v_lshlrev_b32_e32 v24, 2, v128
	v_mov_b32_e32 v25, v177
	v_lshl_add_u64 v[24:25], v[34:35], 0, v[24:25]
	v_mov_b32_e32 v23, v177
	global_store_dwordx4 v[24:25], v[16:19], off offset:192
	s_nop 1
	v_lshl_add_u64 v[16:17], v[32:33], 0, v[22:23]
	v_add_co_u32_e32 v18, vcc, 0x5100000, v16
	s_nop 1
	v_addc_co_u32_e32 v19, vcc, 0, v17, vcc
	global_store_dwordx2 v[18:19], v[20:21], off offset:256
	v_add_co_u32_e32 v18, vcc, 0x5118000, v16
	s_nop 1
	v_addc_co_u32_e32 v19, vcc, 0, v17, vcc
	v_add_co_u32_e32 v18, vcc, 0x5130000, v16
	s_nop 1
	v_addc_co_u32_e32 v19, vcc, 0, v17, vcc
	v_add_co_u32_e32 v18, vcc, 0x5148000, v16
	s_nop 1
	v_addc_co_u32_e32 v19, vcc, 0, v17, vcc
	v_add_co_u32_e32 v18, vcc, 0x5160000, v16
	s_nop 1
	v_addc_co_u32_e32 v19, vcc, 0, v17, vcc
	v_add_co_u32_e32 v18, vcc, 0x5178000, v16
	s_nop 1
	v_addc_co_u32_e32 v19, vcc, 0, v17, vcc
	v_add_co_u32_e32 v18, vcc, 0x5190000, v16
	s_nop 1
	v_addc_co_u32_e32 v19, vcc, 0, v17, vcc
	v_add_co_u32_e32 v16, vcc, 0x51a8000, v16
	s_nop 0
	s_nop 0
	v_addc_co_u32_e32 v17, vcc, 0, v17, vcc
.LBB0_725:
	s_andn2_saveexec_b64 s[58:59], s[58:59]
	s_cbranch_execz .LBB0_727
	v_mov_b32_e32 v23, v177
	v_lshl_add_u64 v[16:17], v[36:37], 0, v[22:23]
	v_add_co_u32_e32 v18, vcc, 0xb900000, v16
	s_nop 1
	v_addc_co_u32_e32 v19, vcc, 0, v17, vcc
	global_store_dwordx2 v[18:19], v[20:21], off offset:256
	v_add_co_u32_e32 v18, vcc, 0xb978000, v16
	s_nop 1
	v_addc_co_u32_e32 v19, vcc, 0, v17, vcc
	v_add_co_u32_e32 v18, vcc, 0xb9f0000, v16
	s_nop 1
	v_addc_co_u32_e32 v19, vcc, 0, v17, vcc
	v_add_co_u32_e32 v18, vcc, 0xba68000, v16
	s_nop 1
	v_addc_co_u32_e32 v19, vcc, 0, v17, vcc
	v_add_co_u32_e32 v18, vcc, 0xbae0000, v16
	s_nop 1
	v_addc_co_u32_e32 v19, vcc, 0, v17, vcc
	v_add_co_u32_e32 v18, vcc, 0xbb58000, v16
	s_nop 1
	v_addc_co_u32_e32 v19, vcc, 0, v17, vcc
	v_add_co_u32_e32 v18, vcc, 0xbbd0000, v16
	s_nop 1
	v_addc_co_u32_e32 v19, vcc, 0, v17, vcc
	v_add_co_u32_e32 v16, vcc, 0xbc48000, v16
	s_nop 0
	s_nop 0
	v_addc_co_u32_e32 v17, vcc, 0, v17, vcc

.LBB0_735:
	s_or_b64 exec, exec, s[58:59]
	v_lshlrev_b64 v[32:33], 9, v[32:33]
	v_lshl_add_u64 v[32:33], s[14:15], 0, v[32:33]
	s_waitcnt lgkmcnt(0)
	v_mov_b32_e32 v35, v24
	s_nop 1
	v_permlane16_swap_b32_e32 v28, v35
	s_waitcnt lgkmcnt(0)
	v_mov_b32_e32 v24, v29
	v_mov_b32_e32 v29, v25
	s_nop 1
	v_permlane16_swap_b32_e32 v24, v29
	s_waitcnt lgkmcnt(0)
	v_mov_b32_e32 v25, v30
	v_mov_b32_e32 v30, v26
	s_nop 1
	v_permlane16_swap_b32_e32 v25, v30
	s_waitcnt lgkmcnt(0)
	v_lshl_add_u64 v[32:33], v[176:177], 1, v[32:33]
	v_mov_b32_e32 v26, v31
	s_nop 1
	v_permlane16_swap_b32_e32 v26, v27
	v_cvt_pk_bf16_f32 v24, v28, v24
	v_cvt_pk_bf16_f32 v25, v25, v26
	v_cvt_pk_bf16_f32 v26, v35, v29
	v_lshlrev_b32_e32 v28, 1, v180
	v_mov_b32_e32 v29, v177
	v_cvt_pk_bf16_f32 v27, v30, v27
	v_lshlrev_b32_e32 v30, 1, v179
	v_mov_b32_e32 v31, v177
	v_lshl_add_u64 v[28:29], v[32:33], 0, v[28:29]
	v_lshl_add_u64 v[28:29], v[28:29], 0, v[30:31]
	s_mov_b32 s58, 0xacff000
	v_add_co_u32_e32 v28, vcc, s58, v28
	s_nop 1
	v_addc_co_u32_e32 v29, vcc, 0, v29, vcc
	global_store_dwordx4 v[28:29], v[24:27], off offset:3328
	s_nop 1
	s_waitcnt lgkmcnt(0)
	v_mov_b32_e32 v24, v16
	s_nop 1
	v_permlane16_swap_b32_e32 v20, v24
	s_waitcnt lgkmcnt(0)
	v_mov_b32_e32 v16, v21
	v_mov_b32_e32 v21, v17
	s_nop 1
	v_permlane16_swap_b32_e32 v16, v21
	s_waitcnt lgkmcnt(0)
	v_mov_b32_e32 v17, v22
	v_mov_b32_e32 v22, v18
	s_nop 1
	v_permlane16_swap_b32_e32 v17, v22
	s_waitcnt lgkmcnt(0)
	v_mov_b32_e32 v18, v23
	s_nop 1
	v_permlane16_swap_b32_e32 v18, v19
	v_cvt_pk_bf16_f32 v16, v20, v16
	v_cvt_pk_bf16_f32 v17, v17, v18
	v_cvt_pk_bf16_f32 v18, v24, v21
	v_cvt_pk_bf16_f32 v19, v22, v19
	global_store_dwordx4 v[28:29], v[16:19], off offset:3392

.LBB0_739:
	s_or_b64 exec, exec, s[58:59]
	v_mov_b64_e32 v[36:37], s[4:5]
	s_movk_i32 vcc_lo, 0x300
	v_mad_i64_i32 v[36:37], s[58:59], v32, vcc_lo, v[36:37]
	v_lshlrev_b64 v[38:39], 1, v[134:135]
	s_waitcnt lgkmcnt(0)
	v_mov_b32_e32 v33, v24
	s_nop 1
	v_permlane16_swap_b32_e32 v28, v33
	s_waitcnt lgkmcnt(0)
	v_mov_b32_e32 v24, v29
	v_mov_b32_e32 v29, v25
	s_nop 1
	v_permlane16_swap_b32_e32 v24, v29
	s_waitcnt lgkmcnt(0)
	v_mov_b32_e32 v25, v30
	v_mov_b32_e32 v30, v26
	s_nop 1
	v_permlane16_swap_b32_e32 v25, v30
	s_waitcnt lgkmcnt(0)
	v_lshl_add_u64 v[36:37], v[36:37], 0, v[38:39]
	v_mov_b32_e32 v26, v31
	s_nop 1
	v_permlane16_swap_b32_e32 v26, v27
	v_cvt_pk_bf16_f32 v24, v28, v24
	v_cvt_pk_bf16_f32 v25, v25, v26
	v_cvt_pk_bf16_f32 v26, v33, v29
	v_lshlrev_b32_e32 v28, 1, v180
	v_mov_b32_e32 v29, v177
	v_cvt_pk_bf16_f32 v27, v30, v27
	v_lshl_add_u64 v[30:31], v[36:37], 0, v[28:29]
	v_lshlrev_b32_e32 v36, 1, v179
	v_mov_b32_e32 v37, v177
	v_lshl_add_u64 v[30:31], v[30:31], 0, v[36:37]
	global_store_dwordx4 v[30:31], v[24:27], off
	v_cndmask_b32_e64 v31, v23, v19, s[40:41]
	ds_bpermute_b32 v31, v34, v31
	v_mov_b64_e32 v[24:25], s[34:35]
	v_mad_i64_i32 v[24:25], s[58:59], v32, vcc_lo, v[24:25]
	v_lshl_add_u64 v[24:25], v[24:25], 0, v[38:39]
	s_waitcnt lgkmcnt(1)
	v_mov_b32_e32 v26, v16
	s_nop 1
	v_permlane16_swap_b32_e32 v20, v26
	s_waitcnt lgkmcnt(1)
	v_mov_b32_e32 v16, v21
	v_mov_b32_e32 v21, v17
	s_nop 1
	v_permlane16_swap_b32_e32 v16, v21
	s_waitcnt lgkmcnt(1)
	v_mov_b32_e32 v17, v22
	v_mov_b32_e32 v22, v18
	s_nop 1
	v_permlane16_swap_b32_e32 v17, v22
	s_waitcnt lgkmcnt(0)
	v_cndmask_b32_e64 v18, v31, v23, s[40:41]
	v_cvt_pk_bf16_f32 v16, v20, v16
	v_cvt_pk_bf16_f32 v17, v17, v18
	v_cvt_pk_bf16_f32 v18, v26, v21
	v_lshl_add_u64 v[20:21], v[24:25], 0, v[28:29]
	v_lshl_add_u64 v[20:21], v[20:21], 0, v[36:37]
	v_cndmask_b32_e64 v19, v19, v31, s[40:41]
	v_add_co_u32_e32 v20, vcc, 0xa700000, v20
	v_cvt_pk_bf16_f32 v19, v22, v19
	s_nop 0
	v_addc_co_u32_e32 v21, vcc, 0, v21, vcc
	global_store_dwordx4 v[20:21], v[16:19], off offset:64

.LBB0_741:
	s_or_b64 exec, exec, s[30:31]
	v_or_b32_e32 v22, 0x70, v182
	v_or_b32_e32 v16, v183, v22
	s_and_saveexec_b64 s[30:31], s[52:53]
	s_xor_b64 s[52:53], exec, s[30:31]
	s_cbranch_execz .LBB0_765
	s_and_saveexec_b64 s[30:31], s[50:51]
	s_xor_b64 s[30:31], exec, s[30:31]
	s_cbranch_execz .LBB0_744
	v_mul_f32_e32 v18, 0xbfb8aa3b, v12
	v_mul_f32_e32 v20, 0xbfb8aa3b, v8
	v_mul_f32_e32 v21, 0xbfb8aa3b, v13
	v_exp_f32_e32 v18, v18
	v_exp_f32_e32 v20, v20
	v_exp_f32_e32 v21, v21
	v_mul_f32_e32 v22, 0xbfb8aa3b, v9
	v_add_f32_e32 v18, 1.0, v18
	v_add_f32_e32 v20, 1.0, v20
	v_add_f32_e32 v21, 1.0, v21
	v_rcp_f32_e32 v18, v18
	v_rcp_f32_e32 v20, v20
	v_rcp_f32_e32 v21, v21
	v_exp_f32_e32 v22, v22
	v_mul_f32_e32 v18, v12, v18
	v_mul_f32_e32 v20, v8, v20
	v_mul_f32_e32 v21, v13, v21
	v_add_f32_e32 v8, 1.0, v22
	v_mul_f32_e32 v12, 0xbfb8aa3b, v14
	v_mul_f32_e32 v13, 0xbfb8aa3b, v10
	v_rcp_f32_e32 v8, v8
	v_exp_f32_e32 v12, v12
	v_exp_f32_e32 v13, v13
	v_ashrrev_i32_e32 v17, 31, v16
	v_mul_f32_e32 v22, v9, v8
	v_add_f32_e32 v8, 1.0, v12
	v_add_f32_e32 v9, 1.0, v13
	v_mul_f32_e32 v12, 0xbfb8aa3b, v15
	v_mul_f32_e32 v13, 0xbfb8aa3b, v11
	v_exp_f32_e32 v12, v12
	v_exp_f32_e32 v13, v13
	v_rcp_f32_e32 v8, v8
	v_rcp_f32_e32 v9, v9
	v_add_f32_e32 v12, 1.0, v12
	v_add_f32_e32 v13, 1.0, v13
	v_rcp_f32_e32 v12, v12
	v_rcp_f32_e32 v13, v13
	v_lshlrev_b64 v[16:17], 11, v[16:17]
	v_cmp_lt_i32_e32 vcc, v189, v202
	v_mul_f32_e32 v14, v14, v8
	v_mul_f32_e32 v10, v10, v9
	v_cndmask_b32_e32 v19, v203, v189, vcc
	v_mul_f32_e32 v15, v15, v12
	v_mul_f32_e32 v11, v11, v13
	v_lshl_add_u64 v[8:9], s[34:35], 0, v[16:17]
	v_lshlrev_b32_e32 v19, 2, v19
	v_lshl_add_u64 v[12:13], v[176:177], 1, v[8:9]
	v_lshlrev_b32_e32 v176, 1, v180
	s_waitcnt lgkmcnt(0)
	s_nop 1
	v_permlane16_swap_b32_e32 v18, v20
	s_waitcnt lgkmcnt(0)
	v_mov_b32_e32 v8, v21
	v_mov_b32_e32 v21, v22
	s_nop 1
	v_permlane16_swap_b32_e32 v8, v21
	s_waitcnt lgkmcnt(0)
	v_mov_b32_e32 v9, v14
	v_mov_b32_e32 v14, v10
	s_nop 1
	v_permlane16_swap_b32_e32 v9, v14
	s_waitcnt lgkmcnt(0)
	v_mov_b32_e32 v10, v15
	s_nop 1
	v_permlane16_swap_b32_e32 v10, v11
	v_cvt_pk_bf16_f32 v11, v14, v11
	v_lshlrev_b32_e32 v14, 1, v179
	v_mov_b32_e32 v15, v177
	v_lshl_add_u64 v[12:13], v[12:13], 0, v[176:177]
	v_lshl_add_u64 v[12:13], v[12:13], 0, v[14:15]
	s_mov_b32 s50, 0x96ff000
	v_add_co_u32_e32 v12, vcc, s50, v12
	v_cvt_pk_bf16_f32 v8, v18, v8
	v_cvt_pk_bf16_f32 v9, v9, v10
	v_cvt_pk_bf16_f32 v10, v20, v21
	v_addc_co_u32_e32 v13, vcc, 0, v13, vcc
	v_mul_f32_e32 v14, 0xbfb8aa3b, v4
	global_store_dwordx4 v[12:13], v[8:11], off offset:2688
	v_exp_f32_e32 v14, v14
	s_nop 0
	v_mul_f32_e32 v9, 0xbfb8aa3b, v0
	v_mul_f32_e32 v10, 0xbfb8aa3b, v5
	v_exp_f32_e32 v9, v9
	v_exp_f32_e32 v10, v10
	v_add_f32_e32 v8, 1.0, v14
	v_mul_f32_e32 v11, 0xbfb8aa3b, v1
	v_add_f32_e32 v9, 1.0, v9
	v_add_f32_e32 v10, 1.0, v10
	v_rcp_f32_e32 v8, v8
	v_rcp_f32_e32 v9, v9
	v_rcp_f32_e32 v10, v10
	v_exp_f32_e32 v11, v11
	v_mul_f32_e32 v4, v4, v8
	v_mul_f32_e32 v0, v0, v9
	v_mul_f32_e32 v5, v5, v10
	v_add_f32_e32 v8, 1.0, v11
	v_mul_f32_e32 v9, 0xbfb8aa3b, v6
	v_mul_f32_e32 v10, 0xbfb8aa3b, v2
	v_rcp_f32_e32 v8, v8
	v_exp_f32_e32 v9, v9
	v_exp_f32_e32 v10, v10
	v_mul_f32_e32 v11, 0xbfb8aa3b, v3
	v_mul_f32_e32 v1, v1, v8
	v_add_f32_e32 v8, 1.0, v9
	v_add_f32_e32 v9, 1.0, v10
	v_mul_f32_e32 v10, 0xbfb8aa3b, v7
	v_exp_f32_e32 v10, v10
	v_exp_f32_e32 v11, v11
	v_rcp_f32_e32 v8, v8
	v_rcp_f32_e32 v9, v9
	v_add_f32_e32 v10, 1.0, v10
	v_add_f32_e32 v11, 1.0, v11
	v_rcp_f32_e32 v10, v10
	v_rcp_f32_e32 v11, v11
	v_mul_f32_e32 v6, v6, v8
	v_mul_f32_e32 v2, v2, v9
	v_mul_f32_e32 v7, v7, v10
	v_mul_f32_e32 v3, v3, v11
	s_waitcnt lgkmcnt(0)
	v_mov_b32_e32 v8, v0
	s_nop 1
	v_permlane16_swap_b32_e32 v4, v8
	s_waitcnt lgkmcnt(0)
	v_mov_b32_e32 v0, v5
	v_mov_b32_e32 v5, v1
	s_nop 1
	v_permlane16_swap_b32_e32 v0, v5
	s_waitcnt lgkmcnt(0)
	v_mov_b32_e32 v1, v6
	v_mov_b32_e32 v6, v2
	s_nop 1
	v_permlane16_swap_b32_e32 v1, v6
	s_waitcnt lgkmcnt(0)
	v_mov_b32_e32 v2, v7
	s_nop 1
	v_permlane16_swap_b32_e32 v2, v3
	v_cvt_pk_bf16_f32 v0, v4, v0
	v_cvt_pk_bf16_f32 v1, v1, v2
	v_cvt_pk_bf16_f32 v2, v8, v5
	v_cvt_pk_bf16_f32 v3, v6, v3
	global_store_dwordx4 v[12:13], v[0:3], off offset:2752

.LBB0_751:
	s_or_b64 exec, exec, s[30:31]
	v_lshlrev_b32_e32 v176, 1, v128
	v_lshl_add_u64 v[30:31], v[30:31], 0, v[176:177]
	v_cvt_pk_bf16_f32 v12, v12, v13
	v_cvt_pk_bf16_f32 v13, v14, v15
	v_lshl_add_u64 v[14:15], v[30:31], 0, v[52:53]
	v_lshl_add_u64 v[14:15], v[30:31], 0, v[50:51]
	v_lshl_add_u64 v[14:15], v[30:31], 0, v[48:49]
	v_lshl_add_u64 v[14:15], v[30:31], 0, v[46:47]
	v_lshl_add_u64 v[14:15], v[30:31], 0, v[44:45]
	v_lshl_add_u64 v[14:15], v[30:31], 0, v[42:43]
	v_lshl_add_u64 v[14:15], v[30:31], 0, v[40:41]
	v_lshl_add_u64 v[14:15], v[30:31], 0, v[38:39]
	v_lshl_add_u64 v[14:15], v[30:31], 0, v[36:37]
	v_lshl_add_u64 v[14:15], v[30:31], 0, v[34:35]
	v_lshl_add_u64 v[14:15], v[30:31], 0, v[32:33]
	v_lshl_add_u64 v[14:15], v[30:31], 0, v[28:29]
	v_lshl_add_u64 v[14:15], v[30:31], 0, v[26:27]
	global_store_dwordx2 v[30:31], v[12:13], off
	v_lshl_add_u64 v[14:15], v[30:31], 0, v[24:25]
	v_or_b32_e32 v12, 16, v128
	v_lshlrev_b32_e32 v176, 1, v12
	v_cvt_pk_bf16_f32 v12, v8, v9
	v_cvt_pk_bf16_f32 v13, v10, v11
	s_and_saveexec_b64 s[30:31], s[44:45]
	s_xor_b64 s[30:31], exec, s[30:31]
	s_cbranch_execz .LBB0_753
	v_mov_b32_e32 v21, v177
	v_lshl_add_u64 v[14:15], v[18:19], 0, v[20:21]
	global_store_dwordx4 v[14:15], v[8:11], off offset:64
	s_nop 1
	v_lshl_add_u64 v[8:9], v[16:17], 0, v[176:177]
	v_add_co_u32_e32 v10, vcc, 0x5100000, v8
	s_nop 1
	v_addc_co_u32_e32 v11, vcc, 0, v9, vcc
	global_store_dwordx2 v[10:11], v[12:13], off offset:256
	v_add_co_u32_e32 v10, vcc, 0x5118000, v8
	s_nop 1
	v_addc_co_u32_e32 v11, vcc, 0, v9, vcc
	v_add_co_u32_e32 v10, vcc, 0x5130000, v8
	s_nop 1
	v_addc_co_u32_e32 v11, vcc, 0, v9, vcc
	v_add_co_u32_e32 v10, vcc, 0x5148000, v8
	s_nop 1
	v_addc_co_u32_e32 v11, vcc, 0, v9, vcc
	v_add_co_u32_e32 v10, vcc, 0x5160000, v8
	s_nop 1
	v_addc_co_u32_e32 v11, vcc, 0, v9, vcc
	v_add_co_u32_e32 v10, vcc, 0x5178000, v8
	s_nop 1
	v_addc_co_u32_e32 v11, vcc, 0, v9, vcc
	v_add_co_u32_e32 v10, vcc, 0x5190000, v8
	s_nop 1
	v_addc_co_u32_e32 v11, vcc, 0, v9, vcc
	v_add_co_u32_e32 v8, vcc, 0x51a8000, v8
	s_nop 0
	s_nop 0
	v_addc_co_u32_e32 v9, vcc, 0, v9, vcc
.LBB0_753:
	s_andn2_saveexec_b64 s[30:31], s[30:31]
	s_cbranch_execz .LBB0_755
	v_lshl_add_u64 v[8:9], v[22:23], 0, v[176:177]
	v_add_co_u32_e32 v10, vcc, 0xb900000, v8
	s_nop 1
	v_addc_co_u32_e32 v11, vcc, 0, v9, vcc
	global_store_dwordx2 v[10:11], v[12:13], off offset:256
	v_add_co_u32_e32 v10, vcc, 0xb978000, v8
	s_nop 1
	v_addc_co_u32_e32 v11, vcc, 0, v9, vcc
	v_add_co_u32_e32 v10, vcc, 0xb9f0000, v8
	s_nop 1
	v_addc_co_u32_e32 v11, vcc, 0, v9, vcc
	v_add_co_u32_e32 v10, vcc, 0xba68000, v8
	s_nop 1
	v_addc_co_u32_e32 v11, vcc, 0, v9, vcc
	v_add_co_u32_e32 v10, vcc, 0xbae0000, v8
	s_nop 1
	v_addc_co_u32_e32 v11, vcc, 0, v9, vcc
	v_add_co_u32_e32 v10, vcc, 0xbb58000, v8
	s_nop 1
	v_addc_co_u32_e32 v11, vcc, 0, v9, vcc
	v_add_co_u32_e32 v10, vcc, 0xbbd0000, v8
	s_nop 1
	v_addc_co_u32_e32 v11, vcc, 0, v9, vcc
	v_add_co_u32_e32 v8, vcc, 0xbc48000, v8
	s_nop 0
	s_nop 0
	v_addc_co_u32_e32 v9, vcc, 0, v9, vcc
.LBB0_755:
	s_or_b64 exec, exec, s[30:31]
	v_or_b32_e32 v8, 32, v128
	v_lshlrev_b32_e32 v176, 1, v8
	v_cvt_pk_bf16_f32 v8, v4, v5
	v_cvt_pk_bf16_f32 v9, v6, v7
	s_and_saveexec_b64 s[30:31], s[44:45]
	s_xor_b64 s[30:31], exec, s[30:31]
	s_cbranch_execz .LBB0_757
	v_mov_b32_e32 v21, v177
	v_lshl_add_u64 v[10:11], v[18:19], 0, v[20:21]
	global_store_dwordx4 v[10:11], v[4:7], off offset:128
	s_nop 1
	v_lshl_add_u64 v[4:5], v[16:17], 0, v[176:177]
	v_add_co_u32_e32 v6, vcc, 0x5100000, v4
	s_nop 1
	v_addc_co_u32_e32 v7, vcc, 0, v5, vcc
	global_store_dwordx2 v[6:7], v[8:9], off offset:256
	v_add_co_u32_e32 v6, vcc, 0x5118000, v4
	s_nop 1
	v_addc_co_u32_e32 v7, vcc, 0, v5, vcc
	v_add_co_u32_e32 v6, vcc, 0x5130000, v4
	s_nop 1
	v_addc_co_u32_e32 v7, vcc, 0, v5, vcc
	v_add_co_u32_e32 v6, vcc, 0x5148000, v4
	s_nop 1
	v_addc_co_u32_e32 v7, vcc, 0, v5, vcc
	v_add_co_u32_e32 v6, vcc, 0x5160000, v4
	s_nop 1
	v_addc_co_u32_e32 v7, vcc, 0, v5, vcc
	v_add_co_u32_e32 v6, vcc, 0x5178000, v4
	s_nop 1
	v_addc_co_u32_e32 v7, vcc, 0, v5, vcc
	v_add_co_u32_e32 v6, vcc, 0x5190000, v4
	s_nop 1
	v_addc_co_u32_e32 v7, vcc, 0, v5, vcc
	v_add_co_u32_e32 v4, vcc, 0x51a8000, v4
	s_nop 0
	s_nop 0
	v_addc_co_u32_e32 v5, vcc, 0, v5, vcc
.LBB0_757:
	s_andn2_saveexec_b64 s[30:31], s[30:31]
	s_cbranch_execz .LBB0_759
	v_lshl_add_u64 v[4:5], v[22:23], 0, v[176:177]
	v_add_co_u32_e32 v6, vcc, 0xb900000, v4
	s_nop 1
	v_addc_co_u32_e32 v7, vcc, 0, v5, vcc
	global_store_dwordx2 v[6:7], v[8:9], off offset:256
	v_add_co_u32_e32 v6, vcc, 0xb978000, v4
	s_nop 1
	v_addc_co_u32_e32 v7, vcc, 0, v5, vcc
	v_add_co_u32_e32 v6, vcc, 0xb9f0000, v4
	s_nop 1
	v_addc_co_u32_e32 v7, vcc, 0, v5, vcc
	v_add_co_u32_e32 v6, vcc, 0xba68000, v4
	s_nop 1
	v_addc_co_u32_e32 v7, vcc, 0, v5, vcc
	v_add_co_u32_e32 v6, vcc, 0xbae0000, v4
	s_nop 1
	v_addc_co_u32_e32 v7, vcc, 0, v5, vcc
	v_add_co_u32_e32 v6, vcc, 0xbb58000, v4
	s_nop 1
	v_addc_co_u32_e32 v7, vcc, 0, v5, vcc
	v_add_co_u32_e32 v6, vcc, 0xbbd0000, v4
	s_nop 1
	v_addc_co_u32_e32 v7, vcc, 0, v5, vcc
	v_add_co_u32_e32 v4, vcc, 0xbc48000, v4
	s_nop 0
	s_nop 0
	v_addc_co_u32_e32 v5, vcc, 0, v5, vcc
.LBB0_759:
	s_or_b64 exec, exec, s[30:31]
	v_or_b32_e32 v4, 48, v128
	v_lshlrev_b32_e32 v176, 1, v4
	v_cvt_pk_bf16_f32 v4, v0, v1
	v_cvt_pk_bf16_f32 v5, v2, v3
	s_and_saveexec_b64 s[30:31], s[44:45]
	s_xor_b64 s[30:31], exec, s[30:31]
	s_cbranch_execz .LBB0_761
	v_mov_b32_e32 v21, v177
	v_lshl_add_u64 v[6:7], v[18:19], 0, v[20:21]
	global_store_dwordx4 v[6:7], v[0:3], off offset:192
	s_nop 1
	v_lshl_add_u64 v[0:1], v[16:17], 0, v[176:177]
	v_add_co_u32_e32 v2, vcc, 0x5100000, v0
	s_nop 1
	v_addc_co_u32_e32 v3, vcc, 0, v1, vcc
	global_store_dwordx2 v[2:3], v[4:5], off offset:256
	v_add_co_u32_e32 v2, vcc, 0x5118000, v0
	s_nop 1
	v_addc_co_u32_e32 v3, vcc, 0, v1, vcc
	v_add_co_u32_e32 v2, vcc, 0x5130000, v0
	s_nop 1
	v_addc_co_u32_e32 v3, vcc, 0, v1, vcc
	v_add_co_u32_e32 v2, vcc, 0x5148000, v0
	s_nop 1
	v_addc_co_u32_e32 v3, vcc, 0, v1, vcc
	v_add_co_u32_e32 v2, vcc, 0x5160000, v0
	s_nop 1
	v_addc_co_u32_e32 v3, vcc, 0, v1, vcc
	v_add_co_u32_e32 v2, vcc, 0x5178000, v0
	s_nop 1
	v_addc_co_u32_e32 v3, vcc, 0, v1, vcc
	v_add_co_u32_e32 v2, vcc, 0x5190000, v0
	s_nop 1
	v_addc_co_u32_e32 v3, vcc, 0, v1, vcc
	v_add_co_u32_e32 v0, vcc, 0x51a8000, v0
	s_nop 0
	s_nop 0
	v_addc_co_u32_e32 v1, vcc, 0, v1, vcc
.LBB0_761:
	s_andn2_saveexec_b64 s[30:31], s[30:31]
	s_cbranch_execz .LBB0_763
	v_lshl_add_u64 v[0:1], v[22:23], 0, v[176:177]
	v_add_co_u32_e32 v2, vcc, 0xb900000, v0
	s_nop 1
	v_addc_co_u32_e32 v3, vcc, 0, v1, vcc
	global_store_dwordx2 v[2:3], v[4:5], off offset:256
	v_add_co_u32_e32 v2, vcc, 0xb978000, v0
	s_nop 1
	v_addc_co_u32_e32 v3, vcc, 0, v1, vcc
	v_add_co_u32_e32 v2, vcc, 0xb9f0000, v0
	s_nop 1
	v_addc_co_u32_e32 v3, vcc, 0, v1, vcc
	v_add_co_u32_e32 v2, vcc, 0xba68000, v0
	s_nop 1
	v_addc_co_u32_e32 v3, vcc, 0, v1, vcc
	v_add_co_u32_e32 v2, vcc, 0xbae0000, v0
	s_nop 1
	v_addc_co_u32_e32 v3, vcc, 0, v1, vcc
	v_add_co_u32_e32 v2, vcc, 0xbb58000, v0
	s_nop 1
	v_addc_co_u32_e32 v3, vcc, 0, v1, vcc
	v_add_co_u32_e32 v2, vcc, 0xbbd0000, v0
	s_nop 1
	v_addc_co_u32_e32 v3, vcc, 0, v1, vcc
	v_add_co_u32_e32 v0, vcc, 0xbc48000, v0
	s_nop 0
	s_nop 0
	v_addc_co_u32_e32 v1, vcc, 0, v1, vcc

.LBB0_771:
	s_or_b64 exec, exec, s[44:45]
	v_lshlrev_b64 v[16:17], 9, v[16:17]
	v_lshl_add_u64 v[16:17], s[14:15], 0, v[16:17]
	v_lshl_add_u64 v[16:17], v[176:177], 1, v[16:17]
	s_waitcnt lgkmcnt(0)
	v_mov_b32_e32 v19, v8
	s_nop 1
	v_permlane16_swap_b32_e32 v12, v19
	s_waitcnt lgkmcnt(0)
	v_mov_b32_e32 v8, v13
	v_mov_b32_e32 v13, v9
	s_nop 1
	v_permlane16_swap_b32_e32 v8, v13
	s_waitcnt lgkmcnt(0)
	v_mov_b32_e32 v9, v14
	v_mov_b32_e32 v14, v10
	s_nop 1
	v_permlane16_swap_b32_e32 v9, v14
	s_waitcnt lgkmcnt(0)
	v_mov_b32_e32 v10, v15
	s_nop 1
	v_permlane16_swap_b32_e32 v10, v11
	v_lshlrev_b32_e32 v176, 1, v180
	v_cvt_pk_bf16_f32 v8, v12, v8
	v_cvt_pk_bf16_f32 v9, v9, v10
	v_cvt_pk_bf16_f32 v10, v19, v13
	v_cvt_pk_bf16_f32 v11, v14, v11
	v_lshlrev_b32_e32 v12, 1, v179
	v_mov_b32_e32 v13, v177
	v_lshl_add_u64 v[14:15], v[16:17], 0, v[176:177]
	v_lshl_add_u64 v[12:13], v[14:15], 0, v[12:13]
	s_mov_b32 s44, 0xacff000
	v_add_co_u32_e32 v12, vcc, s44, v12
	s_nop 1
	v_addc_co_u32_e32 v13, vcc, 0, v13, vcc
	global_store_dwordx4 v[12:13], v[8:11], off offset:3328
	s_nop 1
	s_waitcnt lgkmcnt(0)
	v_mov_b32_e32 v8, v0
	s_nop 1
	v_permlane16_swap_b32_e32 v4, v8
	s_waitcnt lgkmcnt(0)
	v_mov_b32_e32 v0, v5
	v_mov_b32_e32 v5, v1
	s_nop 1
	v_permlane16_swap_b32_e32 v0, v5
	s_waitcnt lgkmcnt(0)
	v_mov_b32_e32 v1, v6
	v_mov_b32_e32 v6, v2
	s_nop 1
	v_permlane16_swap_b32_e32 v1, v6
	s_waitcnt lgkmcnt(0)
	v_mov_b32_e32 v2, v7
	s_nop 1
	v_permlane16_swap_b32_e32 v2, v3
	v_cvt_pk_bf16_f32 v0, v4, v0
	v_cvt_pk_bf16_f32 v1, v1, v2
	v_cvt_pk_bf16_f32 v2, v8, v5
	v_cvt_pk_bf16_f32 v3, v6, v3
	global_store_dwordx4 v[12:13], v[0:3], off offset:3392

.LBB0_802:
	s_waitcnt lgkmcnt(0)
	s_barrier
	ds_read_b128 v[224:227], v184
	ds_read_b128 v[228:231], v184 offset:1024
	ds_read_b128 v[232:235], v184 offset:2048
	ds_read_b128 v[236:239], v184 offset:3072
	ds_read_b128 v[190:193], v185
	ds_read_b128 v[194:197], v185 offset:1024
	ds_read_b128 v[198:201], v185 offset:2048
	ds_read_b128 v[204:207], v185 offset:3072
	ds_read_b128 v[208:211], v185 offset:4096
	ds_read_b128 v[212:215], v185 offset:5120
	ds_read_b128 v[216:219], v185 offset:6144
	ds_read_b128 v[220:223], v185 offset:7168
	s_movk_i32 vcc_lo, 0x6000
	s_cmp_eq_u32 m0, 2
	s_cselect_b32 vcc_lo, 0xffff4000, vcc_lo
	s_add_u32 m0, m0, 1
	s_cmp_eq_u32 m0, 3
	s_cselect_b32 m0, 0, m0
	v_add_u32_e32 v185, vcc_lo, v185
	v_add_u32_e32 v184, vcc_lo, v184
	v_xor_b32_e32 v185, 64, v185
	v_xor_b32_e32 v184, 64, v184
	s_waitcnt lgkmcnt(7)
	v_mfma_f32_16x16x32_bf16 v[172:175], v[224:227], v[190:193], v[172:175]
	v_mfma_f32_16x16x32_bf16 v[168:171], v[228:231], v[190:193], v[168:171]
	v_mfma_f32_16x16x32_bf16 v[164:167], v[232:235], v[190:193], v[164:167]
	v_mfma_f32_16x16x32_bf16 v[160:163], v[236:239], v[190:193], v[160:163]
	ds_read_b128 v[190:193], v185
	s_waitcnt lgkmcnt(7)
	v_mfma_f32_16x16x32_bf16 v[156:159], v[224:227], v[194:197], v[156:159]
	v_mfma_f32_16x16x32_bf16 v[152:155], v[228:231], v[194:197], v[152:155]
	v_mfma_f32_16x16x32_bf16 v[148:151], v[232:235], v[194:197], v[148:151]
	v_mfma_f32_16x16x32_bf16 v[144:147], v[236:239], v[194:197], v[144:147]
	ds_read_b128 v[194:197], v185 offset:1024
	s_waitcnt lgkmcnt(7)
	v_mfma_f32_16x16x32_bf16 v[136:139], v[224:227], v[198:201], v[136:139]
	v_mfma_f32_16x16x32_bf16 v[132:135], v[228:231], v[198:201], v[132:135]
	v_mfma_f32_16x16x32_bf16 v[128:131], v[232:235], v[198:201], v[128:131]
	v_mfma_f32_16x16x32_bf16 v[124:127], v[236:239], v[198:201], v[124:127]
	ds_read_b128 v[198:201], v185 offset:2048
	s_waitcnt lgkmcnt(7)
	v_mfma_f32_16x16x32_bf16 v[120:123], v[224:227], v[204:207], v[120:123]
	v_mfma_f32_16x16x32_bf16 v[108:111], v[228:231], v[204:207], v[108:111]
	v_mfma_f32_16x16x32_bf16 v[100:103], v[232:235], v[204:207], v[100:103]
	v_mfma_f32_16x16x32_bf16 v[96:99], v[236:239], v[204:207], v[96:99]
	ds_read_b128 v[204:207], v185 offset:3072
	s_waitcnt lgkmcnt(7)
	v_mfma_f32_16x16x32_bf16 v[92:95], v[224:227], v[208:211], v[92:95]
	v_mfma_f32_16x16x32_bf16 v[84:87], v[228:231], v[208:211], v[84:87]
	v_mfma_f32_16x16x32_bf16 v[76:79], v[232:235], v[208:211], v[76:79]
	v_mfma_f32_16x16x32_bf16 v[72:75], v[236:239], v[208:211], v[72:75]
	ds_read_b128 v[208:211], v185 offset:4096
	s_waitcnt lgkmcnt(7)
	v_mfma_f32_16x16x32_bf16 v[64:67], v[224:227], v[212:215], v[64:67]
	v_mfma_f32_16x16x32_bf16 v[52:55], v[228:231], v[212:215], v[52:55]
	v_mfma_f32_16x16x32_bf16 v[48:51], v[232:235], v[212:215], v[48:51]
	v_mfma_f32_16x16x32_bf16 v[44:47], v[236:239], v[212:215], v[44:47]
	ds_read_b128 v[212:215], v185 offset:5120
	s_waitcnt lgkmcnt(7)
	v_mfma_f32_16x16x32_bf16 v[36:39], v[224:227], v[216:219], v[36:39]
	v_mfma_f32_16x16x32_bf16 v[28:31], v[228:231], v[216:219], v[28:31]
	v_mfma_f32_16x16x32_bf16 v[24:27], v[232:235], v[216:219], v[24:27]
	v_mfma_f32_16x16x32_bf16 v[20:23], v[236:239], v[216:219], v[20:23]
	ds_read_b128 v[216:219], v185 offset:6144
	s_waitcnt lgkmcnt(7)
	v_mfma_f32_16x16x32_bf16 v[12:15], v[224:227], v[220:223], v[12:15]
	v_mfma_f32_16x16x32_bf16 v[4:7], v[228:231], v[220:223], v[4:7]
	v_mfma_f32_16x16x32_bf16 v[0:3], v[232:235], v[220:223], v[0:3]
	v_mfma_f32_16x16x32_bf16 v[140:143], v[236:239], v[220:223], v[140:143]
	ds_read_b128 v[220:223], v185 offset:7168
	ds_read_b128 v[224:227], v184
	ds_read_b128 v[228:231], v184 offset:1024
	ds_read_b128 v[232:235], v184 offset:2048
	ds_read_b128 v[236:239], v184 offset:3072
	s_movk_i32 vcc_lo, 0x6000
	s_cmp_eq_u32 m0, 2
	s_cselect_b32 vcc_lo, 0xffff4000, vcc_lo
	s_add_u32 m0, m0, 1
	s_cmp_eq_u32 m0, 3
	s_cselect_b32 m0, 0, m0
	v_add_u32_e32 v185, vcc_lo, v185
	v_add_u32_e32 v184, vcc_lo, v184
	v_xor_b32_e32 v185, 64, v185
	v_xor_b32_e32 v184, 64, v184
	s_sub_u32 vcc_lo, s6, s98
	v_add_u32_e32 v186, vcc_lo, v178
	v_add_u32_e32 v187, vcc_lo, v180
	s_barrier
	s_waitcnt lgkmcnt(0)
	v_mfma_f32_16x16x32_bf16 v[172:175], v[224:227], v[190:193], v[172:175]
	s_waitcnt vmcnt(11)
	v_mfma_f32_16x16x32_bf16 v[168:171], v[228:231], v[190:193], v[168:171]
	ds_write_b128 v183, v[116:119]
	v_add_u32_e32 v116, s26, v187
	v_mfma_f32_16x16x32_bf16 v[164:167], v[232:235], v[190:193], v[164:167]
	global_load_dwordx4 v[116:119], v116, s[98:99] offset:128
	v_mfma_f32_16x16x32_bf16 v[160:163], v[236:239], v[190:193], v[160:163]
	s_waitcnt vmcnt(11)
	ds_write_b128 v183, v[112:115] offset:2048
	v_mfma_f32_16x16x32_bf16 v[156:159], v[224:227], v[194:197], v[156:159]
	v_add_u32_e32 v112, s27, v187
	v_mfma_f32_16x16x32_bf16 v[152:155], v[228:231], v[194:197], v[152:155]
	global_load_dwordx4 v[112:115], v112, s[98:99] offset:128
	s_waitcnt vmcnt(11)
	v_mfma_f32_16x16x32_bf16 v[148:151], v[232:235], v[194:197], v[148:151]
	ds_write_b128 v183, v[104:107] offset:4096
	v_mfma_f32_16x16x32_bf16 v[144:147], v[236:239], v[194:197], v[144:147]
	v_add_u32_e32 v104, s20, v187
	global_load_dwordx4 v[104:107], v104, s[98:99] offset:128
	v_mfma_f32_16x16x32_bf16 v[136:139], v[224:227], v[198:201], v[136:139]
	s_waitcnt vmcnt(11)
	v_mfma_f32_16x16x32_bf16 v[132:135], v[228:231], v[198:201], v[132:135]
	ds_write_b128 v183, v[88:91] offset:6144
	v_add_u32_e32 v88, s21, v187
	v_mfma_f32_16x16x32_bf16 v[128:131], v[232:235], v[198:201], v[128:131]
	global_load_dwordx4 v[88:91], v88, s[98:99] offset:128
	v_mfma_f32_16x16x32_bf16 v[124:127], v[236:239], v[198:201], v[124:127]
	s_waitcnt vmcnt(11)
	ds_write_b128 v183, v[80:83] offset:8192
	v_mfma_f32_16x16x32_bf16 v[120:123], v[224:227], v[204:207], v[120:123]
	v_add_u32_e32 v80, s56, v187
	v_mfma_f32_16x16x32_bf16 v[108:111], v[228:231], v[204:207], v[108:111]
	global_load_dwordx4 v[80:83], v80, s[98:99] offset:128
	s_waitcnt vmcnt(11)
	v_mfma_f32_16x16x32_bf16 v[100:103], v[232:235], v[204:207], v[100:103]
	ds_write_b128 v183, v[68:71] offset:10240
	v_mfma_f32_16x16x32_bf16 v[96:99], v[236:239], v[204:207], v[96:99]
	v_add_u32_e32 v68, s57, v187
	global_load_dwordx4 v[68:71], v68, s[98:99] offset:128
	v_mfma_f32_16x16x32_bf16 v[92:95], v[224:227], v[208:211], v[92:95]
	s_waitcnt vmcnt(11)
	v_mfma_f32_16x16x32_bf16 v[84:87], v[228:231], v[208:211], v[84:87]
	ds_write_b128 v183, v[60:63] offset:12288
	v_add_u32_e32 v60, s24, v187
	v_mfma_f32_16x16x32_bf16 v[76:79], v[232:235], v[208:211], v[76:79]
	global_load_dwordx4 v[60:63], v60, s[98:99] offset:128
	v_mfma_f32_16x16x32_bf16 v[72:75], v[236:239], v[208:211], v[72:75]
	s_waitcnt vmcnt(11)
	ds_write_b128 v183, v[40:43] offset:14336
	v_mfma_f32_16x16x32_bf16 v[64:67], v[224:227], v[212:215], v[64:67]
	v_add_u32_e32 v40, s96, v187
	v_mfma_f32_16x16x32_bf16 v[52:55], v[228:231], v[212:215], v[52:55]
	global_load_dwordx4 v[40:43], v40, s[98:99] offset:128
	s_waitcnt vmcnt(11)
	v_mfma_f32_16x16x32_bf16 v[48:51], v[232:235], v[212:215], v[48:51]
	ds_write_b128 v183, v[56:59] offset:16384
	v_mfma_f32_16x16x32_bf16 v[44:47], v[236:239], v[212:215], v[44:47]
	v_mov_b32_e32 v56, v186
	global_load_dwordx4 v[56:59], v56, s[98:99] offset:128
	v_mfma_f32_16x16x32_bf16 v[36:39], v[224:227], v[216:219], v[36:39]
	s_waitcnt vmcnt(11)
	v_mfma_f32_16x16x32_bf16 v[28:31], v[228:231], v[216:219], v[28:31]
	ds_write_b128 v183, v[32:35] offset:18432
	v_add_u32_e32 v32, s13, v186
	v_mfma_f32_16x16x32_bf16 v[24:27], v[232:235], v[216:219], v[24:27]
	global_load_dwordx4 v[32:35], v32, s[98:99] offset:128
	v_mfma_f32_16x16x32_bf16 v[20:23], v[236:239], v[216:219], v[20:23]
	s_waitcnt vmcnt(11)
	ds_write_b128 v183, v[16:19] offset:20480
	v_mfma_f32_16x16x32_bf16 v[12:15], v[224:227], v[220:223], v[12:15]
	v_add_u32_e32 v16, s12, v186
	v_mfma_f32_16x16x32_bf16 v[4:7], v[228:231], v[220:223], v[4:7]
	global_load_dwordx4 v[16:19], v16, s[98:99] offset:128
	s_waitcnt vmcnt(11)
	v_mfma_f32_16x16x32_bf16 v[0:3], v[232:235], v[220:223], v[0:3]
	ds_write_b128 v183, v[8:11] offset:22528
	v_mfma_f32_16x16x32_bf16 v[140:143], v[236:239], v[220:223], v[140:143]
	v_add_u32_e32 v8, s11, v186
	global_load_dwordx4 v[8:11], v8, s[98:99] offset:128
	v_cmp_gt_u32_e32 vcc, 0x6000, v183
	v_add_u32_e32 v182, 0xc000, v183
	v_add_u32_e32 v183, 0xffffa000, v183
	s_nop 0
	v_cndmask_b32_e32 v183, v183, v182, vcc
	s_add_u32 s6, s6, 0x80
	s_addc_u32 s7, s7, 0
	s_cmpk_lg_i32 s6, 0x780
	s_cbranch_scc1 .LBB0_802
	s_waitcnt lgkmcnt(0)
	s_barrier
	ds_read_b128 v[224:227], v184
	ds_read_b128 v[228:231], v184 offset:1024
	ds_read_b128 v[232:235], v184 offset:2048
	ds_read_b128 v[236:239], v184 offset:3072
	ds_read_b128 v[190:193], v185
	ds_read_b128 v[194:197], v185 offset:1024
	ds_read_b128 v[198:201], v185 offset:2048
	ds_read_b128 v[204:207], v185 offset:3072
	ds_read_b128 v[208:211], v185 offset:4096
	ds_read_b128 v[212:215], v185 offset:5120
	ds_read_b128 v[216:219], v185 offset:6144
	ds_read_b128 v[220:223], v185 offset:7168
	s_movk_i32 vcc_lo, 0x6000
	s_cmp_eq_u32 m0, 2
	s_cselect_b32 vcc_lo, 0xffff4000, vcc_lo
	s_add_u32 m0, m0, 1
	s_cmp_eq_u32 m0, 3
	s_cselect_b32 m0, 0, m0
	v_add_u32_e32 v185, vcc_lo, v185
	v_add_u32_e32 v184, vcc_lo, v184
	v_xor_b32_e32 v185, 64, v185
	v_xor_b32_e32 v184, 64, v184
	s_waitcnt lgkmcnt(7)
	v_mfma_f32_16x16x32_bf16 v[172:175], v[224:227], v[190:193], v[172:175]
	v_mfma_f32_16x16x32_bf16 v[168:171], v[228:231], v[190:193], v[168:171]
	v_mfma_f32_16x16x32_bf16 v[164:167], v[232:235], v[190:193], v[164:167]
	v_mfma_f32_16x16x32_bf16 v[160:163], v[236:239], v[190:193], v[160:163]
	ds_read_b128 v[190:193], v185
	s_waitcnt lgkmcnt(7)
	v_mfma_f32_16x16x32_bf16 v[156:159], v[224:227], v[194:197], v[156:159]
	v_mfma_f32_16x16x32_bf16 v[152:155], v[228:231], v[194:197], v[152:155]
	v_mfma_f32_16x16x32_bf16 v[148:151], v[232:235], v[194:197], v[148:151]
	v_mfma_f32_16x16x32_bf16 v[144:147], v[236:239], v[194:197], v[144:147]
	ds_read_b128 v[194:197], v185 offset:1024
	s_waitcnt lgkmcnt(7)
	v_mfma_f32_16x16x32_bf16 v[136:139], v[224:227], v[198:201], v[136:139]
	v_mfma_f32_16x16x32_bf16 v[132:135], v[228:231], v[198:201], v[132:135]
	v_mfma_f32_16x16x32_bf16 v[128:131], v[232:235], v[198:201], v[128:131]
	v_mfma_f32_16x16x32_bf16 v[124:127], v[236:239], v[198:201], v[124:127]
	ds_read_b128 v[198:201], v185 offset:2048
	s_waitcnt lgkmcnt(7)
	v_mfma_f32_16x16x32_bf16 v[120:123], v[224:227], v[204:207], v[120:123]
	v_mfma_f32_16x16x32_bf16 v[108:111], v[228:231], v[204:207], v[108:111]
	v_mfma_f32_16x16x32_bf16 v[100:103], v[232:235], v[204:207], v[100:103]
	v_mfma_f32_16x16x32_bf16 v[96:99], v[236:239], v[204:207], v[96:99]
	ds_read_b128 v[204:207], v185 offset:3072
	s_waitcnt lgkmcnt(7)
	v_mfma_f32_16x16x32_bf16 v[92:95], v[224:227], v[208:211], v[92:95]
	v_mfma_f32_16x16x32_bf16 v[84:87], v[228:231], v[208:211], v[84:87]
	v_mfma_f32_16x16x32_bf16 v[76:79], v[232:235], v[208:211], v[76:79]
	v_mfma_f32_16x16x32_bf16 v[72:75], v[236:239], v[208:211], v[72:75]
	ds_read_b128 v[208:211], v185 offset:4096
	s_waitcnt lgkmcnt(7)
	v_mfma_f32_16x16x32_bf16 v[64:67], v[224:227], v[212:215], v[64:67]
	v_mfma_f32_16x16x32_bf16 v[52:55], v[228:231], v[212:215], v[52:55]
	v_mfma_f32_16x16x32_bf16 v[48:51], v[232:235], v[212:215], v[48:51]
	v_mfma_f32_16x16x32_bf16 v[44:47], v[236:239], v[212:215], v[44:47]
	ds_read_b128 v[212:215], v185 offset:5120
	s_waitcnt lgkmcnt(7)
	v_mfma_f32_16x16x32_bf16 v[36:39], v[224:227], v[216:219], v[36:39]
	v_mfma_f32_16x16x32_bf16 v[28:31], v[228:231], v[216:219], v[28:31]
	v_mfma_f32_16x16x32_bf16 v[24:27], v[232:235], v[216:219], v[24:27]
	v_mfma_f32_16x16x32_bf16 v[20:23], v[236:239], v[216:219], v[20:23]
	ds_read_b128 v[216:219], v185 offset:6144
	s_waitcnt lgkmcnt(7)
	v_mfma_f32_16x16x32_bf16 v[12:15], v[224:227], v[220:223], v[12:15]
	v_mfma_f32_16x16x32_bf16 v[4:7], v[228:231], v[220:223], v[4:7]
	v_mfma_f32_16x16x32_bf16 v[0:3], v[232:235], v[220:223], v[0:3]
	v_mfma_f32_16x16x32_bf16 v[140:143], v[236:239], v[220:223], v[140:143]
	ds_read_b128 v[220:223], v185 offset:7168
	ds_read_b128 v[224:227], v184
	ds_read_b128 v[228:231], v184 offset:1024
	ds_read_b128 v[232:235], v184 offset:2048
	ds_read_b128 v[236:239], v184 offset:3072
	s_movk_i32 vcc_lo, 0x6000
	s_cmp_eq_u32 m0, 2
	s_cselect_b32 vcc_lo, 0xffff4000, vcc_lo
	s_add_u32 m0, m0, 1
	s_cmp_eq_u32 m0, 3
	s_cselect_b32 m0, 0, m0
	v_add_u32_e32 v185, vcc_lo, v185
	v_add_u32_e32 v184, vcc_lo, v184
	v_xor_b32_e32 v185, 64, v185
	v_xor_b32_e32 v184, 64, v184
	s_waitcnt lgkmcnt(0)
	v_mfma_f32_16x16x32_bf16 v[172:175], v[224:227], v[190:193], v[172:175]
	v_mfma_f32_16x16x32_bf16 v[168:171], v[228:231], v[190:193], v[168:171]
	v_mfma_f32_16x16x32_bf16 v[164:167], v[232:235], v[190:193], v[164:167]
	v_mfma_f32_16x16x32_bf16 v[160:163], v[236:239], v[190:193], v[160:163]
	v_mfma_f32_16x16x32_bf16 v[156:159], v[224:227], v[194:197], v[156:159]
	v_mfma_f32_16x16x32_bf16 v[152:155], v[228:231], v[194:197], v[152:155]
	v_mfma_f32_16x16x32_bf16 v[148:151], v[232:235], v[194:197], v[148:151]
	v_mfma_f32_16x16x32_bf16 v[144:147], v[236:239], v[194:197], v[144:147]
	v_mfma_f32_16x16x32_bf16 v[136:139], v[224:227], v[198:201], v[136:139]
	v_mfma_f32_16x16x32_bf16 v[132:135], v[228:231], v[198:201], v[132:135]
	v_mfma_f32_16x16x32_bf16 v[128:131], v[232:235], v[198:201], v[128:131]
	v_mfma_f32_16x16x32_bf16 v[124:127], v[236:239], v[198:201], v[124:127]
	v_mfma_f32_16x16x32_bf16 v[120:123], v[224:227], v[204:207], v[120:123]
	v_mfma_f32_16x16x32_bf16 v[108:111], v[228:231], v[204:207], v[108:111]
	v_mfma_f32_16x16x32_bf16 v[100:103], v[232:235], v[204:207], v[100:103]
	v_mfma_f32_16x16x32_bf16 v[96:99], v[236:239], v[204:207], v[96:99]
	v_mfma_f32_16x16x32_bf16 v[92:95], v[224:227], v[208:211], v[92:95]
	v_mfma_f32_16x16x32_bf16 v[84:87], v[228:231], v[208:211], v[84:87]
	v_mfma_f32_16x16x32_bf16 v[76:79], v[232:235], v[208:211], v[76:79]
	v_mfma_f32_16x16x32_bf16 v[72:75], v[236:239], v[208:211], v[72:75]
	v_mfma_f32_16x16x32_bf16 v[64:67], v[224:227], v[212:215], v[64:67]
	v_mfma_f32_16x16x32_bf16 v[52:55], v[228:231], v[212:215], v[52:55]
	v_mfma_f32_16x16x32_bf16 v[48:51], v[232:235], v[212:215], v[48:51]
	v_mfma_f32_16x16x32_bf16 v[44:47], v[236:239], v[212:215], v[44:47]
	v_mfma_f32_16x16x32_bf16 v[36:39], v[224:227], v[216:219], v[36:39]
	v_mfma_f32_16x16x32_bf16 v[28:31], v[228:231], v[216:219], v[28:31]
	v_mfma_f32_16x16x32_bf16 v[24:27], v[232:235], v[216:219], v[24:27]
	v_mfma_f32_16x16x32_bf16 v[20:23], v[236:239], v[216:219], v[20:23]
	v_mfma_f32_16x16x32_bf16 v[12:15], v[224:227], v[220:223], v[12:15]
	v_mfma_f32_16x16x32_bf16 v[4:7], v[228:231], v[220:223], v[4:7]
	v_mfma_f32_16x16x32_bf16 v[0:3], v[232:235], v[220:223], v[0:3]
	v_mfma_f32_16x16x32_bf16 v[140:143], v[236:239], v[220:223], v[140:143]
	v_lshrrev_b32_e32 v224, 4, v188
	v_and_b32_e32 v225, 7, v188
	v_bitop3_b32 v226, v224, v225, 3 bitop3:0x6c
	v_lshlrev_b32_e32 v227, 7, v188
	v_bfe_u32 v228, v188, 4, 2
	v_and_b32_e32 v229, 0xffffc780, v227
	v_and_b32_e32 v227, 0x2780, v227
	v_bitop3_b32 v228, v228, v225, 4 bitop3:0x36
	v_lshlrev_b32_e32 v226, 4, v226
	v_lshlrev_b32_e32 v228, 4, v228
	v_or_b32_e32 v185, v229, v226
	v_or_b32_e32 v184, v227, v226
	v_or_b32_e32 v183, v229, v228
	v_or_b32_e32 v182, v227, v228
	s_waitcnt vmcnt(0)
	s_barrier
	s_waitcnt vmcnt(10)
	ds_write_b128 v176, v[116:119]
	s_waitcnt vmcnt(9)
	ds_write_b128 v176, v[112:115] offset:4096
	s_waitcnt vmcnt(8)
	ds_write_b128 v176, v[104:107] offset:8192
	s_waitcnt vmcnt(7)
	ds_write_b128 v176, v[88:91] offset:12288
	s_waitcnt vmcnt(6)
	ds_write_b128 v176, v[80:83] offset:16384
	s_waitcnt vmcnt(5)
	ds_write_b128 v176, v[68:71] offset:20480
	s_waitcnt vmcnt(4)
	ds_write_b128 v176, v[60:63] offset:24576
	s_waitcnt vmcnt(3)
	ds_write_b128 v176, v[40:43] offset:28672
	ds_write_b128 v176, v[56:59] offset:32768
	s_waitcnt vmcnt(2)
	ds_write_b128 v176, v[32:35] offset:36864
	s_waitcnt vmcnt(1)
	ds_write_b128 v176, v[16:19] offset:40960
	s_waitcnt vmcnt(0)
	ds_write_b128 v176, v[8:11] offset:45056
	s_waitcnt lgkmcnt(0)
	s_barrier
	ds_read_b128 v[8:11], v185
	ds_read_b128 v[16:19], v185 offset:2048
	ds_read_b128 v[32:35], v185 offset:4096
	ds_read_b128 v[40:43], v185 offset:6144
	ds_read_b128 v[56:59], v185 offset:8192
	ds_read_b128 v[60:63], v185 offset:10240
	ds_read_b128 v[68:71], v185 offset:12288
	ds_read_b128 v[80:83], v185 offset:14336
	ds_read_b128 v[88:91], v184 offset:32768
	ds_read_b128 v[104:107], v184 offset:34816
	ds_read_b128 v[112:115], v184 offset:36864
	ds_read_b128 v[116:119], v184 offset:38912
	s_waitcnt lgkmcnt(3)
	v_mfma_f32_16x16x32_bf16 v[172:175], v[88:91], v[8:11], v[172:175]
	s_waitcnt lgkmcnt(2)
	v_mfma_f32_16x16x32_bf16 v[168:171], v[104:107], v[8:11], v[168:171]
	s_waitcnt lgkmcnt(1)
	v_mfma_f32_16x16x32_bf16 v[164:167], v[112:115], v[8:11], v[164:167]
	s_waitcnt lgkmcnt(0)
	v_mfma_f32_16x16x32_bf16 v[8:11], v[116:119], v[8:11], v[160:163]
	v_mfma_f32_16x16x32_bf16 v[156:159], v[88:91], v[16:19], v[156:159]
	v_mfma_f32_16x16x32_bf16 v[152:155], v[104:107], v[16:19], v[152:155]
	v_mfma_f32_16x16x32_bf16 v[148:151], v[112:115], v[16:19], v[148:151]
	v_mfma_f32_16x16x32_bf16 v[16:19], v[116:119], v[16:19], v[144:147]
	v_mfma_f32_16x16x32_bf16 v[136:139], v[88:91], v[32:35], v[136:139]
	v_mfma_f32_16x16x32_bf16 v[132:135], v[104:107], v[32:35], v[132:135]
	v_mfma_f32_16x16x32_bf16 v[128:131], v[112:115], v[32:35], v[128:131]
	v_mfma_f32_16x16x32_bf16 v[32:35], v[116:119], v[32:35], v[124:127]
	v_mfma_f32_16x16x32_bf16 v[120:123], v[88:91], v[40:43], v[120:123]
	v_mfma_f32_16x16x32_bf16 v[108:111], v[104:107], v[40:43], v[108:111]
	v_mfma_f32_16x16x32_bf16 v[100:103], v[112:115], v[40:43], v[100:103]
	v_mfma_f32_16x16x32_bf16 v[40:43], v[116:119], v[40:43], v[96:99]
	v_mfma_f32_16x16x32_bf16 v[92:95], v[88:91], v[56:59], v[92:95]
	v_mfma_f32_16x16x32_bf16 v[84:87], v[104:107], v[56:59], v[84:87]
	v_mfma_f32_16x16x32_bf16 v[76:79], v[112:115], v[56:59], v[76:79]
	v_mfma_f32_16x16x32_bf16 v[56:59], v[116:119], v[56:59], v[72:75]
	v_mfma_f32_16x16x32_bf16 v[64:67], v[88:91], v[60:63], v[64:67]
	v_mfma_f32_16x16x32_bf16 v[52:55], v[104:107], v[60:63], v[52:55]
	v_mfma_f32_16x16x32_bf16 v[72:75], v[112:115], v[60:63], v[48:51]
	v_mfma_f32_16x16x32_bf16 v[60:63], v[116:119], v[60:63], v[44:47]
	v_mfma_f32_16x16x32_bf16 v[96:99], v[88:91], v[68:71], v[36:39]
	v_mfma_f32_16x16x32_bf16 v[28:31], v[104:107], v[68:71], v[28:31]
	v_mfma_f32_16x16x32_bf16 v[124:127], v[112:115], v[68:71], v[24:27]
	v_mfma_f32_16x16x32_bf16 v[20:23], v[116:119], v[68:71], v[20:23]
	v_mfma_f32_16x16x32_bf16 v[12:15], v[88:91], v[80:83], v[12:15]
	v_mfma_f32_16x16x32_bf16 v[4:7], v[104:107], v[80:83], v[4:7]
	v_mfma_f32_16x16x32_bf16 v[0:3], v[112:115], v[80:83], v[0:3]
	v_mfma_f32_16x16x32_bf16 v[68:71], v[116:119], v[80:83], v[140:143]
	ds_read_b128 v[24:27], v183
	ds_read_b128 v[36:39], v183 offset:2048
	ds_read_b128 v[44:47], v183 offset:4096
	ds_read_b128 v[80:83], v183 offset:6144
	ds_read_b128 v[88:91], v183 offset:8192
	ds_read_b128 v[104:107], v183 offset:10240
	ds_read_b128 v[112:115], v183 offset:12288
	ds_read_b128 v[116:119], v183 offset:14336
	ds_read_b128 v[140:143], v182 offset:32768
	ds_read_b128 v[144:147], v182 offset:34816
	ds_read_b128 v[160:163], v182 offset:36864
	ds_read_b128 v[178:181], v182 offset:38912
	s_waitcnt lgkmcnt(3)
	v_mfma_f32_16x16x32_bf16 v[172:175], v[140:143], v[24:27], v[172:175]
	v_mov_b32_e32 v49, v188
	v_cmp_lt_i32_e32 vcc, v189, v202
	s_waitcnt lgkmcnt(2)
	v_mfma_f32_16x16x32_bf16 v[168:171], v[144:147], v[24:27], v[168:171]
	v_mov_b32_e32 v48, v188
	v_readlane_b32 s6, v253, 24
	s_waitcnt lgkmcnt(1)
	v_mfma_f32_16x16x32_bf16 v[164:167], v[160:163], v[24:27], v[164:167]
	v_and_b32_e32 v50, 0xffffff80, v48
	v_add_u32_e32 v51, s9, v50
	v_and_or_b32 v50, v48, 64, s10
	s_waitcnt lgkmcnt(0)
	v_mfma_f32_16x16x32_bf16 v[8:11], v[178:181], v[24:27], v[8:11]
	v_bfe_u32 v26, v49, 4, 1
	v_cndmask_b32_e32 v24, v203, v189, vcc
	v_cmp_eq_u32_e32 vcc, 0, v26
	v_lshlrev_b32_e32 v186, 2, v24
	v_mfma_f32_16x16x32_bf16 v[182:185], v[178:181], v[36:39], v[16:19]
	v_and_or_b32 v48, v49, 15, v51
	v_ashrrev_i32_e32 v51, 31, v50
	v_lshl_add_u64 v[50:51], v[50:51], 1, s[4:5]
	v_lshlrev_b32_e32 v176, 5, v26
	v_lshrrev_b32_e32 v27, 1, v49
	v_lshl_add_u64 v[24:25], v[50:51], 0, v[176:177]
	v_and_b32_e32 v176, 16, v27
	v_ashrrev_i32_e32 v49, 31, v48
	v_mfma_f32_16x16x32_bf16 v[156:159], v[140:143], v[36:39], v[156:159]
	v_lshl_add_u64 v[50:51], v[24:25], 0, v[176:177]
	v_lshlrev_b64 v[24:25], 11, v[48:49]
	s_waitcnt lgkmcnt(0)
	v_mfma_f32_16x16x32_bf16 v[152:155], v[144:147], v[36:39], v[152:155]
	v_mov_b32_e32 v26, v172
	v_mov_b32_e32 v27, v168
	s_nop 1
	v_permlane16_swap_b32_e32 v26, v27
	s_waitcnt lgkmcnt(0)
	v_lshl_add_u64 v[24:25], v[50:51], 0, v[24:25]
	v_mfma_f32_16x16x32_bf16 v[148:151], v[160:163], v[36:39], v[148:151]
	v_mov_b32_e32 v16, v173
	v_mov_b32_e32 v36, v169
	s_nop 1
	v_permlane16_swap_b32_e32 v16, v36
	s_waitcnt lgkmcnt(0)
	v_cvt_pk_bf16_f32 v16, v26, v16
	v_mfma_f32_16x16x32_bf16 v[190:193], v[178:181], v[44:47], v[32:35]
	v_readlane_b32 s7, v253, 25
	s_nop 1
	v_mov_b32_e32 v17, v174
	v_mov_b32_e32 v32, v170
	s_nop 1
	v_permlane16_swap_b32_e32 v17, v32
	s_waitcnt lgkmcnt(0)
	v_mov_b32_e32 v18, v175
	v_mov_b32_e32 v19, v171
	s_nop 1
	v_permlane16_swap_b32_e32 v18, v19
	v_cvt_pk_bf16_f32 v17, v17, v18
	v_cvt_pk_bf16_f32 v18, v27, v36
	v_cvt_pk_bf16_f32 v19, v32, v19
	global_store_dwordx4 v[24:25], v[16:19], off
	v_mfma_f32_16x16x32_bf16 v[120:123], v[140:143], v[80:83], v[120:123]
	s_nop 0
	v_mfma_f32_16x16x32_bf16 v[108:111], v[144:147], v[80:83], v[108:111]
	s_waitcnt lgkmcnt(0)
	v_mov_b32_e32 v26, v164
	v_mov_b32_e32 v16, v8
	s_nop 1
	v_permlane16_swap_b32_e32 v26, v16
	s_waitcnt lgkmcnt(0)
	v_mov_b32_e32 v8, v165
	v_mov_b32_e32 v17, v9
	s_nop 1
	v_permlane16_swap_b32_e32 v8, v17
	s_waitcnt lgkmcnt(0)
	v_mov_b32_e32 v9, v166
	v_mov_b32_e32 v18, v10
	s_nop 1
	v_permlane16_swap_b32_e32 v9, v18
	s_waitcnt lgkmcnt(0)
	v_mov_b32_e32 v10, v167
	s_nop 1
	v_permlane16_swap_b32_e32 v10, v11
	v_cvt_pk_bf16_f32 v8, v26, v8
	v_cvt_pk_bf16_f32 v9, v9, v10
	v_cvt_pk_bf16_f32 v10, v16, v17
	v_cvt_pk_bf16_f32 v11, v18, v11
	global_store_dwordx4 v[24:25], v[8:11], off offset:64
	v_mfma_f32_16x16x32_bf16 v[100:103], v[160:163], v[80:83], v[100:103]
	s_nop 0
	v_or_b32_e32 v8, 16, v48
	v_ashrrev_i32_e32 v9, 31, v8
	v_lshlrev_b64 v[8:9], 11, v[8:9]
	v_mfma_f32_16x16x32_bf16 v[80:83], v[178:181], v[80:83], v[40:43]
	v_mfma_f32_16x16x32_bf16 v[40:43], v[140:143], v[104:107], v[64:67]
	s_nop 1
	s_nop 0
	v_lshl_add_u64 v[64:65], v[50:51], 0, v[8:9]
	v_mfma_f32_16x16x32_bf16 v[136:139], v[140:143], v[44:47], v[136:139]
	s_waitcnt lgkmcnt(0)
	v_mfma_f32_16x16x32_bf16 v[132:135], v[144:147], v[44:47], v[132:135]
	v_mfma_f32_16x16x32_bf16 v[128:131], v[160:163], v[44:47], v[128:131]
	v_mfma_f32_16x16x32_bf16 v[44:47], v[144:147], v[104:107], v[52:55]
	v_mfma_f32_16x16x32_bf16 v[36:39], v[178:181], v[104:107], v[60:63]
	s_nop 1
	v_mov_b32_e32 v49, v156
	v_mov_b32_e32 v54, v152
	s_nop 1
	v_permlane16_swap_b32_e32 v49, v54
	s_waitcnt lgkmcnt(0)
	v_mov_b32_e32 v8, v157
	v_mov_b32_e32 v55, v153
	s_nop 1
	v_permlane16_swap_b32_e32 v8, v55
	v_mov_b32_e32 v53, v158
	v_mov_b32_e32 v60, v154
	s_nop 1
	v_permlane16_swap_b32_e32 v53, v60
	v_mov_b32_e32 v61, v159
	v_mov_b32_e32 v62, v155
	s_nop 1
	v_permlane16_swap_b32_e32 v61, v62
	v_cvt_pk_bf16_f32 v52, v49, v8
	v_cvt_pk_bf16_f32 v53, v53, v61
	v_cvt_pk_bf16_f32 v54, v54, v55
	v_cvt_pk_bf16_f32 v55, v60, v62
	v_mfma_f32_16x16x32_bf16 v[8:11], v[140:143], v[116:119], v[12:15]
	global_store_dwordx4 v[64:65], v[52:55], off
	v_mfma_f32_16x16x32_bf16 v[12:15], v[144:147], v[116:119], v[4:7]
	s_nop 2
	v_cndmask_b32_e32 v4, v148, v182, vcc
	ds_bpermute_b32 v54, v186, v4
	s_waitcnt lgkmcnt(1)
	v_mov_b32_e32 v60, v149
	v_mov_b32_e32 v49, v183
	s_nop 1
	v_permlane16_swap_b32_e32 v60, v49
	s_waitcnt lgkmcnt(1)
	s_waitcnt lgkmcnt(0)
	v_cndmask_b32_e32 v55, v54, v148, vcc
	v_cndmask_b32_e32 v54, v182, v54, vcc
	v_mov_b32_e32 v61, v150
	v_mov_b32_e32 v62, v184
	s_nop 1
	v_permlane16_swap_b32_e32 v61, v62
	s_waitcnt lgkmcnt(0)
	v_mov_b32_e32 v63, v151
	v_mov_b32_e32 v66, v185
	s_nop 1
	v_permlane16_swap_b32_e32 v63, v66
	v_cvt_pk_bf16_f32 v52, v55, v60
	v_cvt_pk_bf16_f32 v53, v61, v63
	v_cvt_pk_bf16_f32 v54, v54, v49
	v_cvt_pk_bf16_f32 v55, v62, v66
	global_store_dwordx4 v[64:65], v[52:55], off offset:64
	s_nop 1
	v_or_b32_e32 v52, 32, v48
	v_ashrrev_i32_e32 v53, 31, v52
	v_lshlrev_b64 v[52:53], 11, v[52:53]
	v_lshl_add_u64 v[60:61], v[50:51], 0, v[52:53]
	s_waitcnt lgkmcnt(0)
	v_mov_b32_e32 v55, v136
	v_mov_b32_e32 v49, v132
	s_nop 1
	v_permlane16_swap_b32_e32 v55, v49
	s_waitcnt lgkmcnt(0)
	v_mov_b32_e32 v62, v137
	v_mov_b32_e32 v63, v133
	s_nop 1
	v_permlane16_swap_b32_e32 v62, v63
	s_waitcnt lgkmcnt(0)
	v_mov_b32_e32 v64, v138
	v_mov_b32_e32 v65, v134
	s_nop 1
	v_permlane16_swap_b32_e32 v64, v65
	s_waitcnt lgkmcnt(0)
	v_mov_b32_e32 v53, v139
	v_mov_b32_e32 v66, v135
	s_nop 1
	v_permlane16_swap_b32_e32 v53, v66
	v_cvt_pk_bf16_f32 v52, v55, v62
	v_cvt_pk_bf16_f32 v53, v64, v53
	v_cvt_pk_bf16_f32 v54, v49, v63
	v_cvt_pk_bf16_f32 v55, v65, v66
	global_store_dwordx4 v[60:61], v[52:55], off
	s_waitcnt lgkmcnt(0)
	s_nop 0
	v_mov_b32_e32 v55, v128
	v_mov_b32_e32 v49, v190
	s_nop 1
	v_permlane16_swap_b32_e32 v55, v49
	s_waitcnt lgkmcnt(0)
	v_mov_b32_e32 v62, v129
	v_mov_b32_e32 v63, v191
	s_nop 1
	v_permlane16_swap_b32_e32 v62, v63
	s_waitcnt lgkmcnt(0)
	v_mov_b32_e32 v64, v130
	v_mov_b32_e32 v65, v192
	s_nop 1
	v_permlane16_swap_b32_e32 v64, v65
	s_waitcnt lgkmcnt(0)
	v_mov_b32_e32 v53, v131
	v_mov_b32_e32 v66, v193
	s_nop 1
	v_permlane16_swap_b32_e32 v53, v66
	v_cvt_pk_bf16_f32 v52, v55, v62
	v_cvt_pk_bf16_f32 v53, v64, v53
	v_cvt_pk_bf16_f32 v54, v49, v63
	v_cvt_pk_bf16_f32 v55, v65, v66
	global_store_dwordx4 v[60:61], v[52:55], off offset:64
	s_nop 1
	v_or_b32_e32 v52, 48, v48
	v_ashrrev_i32_e32 v53, 31, v52
	v_lshlrev_b64 v[52:53], 11, v[52:53]
	v_lshl_add_u64 v[60:61], v[50:51], 0, v[52:53]
	s_waitcnt lgkmcnt(0)
	v_mov_b32_e32 v55, v120
	v_mov_b32_e32 v49, v108
	s_nop 1
	v_permlane16_swap_b32_e32 v55, v49
	s_waitcnt lgkmcnt(0)
	v_mov_b32_e32 v62, v121
	v_mov_b32_e32 v63, v109
	s_nop 1
	v_permlane16_swap_b32_e32 v62, v63
	s_waitcnt lgkmcnt(0)
	v_mov_b32_e32 v64, v122
	v_mov_b32_e32 v65, v110
	s_nop 1
	v_permlane16_swap_b32_e32 v64, v65
	s_waitcnt lgkmcnt(0)
	v_mov_b32_e32 v53, v123
	v_mov_b32_e32 v66, v111
	s_nop 1
	v_permlane16_swap_b32_e32 v53, v66
	v_cvt_pk_bf16_f32 v52, v55, v62
	v_cvt_pk_bf16_f32 v53, v64, v53
	v_cvt_pk_bf16_f32 v54, v49, v63
	v_cvt_pk_bf16_f32 v55, v65, v66
	global_store_dwordx4 v[60:61], v[52:55], off
	s_waitcnt lgkmcnt(0)
	s_nop 0
	v_mov_b32_e32 v55, v100
	v_mov_b32_e32 v49, v80
	s_nop 1
	v_permlane16_swap_b32_e32 v55, v49
	s_waitcnt lgkmcnt(0)
	v_mov_b32_e32 v62, v101
	v_mov_b32_e32 v63, v81
	s_nop 1
	v_permlane16_swap_b32_e32 v62, v63
	s_waitcnt lgkmcnt(0)
	v_mov_b32_e32 v64, v102
	v_mov_b32_e32 v65, v82
	s_nop 1
	v_permlane16_swap_b32_e32 v64, v65
	s_waitcnt lgkmcnt(0)
	v_mov_b32_e32 v53, v103
	v_mov_b32_e32 v66, v83
	s_nop 1
	v_permlane16_swap_b32_e32 v53, v66
	v_mfma_f32_16x16x32_bf16 v[92:95], v[140:143], v[88:91], v[92:95]
	v_cvt_pk_bf16_f32 v52, v55, v62
	v_cvt_pk_bf16_f32 v53, v64, v53
	v_cvt_pk_bf16_f32 v54, v49, v63
	v_mfma_f32_16x16x32_bf16 v[84:87], v[144:147], v[88:91], v[84:87]
	v_cvt_pk_bf16_f32 v55, v65, v66
	global_store_dwordx4 v[60:61], v[52:55], off offset:64
	v_mfma_f32_16x16x32_bf16 v[76:79], v[160:163], v[88:91], v[76:79]
	s_nop 0
	v_or_b32_e32 v52, 64, v48
	v_ashrrev_i32_e32 v53, 31, v52
	v_lshlrev_b64 v[52:53], 11, v[52:53]
	v_lshl_add_u64 v[60:61], v[50:51], 0, v[52:53]
	v_mfma_f32_16x16x32_bf16 v[56:59], v[178:181], v[88:91], v[56:59]
	s_waitcnt lgkmcnt(0)
	v_mov_b32_e32 v55, v92
	v_mov_b32_e32 v49, v84
	s_nop 1
	v_permlane16_swap_b32_e32 v55, v49
	s_waitcnt lgkmcnt(0)
	v_mov_b32_e32 v62, v93
	v_mov_b32_e32 v63, v85
	s_nop 1
	v_permlane16_swap_b32_e32 v62, v63
	s_waitcnt lgkmcnt(0)
	v_mov_b32_e32 v64, v94
	v_mov_b32_e32 v65, v86
	s_nop 1
	v_permlane16_swap_b32_e32 v64, v65
	s_waitcnt lgkmcnt(0)
	v_mov_b32_e32 v53, v95
	v_mov_b32_e32 v66, v87
	s_nop 1
	v_permlane16_swap_b32_e32 v53, v66
	v_cvt_pk_bf16_f32 v52, v55, v62
	v_cvt_pk_bf16_f32 v53, v64, v53
	v_cvt_pk_bf16_f32 v54, v49, v63
	v_cvt_pk_bf16_f32 v55, v65, v66
	global_store_dwordx4 v[60:61], v[52:55], off
	s_waitcnt lgkmcnt(0)
	s_nop 0
	v_mov_b32_e32 v55, v76
	v_mov_b32_e32 v49, v56
	s_nop 1
	v_permlane16_swap_b32_e32 v55, v49
	s_waitcnt lgkmcnt(0)
	v_mov_b32_e32 v56, v77
	s_nop 1
	v_permlane16_swap_b32_e32 v56, v57
	s_waitcnt lgkmcnt(0)
	v_mov_b32_e32 v62, v78
	s_nop 1
	v_permlane16_swap_b32_e32 v62, v58
	s_waitcnt lgkmcnt(0)
	v_mov_b32_e32 v53, v79
	s_nop 1
	v_permlane16_swap_b32_e32 v53, v59
	v_cvt_pk_bf16_f32 v52, v55, v56
	v_cvt_pk_bf16_f32 v53, v62, v53
	v_cvt_pk_bf16_f32 v54, v49, v57
	v_cvt_pk_bf16_f32 v55, v58, v59
	global_store_dwordx4 v[60:61], v[52:55], off offset:64
	v_mfma_f32_16x16x32_bf16 v[32:35], v[160:163], v[104:107], v[72:75]
	s_nop 0
	v_or_b32_e32 v52, 0x50, v48
	v_ashrrev_i32_e32 v53, 31, v52
	v_lshlrev_b64 v[52:53], 11, v[52:53]
	s_waitcnt lgkmcnt(0)
	s_nop 1
	v_permlane16_swap_b32_e32 v40, v44
	s_waitcnt lgkmcnt(0)
	s_nop 1
	v_permlane16_swap_b32_e32 v41, v45
	s_waitcnt lgkmcnt(0)
	s_nop 1
	v_permlane16_swap_b32_e32 v42, v46
	s_waitcnt lgkmcnt(0)
	s_nop 1
	v_permlane16_swap_b32_e32 v43, v47
	v_lshl_add_u64 v[52:53], v[50:51], 0, v[52:53]
	v_cvt_pk_bf16_f32 v40, v40, v41
	v_cvt_pk_bf16_f32 v41, v42, v43
	v_cvt_pk_bf16_f32 v42, v44, v45
	v_cvt_pk_bf16_f32 v43, v46, v47
	global_store_dwordx4 v[52:53], v[40:43], off
	v_mfma_f32_16x16x32_bf16 v[24:27], v[140:143], v[112:115], v[96:99]
	s_nop 0
	v_mfma_f32_16x16x32_bf16 v[28:31], v[144:147], v[112:115], v[28:31]
	s_waitcnt lgkmcnt(0)
	s_nop 1
	v_permlane16_swap_b32_e32 v32, v36
	s_waitcnt lgkmcnt(0)
	s_nop 1
	v_permlane16_swap_b32_e32 v33, v37
	s_waitcnt lgkmcnt(0)
	s_nop 1
	v_permlane16_swap_b32_e32 v34, v38
	s_waitcnt lgkmcnt(0)
	s_nop 1
	v_permlane16_swap_b32_e32 v35, v39
	v_cvt_pk_bf16_f32 v32, v32, v33
	v_cvt_pk_bf16_f32 v33, v34, v35
	v_cvt_pk_bf16_f32 v34, v36, v37
	v_cvt_pk_bf16_f32 v35, v38, v39
	global_store_dwordx4 v[52:53], v[32:35], off offset:64
	v_mfma_f32_16x16x32_bf16 v[16:19], v[160:163], v[112:115], v[124:127]
	s_nop 0
	v_or_b32_e32 v32, 0x60, v48
	v_ashrrev_i32_e32 v33, 31, v32
	v_lshlrev_b64 v[32:33], 11, v[32:33]
	v_mfma_f32_16x16x32_bf16 v[20:23], v[178:181], v[112:115], v[20:23]
	s_waitcnt lgkmcnt(0)
	s_nop 1
	v_permlane16_swap_b32_e32 v24, v28
	s_waitcnt lgkmcnt(0)
	s_nop 1
	v_permlane16_swap_b32_e32 v25, v29
	s_waitcnt lgkmcnt(0)
	s_nop 1
	v_permlane16_swap_b32_e32 v26, v30
	s_waitcnt lgkmcnt(0)
	s_nop 1
	v_permlane16_swap_b32_e32 v27, v31
	v_lshl_add_u64 v[32:33], v[50:51], 0, v[32:33]
	v_cvt_pk_bf16_f32 v24, v24, v25
	v_cvt_pk_bf16_f32 v25, v26, v27
	v_cvt_pk_bf16_f32 v26, v28, v29
	v_cvt_pk_bf16_f32 v27, v30, v31
	global_store_dwordx4 v[32:33], v[24:27], off
	v_mfma_f32_16x16x32_bf16 v[0:3], v[160:163], v[116:119], v[0:3]
	s_nop 0
	v_mfma_f32_16x16x32_bf16 v[4:7], v[178:181], v[116:119], v[68:71]
	s_waitcnt lgkmcnt(0)
	s_nop 1
	v_permlane16_swap_b32_e32 v16, v20
	s_waitcnt lgkmcnt(0)
	s_nop 1
	v_permlane16_swap_b32_e32 v17, v21
	s_waitcnt lgkmcnt(0)
	s_nop 1
	v_permlane16_swap_b32_e32 v18, v22
	s_waitcnt lgkmcnt(0)
	s_nop 1
	v_permlane16_swap_b32_e32 v19, v23
	v_cvt_pk_bf16_f32 v16, v16, v17
	v_cvt_pk_bf16_f32 v17, v18, v19
	v_cvt_pk_bf16_f32 v18, v20, v21
	v_cvt_pk_bf16_f32 v19, v22, v23
	global_store_dwordx4 v[32:33], v[16:19], off offset:64
	s_nop 1
	v_or_b32_e32 v16, 0x70, v48
	v_ashrrev_i32_e32 v17, 31, v16
	v_lshlrev_b64 v[16:17], 11, v[16:17]
	s_waitcnt lgkmcnt(0)
	s_nop 1
	v_permlane16_swap_b32_e32 v8, v12
	s_waitcnt lgkmcnt(0)
	s_nop 1
	v_permlane16_swap_b32_e32 v9, v13
	s_waitcnt lgkmcnt(0)
	s_nop 1
	v_permlane16_swap_b32_e32 v10, v14
	s_waitcnt lgkmcnt(0)
	s_nop 1
	v_permlane16_swap_b32_e32 v11, v15
	v_lshl_add_u64 v[16:17], v[50:51], 0, v[16:17]
	v_cvt_pk_bf16_f32 v8, v8, v9
	v_cvt_pk_bf16_f32 v9, v10, v11
	v_cvt_pk_bf16_f32 v10, v12, v13
	v_cvt_pk_bf16_f32 v11, v14, v15
	global_store_dwordx4 v[16:17], v[8:11], off
	s_nop 1
	s_waitcnt lgkmcnt(0)
	s_nop 1
	v_permlane16_swap_b32_e32 v0, v4
	s_waitcnt lgkmcnt(0)
	s_nop 1
	v_permlane16_swap_b32_e32 v1, v5
	s_waitcnt lgkmcnt(0)
	s_nop 1
	v_permlane16_swap_b32_e32 v2, v6
	s_waitcnt lgkmcnt(0)
	s_nop 1
	v_permlane16_swap_b32_e32 v3, v7
	v_cvt_pk_bf16_f32 v0, v0, v1
	v_cvt_pk_bf16_f32 v1, v2, v3
	v_cvt_pk_bf16_f32 v2, v4, v5
	v_cvt_pk_bf16_f32 v3, v6, v7
	global_store_dwordx4 v[16:17], v[0:3], off offset:64
	s_load_dword s6, s[6:7], 0x0
	s_waitcnt lgkmcnt(0)
	s_add_i32 s8, s6, s8
	s_cmpk_gt_i32 s8, 0xff
	s_cbranch_scc0 .LBB0_801

.LBB0_1095:
	v_lshrrev_b32_e32 v52, 4, v162
	v_bfe_u32 v178, v162, 4, 1
	v_lshlrev_b32_e32 v52, 2, v52
	v_and_b32_e32 v54, 8, v52
	v_lshlrev_b32_e32 v52, 5, v178
	v_mov_b32_e32 v53, v177
	v_lshl_add_u64 v[52:53], v[160:161], 0, v[52:53]
	v_lshlrev_b32_e32 v160, 1, v54
	v_mov_b32_e32 v161, v177
	v_cmp_lt_i32_e32 vcc, v189, v202
	v_lshl_add_u64 v[162:163], v[52:53], 0, v[160:161]
	v_cmp_eq_u32_e64 s[42:43], 0, v178
	v_cndmask_b32_e32 v52, v203, v189, vcc
	v_lshlrev_b32_e32 v173, 2, v52
	s_andn2_b64 vcc, exec, s[48:49]
	s_waitcnt lgkmcnt(0)
	v_mov_b32_e32 v56, v144
	v_mov_b32_e32 v57, v148
	s_nop 1
	v_permlane16_swap_b32_e32 v56, v57
	s_waitcnt lgkmcnt(0)
	v_mov_b32_e32 v52, v145
	v_mov_b32_e32 v58, v149
	s_nop 1
	v_permlane16_swap_b32_e32 v52, v58
	s_waitcnt lgkmcnt(0)
	v_mov_b32_e32 v53, v146
	v_mov_b32_e32 v59, v150
	s_nop 1
	v_permlane16_swap_b32_e32 v53, v59
	s_waitcnt lgkmcnt(0)
	v_mov_b32_e32 v54, v147
	v_mov_b32_e32 v55, v151
	s_nop 1
	v_permlane16_swap_b32_e32 v54, v55
	v_cvt_pk_bf16_f32 v52, v56, v52
	v_cvt_pk_bf16_f32 v53, v53, v54
	v_cvt_pk_bf16_f32 v54, v57, v58
	v_cvt_pk_bf16_f32 v55, v59, v55
	global_store_dwordx4 v[162:163], v[52:55], off
	s_nop 1
	v_cndmask_b32_e64 v52, 0, 1, s[48:49]
	v_cmp_ne_u32_e64 s[44:45], 1, v52
	s_mov_b64 s[48:49], -1
	s_cbranch_vccnz .LBB0_1099
	v_mov_b64_e32 v[142:143], v[138:139]
	v_mov_b64_e32 v[134:135], v[130:131]
	s_and_b64 vcc, exec, s[40:41]
	v_mov_b64_e32 v[140:141], v[136:137]
	v_mov_b64_e32 v[132:133], v[128:129]
	s_cbranch_vccnz .LBB0_1098
	v_mul_f32_e32 v53, 0xbfb8aa3b, v136
	v_mul_f32_e32 v54, 0xbfb8aa3b, v129
	v_exp_f32_e32 v53, v53
	v_exp_f32_e32 v55, v54
	v_mul_f32_e32 v57, 0xbfb8aa3b, v138
	v_mul_f32_e32 v58, 0xbfb8aa3b, v131
	v_add_f32_e32 v53, 1.0, v53
	v_mul_f32_e32 v52, 0xbfb8aa3b, v128
	v_rcp_f32_e32 v54, v53
	v_add_f32_e32 v53, 1.0, v55
	v_mul_f32_e32 v55, 0xbfb8aa3b, v137
	v_mul_f32_e32 v56, 0xbfb8aa3b, v130
	v_exp_f32_e32 v57, v57
	v_exp_f32_e32 v59, v58
	v_mul_f32_e32 v58, 0xbfb8aa3b, v139
	v_exp_f32_e32 v52, v52
	v_exp_f32_e32 v55, v55
	v_exp_f32_e32 v56, v56
	v_exp_f32_e32 v132, v58
	v_add_f32_e32 v57, 1.0, v57
	v_add_f32_e32 v52, 1.0, v52
	v_add_f32_e32 v55, 1.0, v55
	v_add_f32_e32 v56, 1.0, v56
	v_rcp_f32_e32 v58, v57
	v_add_f32_e32 v57, 1.0, v59
	v_add_f32_e32 v59, 1.0, v132
	v_rcp_f32_e32 v52, v52
	v_rcp_f32_e32 v53, v53
	v_rcp_f32_e32 v56, v56
	v_rcp_f32_e32 v57, v57
	v_rcp_f32_e32 v59, v59
	v_rcp_f32_e32 v55, v55
	v_pk_mul_f32 v[132:133], v[128:129], v[52:53]
	v_pk_mul_f32 v[134:135], v[130:131], v[56:57]
	v_pk_mul_f32 v[142:143], v[138:139], v[58:59]
	v_pk_mul_f32 v[140:141], v[136:137], v[54:55]

.LBB0_1101:
	s_nop 0
	v_mov_b64_e32 v[138:139], v[98:99]
	s_waitcnt lgkmcnt(0)
	v_mov_b32_e32 v56, v132
	v_mov_b32_e32 v57, v140
	s_nop 1
	v_permlane16_swap_b32_e32 v56, v57
	s_waitcnt lgkmcnt(0)
	v_mov_b32_e32 v52, v133
	v_mov_b32_e32 v58, v141
	s_nop 1
	v_permlane16_swap_b32_e32 v52, v58
	s_waitcnt lgkmcnt(0)
	v_mov_b32_e32 v53, v134
	v_mov_b32_e32 v59, v142
	s_nop 1
	v_permlane16_swap_b32_e32 v53, v59
	s_waitcnt lgkmcnt(0)
	v_mov_b32_e32 v54, v135
	v_mov_b32_e32 v55, v143
	s_nop 1
	v_permlane16_swap_b32_e32 v54, v55
	v_mov_b64_e32 v[130:131], v[102:103]
	v_mov_b64_e32 v[142:143], v[106:107]
	v_mov_b64_e32 v[134:135], v[110:111]
	v_cvt_pk_bf16_f32 v52, v56, v52
	v_cvt_pk_bf16_f32 v53, v53, v54
	v_cvt_pk_bf16_f32 v54, v57, v58
	v_cvt_pk_bf16_f32 v55, v59, v55
	v_or_b32_e32 v146, 16, v170
	v_mov_b64_e32 v[136:137], v[96:97]
	v_mov_b64_e32 v[128:129], v[100:101]
	v_mov_b64_e32 v[140:141], v[104:105]
	v_mov_b64_e32 v[132:133], v[108:109]
	global_store_dwordx4 v[162:163], v[52:55], off offset:64
	s_and_saveexec_b64 s[48:49], s[22:23]
	s_cbranch_execz .LBB0_1103
	v_or_b32_e32 v52, v168, v146
	v_lshlrev_b32_e32 v52, 7, v52
	v_mov_b32_e32 v53, v177
	v_lshl_add_u64 v[136:137], v[154:155], 0, v[52:53]
	v_lshl_add_u64 v[140:141], v[152:153], 0, v[52:53]
	global_load_dwordx4 v[52:55], v[136:137], off
	global_load_dwordx4 v[56:59], v[140:141], off
	v_mov_b32_e32 v132, v111
	v_mov_b32_e32 v133, v103
	s_waitcnt vmcnt(1)
	v_mul_f32_e32 v130, v110, v54
	s_waitcnt vmcnt(0)
	v_mul_f32_e32 v134, v102, v58
	v_mul_f32_e32 v138, v110, v58
	v_mov_b32_e32 v58, v55
	v_pk_mul_f32 v[128:129], v[108:109], v[56:57]
	v_pk_mul_f32 v[56:57], v[100:101], v[56:57]
	v_pk_mul_f32 v[132:133], v[132:133], v[58:59]
	v_mul_f32_e32 v54, v102, v54
	v_mov_b32_e32 v131, v132
	v_mov_b32_e32 v135, v133
	v_pk_fma_f32 v[132:133], v[108:109], v[52:53], v[56:57] neg_lo:[0,0,1] neg_hi:[0,0,1]
	v_mov_b32_e32 v56, v103
	v_mov_b32_e32 v57, v111
	v_pk_mul_f32 v[56:57], v[56:57], v[58:59]
	v_pk_add_f32 v[134:135], v[130:131], v[134:135] neg_lo:[0,1] neg_hi:[0,1]
	v_mov_b32_e32 v55, v56
	v_mov_b32_e32 v139, v57
	v_pk_fma_f32 v[128:129], v[100:101], v[52:53], v[128:129]
	v_pk_add_f32 v[130:131], v[54:55], v[138:139]
	global_load_dwordx4 v[136:139], v[136:137], off offset:64
	s_nop 0
	global_load_dwordx4 v[52:55], v[140:141], off offset:64
	v_mov_b32_e32 v140, v107
	v_mov_b32_e32 v141, v99
	s_waitcnt vmcnt(1)
	v_mul_f32_e32 v58, v106, v138
	s_waitcnt vmcnt(0)
	v_mul_f32_e32 v142, v98, v54
	v_mul_f32_e32 v144, v106, v54
	v_mov_b32_e32 v54, v139
	v_pk_mul_f32 v[56:57], v[104:105], v[52:53]
	v_pk_mul_f32 v[52:53], v[96:97], v[52:53]
	v_pk_mul_f32 v[140:141], v[140:141], v[54:55]
	v_mul_f32_e32 v138, v98, v138
	v_mov_b32_e32 v59, v140
	v_mov_b32_e32 v143, v141
	v_pk_fma_f32 v[140:141], v[104:105], v[136:137], v[52:53] neg_lo:[0,0,1] neg_hi:[0,0,1]
	v_mov_b32_e32 v52, v99
	v_mov_b32_e32 v53, v107
	v_pk_mul_f32 v[52:53], v[52:53], v[54:55]
	v_pk_add_f32 v[142:143], v[58:59], v[142:143] neg_lo:[0,1] neg_hi:[0,1]
	v_mov_b32_e32 v139, v52
	v_mov_b32_e32 v145, v53
	v_pk_fma_f32 v[136:137], v[96:97], v[136:137], v[56:57]
	v_pk_add_f32 v[138:139], v[138:139], v[144:145]

.LBB0_1123:
	v_lshlrev_b32_e32 v52, 4, v178
	v_lshlrev_b32_e32 v162, 1, v52
	v_mov_b32_e32 v163, v177
	v_lshl_add_u64 v[52:53], v[164:165], 0, v[162:163]
	v_mov_b32_e32 v161, v177
	v_lshl_add_u64 v[164:165], v[52:53], 0, v[160:161]
	s_and_b64 vcc, exec, s[44:45]
	s_waitcnt lgkmcnt(0)
	v_mov_b32_e32 v56, v144
	v_mov_b32_e32 v57, v148
	s_nop 1
	v_permlane16_swap_b32_e32 v56, v57
	s_waitcnt lgkmcnt(0)
	v_mov_b32_e32 v52, v145
	v_mov_b32_e32 v58, v149
	s_nop 1
	v_permlane16_swap_b32_e32 v52, v58
	s_waitcnt lgkmcnt(0)
	v_mov_b32_e32 v53, v146
	v_mov_b32_e32 v59, v150
	s_nop 1
	v_permlane16_swap_b32_e32 v53, v59
	s_waitcnt lgkmcnt(0)
	v_mov_b32_e32 v54, v147
	v_mov_b32_e32 v55, v151
	s_nop 1
	v_permlane16_swap_b32_e32 v54, v55
	v_cvt_pk_bf16_f32 v52, v56, v52
	v_cvt_pk_bf16_f32 v53, v53, v54
	v_cvt_pk_bf16_f32 v54, v57, v58
	v_cvt_pk_bf16_f32 v55, v59, v55
	s_mov_b64 s[48:49], -1
	global_store_dwordx4 v[164:165], v[52:55], off
	s_cbranch_vccnz .LBB0_1127
	v_mov_b64_e32 v[142:143], v[138:139]
	v_mov_b64_e32 v[134:135], v[130:131]
	s_and_b64 vcc, exec, s[40:41]
	v_mov_b64_e32 v[140:141], v[136:137]
	v_mov_b64_e32 v[132:133], v[128:129]
	s_cbranch_vccnz .LBB0_1126
	v_mul_f32_e32 v53, 0xbfb8aa3b, v136
	v_mul_f32_e32 v54, 0xbfb8aa3b, v129
	v_exp_f32_e32 v53, v53
	v_exp_f32_e32 v55, v54
	v_mul_f32_e32 v57, 0xbfb8aa3b, v138
	v_mul_f32_e32 v58, 0xbfb8aa3b, v131
	v_add_f32_e32 v53, 1.0, v53
	v_mul_f32_e32 v52, 0xbfb8aa3b, v128
	v_rcp_f32_e32 v54, v53
	v_add_f32_e32 v53, 1.0, v55
	v_mul_f32_e32 v55, 0xbfb8aa3b, v137
	v_mul_f32_e32 v56, 0xbfb8aa3b, v130
	v_exp_f32_e32 v57, v57
	v_exp_f32_e32 v59, v58
	v_mul_f32_e32 v58, 0xbfb8aa3b, v139
	v_exp_f32_e32 v52, v52
	v_exp_f32_e32 v55, v55
	v_exp_f32_e32 v56, v56
	v_exp_f32_e32 v132, v58
	v_add_f32_e32 v57, 1.0, v57
	v_add_f32_e32 v52, 1.0, v52
	v_add_f32_e32 v55, 1.0, v55
	v_add_f32_e32 v56, 1.0, v56
	v_rcp_f32_e32 v58, v57
	v_add_f32_e32 v57, 1.0, v59
	v_add_f32_e32 v59, 1.0, v132
	v_rcp_f32_e32 v52, v52
	v_rcp_f32_e32 v53, v53
	v_rcp_f32_e32 v56, v56
	v_rcp_f32_e32 v57, v57
	v_rcp_f32_e32 v59, v59
	v_rcp_f32_e32 v55, v55
	v_pk_mul_f32 v[132:133], v[128:129], v[52:53]
	v_pk_mul_f32 v[134:135], v[130:131], v[56:57]
	v_pk_mul_f32 v[142:143], v[138:139], v[58:59]
	v_pk_mul_f32 v[140:141], v[136:137], v[54:55]

.LBB0_1129:
	s_nop 0
	v_mov_b64_e32 v[138:139], v[82:83]
	s_waitcnt lgkmcnt(0)
	v_mov_b32_e32 v56, v132
	v_mov_b32_e32 v57, v140
	s_nop 1
	v_permlane16_swap_b32_e32 v56, v57
	s_waitcnt lgkmcnt(0)
	v_mov_b32_e32 v52, v133
	v_mov_b32_e32 v58, v141
	s_nop 1
	v_permlane16_swap_b32_e32 v52, v58
	s_waitcnt lgkmcnt(0)
	v_mov_b32_e32 v53, v134
	v_mov_b32_e32 v59, v142
	s_nop 1
	v_permlane16_swap_b32_e32 v53, v59
	s_waitcnt lgkmcnt(0)
	v_mov_b32_e32 v54, v135
	v_mov_b32_e32 v55, v143
	s_nop 1
	v_permlane16_swap_b32_e32 v54, v55
	v_mov_b64_e32 v[130:131], v[86:87]
	v_mov_b64_e32 v[142:143], v[90:91]
	v_mov_b64_e32 v[134:135], v[94:95]
	v_cvt_pk_bf16_f32 v52, v56, v52
	v_cvt_pk_bf16_f32 v53, v53, v54
	v_cvt_pk_bf16_f32 v54, v57, v58
	v_cvt_pk_bf16_f32 v55, v59, v55
	v_or_b32_e32 v146, 32, v170
	v_mov_b64_e32 v[136:137], v[80:81]
	v_mov_b64_e32 v[128:129], v[84:85]
	v_mov_b64_e32 v[140:141], v[88:89]
	v_mov_b64_e32 v[132:133], v[92:93]
	global_store_dwordx4 v[164:165], v[52:55], off offset:64
	s_and_saveexec_b64 s[48:49], s[22:23]
	s_cbranch_execz .LBB0_1131
	v_or_b32_e32 v52, v168, v146
	v_lshlrev_b32_e32 v52, 7, v52
	v_mov_b32_e32 v53, v177
	v_lshl_add_u64 v[136:137], v[154:155], 0, v[52:53]
	v_lshl_add_u64 v[140:141], v[152:153], 0, v[52:53]
	global_load_dwordx4 v[52:55], v[136:137], off
	global_load_dwordx4 v[56:59], v[140:141], off
	v_mov_b32_e32 v132, v95
	v_mov_b32_e32 v133, v87
	s_waitcnt vmcnt(1)
	v_mul_f32_e32 v130, v94, v54
	s_waitcnt vmcnt(0)
	v_mul_f32_e32 v134, v86, v58
	v_mul_f32_e32 v138, v94, v58
	v_mov_b32_e32 v58, v55
	v_pk_mul_f32 v[128:129], v[92:93], v[56:57]
	v_pk_mul_f32 v[56:57], v[84:85], v[56:57]
	v_pk_mul_f32 v[132:133], v[132:133], v[58:59]
	v_mul_f32_e32 v54, v86, v54
	v_mov_b32_e32 v131, v132
	v_mov_b32_e32 v135, v133
	v_pk_fma_f32 v[132:133], v[92:93], v[52:53], v[56:57] neg_lo:[0,0,1] neg_hi:[0,0,1]
	v_mov_b32_e32 v56, v87
	v_mov_b32_e32 v57, v95
	v_pk_mul_f32 v[56:57], v[56:57], v[58:59]
	v_pk_add_f32 v[134:135], v[130:131], v[134:135] neg_lo:[0,1] neg_hi:[0,1]
	v_mov_b32_e32 v55, v56
	v_mov_b32_e32 v139, v57
	v_pk_fma_f32 v[128:129], v[84:85], v[52:53], v[128:129]
	v_pk_add_f32 v[130:131], v[54:55], v[138:139]
	global_load_dwordx4 v[136:139], v[136:137], off offset:64
	s_nop 0
	global_load_dwordx4 v[52:55], v[140:141], off offset:64
	v_mov_b32_e32 v140, v91
	v_mov_b32_e32 v141, v83
	s_waitcnt vmcnt(1)
	v_mul_f32_e32 v58, v90, v138
	s_waitcnt vmcnt(0)
	v_mul_f32_e32 v142, v82, v54
	v_mul_f32_e32 v144, v90, v54
	v_mov_b32_e32 v54, v139
	v_pk_mul_f32 v[56:57], v[88:89], v[52:53]
	v_pk_mul_f32 v[52:53], v[80:81], v[52:53]
	v_pk_mul_f32 v[140:141], v[140:141], v[54:55]
	v_mul_f32_e32 v138, v82, v138
	v_mov_b32_e32 v59, v140
	v_mov_b32_e32 v143, v141
	v_pk_fma_f32 v[140:141], v[88:89], v[136:137], v[52:53] neg_lo:[0,0,1] neg_hi:[0,0,1]
	v_mov_b32_e32 v52, v83
	v_mov_b32_e32 v53, v91
	v_pk_mul_f32 v[52:53], v[52:53], v[54:55]
	v_pk_add_f32 v[142:143], v[58:59], v[142:143] neg_lo:[0,1] neg_hi:[0,1]
	v_mov_b32_e32 v139, v52
	v_mov_b32_e32 v145, v53
	v_pk_fma_f32 v[136:137], v[80:81], v[136:137], v[56:57]
	v_pk_add_f32 v[138:139], v[138:139], v[144:145]

.LBB0_1151:
	v_mov_b32_e32 v163, v177
	v_lshl_add_u64 v[52:53], v[164:165], 0, v[162:163]
	v_mov_b32_e32 v161, v177
	v_lshl_add_u64 v[164:165], v[52:53], 0, v[160:161]
	s_and_b64 vcc, exec, s[44:45]
	s_waitcnt lgkmcnt(0)
	v_mov_b32_e32 v56, v144
	v_mov_b32_e32 v57, v148
	s_nop 1
	v_permlane16_swap_b32_e32 v56, v57
	s_waitcnt lgkmcnt(0)
	v_mov_b32_e32 v52, v145
	v_mov_b32_e32 v58, v149
	s_nop 1
	v_permlane16_swap_b32_e32 v52, v58
	s_waitcnt lgkmcnt(0)
	v_mov_b32_e32 v53, v146
	v_mov_b32_e32 v59, v150
	s_nop 1
	v_permlane16_swap_b32_e32 v53, v59
	s_waitcnt lgkmcnt(0)
	v_mov_b32_e32 v54, v147
	v_mov_b32_e32 v55, v151
	s_nop 1
	v_permlane16_swap_b32_e32 v54, v55
	v_cvt_pk_bf16_f32 v52, v56, v52
	v_cvt_pk_bf16_f32 v53, v53, v54
	v_cvt_pk_bf16_f32 v54, v57, v58
	v_cvt_pk_bf16_f32 v55, v59, v55
	s_mov_b64 s[48:49], -1
	global_store_dwordx4 v[164:165], v[52:55], off
	s_cbranch_vccnz .LBB0_1155
	v_mov_b64_e32 v[142:143], v[138:139]
	v_mov_b64_e32 v[134:135], v[130:131]
	s_and_b64 vcc, exec, s[40:41]
	v_mov_b64_e32 v[140:141], v[136:137]
	v_mov_b64_e32 v[132:133], v[128:129]
	s_cbranch_vccnz .LBB0_1154
	v_mul_f32_e32 v53, 0xbfb8aa3b, v136
	v_mul_f32_e32 v54, 0xbfb8aa3b, v129
	v_exp_f32_e32 v53, v53
	v_exp_f32_e32 v55, v54
	v_mul_f32_e32 v57, 0xbfb8aa3b, v138
	v_mul_f32_e32 v58, 0xbfb8aa3b, v131
	v_add_f32_e32 v53, 1.0, v53
	v_mul_f32_e32 v52, 0xbfb8aa3b, v128
	v_rcp_f32_e32 v54, v53
	v_add_f32_e32 v53, 1.0, v55
	v_mul_f32_e32 v55, 0xbfb8aa3b, v137
	v_mul_f32_e32 v56, 0xbfb8aa3b, v130
	v_exp_f32_e32 v57, v57
	v_exp_f32_e32 v59, v58
	v_mul_f32_e32 v58, 0xbfb8aa3b, v139
	v_exp_f32_e32 v52, v52
	v_exp_f32_e32 v55, v55
	v_exp_f32_e32 v56, v56
	v_exp_f32_e32 v132, v58
	v_add_f32_e32 v57, 1.0, v57
	v_add_f32_e32 v52, 1.0, v52
	v_add_f32_e32 v55, 1.0, v55
	v_add_f32_e32 v56, 1.0, v56
	v_rcp_f32_e32 v58, v57
	v_add_f32_e32 v57, 1.0, v59
	v_add_f32_e32 v59, 1.0, v132
	v_rcp_f32_e32 v52, v52
	v_rcp_f32_e32 v53, v53
	v_rcp_f32_e32 v56, v56
	v_rcp_f32_e32 v57, v57
	v_rcp_f32_e32 v59, v59
	v_rcp_f32_e32 v55, v55
	v_pk_mul_f32 v[132:133], v[128:129], v[52:53]
	v_pk_mul_f32 v[134:135], v[130:131], v[56:57]
	v_pk_mul_f32 v[142:143], v[138:139], v[58:59]
	v_pk_mul_f32 v[140:141], v[136:137], v[54:55]

.LBB0_1157:
	s_nop 0
	v_mov_b64_e32 v[138:139], v[66:67]
	s_waitcnt lgkmcnt(0)
	v_mov_b32_e32 v56, v132
	v_mov_b32_e32 v57, v140
	s_nop 1
	v_permlane16_swap_b32_e32 v56, v57
	s_waitcnt lgkmcnt(0)
	v_mov_b32_e32 v52, v133
	v_mov_b32_e32 v58, v141
	s_nop 1
	v_permlane16_swap_b32_e32 v52, v58
	s_waitcnt lgkmcnt(0)
	v_mov_b32_e32 v53, v134
	v_mov_b32_e32 v59, v142
	s_nop 1
	v_permlane16_swap_b32_e32 v53, v59
	s_waitcnt lgkmcnt(0)
	v_mov_b32_e32 v54, v135
	v_mov_b32_e32 v55, v143
	s_nop 1
	v_permlane16_swap_b32_e32 v54, v55
	v_mov_b64_e32 v[130:131], v[70:71]
	v_mov_b64_e32 v[142:143], v[74:75]
	v_mov_b64_e32 v[134:135], v[78:79]
	v_cvt_pk_bf16_f32 v52, v56, v52
	v_cvt_pk_bf16_f32 v53, v53, v54
	v_cvt_pk_bf16_f32 v54, v57, v58
	v_cvt_pk_bf16_f32 v55, v59, v55
	v_or_b32_e32 v146, 48, v170
	v_mov_b64_e32 v[136:137], v[64:65]
	v_mov_b64_e32 v[128:129], v[68:69]
	v_mov_b64_e32 v[140:141], v[72:73]
	v_mov_b64_e32 v[132:133], v[76:77]
	global_store_dwordx4 v[164:165], v[52:55], off offset:64
	s_and_saveexec_b64 s[48:49], s[22:23]
	s_cbranch_execz .LBB0_1159
	v_or_b32_e32 v52, v168, v146
	v_lshlrev_b32_e32 v52, 7, v52
	v_mov_b32_e32 v53, v177
	v_lshl_add_u64 v[136:137], v[154:155], 0, v[52:53]
	v_lshl_add_u64 v[140:141], v[152:153], 0, v[52:53]
	global_load_dwordx4 v[52:55], v[136:137], off
	global_load_dwordx4 v[56:59], v[140:141], off
	v_mov_b32_e32 v132, v79
	v_mov_b32_e32 v133, v71
	s_waitcnt vmcnt(1)
	v_mul_f32_e32 v130, v78, v54
	s_waitcnt vmcnt(0)
	v_mul_f32_e32 v134, v70, v58
	v_mul_f32_e32 v138, v78, v58
	v_mov_b32_e32 v58, v55
	v_pk_mul_f32 v[128:129], v[76:77], v[56:57]
	v_pk_mul_f32 v[56:57], v[68:69], v[56:57]
	v_pk_mul_f32 v[132:133], v[132:133], v[58:59]
	v_mul_f32_e32 v54, v70, v54
	v_mov_b32_e32 v131, v132
	v_mov_b32_e32 v135, v133
	v_pk_fma_f32 v[132:133], v[76:77], v[52:53], v[56:57] neg_lo:[0,0,1] neg_hi:[0,0,1]
	v_mov_b32_e32 v56, v71
	v_mov_b32_e32 v57, v79
	v_pk_mul_f32 v[56:57], v[56:57], v[58:59]
	v_pk_add_f32 v[134:135], v[130:131], v[134:135] neg_lo:[0,1] neg_hi:[0,1]
	v_mov_b32_e32 v55, v56
	v_mov_b32_e32 v139, v57
	v_pk_fma_f32 v[128:129], v[68:69], v[52:53], v[128:129]
	v_pk_add_f32 v[130:131], v[54:55], v[138:139]
	global_load_dwordx4 v[136:139], v[136:137], off offset:64
	s_nop 0
	global_load_dwordx4 v[52:55], v[140:141], off offset:64
	v_mov_b32_e32 v140, v75
	v_mov_b32_e32 v141, v67
	s_waitcnt vmcnt(1)
	v_mul_f32_e32 v58, v74, v138
	s_waitcnt vmcnt(0)
	v_mul_f32_e32 v142, v66, v54
	v_mul_f32_e32 v144, v74, v54
	v_mov_b32_e32 v54, v139
	v_pk_mul_f32 v[56:57], v[72:73], v[52:53]
	v_pk_mul_f32 v[52:53], v[64:65], v[52:53]
	v_pk_mul_f32 v[140:141], v[140:141], v[54:55]
	v_mul_f32_e32 v138, v66, v138
	v_mov_b32_e32 v59, v140
	v_mov_b32_e32 v143, v141
	v_pk_fma_f32 v[140:141], v[72:73], v[136:137], v[52:53] neg_lo:[0,0,1] neg_hi:[0,0,1]
	v_mov_b32_e32 v52, v67
	v_mov_b32_e32 v53, v75
	v_pk_mul_f32 v[52:53], v[52:53], v[54:55]
	v_pk_add_f32 v[142:143], v[58:59], v[142:143] neg_lo:[0,1] neg_hi:[0,1]
	v_mov_b32_e32 v139, v52
	v_mov_b32_e32 v145, v53
	v_pk_fma_f32 v[136:137], v[64:65], v[136:137], v[56:57]
	v_pk_add_f32 v[138:139], v[138:139], v[144:145]

.LBB0_1185:
	s_nop 0
	v_mov_b64_e32 v[138:139], v[50:51]
	s_waitcnt lgkmcnt(0)
	v_mov_b32_e32 v56, v132
	v_mov_b32_e32 v57, v140
	s_nop 1
	v_permlane16_swap_b32_e32 v56, v57
	s_waitcnt lgkmcnt(0)
	v_mov_b32_e32 v52, v133
	v_mov_b32_e32 v58, v141
	s_nop 1
	v_permlane16_swap_b32_e32 v52, v58
	s_waitcnt lgkmcnt(0)
	v_mov_b32_e32 v53, v134
	v_mov_b32_e32 v59, v142
	s_nop 1
	v_permlane16_swap_b32_e32 v53, v59
	s_waitcnt lgkmcnt(0)
	v_mov_b32_e32 v54, v135
	v_mov_b32_e32 v55, v143
	s_nop 1
	v_permlane16_swap_b32_e32 v54, v55
	v_mov_b64_e32 v[128:129], v[180:181]
	v_mov_b64_e32 v[140:141], v[184:185]
	v_mov_b64_e32 v[134:135], v[62:63]
	v_cvt_pk_bf16_f32 v52, v56, v52
	v_cvt_pk_bf16_f32 v53, v53, v54
	v_cvt_pk_bf16_f32 v54, v57, v58
	v_cvt_pk_bf16_f32 v55, v59, v55
	v_or_b32_e32 v146, 64, v170
	v_mov_b64_e32 v[136:137], v[48:49]
	v_mov_b64_e32 v[130:131], v[182:183]
	v_mov_b64_e32 v[142:143], v[186:187]
	v_mov_b64_e32 v[132:133], v[60:61]
	global_store_dwordx4 v[164:165], v[52:55], off offset:64
	s_and_saveexec_b64 s[48:49], s[22:23]
	s_cbranch_execz .LBB0_1187
	v_or_b32_e32 v52, v168, v146
	v_lshlrev_b32_e32 v52, 7, v52
	v_mov_b32_e32 v53, v177
	v_lshl_add_u64 v[136:137], v[154:155], 0, v[52:53]
	v_lshl_add_u64 v[140:141], v[152:153], 0, v[52:53]
	global_load_dwordx4 v[52:55], v[136:137], off
	global_load_dwordx4 v[56:59], v[140:141], off
	v_mov_b32_e32 v132, v63
	v_mov_b32_e32 v133, v183
	s_waitcnt vmcnt(1)
	v_mul_f32_e32 v130, v62, v54
	s_waitcnt vmcnt(0)
	v_mul_f32_e32 v134, v182, v58
	v_mul_f32_e32 v138, v62, v58
	v_mov_b32_e32 v58, v55
	v_pk_mul_f32 v[128:129], v[60:61], v[56:57]
	v_pk_mul_f32 v[56:57], v[180:181], v[56:57]
	v_pk_mul_f32 v[132:133], v[132:133], v[58:59]
	v_mul_f32_e32 v54, v182, v54
	v_mov_b32_e32 v131, v132
	v_mov_b32_e32 v135, v133
	v_pk_fma_f32 v[132:133], v[60:61], v[52:53], v[56:57] neg_lo:[0,0,1] neg_hi:[0,0,1]
	v_mov_b32_e32 v56, v183
	v_mov_b32_e32 v57, v63
	v_pk_mul_f32 v[56:57], v[56:57], v[58:59]
	v_pk_add_f32 v[134:135], v[130:131], v[134:135] neg_lo:[0,1] neg_hi:[0,1]
	v_mov_b32_e32 v55, v56
	v_mov_b32_e32 v139, v57
	v_pk_fma_f32 v[128:129], v[180:181], v[52:53], v[128:129]
	v_pk_add_f32 v[130:131], v[54:55], v[138:139]
	global_load_dwordx4 v[136:139], v[136:137], off offset:64
	s_nop 0
	global_load_dwordx4 v[52:55], v[140:141], off offset:64
	v_mov_b32_e32 v140, v187
	v_mov_b32_e32 v141, v51
	s_waitcnt vmcnt(1)
	v_mul_f32_e32 v58, v186, v138
	s_waitcnt vmcnt(0)
	v_mul_f32_e32 v142, v50, v54
	v_mul_f32_e32 v144, v186, v54
	v_mov_b32_e32 v54, v139
	v_pk_mul_f32 v[56:57], v[184:185], v[52:53]
	v_pk_mul_f32 v[52:53], v[48:49], v[52:53]
	v_pk_mul_f32 v[140:141], v[140:141], v[54:55]
	v_mul_f32_e32 v138, v50, v138
	v_mov_b32_e32 v59, v140
	v_mov_b32_e32 v143, v141
	v_pk_fma_f32 v[140:141], v[184:185], v[136:137], v[52:53] neg_lo:[0,0,1] neg_hi:[0,0,1]
	v_mov_b32_e32 v52, v51
	v_mov_b32_e32 v53, v187
	v_pk_mul_f32 v[52:53], v[52:53], v[54:55]
	v_pk_add_f32 v[142:143], v[58:59], v[142:143] neg_lo:[0,1] neg_hi:[0,1]
	v_mov_b32_e32 v139, v52
	v_mov_b32_e32 v145, v53
	v_pk_fma_f32 v[136:137], v[48:49], v[136:137], v[56:57]
	v_pk_add_f32 v[138:139], v[138:139], v[144:145]

.LBB0_1213:
	s_nop 0
	v_mov_b64_e32 v[138:139], v[34:35]
	s_waitcnt lgkmcnt(0)
	v_mov_b32_e32 v56, v132
	v_mov_b32_e32 v57, v140
	s_nop 1
	v_permlane16_swap_b32_e32 v56, v57
	s_waitcnt lgkmcnt(0)
	v_mov_b32_e32 v52, v133
	v_mov_b32_e32 v58, v141
	s_nop 1
	v_permlane16_swap_b32_e32 v52, v58
	s_waitcnt lgkmcnt(0)
	v_mov_b32_e32 v53, v134
	v_mov_b32_e32 v59, v142
	s_nop 1
	v_permlane16_swap_b32_e32 v53, v59
	s_waitcnt lgkmcnt(0)
	v_mov_b32_e32 v54, v135
	v_mov_b32_e32 v55, v143
	s_nop 1
	v_permlane16_swap_b32_e32 v54, v55
	v_mov_b64_e32 v[130:131], v[38:39]
	v_mov_b64_e32 v[142:143], v[42:43]
	v_mov_b64_e32 v[134:135], v[46:47]
	v_cvt_pk_bf16_f32 v52, v56, v52
	v_cvt_pk_bf16_f32 v53, v53, v54
	v_cvt_pk_bf16_f32 v54, v57, v58
	v_cvt_pk_bf16_f32 v55, v59, v55
	v_or_b32_e32 v146, 0x50, v170
	v_mov_b64_e32 v[136:137], v[32:33]
	v_mov_b64_e32 v[128:129], v[36:37]
	v_mov_b64_e32 v[140:141], v[40:41]
	v_mov_b64_e32 v[132:133], v[44:45]
	global_store_dwordx4 v[164:165], v[52:55], off offset:64
	s_and_saveexec_b64 s[48:49], s[22:23]
	s_cbranch_execz .LBB0_1215
	v_or_b32_e32 v52, v168, v146
	v_lshlrev_b32_e32 v52, 7, v52
	v_mov_b32_e32 v53, v177
	v_lshl_add_u64 v[136:137], v[154:155], 0, v[52:53]
	v_lshl_add_u64 v[140:141], v[152:153], 0, v[52:53]
	global_load_dwordx4 v[52:55], v[136:137], off
	global_load_dwordx4 v[56:59], v[140:141], off
	v_mov_b32_e32 v132, v47
	v_mov_b32_e32 v133, v39
	s_waitcnt vmcnt(1)
	v_mul_f32_e32 v130, v46, v54
	s_waitcnt vmcnt(0)
	v_mul_f32_e32 v134, v38, v58
	v_mul_f32_e32 v138, v46, v58
	v_mov_b32_e32 v58, v55
	v_pk_mul_f32 v[128:129], v[44:45], v[56:57]
	v_pk_mul_f32 v[56:57], v[36:37], v[56:57]
	v_pk_mul_f32 v[132:133], v[132:133], v[58:59]
	v_mul_f32_e32 v54, v38, v54
	v_mov_b32_e32 v131, v132
	v_mov_b32_e32 v135, v133
	v_pk_fma_f32 v[132:133], v[44:45], v[52:53], v[56:57] neg_lo:[0,0,1] neg_hi:[0,0,1]
	v_mov_b32_e32 v56, v39
	v_mov_b32_e32 v57, v47
	v_pk_mul_f32 v[56:57], v[56:57], v[58:59]
	v_pk_add_f32 v[134:135], v[130:131], v[134:135] neg_lo:[0,1] neg_hi:[0,1]
	v_mov_b32_e32 v55, v56
	v_mov_b32_e32 v139, v57
	v_pk_fma_f32 v[128:129], v[36:37], v[52:53], v[128:129]
	v_pk_add_f32 v[130:131], v[54:55], v[138:139]
	global_load_dwordx4 v[136:139], v[136:137], off offset:64
	s_nop 0
	global_load_dwordx4 v[52:55], v[140:141], off offset:64
	v_mov_b32_e32 v140, v43
	v_mov_b32_e32 v141, v35
	s_waitcnt vmcnt(1)
	v_mul_f32_e32 v58, v42, v138
	s_waitcnt vmcnt(0)
	v_mul_f32_e32 v142, v34, v54
	v_mul_f32_e32 v144, v42, v54
	v_mov_b32_e32 v54, v139
	v_pk_mul_f32 v[56:57], v[40:41], v[52:53]
	v_pk_mul_f32 v[52:53], v[32:33], v[52:53]
	v_pk_mul_f32 v[140:141], v[140:141], v[54:55]
	v_mul_f32_e32 v138, v34, v138
	v_mov_b32_e32 v59, v140
	v_mov_b32_e32 v143, v141
	v_pk_fma_f32 v[140:141], v[40:41], v[136:137], v[52:53] neg_lo:[0,0,1] neg_hi:[0,0,1]
	v_mov_b32_e32 v52, v35
	v_mov_b32_e32 v53, v43
	v_pk_mul_f32 v[52:53], v[52:53], v[54:55]
	v_pk_add_f32 v[142:143], v[58:59], v[142:143] neg_lo:[0,1] neg_hi:[0,1]
	v_mov_b32_e32 v139, v52
	v_mov_b32_e32 v145, v53
	v_pk_fma_f32 v[136:137], v[32:33], v[136:137], v[56:57]
	v_pk_add_f32 v[138:139], v[138:139], v[144:145]

.LBB0_1241:
	s_nop 0
	v_mov_b64_e32 v[138:139], v[18:19]
	s_waitcnt lgkmcnt(0)
	v_mov_b32_e32 v56, v132
	v_mov_b32_e32 v57, v140
	s_nop 1
	v_permlane16_swap_b32_e32 v56, v57
	s_waitcnt lgkmcnt(0)
	v_mov_b32_e32 v52, v133
	v_mov_b32_e32 v58, v141
	s_nop 1
	v_permlane16_swap_b32_e32 v52, v58
	s_waitcnt lgkmcnt(0)
	v_mov_b32_e32 v53, v134
	v_mov_b32_e32 v59, v142
	s_nop 1
	v_permlane16_swap_b32_e32 v53, v59
	s_waitcnt lgkmcnt(0)
	v_mov_b32_e32 v54, v135
	v_mov_b32_e32 v55, v143
	s_nop 1
	v_permlane16_swap_b32_e32 v54, v55
	v_mov_b64_e32 v[130:131], v[22:23]
	v_mov_b64_e32 v[142:143], v[26:27]
	v_mov_b64_e32 v[134:135], v[30:31]
	v_cvt_pk_bf16_f32 v52, v56, v52
	v_cvt_pk_bf16_f32 v53, v53, v54
	v_cvt_pk_bf16_f32 v54, v57, v58
	v_cvt_pk_bf16_f32 v55, v59, v55
	v_or_b32_e32 v146, 0x60, v170
	v_mov_b64_e32 v[136:137], v[16:17]
	v_mov_b64_e32 v[128:129], v[20:21]
	v_mov_b64_e32 v[140:141], v[24:25]
	v_mov_b64_e32 v[132:133], v[28:29]
	global_store_dwordx4 v[164:165], v[52:55], off offset:64
	s_and_saveexec_b64 s[48:49], s[22:23]
	s_cbranch_execz .LBB0_1243
	v_or_b32_e32 v52, v168, v146
	v_lshlrev_b32_e32 v52, 7, v52
	v_mov_b32_e32 v53, v177
	v_lshl_add_u64 v[136:137], v[154:155], 0, v[52:53]
	v_lshl_add_u64 v[140:141], v[152:153], 0, v[52:53]
	global_load_dwordx4 v[52:55], v[136:137], off
	global_load_dwordx4 v[56:59], v[140:141], off
	v_mov_b32_e32 v132, v31
	v_mov_b32_e32 v133, v23
	s_waitcnt vmcnt(1)
	v_mul_f32_e32 v130, v30, v54
	s_waitcnt vmcnt(0)
	v_mul_f32_e32 v134, v22, v58
	v_mul_f32_e32 v138, v30, v58
	v_mov_b32_e32 v58, v55
	v_pk_mul_f32 v[128:129], v[28:29], v[56:57]
	v_pk_mul_f32 v[56:57], v[20:21], v[56:57]
	v_pk_mul_f32 v[132:133], v[132:133], v[58:59]
	v_mul_f32_e32 v54, v22, v54
	v_mov_b32_e32 v131, v132
	v_mov_b32_e32 v135, v133
	v_pk_fma_f32 v[132:133], v[28:29], v[52:53], v[56:57] neg_lo:[0,0,1] neg_hi:[0,0,1]
	v_mov_b32_e32 v56, v23
	v_mov_b32_e32 v57, v31
	v_pk_mul_f32 v[56:57], v[56:57], v[58:59]
	v_pk_add_f32 v[134:135], v[130:131], v[134:135] neg_lo:[0,1] neg_hi:[0,1]
	v_mov_b32_e32 v55, v56
	v_mov_b32_e32 v139, v57
	v_pk_fma_f32 v[128:129], v[20:21], v[52:53], v[128:129]
	v_pk_add_f32 v[130:131], v[54:55], v[138:139]
	global_load_dwordx4 v[136:139], v[136:137], off offset:64
	s_nop 0
	global_load_dwordx4 v[52:55], v[140:141], off offset:64
	v_mov_b32_e32 v140, v27
	v_mov_b32_e32 v141, v19
	s_waitcnt vmcnt(1)
	v_mul_f32_e32 v58, v26, v138
	s_waitcnt vmcnt(0)
	v_mul_f32_e32 v142, v18, v54
	v_mul_f32_e32 v144, v26, v54
	v_mov_b32_e32 v54, v139
	v_pk_mul_f32 v[56:57], v[24:25], v[52:53]
	v_pk_mul_f32 v[52:53], v[16:17], v[52:53]
	v_pk_mul_f32 v[140:141], v[140:141], v[54:55]
	v_mul_f32_e32 v138, v18, v138
	v_mov_b32_e32 v59, v140
	v_mov_b32_e32 v143, v141
	v_pk_fma_f32 v[140:141], v[24:25], v[136:137], v[52:53] neg_lo:[0,0,1] neg_hi:[0,0,1]
	v_mov_b32_e32 v52, v19
	v_mov_b32_e32 v53, v27
	v_pk_mul_f32 v[52:53], v[52:53], v[54:55]
	v_pk_add_f32 v[142:143], v[58:59], v[142:143] neg_lo:[0,1] neg_hi:[0,1]
	v_mov_b32_e32 v139, v52
	v_mov_b32_e32 v145, v53
	v_pk_fma_f32 v[136:137], v[16:17], v[136:137], v[56:57]
	v_pk_add_f32 v[138:139], v[138:139], v[144:145]

.LBB0_1269:
	s_nop 0
	v_mov_b64_e32 v[138:139], v[2:3]
	s_waitcnt lgkmcnt(0)
	v_mov_b32_e32 v56, v132
	v_mov_b32_e32 v57, v140
	s_nop 1
	v_permlane16_swap_b32_e32 v56, v57
	s_waitcnt lgkmcnt(0)
	v_mov_b32_e32 v52, v133
	v_mov_b32_e32 v58, v141
	s_nop 1
	v_permlane16_swap_b32_e32 v52, v58
	s_waitcnt lgkmcnt(0)
	v_mov_b32_e32 v53, v134
	v_mov_b32_e32 v59, v142
	s_nop 1
	v_permlane16_swap_b32_e32 v53, v59
	s_waitcnt lgkmcnt(0)
	v_mov_b32_e32 v54, v135
	v_mov_b32_e32 v55, v143
	s_nop 1
	v_permlane16_swap_b32_e32 v54, v55
	v_mov_b64_e32 v[130:131], v[6:7]
	v_mov_b64_e32 v[142:143], v[10:11]
	v_mov_b64_e32 v[134:135], v[14:15]
	v_cvt_pk_bf16_f32 v52, v56, v52
	v_cvt_pk_bf16_f32 v53, v53, v54
	v_cvt_pk_bf16_f32 v54, v57, v58
	v_cvt_pk_bf16_f32 v55, v59, v55
	v_or_b32_e32 v146, 0x70, v170
	v_mov_b64_e32 v[136:137], v[0:1]
	v_mov_b64_e32 v[128:129], v[4:5]
	v_mov_b64_e32 v[140:141], v[8:9]
	v_mov_b64_e32 v[132:133], v[12:13]
	global_store_dwordx4 v[164:165], v[52:55], off offset:64
	s_and_saveexec_b64 s[48:49], s[22:23]
	s_cbranch_execz .LBB0_1271
	v_or_b32_e32 v52, v168, v146
	v_lshlrev_b32_e32 v52, 7, v52
	v_mov_b32_e32 v53, v177
	v_lshl_add_u64 v[136:137], v[154:155], 0, v[52:53]
	v_lshl_add_u64 v[140:141], v[152:153], 0, v[52:53]
	global_load_dwordx4 v[52:55], v[136:137], off
	global_load_dwordx4 v[56:59], v[140:141], off
	v_mov_b32_e32 v132, v15
	v_mov_b32_e32 v133, v7
	s_waitcnt vmcnt(1)
	v_mul_f32_e32 v130, v14, v54
	s_waitcnt vmcnt(0)
	v_mul_f32_e32 v134, v6, v58
	v_mul_f32_e32 v138, v14, v58
	v_mov_b32_e32 v58, v55
	v_pk_mul_f32 v[128:129], v[12:13], v[56:57]
	v_pk_mul_f32 v[56:57], v[4:5], v[56:57]
	v_pk_mul_f32 v[132:133], v[132:133], v[58:59]
	v_mul_f32_e32 v54, v6, v54
	v_mov_b32_e32 v131, v132
	v_mov_b32_e32 v135, v133
	v_pk_fma_f32 v[132:133], v[12:13], v[52:53], v[56:57] neg_lo:[0,0,1] neg_hi:[0,0,1]
	v_mov_b32_e32 v56, v7
	v_mov_b32_e32 v57, v15
	v_pk_mul_f32 v[56:57], v[56:57], v[58:59]
	v_pk_add_f32 v[134:135], v[130:131], v[134:135] neg_lo:[0,1] neg_hi:[0,1]
	v_mov_b32_e32 v55, v56
	v_mov_b32_e32 v139, v57
	v_pk_fma_f32 v[128:129], v[4:5], v[52:53], v[128:129]
	v_pk_add_f32 v[130:131], v[54:55], v[138:139]
	global_load_dwordx4 v[136:139], v[136:137], off offset:64
	s_nop 0
	global_load_dwordx4 v[52:55], v[140:141], off offset:64
	v_mov_b32_e32 v140, v11
	v_mov_b32_e32 v141, v3
	s_waitcnt vmcnt(1)
	v_mul_f32_e32 v58, v10, v138
	s_waitcnt vmcnt(0)
	v_mul_f32_e32 v142, v2, v54
	v_mul_f32_e32 v144, v10, v54
	v_mov_b32_e32 v54, v139
	v_pk_mul_f32 v[56:57], v[8:9], v[52:53]
	v_pk_mul_f32 v[52:53], v[0:1], v[52:53]
	v_pk_mul_f32 v[140:141], v[140:141], v[54:55]
	v_mul_f32_e32 v138, v2, v138
	v_mov_b32_e32 v59, v140
	v_mov_b32_e32 v143, v141
	v_pk_fma_f32 v[140:141], v[8:9], v[136:137], v[52:53] neg_lo:[0,0,1] neg_hi:[0,0,1]
	v_mov_b32_e32 v52, v3
	v_mov_b32_e32 v53, v11
	v_pk_mul_f32 v[52:53], v[52:53], v[54:55]
	v_pk_add_f32 v[142:143], v[58:59], v[142:143] neg_lo:[0,1] neg_hi:[0,1]
	v_mov_b32_e32 v139, v52
	v_mov_b32_e32 v145, v53
	v_pk_fma_f32 v[136:137], v[0:1], v[136:137], v[56:57]
	v_pk_add_f32 v[138:139], v[138:139], v[144:145]

.LBB0_1291:
	v_mov_b32_e32 v163, v177
	v_lshl_add_u64 v[52:53], v[152:153], 0, v[162:163]
	v_mov_b32_e32 v161, v177
	v_lshl_add_u64 v[152:153], v[52:53], 0, v[160:161]
	s_and_b64 vcc, exec, s[44:45]
	s_waitcnt lgkmcnt(0)
	v_mov_b32_e32 v56, v144
	v_mov_b32_e32 v57, v148
	s_nop 1
	v_permlane16_swap_b32_e32 v56, v57
	s_waitcnt lgkmcnt(0)
	v_mov_b32_e32 v52, v145
	v_mov_b32_e32 v58, v149
	s_nop 1
	v_permlane16_swap_b32_e32 v52, v58
	s_waitcnt lgkmcnt(0)
	v_mov_b32_e32 v53, v146
	v_mov_b32_e32 v59, v150
	s_nop 1
	v_permlane16_swap_b32_e32 v53, v59
	s_waitcnt lgkmcnt(0)
	v_mov_b32_e32 v54, v147
	v_mov_b32_e32 v55, v151
	s_nop 1
	v_permlane16_swap_b32_e32 v54, v55
	v_cvt_pk_bf16_f32 v52, v56, v52
	v_cvt_pk_bf16_f32 v53, v53, v54
	v_cvt_pk_bf16_f32 v54, v57, v58
	v_cvt_pk_bf16_f32 v55, v59, v55
	s_mov_b64 s[22:23], -1
	global_store_dwordx4 v[152:153], v[52:55], off
	s_cbranch_vccnz .LBB0_1295
	v_mov_b64_e32 v[142:143], v[138:139]
	v_mov_b64_e32 v[134:135], v[130:131]
	s_and_b64 vcc, exec, s[40:41]
	v_mov_b64_e32 v[140:141], v[136:137]
	v_mov_b64_e32 v[132:133], v[128:129]
	s_cbranch_vccnz .LBB0_1294
	v_mul_f32_e32 v53, 0xbfb8aa3b, v136
	v_mul_f32_e32 v54, 0xbfb8aa3b, v129
	v_exp_f32_e32 v53, v53
	v_exp_f32_e32 v55, v54
	v_mul_f32_e32 v57, 0xbfb8aa3b, v138
	v_mul_f32_e32 v58, 0xbfb8aa3b, v131
	v_add_f32_e32 v53, 1.0, v53
	v_mul_f32_e32 v52, 0xbfb8aa3b, v128
	v_rcp_f32_e32 v54, v53
	v_add_f32_e32 v53, 1.0, v55
	v_mul_f32_e32 v55, 0xbfb8aa3b, v137
	v_mul_f32_e32 v56, 0xbfb8aa3b, v130
	v_exp_f32_e32 v57, v57
	v_exp_f32_e32 v59, v58
	v_mul_f32_e32 v58, 0xbfb8aa3b, v139
	v_exp_f32_e32 v52, v52
	v_exp_f32_e32 v55, v55
	v_exp_f32_e32 v56, v56
	v_exp_f32_e32 v132, v58
	v_add_f32_e32 v57, 1.0, v57
	v_add_f32_e32 v52, 1.0, v52
	v_add_f32_e32 v55, 1.0, v55
	v_add_f32_e32 v56, 1.0, v56
	v_rcp_f32_e32 v58, v57
	v_add_f32_e32 v57, 1.0, v59
	v_add_f32_e32 v59, 1.0, v132
	v_rcp_f32_e32 v52, v52
	v_rcp_f32_e32 v53, v53
	v_rcp_f32_e32 v56, v56
	v_rcp_f32_e32 v57, v57
	v_rcp_f32_e32 v59, v59
	v_rcp_f32_e32 v55, v55
	v_pk_mul_f32 v[132:133], v[128:129], v[52:53]
	v_pk_mul_f32 v[134:135], v[130:131], v[56:57]
	v_pk_mul_f32 v[142:143], v[138:139], v[58:59]
	v_pk_mul_f32 v[140:141], v[136:137], v[54:55]

.LBB0_1297:
	s_nop 0
	s_mov_b64 s[30:31], 0
	s_waitcnt lgkmcnt(0)
	v_mov_b32_e32 v56, v132
	v_mov_b32_e32 v57, v140
	s_nop 1
	v_permlane16_swap_b32_e32 v56, v57
	s_waitcnt lgkmcnt(0)
	v_mov_b32_e32 v52, v133
	v_mov_b32_e32 v58, v141
	s_nop 1
	v_permlane16_swap_b32_e32 v52, v58
	s_waitcnt lgkmcnt(0)
	v_mov_b32_e32 v53, v134
	v_mov_b32_e32 v59, v142
	s_nop 1
	v_permlane16_swap_b32_e32 v53, v59
	s_waitcnt lgkmcnt(0)
	v_mov_b32_e32 v54, v135
	v_mov_b32_e32 v55, v143
	s_nop 1
	v_permlane16_swap_b32_e32 v54, v55
	v_cvt_pk_bf16_f32 v52, v56, v52
	v_cvt_pk_bf16_f32 v53, v53, v54
	v_cvt_pk_bf16_f32 v54, v57, v58
	v_cvt_pk_bf16_f32 v55, v59, v55
	global_store_dwordx4 v[152:153], v[52:55], off offset:64
